# xor-16 / xor-32 cross-lane sums (row statistics, softmax max and sum) via v_permlane16_swap / v_permlane32_swap instead of ds_bpermute round trips
# speedup vs baseline: 1.0179x; 1.0030x over previous
.LBB0_89:
	s_waitcnt vmcnt(7)
	v_mul_f32_e32 v99, v93, v93
	v_mul_f32_e32 v100, v95, v95
	v_fmac_f32_e32 v99, v92, v92
	v_fmac_f32_e32 v100, v94, v94
	v_add_f32_e32 v99, v99, v100
	s_waitcnt vmcnt(6)
	v_mul_f32_e32 v100, v89, v89
	v_mul_f32_e32 v101, v91, v91
	v_fmac_f32_e32 v100, v88, v88
	v_fmac_f32_e32 v101, v90, v90
	v_add_f32_e32 v100, v100, v101
	v_add_f32_e32 v99, v99, v100
	s_waitcnt vmcnt(5)
	v_mul_f32_e32 v100, v85, v85
	v_mul_f32_e32 v101, v87, v87
	v_fmac_f32_e32 v100, v84, v84
	v_fmac_f32_e32 v101, v86, v86
	v_add_f32_e32 v100, v100, v101
	v_add_f32_e32 v99, v99, v100
	s_waitcnt vmcnt(4)
	v_mul_f32_e32 v100, v77, v77
	v_mul_f32_e32 v101, v79, v79
	v_fmac_f32_e32 v100, v76, v76
	v_fmac_f32_e32 v101, v78, v78
	v_add_f32_e32 v100, v100, v101
	v_add_f32_e32 v99, v99, v100
	s_waitcnt vmcnt(3)
	v_mul_f32_e32 v100, v81, v81
	v_mul_f32_e32 v101, v83, v83
	v_fmac_f32_e32 v100, v80, v80
	v_fmac_f32_e32 v101, v82, v82
	v_add_f32_e32 v100, v100, v101
	v_add_f32_e32 v99, v99, v100
	s_waitcnt vmcnt(2)
	v_mul_f32_e32 v100, v73, v73
	v_mul_f32_e32 v101, v75, v75
	v_fmac_f32_e32 v100, v72, v72
	v_fmac_f32_e32 v101, v74, v74
	v_add_f32_e32 v100, v100, v101
	v_add_f32_e32 v99, v99, v100
	s_waitcnt vmcnt(1)
	v_mul_f32_e32 v100, v69, v69
	v_mul_f32_e32 v101, v71, v71
	v_fmac_f32_e32 v100, v68, v68
	v_fmac_f32_e32 v101, v70, v70
	v_add_f32_e32 v100, v100, v101
	v_add_f32_e32 v99, v99, v100
	s_waitcnt vmcnt(0)
	v_mul_f32_e32 v100, v65, v65
	v_mul_f32_e32 v101, v67, v67
	v_fmac_f32_e32 v100, v64, v64
	v_fmac_f32_e32 v101, v66, v66
	v_add_f32_e32 v100, v100, v101
	v_add_f32_e32 v100, v99, v100
	v_and_b32_e32 v99, 64, v98
	v_add_u32_e32 v104, 64, v99
	v_xor_b32_e32 v99, 1, v98
	v_cmp_lt_i32_e32 vcc, v99, v104
	s_and_b64 s[22:23], s[16:17], exec
	s_cselect_b32 s23, s27, 0
	v_cndmask_b32_e32 v99, v98, v99, vcc
	v_lshlrev_b32_e32 v99, 2, v99
	ds_bpermute_b32 v101, v99, v100
	s_cselect_b32 s22, s26, s0
	s_cselect_b32 s9, s37, s35
	s_cselect_b32 s11, s36, s34
	s_lshl_b64 s[28:29], s[22:23], 12
	s_waitcnt lgkmcnt(0)
	v_add_f32_e32 v101, v100, v101
	v_xor_b32_e32 v100, 2, v98
	v_cmp_lt_i32_e32 vcc, v100, v104
	s_add_u32 s28, s11, s28
	s_addc_u32 s29, s9, s29
	v_cndmask_b32_e32 v100, v98, v100, vcc
	v_lshlrev_b32_e32 v100, 2, v100
	ds_bpermute_b32 v102, v100, v101
	v_cvt_pk_bf16_f32 v92, v92, v93
	v_cvt_pk_bf16_f32 v93, v94, v95
	v_lshl_add_u64 v[94:95], v[96:97], 3, s[28:29]
	global_store_dwordx2 v[94:95], v[92:93], off
	s_waitcnt lgkmcnt(0)
	v_add_f32_e32 v102, v101, v102
	v_xor_b32_e32 v101, 4, v98
	v_cmp_lt_i32_e32 vcc, v101, v104
	v_cvt_pk_bf16_f32 v88, v88, v89
	v_cvt_pk_bf16_f32 v89, v90, v91
	global_store_dwordx2 v[94:95], v[88:89], off offset:512
	v_cvt_pk_bf16_f32 v84, v84, v85
	v_cvt_pk_bf16_f32 v85, v86, v87
	s_nop 0
	v_cndmask_b32_e32 v101, v98, v101, vcc
	v_lshlrev_b32_e32 v101, 2, v101
	ds_bpermute_b32 v103, v101, v102
	global_store_dwordx2 v[94:95], v[84:85], off offset:1024
	v_cvt_pk_bf16_f32 v76, v76, v77
	v_cvt_pk_bf16_f32 v77, v78, v79
	global_store_dwordx2 v[94:95], v[76:77], off offset:1536
	s_waitcnt lgkmcnt(0)
	v_add_f32_e32 v103, v102, v103
	v_xor_b32_e32 v102, 8, v98
	v_cmp_lt_i32_e32 vcc, v102, v104
	v_cvt_pk_bf16_f32 v76, v80, v81
	v_cvt_pk_bf16_f32 v77, v82, v83
	global_store_dwordx2 v[94:95], v[76:77], off offset:2048
	v_cvt_pk_bf16_f32 v72, v72, v73
	v_cvt_pk_bf16_f32 v73, v74, v75
	s_nop 0
	v_cndmask_b32_e32 v102, v98, v102, vcc
	v_lshlrev_b32_e32 v102, 2, v102
	ds_bpermute_b32 v105, v102, v103
	global_store_dwordx2 v[94:95], v[72:73], off offset:2560
	v_cvt_pk_bf16_f32 v68, v68, v69
	v_cvt_pk_bf16_f32 v69, v70, v71
	global_store_dwordx2 v[94:95], v[68:69], off offset:3072
	s_waitcnt lgkmcnt(0)
	v_add_f32_e32 v105, v103, v105
	v_xor_b32_e32 v103, 16, v98
	v_cmp_lt_i32_e32 vcc, v103, v104
	v_cvt_pk_bf16_f32 v64, v64, v65
	v_cvt_pk_bf16_f32 v65, v66, v67
	global_store_dwordx2 v[94:95], v[64:65], off offset:3584
	s_nop 0
	v_cndmask_b32_e32 v103, v98, v103, vcc
	v_lshlrev_b32_e32 v103, 2, v103
	v_mov_b32_e32 v106, v105
	s_nop 1
	v_permlane16_swap_b32_e32 v106, v105
	s_waitcnt lgkmcnt(0)
	v_add_f32_e32 v105, v105, v106
	v_xor_b32_e32 v106, 32, v98
	v_cmp_lt_i32_e32 vcc, v106, v104
	s_nop 1
	v_cndmask_b32_e32 v104, v98, v106, vcc
	v_lshlrev_b32_e32 v104, 2, v104
	ds_bpermute_b32 v106, v104, v105
	s_and_saveexec_b64 s[28:29], s[6:7]
	s_cbranch_execnz .LBB0_92
	s_or_b64 exec, exec, s[28:29]
	s_andn2_b64 vcc, exec, s[18:19]
	s_cbranch_vccz .LBB0_93

.LBB0_93:
	v_mul_f32_e32 v64, v49, v49
	v_mul_f32_e32 v65, v51, v51
	v_fmac_f32_e32 v64, v48, v48
	v_fmac_f32_e32 v65, v50, v50
	v_add_f32_e32 v64, v64, v65
	v_mul_f32_e32 v65, v37, v37
	v_mul_f32_e32 v66, v39, v39
	v_fmac_f32_e32 v65, v36, v36
	v_fmac_f32_e32 v66, v38, v38
	v_add_f32_e32 v65, v65, v66
	v_add_f32_e32 v64, v65, v64
	v_mul_f32_e32 v65, v29, v29
	v_mul_f32_e32 v66, v31, v31
	v_fmac_f32_e32 v65, v28, v28
	v_fmac_f32_e32 v66, v30, v30
	v_add_f32_e32 v65, v65, v66
	v_add_f32_e32 v64, v65, v64
	v_mul_f32_e32 v65, v17, v17
	v_mul_f32_e32 v66, v19, v19
	v_fmac_f32_e32 v65, v16, v16
	v_fmac_f32_e32 v66, v18, v18
	v_add_f32_e32 v65, v65, v66
	v_add_f32_e32 v64, v65, v64
	v_mul_f32_e32 v65, v21, v21
	v_mul_f32_e32 v66, v23, v23
	v_fmac_f32_e32 v65, v20, v20
	v_fmac_f32_e32 v66, v22, v22
	v_add_f32_e32 v65, v65, v66
	v_add_f32_e32 v64, v65, v64
	v_mul_f32_e32 v65, v9, v9
	v_mul_f32_e32 v66, v11, v11
	v_fmac_f32_e32 v65, v8, v8
	v_fmac_f32_e32 v66, v10, v10
	v_add_f32_e32 v65, v65, v66
	v_add_f32_e32 v64, v65, v64
	v_mul_f32_e32 v65, v5, v5
	v_mul_f32_e32 v66, v7, v7
	v_fmac_f32_e32 v65, v4, v4
	v_fmac_f32_e32 v66, v6, v6
	v_add_f32_e32 v65, v65, v66
	v_add_f32_e32 v64, v65, v64
	v_mul_f32_e32 v65, v1, v1
	v_mul_f32_e32 v66, v3, v3
	v_fmac_f32_e32 v65, v0, v0
	v_fmac_f32_e32 v66, v2, v2
	v_add_f32_e32 v65, v65, v66
	v_add_f32_e32 v64, v65, v64
	ds_bpermute_b32 v65, v99, v64
	s_ashr_i32 s9, s10, 31
	s_cmpk_lt_i32 s10, 0x2000
	s_cselect_b64 s[16:17], -1, 0
	s_and_b64 s[18:19], s[16:17], exec
	s_waitcnt lgkmcnt(0)
	v_add_f32_e32 v64, v64, v65
	ds_bpermute_b32 v65, v100, v64
	s_cselect_b32 s9, s9, 0
	s_cselect_b32 s8, s10, s8
	s_cselect_b32 s13, s37, s35
	s_cselect_b32 s15, s36, s34
	s_waitcnt lgkmcnt(0)
	v_add_f32_e32 v64, v64, v65
	ds_bpermute_b32 v65, v101, v64
	s_lshl_b64 s[10:11], s[8:9], 12
	s_add_u32 s10, s15, s10
	s_addc_u32 s11, s13, s11
	v_cvt_pk_bf16_f32 v48, v48, v49
	s_waitcnt lgkmcnt(0)
	v_add_f32_e32 v64, v64, v65
	ds_bpermute_b32 v65, v102, v64
	v_cvt_pk_bf16_f32 v49, v50, v51
	v_lshl_add_u64 v[50:51], v[96:97], 3, s[10:11]
	global_store_dwordx2 v[50:51], v[48:49], off
	v_cvt_pk_bf16_f32 v36, v36, v37
	s_waitcnt lgkmcnt(0)
	v_add_f32_e32 v64, v64, v65
	v_mov_b32_e32 v65, v64
	s_nop 1
	v_permlane16_swap_b32_e32 v65, v64
	v_cvt_pk_bf16_f32 v37, v38, v39
	global_store_dwordx2 v[50:51], v[36:37], off offset:512
	v_cvt_pk_bf16_f32 v28, v28, v29
	v_cvt_pk_bf16_f32 v29, v30, v31
	s_waitcnt lgkmcnt(0)
	v_add_f32_e32 v64, v64, v65
	v_mov_b32_e32 v65, v64
	s_nop 1
	v_permlane32_swap_b32_e32 v65, v64
	global_store_dwordx2 v[50:51], v[28:29], off offset:1024
	v_cvt_pk_bf16_f32 v16, v16, v17
	v_cvt_pk_bf16_f32 v17, v18, v19
	global_store_dwordx2 v[50:51], v[16:17], off offset:1536
	v_cvt_pk_bf16_f32 v16, v20, v21
	v_cvt_pk_bf16_f32 v17, v22, v23
	global_store_dwordx2 v[50:51], v[16:17], off offset:2048
	v_cvt_pk_bf16_f32 v8, v8, v9
	v_cvt_pk_bf16_f32 v9, v10, v11
	global_store_dwordx2 v[50:51], v[8:9], off offset:2560
	v_cvt_pk_bf16_f32 v4, v4, v5
	v_cvt_pk_bf16_f32 v5, v6, v7
	global_store_dwordx2 v[50:51], v[4:5], off offset:3072
	v_cvt_pk_bf16_f32 v0, v0, v1
	v_cvt_pk_bf16_f32 v1, v2, v3
	global_store_dwordx2 v[50:51], v[0:1], off offset:3584
	s_and_saveexec_b64 s[10:11], s[6:7]
	s_cbranch_execz .LBB0_95
	s_and_b64 s[16:17], s[16:17], exec
	s_cselect_b32 s13, s41, s39
	s_cselect_b32 s15, s40, s38
	s_lshl_b64 s[8:9], s[8:9], 8
	s_add_u32 s8, s15, s8
	s_waitcnt lgkmcnt(0)
	v_add_f32_e32 v0, v64, v65
	s_addc_u32 s9, s13, s9
	v_cndmask_b32_e64 v2, 0, v0, s[4:5]
	v_lshl_add_u64 v[0:1], v[96:97], 2, s[8:9]
	global_store_dword v[0:1], v2, off

.LBB0_96:
	v_mul_f32_e32 v0, v61, v61
	v_mul_f32_e32 v1, v63, v63
	v_fmac_f32_e32 v0, v60, v60
	v_fmac_f32_e32 v1, v62, v62
	v_add_f32_e32 v0, v0, v1
	v_mul_f32_e32 v1, v57, v57
	v_mul_f32_e32 v2, v59, v59
	v_fmac_f32_e32 v1, v56, v56
	v_fmac_f32_e32 v2, v58, v58
	v_add_f32_e32 v1, v1, v2
	v_add_f32_e32 v0, v1, v0
	v_mul_f32_e32 v1, v53, v53
	v_mul_f32_e32 v2, v55, v55
	v_fmac_f32_e32 v1, v52, v52
	v_fmac_f32_e32 v2, v54, v54
	v_add_f32_e32 v1, v1, v2
	v_add_f32_e32 v0, v1, v0
	v_mul_f32_e32 v1, v41, v41
	v_mul_f32_e32 v2, v43, v43
	v_fmac_f32_e32 v1, v40, v40
	v_fmac_f32_e32 v2, v42, v42
	v_add_f32_e32 v1, v1, v2
	v_add_f32_e32 v0, v1, v0
	v_mul_f32_e32 v1, v45, v45
	v_mul_f32_e32 v2, v47, v47
	v_fmac_f32_e32 v1, v44, v44
	v_fmac_f32_e32 v2, v46, v46
	v_add_f32_e32 v1, v1, v2
	v_add_f32_e32 v0, v1, v0
	v_mul_f32_e32 v1, v33, v33
	v_mul_f32_e32 v2, v35, v35
	v_fmac_f32_e32 v1, v32, v32
	v_fmac_f32_e32 v2, v34, v34
	v_add_f32_e32 v1, v1, v2
	v_add_f32_e32 v0, v1, v0
	v_mul_f32_e32 v1, v25, v25
	v_mul_f32_e32 v2, v27, v27
	v_fmac_f32_e32 v1, v24, v24
	v_fmac_f32_e32 v2, v26, v26
	v_add_f32_e32 v1, v1, v2
	v_add_f32_e32 v0, v1, v0
	v_mul_f32_e32 v1, v13, v13
	v_mul_f32_e32 v2, v15, v15
	v_fmac_f32_e32 v1, v12, v12
	v_fmac_f32_e32 v2, v14, v14
	v_add_f32_e32 v1, v1, v2
	v_add_f32_e32 v0, v1, v0
	ds_bpermute_b32 v1, v99, v0
	s_ashr_i32 s13, s14, 31
	s_cmpk_lt_i32 s14, 0x2000
	s_cselect_b64 s[8:9], -1, 0
	s_and_b64 s[10:11], s[8:9], exec
	s_waitcnt lgkmcnt(0)
	v_add_f32_e32 v0, v0, v1
	ds_bpermute_b32 v1, v100, v0
	s_cselect_b32 s11, s13, 0
	s_cselect_b32 s10, s14, s12
	s_cselect_b32 s14, s37, s35
	s_cselect_b32 s15, s36, s34
	s_waitcnt lgkmcnt(0)
	v_add_f32_e32 v0, v0, v1
	ds_bpermute_b32 v1, v101, v0
	s_lshl_b64 s[12:13], s[10:11], 12
	s_add_u32 s12, s15, s12
	s_addc_u32 s13, s14, s13
	v_cvt_pk_bf16_f32 v2, v60, v61
	s_waitcnt lgkmcnt(0)
	v_add_f32_e32 v0, v0, v1
	ds_bpermute_b32 v1, v102, v0
	v_cvt_pk_bf16_f32 v3, v62, v63
	v_lshl_add_u64 v[4:5], v[96:97], 3, s[12:13]
	global_store_dwordx2 v[4:5], v[2:3], off
	v_cvt_pk_bf16_f32 v2, v56, v57
	s_waitcnt lgkmcnt(0)
	v_add_f32_e32 v0, v0, v1
	v_mov_b32_e32 v1, v0
	s_nop 1
	v_permlane16_swap_b32_e32 v1, v0
	v_cvt_pk_bf16_f32 v3, v58, v59
	global_store_dwordx2 v[4:5], v[2:3], off offset:512
	v_cvt_pk_bf16_f32 v2, v52, v53
	v_cvt_pk_bf16_f32 v3, v54, v55
	s_waitcnt lgkmcnt(0)
	v_add_f32_e32 v0, v0, v1
	v_mov_b32_e32 v1, v0
	s_nop 1
	v_permlane32_swap_b32_e32 v1, v0
	global_store_dwordx2 v[4:5], v[2:3], off offset:1024
	v_cvt_pk_bf16_f32 v2, v40, v41
	v_cvt_pk_bf16_f32 v3, v42, v43
	global_store_dwordx2 v[4:5], v[2:3], off offset:1536
	v_cvt_pk_bf16_f32 v2, v44, v45
	v_cvt_pk_bf16_f32 v3, v46, v47
	global_store_dwordx2 v[4:5], v[2:3], off offset:2048
	v_cvt_pk_bf16_f32 v2, v32, v33
	v_cvt_pk_bf16_f32 v3, v34, v35
	global_store_dwordx2 v[4:5], v[2:3], off offset:2560
	v_cvt_pk_bf16_f32 v2, v24, v25
	v_cvt_pk_bf16_f32 v3, v26, v27
	global_store_dwordx2 v[4:5], v[2:3], off offset:3072
	v_cvt_pk_bf16_f32 v2, v12, v13
	v_cvt_pk_bf16_f32 v3, v14, v15
	global_store_dwordx2 v[4:5], v[2:3], off offset:3584
	s_and_saveexec_b64 s[12:13], s[6:7]
	s_cbranch_execz .LBB0_71
	s_and_b64 s[8:9], s[8:9], exec
	s_cselect_b32 s14, s41, s39
	s_cselect_b32 s15, s40, s38
	s_lshl_b64 s[8:9], s[10:11], 8
	s_add_u32 s8, s15, s8
	s_waitcnt lgkmcnt(0)
	v_add_f32_e32 v0, v0, v1
	s_addc_u32 s9, s14, s9
	v_cndmask_b32_e64 v2, 0, v0, s[4:5]
	v_lshl_add_u64 v[0:1], v[96:97], 2, s[8:9]
	global_store_dword v[0:1], v2, off
	s_branch .LBB0_71

.LBB0_168:
	s_lshl_b64 s[0:1], s[0:1], 21
	s_add_u32 s0, s94, s0
	s_addc_u32 s1, s95, s1
	s_add_u32 s6, s0, 0x11400000
	s_addc_u32 s7, s1, 0
	s_add_u32 s10, s0, 0x11800000
	s_addc_u32 s11, s1, 0
	s_add_u32 s8, s0, 0x11c00000
	s_addc_u32 s9, s1, 0
	s_add_u32 s12, s94, 0x12400000
	s_addc_u32 s13, s95, 0
	s_lshr_b32 s0, s22, 1
	s_lshl_b32 s1, s21, 8
	v_ashrrev_i32_e32 v128, 4, v144
	s_add_i32 s1, s1, s26
	s_lshl_b32 s0, s0, 8
	v_add_u32_e32 v130, s1, v140
	v_ashrrev_i32_e32 v131, 31, v130
	v_lshlrev_b32_e32 v128, 3, v128
	v_lshlrev_b64 v[132:133], 8, v[130:131]
	v_ashrrev_i32_e32 v129, 31, v128
	v_lshl_add_u64 v[132:133], s[12:13], 0, v[132:133]
	v_lshl_add_u64 v[132:133], v[128:129], 2, v[132:133]
	global_load_dwordx4 v[146:149], v[132:133], off
	global_load_dwordx4 v[150:153], v[132:133], off offset:16
	v_mbcnt_lo_u32_b32 v131, -1, 0
	v_mbcnt_hi_u32_b32 v131, -1, v131
	v_and_b32_e32 v135, 64, v131
	v_xor_b32_e32 v134, 16, v131
	v_add_u32_e32 v135, 64, v135
	v_cmp_lt_i32_e32 vcc, v134, v135
	v_xor_b32_e32 v136, 32, v131
	v_mov_b32_e32 v132, 0x358637bd
	v_cndmask_b32_e32 v134, v131, v134, vcc
	v_cmp_lt_i32_e32 vcc, v136, v135
	v_lshlrev_b32_e32 v137, 2, v134
	v_lshlrev_b32_e32 v142, 1, v130
	v_cndmask_b32_e32 v131, v131, v136, vcc
	v_lshlrev_b32_e32 v136, 2, v131
	v_lshrrev_b32_e32 v131, 2, v140
	s_or_b32 s0, s0, s20
	v_and_b32_e32 v143, 0xe3, v130
	s_movk_i32 s1, 0x7ff
	v_ashrrev_i32_e32 v141, 8, v130
	v_mov_b32_e32 v133, 0
	v_lshlrev_b32_e32 v140, 2, v141
	s_waitcnt vmcnt(0)
	v_mov_b32_e32 v134, v147
	v_mov_b32_e32 v135, v148
	v_mov_b32_e32 v147, v149
	v_mov_b32_e32 v138, v152
	v_mov_b32_e32 v139, v150
	v_mov_b32_e32 v150, v153
	v_pk_add_f32 v[134:135], v[134:135], v[146:147]
	v_pk_add_f32 v[138:139], v[138:139], v[150:151]
	v_add_f32_e32 v134, v134, v135
	v_add_f32_e32 v134, v134, v139
	v_add_f32_e32 v134, v138, v134
	v_mov_b32_e32 v135, v134
	s_nop 1
	v_permlane16_swap_b32_e32 v135, v134
	v_and_b32_e32 v138, 4, v131
	v_add_u32_e32 v131, s0, v128
	v_and_b32_e32 v139, 0xff, v130
	v_cmp_lt_i32_e32 vcc, s1, v131
	s_waitcnt lgkmcnt(0)
	v_add_f32_e32 v134, v134, v135
	ds_bpermute_b32 v135, v136, v134
	s_waitcnt lgkmcnt(0)
	v_add_f32_e32 v134, v134, v135
	v_fmac_f32_e32 v132, 0x3a000000, v134
	v_rsq_f32_e32 v134, v132
	v_and_b32_e32 v132, 24, v142
	v_or3_b32 v132, v143, v132, v138
	v_pk_mul_f32 v[124:125], v[124:125], v[134:135] op_sel_hi:[1,0]
	v_pk_mul_f32 v[142:143], v[122:123], v[134:135] op_sel_hi:[1,0]
	v_pk_mul_f32 v[122:123], v[120:121], v[134:135] op_sel_hi:[1,0]
	v_cvt_pk_bf16_f32 v120, v124, v125
	v_lshlrev_b32_e32 v124, 1, v132
	v_pk_mul_f32 v[126:127], v[126:127], v[134:135] op_sel_hi:[1,0]
	s_nop 0
	v_cvt_pk_bf16_f32 v121, v126, v127
	v_cvt_pk_bf16_f32 v122, v122, v123
	v_cvt_pk_bf16_f32 v123, v142, v143
	s_and_saveexec_b64 s[0:1], vcc
	s_xor_b64 s[0:1], exec, s[0:1]
	s_cbranch_execz .LBB0_170
	v_add_u32_e32 v125, 0xfffff800, v131
	v_lshrrev_b32_e32 v125, 9, v125
	v_add_u32_e32 v125, v125, v140
	v_lshl_or_b32 v126, v125, 8, v139
	v_ashrrev_i32_e32 v127, 31, v126
	v_and_b32_e32 v135, 0x1f8, v131
	v_lshlrev_b64 v[126:127], 10, v[126:127]
	v_lshl_add_u64 v[126:127], s[10:11], 0, v[126:127]
	v_lshlrev_b32_e32 v132, 1, v135
	v_lshl_add_u64 v[126:127], v[126:127], 0, v[132:133]
	global_store_dwordx4 v[126:127], v[120:123], off
	v_lshl_or_b32 v126, v125, 9, v135
	v_ashrrev_i32_e32 v127, 31, v126
	v_lshlrev_b64 v[126:127], 9, v[126:127]
	v_lshl_add_u64 v[126:127], s[8:9], 0, v[126:127]
	v_mov_b32_e32 v125, v133
	v_lshl_add_u64 v[126:127], v[126:127], 0, v[124:125]
	global_store_short v[126:127], v120, off
	global_store_short_d16_hi v[126:127], v120, off offset:512
	global_store_short v[126:127], v121, off offset:1024
	global_store_short_d16_hi v[126:127], v121, off offset:1536
	global_store_short v[126:127], v122, off offset:2048
	global_store_short_d16_hi v[126:127], v122, off offset:2560
	global_store_short v[126:127], v123, off offset:3072
	global_store_short_d16_hi v[126:127], v123, off offset:3584

.LBB0_176:
	s_or_b64 exec, exec, s[0:1]
	v_add_u32_e32 v122, 16, v130
	v_ashrrev_i32_e32 v123, 31, v122
	v_lshlrev_b64 v[112:113], 8, v[122:123]
	v_lshl_add_u64 v[112:113], s[12:13], 0, v[112:113]
	v_lshl_add_u64 v[118:119], v[128:129], 2, v[112:113]
	global_load_dwordx4 v[112:115], v[118:119], off
	s_nop 0
	global_load_dwordx4 v[118:121], v[118:119], off offset:16
	v_and_b32_e32 v123, 0xe3, v122
	s_waitcnt vmcnt(1)
	v_mov_b32_e32 v124, v113
	v_mov_b32_e32 v125, v114
	v_mov_b32_e32 v113, v115
	s_waitcnt vmcnt(0)
	v_mov_b32_e32 v114, v120
	v_mov_b32_e32 v115, v118
	v_mov_b32_e32 v118, v121
	v_pk_add_f32 v[112:113], v[124:125], v[112:113]
	v_pk_add_f32 v[114:115], v[114:115], v[118:119]
	v_add_f32_e32 v112, v112, v113
	v_add_f32_e32 v112, v112, v115
	v_add_f32_e32 v112, v114, v112
	v_mov_b32_e32 v113, v112
	s_nop 1
	v_permlane16_swap_b32_e32 v113, v112
	v_mov_b32_e32 v114, 0x358637bd
	v_ashrrev_i32_e32 v120, 8, v122
	v_and_b32_e32 v118, 0xff, v122
	v_lshlrev_b32_e32 v121, 1, v122
	s_waitcnt lgkmcnt(0)
	v_add_f32_e32 v112, v112, v113
	v_mov_b32_e32 v113, v112
	s_nop 1
	v_permlane32_swap_b32_e32 v113, v112
	v_lshrrev_b32_e32 v122, 2, v122
	v_mov_b32_e32 v115, 0
	v_lshlrev_b32_e32 v119, 2, v120
	s_waitcnt lgkmcnt(0)
	v_add_f32_e32 v112, v112, v113
	v_fmac_f32_e32 v114, 0x3a000000, v112
	v_rsq_f32_e32 v112, v114
	v_and_b32_e32 v113, 24, v121
	v_and_b32_e32 v114, 4, v122
	v_or3_b32 v113, v114, v123, v113
	v_pk_mul_f32 v[108:109], v[108:109], v[112:113] op_sel_hi:[1,0]
	v_pk_mul_f32 v[122:123], v[106:107], v[112:113] op_sel_hi:[1,0]
	v_pk_mul_f32 v[106:107], v[104:105], v[112:113] op_sel_hi:[1,0]
	v_cvt_pk_bf16_f32 v104, v108, v109
	v_lshlrev_b32_e32 v108, 1, v113
	v_pk_mul_f32 v[110:111], v[110:111], v[112:113] op_sel_hi:[1,0]
	s_nop 0
	v_cvt_pk_bf16_f32 v105, v110, v111
	v_cvt_pk_bf16_f32 v106, v106, v107
	v_cvt_pk_bf16_f32 v107, v122, v123
	s_and_saveexec_b64 s[0:1], vcc
	s_xor_b64 s[0:1], exec, s[0:1]
	s_cbranch_execz .LBB0_178
	v_add_u32_e32 v109, 0xfffff800, v131
	v_lshrrev_b32_e32 v109, 9, v109
	v_add_u32_e32 v109, v119, v109
	v_lshl_or_b32 v110, v109, 8, v118
	v_ashrrev_i32_e32 v111, 31, v110
	v_and_b32_e32 v113, 0x1f8, v131
	v_lshlrev_b64 v[110:111], 10, v[110:111]
	v_lshl_add_u64 v[110:111], s[10:11], 0, v[110:111]
	v_lshlrev_b32_e32 v114, 1, v113
	v_lshl_add_u64 v[110:111], v[110:111], 0, v[114:115]
	global_store_dwordx4 v[110:111], v[104:107], off
	v_lshl_or_b32 v110, v109, 9, v113
	v_ashrrev_i32_e32 v111, 31, v110
	v_lshlrev_b64 v[110:111], 9, v[110:111]
	v_lshl_add_u64 v[110:111], s[8:9], 0, v[110:111]
	v_mov_b32_e32 v109, v115
	v_lshl_add_u64 v[110:111], v[110:111], 0, v[108:109]
	global_store_short v[110:111], v104, off
	global_store_short_d16_hi v[110:111], v104, off offset:512
	global_store_short v[110:111], v105, off offset:1024
	global_store_short_d16_hi v[110:111], v105, off offset:1536
	global_store_short v[110:111], v106, off offset:2048
	global_store_short_d16_hi v[110:111], v106, off offset:2560
	global_store_short v[110:111], v107, off offset:3072
	global_store_short_d16_hi v[110:111], v107, off offset:3584

.LBB0_184:
	s_or_b64 exec, exec, s[0:1]
	v_add_u32_e32 v104, 32, v130
	v_ashrrev_i32_e32 v105, 31, v104
	v_lshlrev_b64 v[96:97], 8, v[104:105]
	v_lshl_add_u64 v[96:97], s[12:13], 0, v[96:97]
	v_lshl_add_u64 v[106:107], v[128:129], 2, v[96:97]
	global_load_dwordx4 v[96:99], v[106:107], off
	global_load_dwordx4 v[100:103], v[106:107], off offset:16
	s_waitcnt vmcnt(1)
	v_mov_b32_e32 v106, v97
	v_mov_b32_e32 v107, v98
	v_mov_b32_e32 v97, v99
	s_waitcnt vmcnt(0)
	v_mov_b32_e32 v98, v102
	v_mov_b32_e32 v99, v100
	v_mov_b32_e32 v100, v103
	v_pk_add_f32 v[96:97], v[106:107], v[96:97]
	v_pk_add_f32 v[98:99], v[98:99], v[100:101]
	v_add_f32_e32 v96, v96, v97
	v_add_f32_e32 v96, v96, v99
	v_add_f32_e32 v96, v98, v96
	v_mov_b32_e32 v97, v96
	s_nop 1
	v_permlane16_swap_b32_e32 v97, v96
	v_mov_b32_e32 v98, 0x358637bd
	v_lshlrev_b32_e32 v103, 1, v104
	v_ashrrev_i32_e32 v102, 8, v104
	v_and_b32_e32 v100, 0xff, v104
	s_waitcnt lgkmcnt(0)
	v_add_f32_e32 v96, v96, v97
	v_mov_b32_e32 v97, v96
	s_nop 1
	v_permlane32_swap_b32_e32 v97, v96
	v_and_b32_e32 v104, 0xe3, v104
	v_mov_b32_e32 v99, 0
	v_lshlrev_b32_e32 v101, 2, v102
	s_waitcnt lgkmcnt(0)
	v_add_f32_e32 v96, v96, v97
	v_fmac_f32_e32 v98, 0x3a000000, v96
	v_rsq_f32_e32 v96, v98
	v_and_b32_e32 v97, 24, v103
	v_or3_b32 v97, v104, v97, v138
	v_pk_mul_f32 v[92:93], v[92:93], v[96:97] op_sel_hi:[1,0]
	v_pk_mul_f32 v[104:105], v[90:91], v[96:97] op_sel_hi:[1,0]
	v_pk_mul_f32 v[90:91], v[88:89], v[96:97] op_sel_hi:[1,0]
	v_cvt_pk_bf16_f32 v88, v92, v93
	v_lshlrev_b32_e32 v92, 1, v97
	v_pk_mul_f32 v[94:95], v[94:95], v[96:97] op_sel_hi:[1,0]
	s_nop 0
	v_cvt_pk_bf16_f32 v89, v94, v95
	v_cvt_pk_bf16_f32 v90, v90, v91
	v_cvt_pk_bf16_f32 v91, v104, v105
	s_and_saveexec_b64 s[0:1], vcc
	s_xor_b64 s[0:1], exec, s[0:1]
	s_cbranch_execz .LBB0_186
	v_add_u32_e32 v93, 0xfffff800, v131
	v_lshrrev_b32_e32 v93, 9, v93
	v_add_u32_e32 v93, v101, v93
	v_lshl_or_b32 v94, v93, 8, v100
	v_ashrrev_i32_e32 v95, 31, v94
	v_and_b32_e32 v97, 0x1f8, v131
	v_lshlrev_b64 v[94:95], 10, v[94:95]
	v_lshl_add_u64 v[94:95], s[10:11], 0, v[94:95]
	v_lshlrev_b32_e32 v98, 1, v97
	v_lshl_add_u64 v[94:95], v[94:95], 0, v[98:99]
	global_store_dwordx4 v[94:95], v[88:91], off
	v_lshl_or_b32 v94, v93, 9, v97
	v_ashrrev_i32_e32 v95, 31, v94
	v_lshlrev_b64 v[94:95], 9, v[94:95]
	v_lshl_add_u64 v[94:95], s[8:9], 0, v[94:95]
	v_mov_b32_e32 v93, v99
	v_lshl_add_u64 v[94:95], v[94:95], 0, v[92:93]
	global_store_short v[94:95], v88, off
	global_store_short_d16_hi v[94:95], v88, off offset:512
	global_store_short v[94:95], v89, off offset:1024
	global_store_short_d16_hi v[94:95], v89, off offset:1536
	global_store_short v[94:95], v90, off offset:2048
	global_store_short_d16_hi v[94:95], v90, off offset:2560
	global_store_short v[94:95], v91, off offset:3072
	global_store_short_d16_hi v[94:95], v91, off offset:3584

.LBB0_192:
	s_or_b64 exec, exec, s[0:1]
	v_add_u32_e32 v88, 48, v130
	v_ashrrev_i32_e32 v89, 31, v88
	v_lshlrev_b64 v[80:81], 8, v[88:89]
	v_lshl_add_u64 v[80:81], s[12:13], 0, v[80:81]
	v_lshl_add_u64 v[90:91], v[128:129], 2, v[80:81]
	global_load_dwordx4 v[80:83], v[90:91], off
	global_load_dwordx4 v[84:87], v[90:91], off offset:16
	v_and_b32_e32 v89, 0xe3, v88
	s_waitcnt vmcnt(1)
	v_mov_b32_e32 v90, v81
	v_mov_b32_e32 v91, v82
	v_mov_b32_e32 v81, v83
	s_waitcnt vmcnt(0)
	v_mov_b32_e32 v82, v86
	v_mov_b32_e32 v83, v84
	v_mov_b32_e32 v84, v87
	v_pk_add_f32 v[80:81], v[90:91], v[80:81]
	v_pk_add_f32 v[82:83], v[82:83], v[84:85]
	v_add_f32_e32 v80, v80, v81
	v_add_f32_e32 v80, v80, v83
	v_add_f32_e32 v80, v82, v80
	v_mov_b32_e32 v81, v80
	s_nop 1
	v_permlane16_swap_b32_e32 v81, v80
	v_mov_b32_e32 v82, 0x358637bd
	v_ashrrev_i32_e32 v86, 8, v88
	v_and_b32_e32 v84, 0xff, v88
	v_lshlrev_b32_e32 v87, 1, v88
	s_waitcnt lgkmcnt(0)
	v_add_f32_e32 v80, v80, v81
	v_mov_b32_e32 v81, v80
	s_nop 1
	v_permlane32_swap_b32_e32 v81, v80
	v_lshrrev_b32_e32 v88, 2, v88
	v_mov_b32_e32 v83, 0
	v_lshlrev_b32_e32 v85, 2, v86
	s_waitcnt lgkmcnt(0)
	v_add_f32_e32 v80, v80, v81
	v_fmac_f32_e32 v82, 0x3a000000, v80
	v_rsq_f32_e32 v80, v82
	v_and_b32_e32 v81, 24, v87
	v_and_b32_e32 v82, 4, v88
	v_or3_b32 v81, v82, v89, v81
	v_pk_mul_f32 v[76:77], v[76:77], v[80:81] op_sel_hi:[1,0]
	v_pk_mul_f32 v[88:89], v[74:75], v[80:81] op_sel_hi:[1,0]
	v_pk_mul_f32 v[74:75], v[72:73], v[80:81] op_sel_hi:[1,0]
	v_cvt_pk_bf16_f32 v72, v76, v77
	v_lshlrev_b32_e32 v76, 1, v81
	v_pk_mul_f32 v[78:79], v[78:79], v[80:81] op_sel_hi:[1,0]
	s_nop 0
	v_cvt_pk_bf16_f32 v73, v78, v79
	v_cvt_pk_bf16_f32 v74, v74, v75
	v_cvt_pk_bf16_f32 v75, v88, v89
	s_and_saveexec_b64 s[0:1], vcc
	s_xor_b64 s[0:1], exec, s[0:1]
	s_cbranch_execz .LBB0_194
	v_add_u32_e32 v77, 0xfffff800, v131
	v_lshrrev_b32_e32 v77, 9, v77
	v_add_u32_e32 v77, v85, v77
	v_lshl_or_b32 v78, v77, 8, v84
	v_ashrrev_i32_e32 v79, 31, v78
	v_and_b32_e32 v81, 0x1f8, v131
	v_lshlrev_b64 v[78:79], 10, v[78:79]
	v_lshl_add_u64 v[78:79], s[10:11], 0, v[78:79]
	v_lshlrev_b32_e32 v82, 1, v81
	v_lshl_add_u64 v[78:79], v[78:79], 0, v[82:83]
	global_store_dwordx4 v[78:79], v[72:75], off
	v_lshl_or_b32 v78, v77, 9, v81
	v_ashrrev_i32_e32 v79, 31, v78
	v_lshlrev_b64 v[78:79], 9, v[78:79]
	v_lshl_add_u64 v[78:79], s[8:9], 0, v[78:79]
	v_mov_b32_e32 v77, v83
	v_lshl_add_u64 v[78:79], v[78:79], 0, v[76:77]
	global_store_short v[78:79], v72, off
	global_store_short_d16_hi v[78:79], v72, off offset:512
	global_store_short v[78:79], v73, off offset:1024
	global_store_short_d16_hi v[78:79], v73, off offset:1536
	global_store_short v[78:79], v74, off offset:2048
	global_store_short_d16_hi v[78:79], v74, off offset:2560
	global_store_short v[78:79], v75, off offset:3072
	global_store_short_d16_hi v[78:79], v75, off offset:3584

.LBB0_200:
	s_or_b64 exec, exec, s[0:1]
	v_add_u32_e32 v72, 0x80, v130
	v_ashrrev_i32_e32 v73, 31, v72
	v_lshlrev_b64 v[64:65], 8, v[72:73]
	v_lshl_add_u64 v[64:65], s[12:13], 0, v[64:65]
	v_lshl_add_u64 v[74:75], v[128:129], 2, v[64:65]
	global_load_dwordx4 v[64:67], v[74:75], off
	global_load_dwordx4 v[68:71], v[74:75], off offset:16
	s_waitcnt vmcnt(1)
	v_mov_b32_e32 v74, v65
	v_mov_b32_e32 v75, v66
	v_mov_b32_e32 v65, v67
	s_waitcnt vmcnt(0)
	v_mov_b32_e32 v66, v70
	v_mov_b32_e32 v67, v68
	v_mov_b32_e32 v68, v71
	v_pk_add_f32 v[64:65], v[74:75], v[64:65]
	v_pk_add_f32 v[66:67], v[66:67], v[68:69]
	v_add_f32_e32 v64, v64, v65
	v_add_f32_e32 v64, v64, v67
	v_add_f32_e32 v64, v66, v64
	v_mov_b32_e32 v65, v64
	s_nop 1
	v_permlane16_swap_b32_e32 v65, v64
	v_mov_b32_e32 v66, 0x358637bd
	v_lshlrev_b32_e32 v71, 1, v72
	v_ashrrev_i32_e32 v70, 8, v72
	v_and_b32_e32 v68, 0xff, v72
	s_waitcnt lgkmcnt(0)
	v_add_f32_e32 v64, v64, v65
	v_mov_b32_e32 v65, v64
	s_nop 1
	v_permlane32_swap_b32_e32 v65, v64
	v_and_b32_e32 v72, 0xe3, v72
	v_mov_b32_e32 v67, 0
	v_lshlrev_b32_e32 v69, 2, v70
	s_waitcnt lgkmcnt(0)
	v_add_f32_e32 v64, v64, v65
	v_fmac_f32_e32 v66, 0x3a000000, v64
	v_rsq_f32_e32 v64, v66
	v_and_b32_e32 v65, 24, v71
	v_or3_b32 v65, v72, v65, v138
	v_pk_mul_f32 v[60:61], v[60:61], v[64:65] op_sel_hi:[1,0]
	v_pk_mul_f32 v[72:73], v[58:59], v[64:65] op_sel_hi:[1,0]
	v_pk_mul_f32 v[58:59], v[56:57], v[64:65] op_sel_hi:[1,0]
	v_cvt_pk_bf16_f32 v56, v60, v61
	v_lshlrev_b32_e32 v60, 1, v65
	v_pk_mul_f32 v[62:63], v[62:63], v[64:65] op_sel_hi:[1,0]
	s_nop 0
	v_cvt_pk_bf16_f32 v57, v62, v63
	v_cvt_pk_bf16_f32 v58, v58, v59
	v_cvt_pk_bf16_f32 v59, v72, v73
	s_and_saveexec_b64 s[0:1], vcc
	s_xor_b64 s[0:1], exec, s[0:1]
	s_cbranch_execz .LBB0_202
	v_add_u32_e32 v61, 0xfffff800, v131
	v_lshrrev_b32_e32 v61, 9, v61
	v_add_u32_e32 v61, v69, v61
	v_lshl_or_b32 v62, v61, 8, v68
	v_ashrrev_i32_e32 v63, 31, v62
	v_and_b32_e32 v65, 0x1f8, v131
	v_lshlrev_b64 v[62:63], 10, v[62:63]
	v_lshl_add_u64 v[62:63], s[10:11], 0, v[62:63]
	v_lshlrev_b32_e32 v66, 1, v65
	v_lshl_add_u64 v[62:63], v[62:63], 0, v[66:67]
	global_store_dwordx4 v[62:63], v[56:59], off
	v_lshl_or_b32 v62, v61, 9, v65
	v_ashrrev_i32_e32 v63, 31, v62
	v_lshlrev_b64 v[62:63], 9, v[62:63]
	v_lshl_add_u64 v[62:63], s[8:9], 0, v[62:63]
	v_mov_b32_e32 v61, v67
	v_lshl_add_u64 v[62:63], v[62:63], 0, v[60:61]
	global_store_short v[62:63], v56, off
	global_store_short_d16_hi v[62:63], v56, off offset:512
	global_store_short v[62:63], v57, off offset:1024
	global_store_short_d16_hi v[62:63], v57, off offset:1536
	global_store_short v[62:63], v58, off offset:2048
	global_store_short_d16_hi v[62:63], v58, off offset:2560
	global_store_short v[62:63], v59, off offset:3072
	global_store_short_d16_hi v[62:63], v59, off offset:3584

.LBB0_208:
	s_or_b64 exec, exec, s[0:1]
	v_add_u32_e32 v56, 0x90, v130
	v_ashrrev_i32_e32 v57, 31, v56
	v_lshlrev_b64 v[48:49], 8, v[56:57]
	v_lshl_add_u64 v[48:49], s[12:13], 0, v[48:49]
	v_lshl_add_u64 v[58:59], v[128:129], 2, v[48:49]
	global_load_dwordx4 v[48:51], v[58:59], off
	global_load_dwordx4 v[52:55], v[58:59], off offset:16
	v_and_b32_e32 v57, 0xe3, v56
	s_waitcnt vmcnt(1)
	v_mov_b32_e32 v58, v49
	v_mov_b32_e32 v59, v50
	v_mov_b32_e32 v49, v51
	s_waitcnt vmcnt(0)
	v_mov_b32_e32 v50, v54
	v_mov_b32_e32 v51, v52
	v_mov_b32_e32 v52, v55
	v_pk_add_f32 v[48:49], v[58:59], v[48:49]
	v_pk_add_f32 v[50:51], v[50:51], v[52:53]
	v_add_f32_e32 v48, v48, v49
	v_add_f32_e32 v48, v48, v51
	v_add_f32_e32 v48, v50, v48
	v_mov_b32_e32 v49, v48
	s_nop 1
	v_permlane16_swap_b32_e32 v49, v48
	v_mov_b32_e32 v50, 0x358637bd
	v_ashrrev_i32_e32 v54, 8, v56
	v_and_b32_e32 v52, 0xff, v56
	v_lshlrev_b32_e32 v55, 1, v56
	s_waitcnt lgkmcnt(0)
	v_add_f32_e32 v48, v48, v49
	v_mov_b32_e32 v49, v48
	s_nop 1
	v_permlane32_swap_b32_e32 v49, v48
	v_lshrrev_b32_e32 v56, 2, v56
	v_mov_b32_e32 v51, 0
	v_lshlrev_b32_e32 v53, 2, v54
	s_waitcnt lgkmcnt(0)
	v_add_f32_e32 v48, v48, v49
	v_fmac_f32_e32 v50, 0x3a000000, v48
	v_rsq_f32_e32 v48, v50
	v_and_b32_e32 v49, 24, v55
	v_and_b32_e32 v50, 4, v56
	v_or3_b32 v49, v50, v57, v49
	v_pk_mul_f32 v[44:45], v[44:45], v[48:49] op_sel_hi:[1,0]
	v_pk_mul_f32 v[56:57], v[42:43], v[48:49] op_sel_hi:[1,0]
	v_pk_mul_f32 v[42:43], v[40:41], v[48:49] op_sel_hi:[1,0]
	v_cvt_pk_bf16_f32 v40, v44, v45
	v_lshlrev_b32_e32 v44, 1, v49
	v_pk_mul_f32 v[46:47], v[46:47], v[48:49] op_sel_hi:[1,0]
	s_nop 0
	v_cvt_pk_bf16_f32 v41, v46, v47
	v_cvt_pk_bf16_f32 v42, v42, v43
	v_cvt_pk_bf16_f32 v43, v56, v57
	s_and_saveexec_b64 s[0:1], vcc
	s_xor_b64 s[0:1], exec, s[0:1]
	s_cbranch_execz .LBB0_210
	v_add_u32_e32 v45, 0xfffff800, v131
	v_lshrrev_b32_e32 v45, 9, v45
	v_add_u32_e32 v45, v53, v45
	v_lshl_or_b32 v46, v45, 8, v52
	v_ashrrev_i32_e32 v47, 31, v46
	v_and_b32_e32 v49, 0x1f8, v131
	v_lshlrev_b64 v[46:47], 10, v[46:47]
	v_lshl_add_u64 v[46:47], s[10:11], 0, v[46:47]
	v_lshlrev_b32_e32 v50, 1, v49
	v_lshl_add_u64 v[46:47], v[46:47], 0, v[50:51]
	global_store_dwordx4 v[46:47], v[40:43], off
	v_lshl_or_b32 v46, v45, 9, v49
	v_ashrrev_i32_e32 v47, 31, v46
	v_lshlrev_b64 v[46:47], 9, v[46:47]
	v_lshl_add_u64 v[46:47], s[8:9], 0, v[46:47]
	v_mov_b32_e32 v45, v51
	v_lshl_add_u64 v[46:47], v[46:47], 0, v[44:45]
	global_store_short v[46:47], v40, off
	global_store_short_d16_hi v[46:47], v40, off offset:512
	global_store_short v[46:47], v41, off offset:1024
	global_store_short_d16_hi v[46:47], v41, off offset:1536
	global_store_short v[46:47], v42, off offset:2048
	global_store_short_d16_hi v[46:47], v42, off offset:2560
	global_store_short v[46:47], v43, off offset:3072
	global_store_short_d16_hi v[46:47], v43, off offset:3584

.LBB0_216:
	s_or_b64 exec, exec, s[0:1]
	v_add_u32_e32 v40, 0xa0, v130
	v_ashrrev_i32_e32 v41, 31, v40
	v_lshlrev_b64 v[32:33], 8, v[40:41]
	v_lshl_add_u64 v[32:33], s[12:13], 0, v[32:33]
	v_lshl_add_u64 v[42:43], v[128:129], 2, v[32:33]
	global_load_dwordx4 v[32:35], v[42:43], off
	global_load_dwordx4 v[36:39], v[42:43], off offset:16
	s_waitcnt vmcnt(1)
	v_mov_b32_e32 v42, v33
	v_mov_b32_e32 v43, v34
	v_mov_b32_e32 v33, v35
	s_waitcnt vmcnt(0)
	v_mov_b32_e32 v34, v38
	v_mov_b32_e32 v35, v36
	v_mov_b32_e32 v36, v39
	v_pk_add_f32 v[32:33], v[42:43], v[32:33]
	v_pk_add_f32 v[34:35], v[34:35], v[36:37]
	v_add_f32_e32 v32, v32, v33
	v_add_f32_e32 v32, v32, v35
	v_add_f32_e32 v32, v34, v32
	v_mov_b32_e32 v33, v32
	s_nop 1
	v_permlane16_swap_b32_e32 v33, v32
	v_mov_b32_e32 v34, 0x358637bd
	v_lshlrev_b32_e32 v39, 1, v40
	v_ashrrev_i32_e32 v38, 8, v40
	v_and_b32_e32 v36, 0xff, v40
	s_waitcnt lgkmcnt(0)
	v_add_f32_e32 v32, v32, v33
	v_mov_b32_e32 v33, v32
	s_nop 1
	v_permlane32_swap_b32_e32 v33, v32
	v_and_b32_e32 v40, 0xe3, v40
	v_mov_b32_e32 v35, 0
	v_lshlrev_b32_e32 v37, 2, v38
	s_waitcnt lgkmcnt(0)
	v_add_f32_e32 v32, v32, v33
	v_fmac_f32_e32 v34, 0x3a000000, v32
	v_rsq_f32_e32 v32, v34
	v_and_b32_e32 v33, 24, v39
	v_or3_b32 v33, v40, v33, v138
	v_pk_mul_f32 v[28:29], v[28:29], v[32:33] op_sel_hi:[1,0]
	v_pk_mul_f32 v[40:41], v[26:27], v[32:33] op_sel_hi:[1,0]
	v_pk_mul_f32 v[26:27], v[24:25], v[32:33] op_sel_hi:[1,0]
	v_cvt_pk_bf16_f32 v24, v28, v29
	v_lshlrev_b32_e32 v28, 1, v33
	v_pk_mul_f32 v[30:31], v[30:31], v[32:33] op_sel_hi:[1,0]
	s_nop 0
	v_cvt_pk_bf16_f32 v25, v30, v31
	v_cvt_pk_bf16_f32 v26, v26, v27
	v_cvt_pk_bf16_f32 v27, v40, v41
	s_and_saveexec_b64 s[0:1], vcc
	s_xor_b64 s[0:1], exec, s[0:1]
	s_cbranch_execz .LBB0_218
	v_add_u32_e32 v29, 0xfffff800, v131
	v_lshrrev_b32_e32 v29, 9, v29
	v_add_u32_e32 v29, v37, v29
	v_lshl_or_b32 v30, v29, 8, v36
	v_ashrrev_i32_e32 v31, 31, v30
	v_and_b32_e32 v33, 0x1f8, v131
	v_lshlrev_b64 v[30:31], 10, v[30:31]
	v_lshl_add_u64 v[30:31], s[10:11], 0, v[30:31]
	v_lshlrev_b32_e32 v34, 1, v33
	v_lshl_add_u64 v[30:31], v[30:31], 0, v[34:35]
	global_store_dwordx4 v[30:31], v[24:27], off
	v_lshl_or_b32 v30, v29, 9, v33
	v_ashrrev_i32_e32 v31, 31, v30
	v_lshlrev_b64 v[30:31], 9, v[30:31]
	v_lshl_add_u64 v[30:31], s[8:9], 0, v[30:31]
	v_mov_b32_e32 v29, v35
	v_lshl_add_u64 v[30:31], v[30:31], 0, v[28:29]
	global_store_short v[30:31], v24, off
	global_store_short_d16_hi v[30:31], v24, off offset:512
	global_store_short v[30:31], v25, off offset:1024
	global_store_short_d16_hi v[30:31], v25, off offset:1536
	global_store_short v[30:31], v26, off offset:2048
	global_store_short_d16_hi v[30:31], v26, off offset:2560
	global_store_short v[30:31], v27, off offset:3072
	global_store_short_d16_hi v[30:31], v27, off offset:3584

.LBB0_224:
	s_or_b64 exec, exec, s[0:1]
	v_add_u32_e32 v24, 0xb0, v130
	v_ashrrev_i32_e32 v25, 31, v24
	v_lshlrev_b64 v[16:17], 8, v[24:25]
	v_lshl_add_u64 v[16:17], s[12:13], 0, v[16:17]
	v_lshl_add_u64 v[26:27], v[128:129], 2, v[16:17]
	global_load_dwordx4 v[16:19], v[26:27], off
	global_load_dwordx4 v[20:23], v[26:27], off offset:16
	v_and_b32_e32 v25, 0xe3, v24
	s_waitcnt vmcnt(1)
	v_mov_b32_e32 v26, v17
	v_mov_b32_e32 v27, v18
	v_mov_b32_e32 v17, v19
	s_waitcnt vmcnt(0)
	v_mov_b32_e32 v18, v22
	v_mov_b32_e32 v19, v20
	v_mov_b32_e32 v20, v23
	v_pk_add_f32 v[16:17], v[26:27], v[16:17]
	v_pk_add_f32 v[18:19], v[18:19], v[20:21]
	v_add_f32_e32 v16, v16, v17
	v_add_f32_e32 v16, v16, v19
	v_add_f32_e32 v16, v18, v16
	v_mov_b32_e32 v17, v16
	s_nop 1
	v_permlane16_swap_b32_e32 v17, v16
	v_mov_b32_e32 v18, 0x358637bd
	v_ashrrev_i32_e32 v22, 8, v24
	v_and_b32_e32 v20, 0xff, v24
	v_lshlrev_b32_e32 v23, 1, v24
	s_waitcnt lgkmcnt(0)
	v_add_f32_e32 v16, v16, v17
	v_mov_b32_e32 v17, v16
	s_nop 1
	v_permlane32_swap_b32_e32 v17, v16
	v_lshrrev_b32_e32 v24, 2, v24
	v_mov_b32_e32 v19, 0
	v_lshlrev_b32_e32 v21, 2, v22
	s_waitcnt lgkmcnt(0)
	v_add_f32_e32 v16, v16, v17
	v_fmac_f32_e32 v18, 0x3a000000, v16
	v_rsq_f32_e32 v16, v18
	v_and_b32_e32 v17, 24, v23
	v_and_b32_e32 v18, 4, v24
	v_or3_b32 v17, v18, v25, v17
	v_pk_mul_f32 v[12:13], v[12:13], v[16:17] op_sel_hi:[1,0]
	v_pk_mul_f32 v[24:25], v[10:11], v[16:17] op_sel_hi:[1,0]
	v_pk_mul_f32 v[10:11], v[8:9], v[16:17] op_sel_hi:[1,0]
	v_cvt_pk_bf16_f32 v8, v12, v13
	v_lshlrev_b32_e32 v12, 1, v17
	v_pk_mul_f32 v[14:15], v[14:15], v[16:17] op_sel_hi:[1,0]
	s_nop 0
	v_cvt_pk_bf16_f32 v9, v14, v15
	v_cvt_pk_bf16_f32 v10, v10, v11
	v_cvt_pk_bf16_f32 v11, v24, v25
	s_and_saveexec_b64 s[0:1], vcc
	s_xor_b64 s[0:1], exec, s[0:1]
	s_cbranch_execz .LBB0_226
	v_add_u32_e32 v13, 0xfffff800, v131
	v_lshrrev_b32_e32 v13, 9, v13
	v_add_u32_e32 v13, v21, v13
	v_lshl_or_b32 v14, v13, 8, v20
	v_ashrrev_i32_e32 v15, 31, v14
	v_and_b32_e32 v17, 0x1f8, v131
	v_lshlrev_b64 v[14:15], 10, v[14:15]
	v_lshl_add_u64 v[14:15], s[10:11], 0, v[14:15]
	v_lshlrev_b32_e32 v18, 1, v17
	v_lshl_add_u64 v[14:15], v[14:15], 0, v[18:19]
	global_store_dwordx4 v[14:15], v[8:11], off
	v_lshl_or_b32 v14, v13, 9, v17
	v_ashrrev_i32_e32 v15, 31, v14
	v_lshlrev_b64 v[14:15], 9, v[14:15]
	v_lshl_add_u64 v[14:15], s[8:9], 0, v[14:15]
	v_mov_b32_e32 v13, v19
	v_lshl_add_u64 v[14:15], v[14:15], 0, v[12:13]
	global_store_short v[14:15], v8, off
	global_store_short_d16_hi v[14:15], v8, off offset:512
	global_store_short v[14:15], v9, off offset:1024
	global_store_short_d16_hi v[14:15], v9, off offset:1536
	global_store_short v[14:15], v10, off offset:2048
	global_store_short_d16_hi v[14:15], v10, off offset:2560
	global_store_short v[14:15], v11, off offset:3072
	global_store_short_d16_hi v[14:15], v11, off offset:3584

.LBB0_658:
	s_mov_b32 s0, s38
	s_lshl_b32 s0, s0, 8
	v_mov_b32_e32 v132, v228
	v_mov_b32_e32 v120, v229
	s_add_i32 s0, s0, s44
	s_nop 0
	v_add_u32_e32 v226, s0, v120
	s_lshl_b32 s0, s20, 8
	s_or_b32 s0, s0, s45
	v_lshl_add_u32 v196, v132, 3, s0
	v_ashrrev_i32_e32 v197, 31, v196
	v_lshlrev_b64 v[244:245], 1, v[196:197]
	v_ashrrev_i32_e32 v227, 31, v226
	v_lshl_add_u64 v[120:121], s[14:15], 0, v[244:245]
	v_lshlrev_b64 v[246:247], 12, v[226:227]
	v_lshl_add_u64 v[122:123], v[120:121], 0, v[246:247]
	global_load_dwordx4 v[236:239], v[122:123], off
	global_load_dwordx4 v[240:243], v[122:123], off offset:256
	v_add_u32_e32 v222, 16, v226
	v_add_u32_e32 v218, 32, v226
	v_add_u32_e32 v214, 48, v226
	v_add_u32_e32 v210, 0x80, v226
	v_add_u32_e32 v206, 0x90, v226
	v_add_u32_e32 v202, 0xa0, v226
	v_add_u32_e32 v198, 0xb0, v226
	v_ashrrev_i32_e32 v223, 31, v222
	v_ashrrev_i32_e32 v219, 31, v218
	v_ashrrev_i32_e32 v215, 31, v214
	v_ashrrev_i32_e32 v211, 31, v210
	v_ashrrev_i32_e32 v207, 31, v206
	v_ashrrev_i32_e32 v203, 31, v202
	v_ashrrev_i32_e32 v199, 31, v198
	v_lshlrev_b64 v[224:225], 12, v[222:223]
	v_lshlrev_b64 v[220:221], 12, v[218:219]
	v_lshlrev_b64 v[216:217], 12, v[214:215]
	v_lshlrev_b64 v[212:213], 12, v[210:211]
	v_lshlrev_b64 v[208:209], 12, v[206:207]
	v_lshlrev_b64 v[204:205], 12, v[202:203]
	v_lshlrev_b64 v[200:201], 12, v[198:199]
	v_cmp_eq_u32_e32 vcc, 0, v132
	v_lshl_add_u64 v[122:123], v[120:121], 0, v[224:225]
	v_lshl_add_u64 v[132:133], v[120:121], 0, v[220:221]
	v_lshl_add_u64 v[134:135], v[120:121], 0, v[216:217]
	v_lshl_add_u64 v[136:137], v[120:121], 0, v[212:213]
	v_lshl_add_u64 v[138:139], v[120:121], 0, v[208:209]
	v_lshl_add_u64 v[248:249], v[120:121], 0, v[204:205]
	v_lshl_add_u64 v[120:121], v[120:121], 0, v[200:201]
	global_load_dwordx4 v[180:183], v[122:123], off
	global_load_dwordx4 v[176:179], v[122:123], off offset:256
	global_load_dwordx4 v[172:175], v[132:133], off
	global_load_dwordx4 v[168:171], v[132:133], off offset:256
	global_load_dwordx4 v[164:167], v[134:135], off
	global_load_dwordx4 v[160:163], v[134:135], off offset:256
	global_load_dwordx4 v[156:159], v[136:137], off
	global_load_dwordx4 v[152:155], v[136:137], off offset:256
	global_load_dwordx4 v[148:151], v[138:139], off
	global_load_dwordx4 v[144:147], v[138:139], off offset:256
	global_load_dwordx4 v[140:143], v[248:249], off
	s_nop 0
	global_load_dwordx4 v[136:139], v[248:249], off offset:256
	global_load_dwordx4 v[132:135], v[120:121], off
	s_nop 0
	global_load_dwordx4 v[120:123], v[120:121], off offset:256
	s_lshl_b32 s0, s20, 2
	s_ashr_i32 s1, s0, 31
	s_waitcnt vmcnt(0)
	v_lshlrev_b32_e32 v248, 16, v236
	v_and_b32_e32 v236, 0xffff0000, v236
	v_lshlrev_b32_e32 v250, 16, v238
	v_lshlrev_b32_e32 v251, 16, v239
	v_and_b32_e32 v239, 0xffff0000, v239
	v_add_f32_e32 v129, v129, v236
	v_add_f32_e32 v128, v128, v248
	v_add_f32_e32 v236, v124, v250
	v_add_f32_e32 v127, v127, v239
	v_mul_f32_e32 v239, v129, v129
	v_cvt_pk_bf16_f32 v124, v128, v129
	v_lshlrev_b32_e32 v129, 16, v240
	v_add_f32_e32 v116, v116, v129
	v_and_b32_e32 v129, 0xffff0000, v240
	v_lshlrev_b32_e32 v249, 16, v237
	v_and_b32_e32 v237, 0xffff0000, v237
	v_add_f32_e32 v117, v117, v129
	v_lshlrev_b32_e32 v129, 16, v241
	v_add_f32_e32 v131, v131, v237
	v_add_f32_e32 v118, v118, v129
	v_and_b32_e32 v129, 0xffff0000, v241
	v_and_b32_e32 v238, 0xffff0000, v238
	v_add_f32_e32 v130, v130, v249
	v_mul_f32_e32 v248, v131, v131
	v_add_f32_e32 v119, v119, v129
	v_lshlrev_b32_e32 v129, 16, v242
	v_add_f32_e32 v237, v125, v238
	v_cvt_pk_bf16_f32 v125, v130, v131
	v_fmac_f32_e32 v248, v130, v130
	v_add_f32_e32 v130, v112, v129
	v_and_b32_e32 v112, 0xffff0000, v242
	v_mul_f32_e32 v249, v237, v237
	v_add_f32_e32 v131, v113, v112
	v_lshlrev_b32_e32 v112, 16, v243
	v_add_f32_e32 v238, v126, v251
	v_cvt_pk_bf16_f32 v126, v236, v237
	v_fmac_f32_e32 v249, v236, v236
	v_add_f32_e32 v236, v114, v112
	v_and_b32_e32 v112, 0xffff0000, v243
	v_add_f32_e32 v237, v115, v112
	v_mul_f32_e32 v112, v117, v117
	v_mul_f32_e32 v113, v119, v119
	v_fmac_f32_e32 v112, v116, v116
	v_fmac_f32_e32 v113, v118, v118
	v_add_f32_e32 v112, v112, v113
	v_mul_f32_e32 v113, v131, v131
	v_fmac_f32_e32 v239, v128, v128
	v_fmac_f32_e32 v113, v130, v130
	v_mul_f32_e32 v250, v127, v127
	v_add_f32_e32 v128, v239, v248
	v_add_f32_e32 v112, v113, v112
	v_mul_f32_e32 v113, v237, v237
	v_fmac_f32_e32 v250, v238, v238
	v_add_f32_e32 v128, v249, v128
	v_fmac_f32_e32 v113, v236, v236
	v_add_f32_e32 v128, v250, v128
	v_add_f32_e32 v112, v113, v112
	v_and_b32_e32 v114, 64, v233
	v_cvt_pk_bf16_f32 v127, v238, v127
	v_add_f32_e32 v113, v128, v112
	v_xor_b32_e32 v112, 16, v233
	v_add_u32_e32 v238, 64, v114
	v_cmp_lt_i32_e64 s[2:3], v112, v238
	v_lshl_add_u64 v[114:115], s[14:15], 0, v[246:247]
	v_lshl_add_u64 v[128:129], v[114:115], 0, v[244:245]
	v_cndmask_b32_e64 v112, v233, v112, s[2:3]
	v_lshlrev_b32_e32 v112, 2, v112
	v_mov_b32_e32 v239, v113
	s_nop 1
	v_permlane16_swap_b32_e32 v239, v113
	global_store_dwordx4 v[128:129], v[124:127], off
	v_cvt_pk_bf16_f32 v116, v116, v117
	v_cvt_pk_bf16_f32 v117, v118, v119
	v_cvt_pk_bf16_f32 v118, v130, v131
	s_waitcnt lgkmcnt(0)
	v_add_f32_e32 v114, v113, v239
	v_xor_b32_e32 v113, 32, v233
	v_cmp_lt_i32_e64 s[2:3], v113, v238
	v_cvt_pk_bf16_f32 v119, v236, v237
	global_store_dwordx4 v[128:129], v[116:119], off offset:256
	s_nop 0
	v_cndmask_b32_e64 v113, v233, v113, s[2:3]
	v_lshlrev_b32_e32 v113, 2, v113
	v_mov_b32_e32 v115, v114
	s_nop 1
	v_permlane32_swap_b32_e32 v115, v114
	s_and_saveexec_b64 s[2:3], vcc
	s_cbranch_execz .LBB0_660
	v_lshlrev_b64 v[116:117], 8, v[226:227]
	v_lshl_add_u64 v[116:117], s[16:17], 0, v[116:117]
	v_lshl_add_u64 v[116:117], s[0:1], 2, v[116:117]
	s_lshl_b32 s20, s43, 2
	v_lshl_add_u64 v[116:117], v[116:117], 0, s[20:21]
	s_waitcnt lgkmcnt(0)
	v_add_f32_e32 v114, v114, v115
	global_store_dword v[116:117], v114, off
.LBB0_660:
	s_or_b64 exec, exec, s[2:3]
	v_lshlrev_b32_e32 v114, 16, v180
	v_add_f32_e32 v108, v108, v114
	v_and_b32_e32 v114, 0xffff0000, v180
	v_add_f32_e32 v109, v109, v114
	v_lshlrev_b32_e32 v114, 16, v181
	v_add_f32_e32 v110, v110, v114
	v_and_b32_e32 v114, 0xffff0000, v181
	v_add_f32_e32 v111, v111, v114
	v_lshlrev_b32_e32 v114, 16, v182
	v_add_f32_e32 v114, v104, v114
	v_and_b32_e32 v104, 0xffff0000, v182
	s_waitcnt lgkmcnt(0)
	v_add_f32_e32 v115, v105, v104
	v_lshlrev_b32_e32 v104, 16, v183
	v_add_f32_e32 v116, v106, v104
	v_and_b32_e32 v104, 0xffff0000, v183
	v_add_f32_e32 v107, v107, v104
	v_mul_f32_e32 v104, v109, v109
	v_mul_f32_e32 v105, v111, v111
	v_fmac_f32_e32 v104, v108, v108
	v_fmac_f32_e32 v105, v110, v110
	v_add_f32_e32 v104, v104, v105
	v_mul_f32_e32 v105, v115, v115
	v_fmac_f32_e32 v105, v114, v114
	v_add_f32_e32 v104, v105, v104
	v_mul_f32_e32 v105, v107, v107
	v_fmac_f32_e32 v105, v116, v116
	v_add_f32_e32 v117, v105, v104
	v_cvt_pk_bf16_f32 v104, v108, v109
	v_lshlrev_b32_e32 v108, 16, v176
	v_add_f32_e32 v100, v100, v108
	v_and_b32_e32 v108, 0xffff0000, v176
	v_add_f32_e32 v101, v101, v108
	v_lshlrev_b32_e32 v108, 16, v177
	v_add_f32_e32 v108, v102, v108
	v_and_b32_e32 v102, 0xffff0000, v177
	v_add_f32_e32 v109, v103, v102
	v_lshlrev_b32_e32 v102, 16, v178
	v_cvt_pk_bf16_f32 v105, v110, v111
	v_add_f32_e32 v110, v96, v102
	v_and_b32_e32 v96, 0xffff0000, v178
	v_add_f32_e32 v111, v97, v96
	v_lshlrev_b32_e32 v96, 16, v179
	v_cvt_pk_bf16_f32 v106, v114, v115
	v_add_f32_e32 v114, v98, v96
	v_and_b32_e32 v96, 0xffff0000, v179
	v_add_f32_e32 v115, v99, v96
	v_mul_f32_e32 v96, v101, v101
	v_mul_f32_e32 v97, v109, v109
	v_fmac_f32_e32 v96, v100, v100
	v_fmac_f32_e32 v97, v108, v108
	v_add_f32_e32 v96, v96, v97
	v_mul_f32_e32 v97, v111, v111
	v_fmac_f32_e32 v97, v110, v110
	v_add_f32_e32 v96, v97, v96
	v_mul_f32_e32 v97, v115, v115
	v_fmac_f32_e32 v97, v114, v114
	v_add_f32_e32 v96, v97, v96
	v_add_f32_e32 v99, v117, v96
	v_cvt_pk_bf16_f32 v107, v116, v107
	v_mov_b32_e32 v116, v99
	s_nop 1
	v_permlane16_swap_b32_e32 v116, v99
	v_lshl_add_u64 v[96:97], s[14:15], 0, v[224:225]
	v_lshl_add_u64 v[102:103], v[196:197], 1, v[96:97]
	global_store_dwordx4 v[102:103], v[104:107], off
	v_cvt_pk_bf16_f32 v98, v100, v101
	s_waitcnt lgkmcnt(0)
	v_add_f32_e32 v96, v99, v116
	v_mov_b32_e32 v97, v96
	s_nop 1
	v_permlane32_swap_b32_e32 v97, v96
	v_cvt_pk_bf16_f32 v99, v108, v109
	v_cvt_pk_bf16_f32 v100, v110, v111
	v_cvt_pk_bf16_f32 v101, v114, v115
	global_store_dwordx4 v[102:103], v[98:101], off offset:256
	s_and_saveexec_b64 s[2:3], vcc
	s_cbranch_execz .LBB0_662
	v_lshlrev_b64 v[98:99], 8, v[222:223]
	v_lshl_add_u64 v[98:99], s[16:17], 0, v[98:99]
	v_lshl_add_u64 v[98:99], s[0:1], 2, v[98:99]
	s_lshl_b32 s20, s43, 2
	v_lshl_add_u64 v[98:99], v[98:99], 0, s[20:21]
	s_waitcnt lgkmcnt(0)
	v_add_f32_e32 v96, v96, v97
	global_store_dword v[98:99], v96, off
.LBB0_662:
	s_or_b64 exec, exec, s[2:3]
	v_lshlrev_b32_e32 v96, 16, v172
	v_add_f32_e32 v92, v92, v96
	v_and_b32_e32 v96, 0xffff0000, v172
	v_add_f32_e32 v93, v93, v96
	v_lshlrev_b32_e32 v96, 16, v173
	v_add_f32_e32 v94, v94, v96
	v_and_b32_e32 v96, 0xffff0000, v173
	v_add_f32_e32 v95, v95, v96
	v_lshlrev_b32_e32 v96, 16, v174
	v_add_f32_e32 v96, v88, v96
	v_and_b32_e32 v88, 0xffff0000, v174
	s_waitcnt lgkmcnt(0)
	v_add_f32_e32 v97, v89, v88
	v_lshlrev_b32_e32 v88, 16, v175
	v_add_f32_e32 v98, v90, v88
	v_and_b32_e32 v88, 0xffff0000, v175
	v_add_f32_e32 v91, v91, v88
	v_mul_f32_e32 v88, v93, v93
	v_mul_f32_e32 v89, v95, v95
	v_fmac_f32_e32 v88, v92, v92
	v_fmac_f32_e32 v89, v94, v94
	v_add_f32_e32 v88, v88, v89
	v_mul_f32_e32 v89, v97, v97
	v_fmac_f32_e32 v89, v96, v96
	v_add_f32_e32 v88, v89, v88
	v_mul_f32_e32 v89, v91, v91
	v_fmac_f32_e32 v89, v98, v98
	v_add_f32_e32 v99, v89, v88
	v_cvt_pk_bf16_f32 v88, v92, v93
	v_lshlrev_b32_e32 v92, 16, v168
	v_add_f32_e32 v84, v84, v92
	v_and_b32_e32 v92, 0xffff0000, v168
	v_add_f32_e32 v85, v85, v92
	v_lshlrev_b32_e32 v92, 16, v169
	v_add_f32_e32 v92, v86, v92
	v_and_b32_e32 v86, 0xffff0000, v169
	v_add_f32_e32 v93, v87, v86
	v_lshlrev_b32_e32 v86, 16, v170
	v_cvt_pk_bf16_f32 v89, v94, v95
	v_add_f32_e32 v94, v80, v86
	v_and_b32_e32 v80, 0xffff0000, v170
	v_add_f32_e32 v95, v81, v80
	v_lshlrev_b32_e32 v80, 16, v171
	v_cvt_pk_bf16_f32 v90, v96, v97
	v_add_f32_e32 v96, v82, v80
	v_and_b32_e32 v80, 0xffff0000, v171
	v_add_f32_e32 v97, v83, v80
	v_mul_f32_e32 v80, v85, v85
	v_mul_f32_e32 v81, v93, v93
	v_fmac_f32_e32 v80, v84, v84
	v_fmac_f32_e32 v81, v92, v92
	v_add_f32_e32 v80, v80, v81
	v_mul_f32_e32 v81, v95, v95
	v_fmac_f32_e32 v81, v94, v94
	v_add_f32_e32 v80, v81, v80
	v_mul_f32_e32 v81, v97, v97
	v_fmac_f32_e32 v81, v96, v96
	v_add_f32_e32 v80, v81, v80
	v_add_f32_e32 v83, v99, v80
	v_cvt_pk_bf16_f32 v91, v98, v91
	v_mov_b32_e32 v98, v83
	s_nop 1
	v_permlane16_swap_b32_e32 v98, v83
	v_lshl_add_u64 v[80:81], s[14:15], 0, v[220:221]
	v_lshl_add_u64 v[86:87], v[196:197], 1, v[80:81]
	global_store_dwordx4 v[86:87], v[88:91], off
	v_cvt_pk_bf16_f32 v82, v84, v85
	s_waitcnt lgkmcnt(0)
	v_add_f32_e32 v80, v83, v98
	v_mov_b32_e32 v81, v80
	s_nop 1
	v_permlane32_swap_b32_e32 v81, v80
	v_cvt_pk_bf16_f32 v83, v92, v93
	v_cvt_pk_bf16_f32 v84, v94, v95
	v_cvt_pk_bf16_f32 v85, v96, v97
	global_store_dwordx4 v[86:87], v[82:85], off offset:256
	s_and_saveexec_b64 s[2:3], vcc
	s_cbranch_execz .LBB0_664
	v_lshlrev_b64 v[82:83], 8, v[218:219]
	v_lshl_add_u64 v[82:83], s[16:17], 0, v[82:83]
	v_lshl_add_u64 v[82:83], s[0:1], 2, v[82:83]
	s_lshl_b32 s20, s43, 2
	v_lshl_add_u64 v[82:83], v[82:83], 0, s[20:21]
	s_waitcnt lgkmcnt(0)
	v_add_f32_e32 v80, v80, v81
	global_store_dword v[82:83], v80, off
.LBB0_664:
	s_or_b64 exec, exec, s[2:3]
	v_lshlrev_b32_e32 v80, 16, v164
	v_add_f32_e32 v76, v76, v80
	v_and_b32_e32 v80, 0xffff0000, v164
	v_add_f32_e32 v77, v77, v80
	v_lshlrev_b32_e32 v80, 16, v165
	v_add_f32_e32 v78, v78, v80
	v_and_b32_e32 v80, 0xffff0000, v165
	v_add_f32_e32 v79, v79, v80
	v_lshlrev_b32_e32 v80, 16, v166
	v_add_f32_e32 v80, v72, v80
	v_and_b32_e32 v72, 0xffff0000, v166
	s_waitcnt lgkmcnt(0)
	v_add_f32_e32 v81, v73, v72
	v_lshlrev_b32_e32 v72, 16, v167
	v_add_f32_e32 v82, v74, v72
	v_and_b32_e32 v72, 0xffff0000, v167
	v_add_f32_e32 v75, v75, v72
	v_mul_f32_e32 v72, v77, v77
	v_mul_f32_e32 v73, v79, v79
	v_fmac_f32_e32 v72, v76, v76
	v_fmac_f32_e32 v73, v78, v78
	v_add_f32_e32 v72, v72, v73
	v_mul_f32_e32 v73, v81, v81
	v_fmac_f32_e32 v73, v80, v80
	v_add_f32_e32 v72, v73, v72
	v_mul_f32_e32 v73, v75, v75
	v_fmac_f32_e32 v73, v82, v82
	v_add_f32_e32 v83, v73, v72
	v_cvt_pk_bf16_f32 v72, v76, v77
	v_lshlrev_b32_e32 v76, 16, v160
	v_add_f32_e32 v68, v68, v76
	v_and_b32_e32 v76, 0xffff0000, v160
	v_add_f32_e32 v69, v69, v76
	v_lshlrev_b32_e32 v76, 16, v161
	v_add_f32_e32 v76, v70, v76
	v_and_b32_e32 v70, 0xffff0000, v161
	v_add_f32_e32 v77, v71, v70
	v_lshlrev_b32_e32 v70, 16, v162
	v_cvt_pk_bf16_f32 v73, v78, v79
	v_add_f32_e32 v78, v64, v70
	v_and_b32_e32 v64, 0xffff0000, v162
	v_add_f32_e32 v79, v65, v64
	v_lshlrev_b32_e32 v64, 16, v163
	v_cvt_pk_bf16_f32 v74, v80, v81
	v_add_f32_e32 v80, v66, v64
	v_and_b32_e32 v64, 0xffff0000, v163
	v_add_f32_e32 v81, v67, v64
	v_mul_f32_e32 v64, v69, v69
	v_mul_f32_e32 v65, v77, v77
	v_fmac_f32_e32 v64, v68, v68
	v_fmac_f32_e32 v65, v76, v76
	v_add_f32_e32 v64, v64, v65
	v_mul_f32_e32 v65, v79, v79
	v_fmac_f32_e32 v65, v78, v78
	v_add_f32_e32 v64, v65, v64
	v_mul_f32_e32 v65, v81, v81
	v_fmac_f32_e32 v65, v80, v80
	v_add_f32_e32 v64, v65, v64
	v_add_f32_e32 v67, v83, v64
	v_cvt_pk_bf16_f32 v75, v82, v75
	v_mov_b32_e32 v82, v67
	s_nop 1
	v_permlane16_swap_b32_e32 v82, v67
	v_lshl_add_u64 v[64:65], s[14:15], 0, v[216:217]
	v_lshl_add_u64 v[70:71], v[196:197], 1, v[64:65]
	global_store_dwordx4 v[70:71], v[72:75], off
	v_cvt_pk_bf16_f32 v66, v68, v69
	s_waitcnt lgkmcnt(0)
	v_add_f32_e32 v64, v67, v82
	v_mov_b32_e32 v65, v64
	s_nop 1
	v_permlane32_swap_b32_e32 v65, v64
	v_cvt_pk_bf16_f32 v67, v76, v77
	v_cvt_pk_bf16_f32 v68, v78, v79
	v_cvt_pk_bf16_f32 v69, v80, v81
	global_store_dwordx4 v[70:71], v[66:69], off offset:256
	s_and_saveexec_b64 s[2:3], vcc
	s_cbranch_execz .LBB0_666
	v_lshlrev_b64 v[66:67], 8, v[214:215]
	v_lshl_add_u64 v[66:67], s[16:17], 0, v[66:67]
	v_lshl_add_u64 v[66:67], s[0:1], 2, v[66:67]
	s_lshl_b32 s20, s43, 2
	v_lshl_add_u64 v[66:67], v[66:67], 0, s[20:21]
	s_waitcnt lgkmcnt(0)
	v_add_f32_e32 v64, v64, v65
	global_store_dword v[66:67], v64, off
.LBB0_666:
	s_or_b64 exec, exec, s[2:3]
	v_lshlrev_b32_e32 v64, 16, v156
	v_add_f32_e32 v60, v60, v64
	v_and_b32_e32 v64, 0xffff0000, v156
	v_add_f32_e32 v61, v61, v64
	v_lshlrev_b32_e32 v64, 16, v157
	v_add_f32_e32 v62, v62, v64
	v_and_b32_e32 v64, 0xffff0000, v157
	v_add_f32_e32 v63, v63, v64
	v_lshlrev_b32_e32 v64, 16, v158
	v_add_f32_e32 v64, v56, v64
	v_and_b32_e32 v56, 0xffff0000, v158
	s_waitcnt lgkmcnt(0)
	v_add_f32_e32 v65, v57, v56
	v_lshlrev_b32_e32 v56, 16, v159
	v_add_f32_e32 v66, v58, v56
	v_and_b32_e32 v56, 0xffff0000, v159
	v_add_f32_e32 v59, v59, v56
	v_mul_f32_e32 v56, v61, v61
	v_mul_f32_e32 v57, v63, v63
	v_fmac_f32_e32 v56, v60, v60
	v_fmac_f32_e32 v57, v62, v62
	v_add_f32_e32 v56, v56, v57
	v_mul_f32_e32 v57, v65, v65
	v_fmac_f32_e32 v57, v64, v64
	v_add_f32_e32 v56, v57, v56
	v_mul_f32_e32 v57, v59, v59
	v_fmac_f32_e32 v57, v66, v66
	v_add_f32_e32 v67, v57, v56
	v_cvt_pk_bf16_f32 v56, v60, v61
	v_lshlrev_b32_e32 v60, 16, v152
	v_add_f32_e32 v52, v52, v60
	v_and_b32_e32 v60, 0xffff0000, v152
	v_add_f32_e32 v53, v53, v60
	v_lshlrev_b32_e32 v60, 16, v153
	v_add_f32_e32 v60, v54, v60
	v_and_b32_e32 v54, 0xffff0000, v153
	v_add_f32_e32 v61, v55, v54
	v_lshlrev_b32_e32 v54, 16, v154
	v_cvt_pk_bf16_f32 v57, v62, v63
	v_add_f32_e32 v62, v48, v54
	v_and_b32_e32 v48, 0xffff0000, v154
	v_add_f32_e32 v63, v49, v48
	v_lshlrev_b32_e32 v48, 16, v155
	v_cvt_pk_bf16_f32 v58, v64, v65
	v_add_f32_e32 v64, v50, v48
	v_and_b32_e32 v48, 0xffff0000, v155
	v_add_f32_e32 v65, v51, v48
	v_mul_f32_e32 v48, v53, v53
	v_mul_f32_e32 v49, v61, v61
	v_fmac_f32_e32 v48, v52, v52
	v_fmac_f32_e32 v49, v60, v60
	v_add_f32_e32 v48, v48, v49
	v_mul_f32_e32 v49, v63, v63
	v_fmac_f32_e32 v49, v62, v62
	v_add_f32_e32 v48, v49, v48
	v_mul_f32_e32 v49, v65, v65
	v_fmac_f32_e32 v49, v64, v64
	v_add_f32_e32 v48, v49, v48
	v_add_f32_e32 v51, v67, v48
	v_cvt_pk_bf16_f32 v59, v66, v59
	v_mov_b32_e32 v66, v51
	s_nop 1
	v_permlane16_swap_b32_e32 v66, v51
	v_lshl_add_u64 v[48:49], s[14:15], 0, v[212:213]
	v_lshl_add_u64 v[54:55], v[196:197], 1, v[48:49]
	global_store_dwordx4 v[54:55], v[56:59], off
	v_cvt_pk_bf16_f32 v50, v52, v53
	s_waitcnt lgkmcnt(0)
	v_add_f32_e32 v48, v51, v66
	v_mov_b32_e32 v49, v48
	s_nop 1
	v_permlane32_swap_b32_e32 v49, v48
	v_cvt_pk_bf16_f32 v51, v60, v61
	v_cvt_pk_bf16_f32 v52, v62, v63
	v_cvt_pk_bf16_f32 v53, v64, v65
	global_store_dwordx4 v[54:55], v[50:53], off offset:256
	s_and_saveexec_b64 s[2:3], vcc
	s_cbranch_execz .LBB0_668
	v_lshlrev_b64 v[50:51], 8, v[210:211]
	v_lshl_add_u64 v[50:51], s[16:17], 0, v[50:51]
	v_lshl_add_u64 v[50:51], s[0:1], 2, v[50:51]
	s_lshl_b32 s20, s43, 2
	v_lshl_add_u64 v[50:51], v[50:51], 0, s[20:21]
	s_waitcnt lgkmcnt(0)
	v_add_f32_e32 v48, v48, v49
	global_store_dword v[50:51], v48, off
.LBB0_668:
	s_or_b64 exec, exec, s[2:3]
	v_lshlrev_b32_e32 v48, 16, v148
	v_add_f32_e32 v44, v44, v48
	v_and_b32_e32 v48, 0xffff0000, v148
	v_add_f32_e32 v45, v45, v48
	v_lshlrev_b32_e32 v48, 16, v149
	v_add_f32_e32 v46, v46, v48
	v_and_b32_e32 v48, 0xffff0000, v149
	v_add_f32_e32 v47, v47, v48
	v_lshlrev_b32_e32 v48, 16, v150
	v_add_f32_e32 v48, v40, v48
	v_and_b32_e32 v40, 0xffff0000, v150
	s_waitcnt lgkmcnt(0)
	v_add_f32_e32 v49, v41, v40
	v_lshlrev_b32_e32 v40, 16, v151
	v_add_f32_e32 v50, v42, v40
	v_and_b32_e32 v40, 0xffff0000, v151
	v_add_f32_e32 v43, v43, v40
	v_mul_f32_e32 v40, v45, v45
	v_mul_f32_e32 v41, v47, v47
	v_fmac_f32_e32 v40, v44, v44
	v_fmac_f32_e32 v41, v46, v46
	v_add_f32_e32 v40, v40, v41
	v_mul_f32_e32 v41, v49, v49
	v_fmac_f32_e32 v41, v48, v48
	v_add_f32_e32 v40, v41, v40
	v_mul_f32_e32 v41, v43, v43
	v_fmac_f32_e32 v41, v50, v50
	v_add_f32_e32 v51, v41, v40
	v_cvt_pk_bf16_f32 v40, v44, v45
	v_lshlrev_b32_e32 v44, 16, v144
	v_add_f32_e32 v36, v36, v44
	v_and_b32_e32 v44, 0xffff0000, v144
	v_add_f32_e32 v37, v37, v44
	v_lshlrev_b32_e32 v44, 16, v145
	v_add_f32_e32 v44, v38, v44
	v_and_b32_e32 v38, 0xffff0000, v145
	v_add_f32_e32 v45, v39, v38
	v_lshlrev_b32_e32 v38, 16, v146
	v_cvt_pk_bf16_f32 v41, v46, v47
	v_add_f32_e32 v46, v32, v38
	v_and_b32_e32 v32, 0xffff0000, v146
	v_add_f32_e32 v47, v33, v32
	v_lshlrev_b32_e32 v32, 16, v147
	v_cvt_pk_bf16_f32 v42, v48, v49
	v_add_f32_e32 v48, v34, v32
	v_and_b32_e32 v32, 0xffff0000, v147
	v_add_f32_e32 v49, v35, v32
	v_mul_f32_e32 v32, v37, v37
	v_mul_f32_e32 v33, v45, v45
	v_fmac_f32_e32 v32, v36, v36
	v_fmac_f32_e32 v33, v44, v44
	v_add_f32_e32 v32, v32, v33
	v_mul_f32_e32 v33, v47, v47
	v_fmac_f32_e32 v33, v46, v46
	v_add_f32_e32 v32, v33, v32
	v_mul_f32_e32 v33, v49, v49
	v_fmac_f32_e32 v33, v48, v48
	v_add_f32_e32 v32, v33, v32
	v_add_f32_e32 v35, v51, v32
	v_cvt_pk_bf16_f32 v43, v50, v43
	v_mov_b32_e32 v50, v35
	s_nop 1
	v_permlane16_swap_b32_e32 v50, v35
	v_lshl_add_u64 v[32:33], s[14:15], 0, v[208:209]
	v_lshl_add_u64 v[38:39], v[196:197], 1, v[32:33]
	global_store_dwordx4 v[38:39], v[40:43], off
	v_cvt_pk_bf16_f32 v34, v36, v37
	s_waitcnt lgkmcnt(0)
	v_add_f32_e32 v32, v35, v50
	v_mov_b32_e32 v33, v32
	s_nop 1
	v_permlane32_swap_b32_e32 v33, v32
	v_cvt_pk_bf16_f32 v35, v44, v45
	v_cvt_pk_bf16_f32 v36, v46, v47
	v_cvt_pk_bf16_f32 v37, v48, v49
	global_store_dwordx4 v[38:39], v[34:37], off offset:256
	s_and_saveexec_b64 s[2:3], vcc
	s_cbranch_execz .LBB0_670
	v_lshlrev_b64 v[34:35], 8, v[206:207]
	v_lshl_add_u64 v[34:35], s[16:17], 0, v[34:35]
	v_lshl_add_u64 v[34:35], s[0:1], 2, v[34:35]
	s_lshl_b32 s20, s43, 2
	v_lshl_add_u64 v[34:35], v[34:35], 0, s[20:21]
	s_waitcnt lgkmcnt(0)
	v_add_f32_e32 v32, v32, v33
	global_store_dword v[34:35], v32, off
.LBB0_670:
	s_or_b64 exec, exec, s[2:3]
	v_lshlrev_b32_e32 v32, 16, v140
	v_add_f32_e32 v28, v28, v32
	v_and_b32_e32 v32, 0xffff0000, v140
	v_add_f32_e32 v29, v29, v32
	v_lshlrev_b32_e32 v32, 16, v141
	v_add_f32_e32 v30, v30, v32
	v_and_b32_e32 v32, 0xffff0000, v141
	v_add_f32_e32 v31, v31, v32
	v_lshlrev_b32_e32 v32, 16, v142
	v_add_f32_e32 v32, v24, v32
	v_and_b32_e32 v24, 0xffff0000, v142
	s_waitcnt lgkmcnt(0)
	v_add_f32_e32 v33, v25, v24
	v_lshlrev_b32_e32 v24, 16, v143
	v_add_f32_e32 v34, v26, v24
	v_and_b32_e32 v24, 0xffff0000, v143
	v_add_f32_e32 v27, v27, v24
	v_mul_f32_e32 v24, v29, v29
	v_mul_f32_e32 v25, v31, v31
	v_fmac_f32_e32 v24, v28, v28
	v_fmac_f32_e32 v25, v30, v30
	v_add_f32_e32 v24, v24, v25
	v_mul_f32_e32 v25, v33, v33
	v_fmac_f32_e32 v25, v32, v32
	v_add_f32_e32 v24, v25, v24
	v_mul_f32_e32 v25, v27, v27
	v_fmac_f32_e32 v25, v34, v34
	v_add_f32_e32 v35, v25, v24
	v_cvt_pk_bf16_f32 v24, v28, v29
	v_lshlrev_b32_e32 v28, 16, v136
	v_add_f32_e32 v20, v20, v28
	v_and_b32_e32 v28, 0xffff0000, v136
	v_add_f32_e32 v21, v21, v28
	v_lshlrev_b32_e32 v28, 16, v137
	v_add_f32_e32 v28, v22, v28
	v_and_b32_e32 v22, 0xffff0000, v137
	v_add_f32_e32 v29, v23, v22
	v_lshlrev_b32_e32 v22, 16, v138
	v_cvt_pk_bf16_f32 v25, v30, v31
	v_add_f32_e32 v30, v16, v22
	v_and_b32_e32 v16, 0xffff0000, v138
	v_add_f32_e32 v31, v17, v16
	v_lshlrev_b32_e32 v16, 16, v139
	v_cvt_pk_bf16_f32 v26, v32, v33
	v_add_f32_e32 v32, v18, v16
	v_and_b32_e32 v16, 0xffff0000, v139
	v_add_f32_e32 v33, v19, v16
	v_mul_f32_e32 v16, v21, v21
	v_mul_f32_e32 v17, v29, v29
	v_fmac_f32_e32 v16, v20, v20
	v_fmac_f32_e32 v17, v28, v28
	v_add_f32_e32 v16, v16, v17
	v_mul_f32_e32 v17, v31, v31
	v_fmac_f32_e32 v17, v30, v30
	v_add_f32_e32 v16, v17, v16
	v_mul_f32_e32 v17, v33, v33
	v_fmac_f32_e32 v17, v32, v32
	v_add_f32_e32 v16, v17, v16
	v_add_f32_e32 v19, v35, v16
	v_cvt_pk_bf16_f32 v27, v34, v27
	v_mov_b32_e32 v34, v19
	s_nop 1
	v_permlane16_swap_b32_e32 v34, v19
	v_lshl_add_u64 v[16:17], s[14:15], 0, v[204:205]
	v_lshl_add_u64 v[22:23], v[196:197], 1, v[16:17]
	global_store_dwordx4 v[22:23], v[24:27], off
	v_cvt_pk_bf16_f32 v18, v20, v21
	s_waitcnt lgkmcnt(0)
	v_add_f32_e32 v16, v19, v34
	v_mov_b32_e32 v17, v16
	s_nop 1
	v_permlane32_swap_b32_e32 v17, v16
	v_cvt_pk_bf16_f32 v19, v28, v29
	v_cvt_pk_bf16_f32 v20, v30, v31
	v_cvt_pk_bf16_f32 v21, v32, v33
	global_store_dwordx4 v[22:23], v[18:21], off offset:256
	s_and_saveexec_b64 s[2:3], vcc
	s_cbranch_execz .LBB0_672
	v_lshlrev_b64 v[18:19], 8, v[202:203]
	v_lshl_add_u64 v[18:19], s[16:17], 0, v[18:19]
	v_lshl_add_u64 v[18:19], s[0:1], 2, v[18:19]
	s_lshl_b32 s20, s43, 2
	v_lshl_add_u64 v[18:19], v[18:19], 0, s[20:21]
	s_waitcnt lgkmcnt(0)
	v_add_f32_e32 v16, v16, v17
	global_store_dword v[18:19], v16, off
.LBB0_672:
	s_or_b64 exec, exec, s[2:3]
	v_lshlrev_b32_e32 v16, 16, v132
	v_add_f32_e32 v12, v12, v16
	v_and_b32_e32 v16, 0xffff0000, v132
	v_add_f32_e32 v13, v13, v16
	v_lshlrev_b32_e32 v16, 16, v133
	v_add_f32_e32 v14, v14, v16
	v_and_b32_e32 v16, 0xffff0000, v133
	v_add_f32_e32 v15, v15, v16
	v_lshlrev_b32_e32 v16, 16, v134
	v_add_f32_e32 v16, v8, v16
	v_and_b32_e32 v8, 0xffff0000, v134
	s_waitcnt lgkmcnt(0)
	v_add_f32_e32 v17, v9, v8
	v_lshlrev_b32_e32 v8, 16, v135
	v_add_f32_e32 v18, v10, v8
	v_and_b32_e32 v8, 0xffff0000, v135
	v_add_f32_e32 v11, v11, v8
	v_mul_f32_e32 v8, v13, v13
	v_mul_f32_e32 v9, v15, v15
	v_fmac_f32_e32 v8, v12, v12
	v_fmac_f32_e32 v9, v14, v14
	v_add_f32_e32 v8, v8, v9
	v_mul_f32_e32 v9, v17, v17
	v_fmac_f32_e32 v9, v16, v16
	v_add_f32_e32 v8, v9, v8
	v_mul_f32_e32 v9, v11, v11
	v_fmac_f32_e32 v9, v18, v18
	v_add_f32_e32 v19, v9, v8
	v_cvt_pk_bf16_f32 v8, v12, v13
	v_lshlrev_b32_e32 v12, 16, v120
	v_add_f32_e32 v4, v4, v12
	v_and_b32_e32 v12, 0xffff0000, v120
	v_add_f32_e32 v5, v5, v12
	v_lshlrev_b32_e32 v12, 16, v121
	v_add_f32_e32 v12, v6, v12
	v_and_b32_e32 v6, 0xffff0000, v121
	v_add_f32_e32 v13, v7, v6
	v_lshlrev_b32_e32 v6, 16, v122
	v_cvt_pk_bf16_f32 v9, v14, v15
	v_add_f32_e32 v14, v0, v6
	v_and_b32_e32 v0, 0xffff0000, v122
	v_add_f32_e32 v15, v1, v0
	v_lshlrev_b32_e32 v0, 16, v123
	v_cvt_pk_bf16_f32 v10, v16, v17
	v_add_f32_e32 v16, v2, v0
	v_and_b32_e32 v0, 0xffff0000, v123
	v_add_f32_e32 v17, v3, v0
	v_mul_f32_e32 v0, v5, v5
	v_mul_f32_e32 v1, v13, v13
	v_fmac_f32_e32 v0, v4, v4
	v_fmac_f32_e32 v1, v12, v12
	v_add_f32_e32 v0, v0, v1
	v_mul_f32_e32 v1, v15, v15
	v_fmac_f32_e32 v1, v14, v14
	v_add_f32_e32 v0, v1, v0
	v_mul_f32_e32 v1, v17, v17
	v_fmac_f32_e32 v1, v16, v16
	v_add_f32_e32 v0, v1, v0
	v_add_f32_e32 v3, v19, v0
	v_cvt_pk_bf16_f32 v11, v18, v11
	v_mov_b32_e32 v18, v3
	s_nop 1
	v_permlane16_swap_b32_e32 v18, v3
	v_lshl_add_u64 v[0:1], s[14:15], 0, v[200:201]
	v_lshl_add_u64 v[6:7], v[196:197], 1, v[0:1]
	global_store_dwordx4 v[6:7], v[8:11], off
	v_cvt_pk_bf16_f32 v2, v4, v5
	s_waitcnt lgkmcnt(0)
	v_add_f32_e32 v0, v3, v18
	v_mov_b32_e32 v1, v0
	s_nop 1
	v_permlane32_swap_b32_e32 v1, v0
	v_cvt_pk_bf16_f32 v3, v12, v13
	v_cvt_pk_bf16_f32 v4, v14, v15
	v_cvt_pk_bf16_f32 v5, v16, v17
	global_store_dwordx4 v[6:7], v[2:5], off offset:256
	s_and_saveexec_b64 s[2:3], vcc
	s_cbranch_execz .LBB0_674
	v_lshlrev_b64 v[2:3], 8, v[198:199]
	v_lshl_add_u64 v[2:3], s[16:17], 0, v[2:3]
	v_lshl_add_u64 v[2:3], s[0:1], 2, v[2:3]
	s_lshl_b32 s20, s43, 2
	v_lshl_add_u64 v[2:3], v[2:3], 0, s[20:21]
	s_waitcnt lgkmcnt(0)
	v_add_f32_e32 v0, v0, v1
	global_store_dword v[2:3], v0, off

.LBB0_868:
.LBB0_869:
	s_add_i32 s0, 0, 0x23f94
	s_waitcnt vmcnt(0)
	v_mov_b32_e32 v0, s0
	v_mbcnt_lo_u32_b32 v58, -1, 0
	v_mbcnt_hi_u32_b32 v58, -1, v58
	ds_read_b32 v0, v0
	v_lshlrev_b32_e32 v71, 4, v58
	v_and_b32_e32 v59, 15, v58
	s_mov_b32 s1, 0
	v_ashrrev_i32_e32 v70, 4, v58
	s_waitcnt lgkmcnt(0)
	v_readfirstlane_b32 s0, v0
	s_and_b32 s4, s0, 7
	s_mul_i32 s5, s4, 0x1400000
	s_add_u32 s5, s94, s5
	s_addc_u32 s6, s95, 0
	s_lshl_b32 s4, s4, 22
	s_sub_u32 s4, 0, s4
	s_subb_u32 s7, 0, 0
	s_add_u32 s4, s5, s4
	s_addc_u32 s5, s6, s7
	s_lshl_b32 s8, s88, 10
	v_add_u32_e32 v0, s8, v71
	v_ashrrev_i32_e32 v1, 31, v0
	v_lshrrev_b32_e32 v1, 22, v1
	v_add_u32_e32 v1, v0, v1
	v_ashrrev_i32_e32 v1, 10, v1
	v_mul_i32_i24_e32 v2, 0x400, v1
	v_sub_u32_e32 v2, v0, v2
	v_lshrrev_b32_e32 v3, 4, v2
	v_bitop3_b32 v2, v3, v2, 32 bitop3:0x6c
	v_ashrrev_i32_e32 v4, 31, v2
	v_lshrrev_b32_e32 v4, 26, v4
	v_lshlrev_b32_e32 v3, 3, v1
	v_add_u32_e32 v4, v2, v4
	v_and_b32_e32 v3, -16, v3
	v_ashrrev_i32_e32 v5, 6, v4
	v_add_u32_e32 v104, v5, v3
	v_and_b32_e32 v3, 0xc0, v4
	v_lshlrev_b32_e32 v1, 5, v1
	v_sub_u32_e32 v2, v2, v3
	v_mov_b32_e32 v3, 1
	v_and_b32_e32 v1, 32, v1
	v_ashrrev_i16_sdwa v2, v3, sext(v2) dst_sel:DWORD dst_unused:UNUSED_PAD src0_sel:DWORD src1_sel:BYTE_0
	v_add_u32_sdwa v1, v1, sext(v2) dst_sel:DWORD dst_unused:UNUSED_PAD src0_sel:DWORD src1_sel:WORD_0
	v_lshlrev_b32_e32 v2, 10, v104
	v_add_u32_e32 v0, 0x2000, v0
	v_lshl_add_u32 v62, v1, 1, v2
	v_ashrrev_i32_e32 v1, 31, v0
	v_lshrrev_b32_e32 v1, 22, v1
	v_add_u32_e32 v1, v0, v1
	v_ashrrev_i32_e32 v1, 10, v1
	v_mul_i32_i24_e32 v2, 0x400, v1
	v_sub_u32_e32 v0, v0, v2
	v_lshrrev_b32_e32 v2, 4, v0
	s_lshl_b32 s6, s0, 3
	v_bitop3_b32 v0, v2, v0, 32 bitop3:0x6c
	s_and_b32 s6, s6, 56
	s_ashr_i32 s7, s0, 5
	v_ashrrev_i32_e32 v4, 31, v0
	s_add_i32 s9, s6, s7
	v_lshrrev_b32_e32 v4, 26, v4
	s_ashr_i32 s12, s9, 5
	v_lshlrev_b32_e32 v2, 3, v1
	v_add_u32_e32 v4, v0, v4
	s_bfe_u32 s0, s0, 0x20003
	s_lshl_b32 s6, s12, 2
	v_and_b32_e32 v2, -16, v2
	v_ashrrev_i32_e32 v5, 6, v4
	s_or_b32 s6, s6, s0
	v_add_u32_e32 v108, v5, v2
	v_and_b32_e32 v2, 0xffc0, v4
	s_ashr_i32 s7, s6, 31
	v_sub_u32_e32 v0, v0, v2
	s_lshl_b64 s[6:7], s[6:7], 18
	v_lshrrev_b16_e32 v2, 7, v0
	s_add_u32 s10, s94, s6
	v_and_b32_e32 v2, 1, v2
	s_addc_u32 s11, s95, s7
	v_lshlrev_b32_e32 v1, 5, v1
	v_add_u16_e32 v0, v0, v2
	s_add_u32 s6, s10, 0x11400000
	v_and_b32_e32 v1, 32, v1
	v_ashrrev_i16_sdwa v0, v3, sext(v0) dst_sel:DWORD dst_unused:UNUSED_PAD src0_sel:DWORD src1_sel:BYTE_0
	s_addc_u32 s7, s11, 0
	s_lshl_b32 s9, s9, 7
	v_add_u32_sdwa v0, v1, sext(v0) dst_sel:DWORD dst_unused:UNUSED_PAD src0_sel:DWORD src1_sel:WORD_0
	v_lshlrev_b32_e32 v1, 10, v108
	s_lshl_b32 s12, s12, 12
	s_and_b32 s9, s9, 0xf80
	v_lshl_add_u32 v64, v0, 1, v1
	v_lshl_or_b32 v1, s88, 4, v59
	s_or_b32 s9, s12, s9
	v_add_u32_e32 v2, s9, v1
	v_ashrrev_i32_e32 v3, 31, v2
	v_lshlrev_b64 v[2:3], 12, v[2:3]
	s_lshl_b32 s0, s0, 10
	v_lshl_add_u64 v[2:3], s[4:5], 0, v[2:3]
	v_lshlrev_b32_e32 v0, 3, v70
	v_lshl_add_u64 v[2:3], v[2:3], 0, s[0:1]
	s_mov_b64 s[0:1], 0x13000000
	v_ashrrev_i32_e32 v1, 31, v0
	v_lshl_add_u64 v[60:61], v[2:3], 0, s[0:1]
	v_lshl_add_u64 v[0:1], v[0:1], 1, v[60:61]
	s_mov_b64 s[0:1], 0xc00000
	v_lshl_add_u64 v[2:3], v[0:1], 0, s[0:1]
	s_mov_b32 s0, 0xc00000
	v_add_co_u32_e32 v0, vcc, s0, v0
	s_add_i32 s22, s8, 0
	s_nop 0
	v_addc_co_u32_e32 v1, vcc, 0, v1, vcc
	v_mov_b32_e32 v63, 0
	s_mov_b32 m0, s22
	s_add_i32 s21, s22, 0x2000
	global_load_dwordx4 v[72:75], v[2:3], off offset:64
	global_load_dwordx4 v[52:55], v[2:3], off offset:128
	global_load_dwordx4 v[48:51], v[2:3], off offset:192
	global_load_dwordx4 v[44:47], v[2:3], off offset:256
	global_load_dwordx4 v[40:43], v[2:3], off offset:320
	global_load_dwordx4 v[36:39], v[2:3], off offset:384
	global_load_dwordx4 v[32:35], v[2:3], off offset:448
	global_load_dwordx4 v[28:31], v[2:3], off offset:512
	global_load_dwordx4 v[24:27], v[2:3], off offset:576
	global_load_dwordx4 v[20:23], v[2:3], off offset:640
	global_load_dwordx4 v[16:19], v[2:3], off offset:704
	global_load_dwordx4 v[12:15], v[2:3], off offset:768
	global_load_dwordx4 v[8:11], v[2:3], off offset:832
	global_load_dwordx4 v[4:7], v[2:3], off offset:896
	global_load_dwordx4 v[76:79], v[0:1], off
	s_nop 0
	global_load_dwordx4 v[0:3], v[2:3], off offset:960
	v_mov_b32_e32 v65, v63
	global_load_lds_dwordx4 v62, s[6:7]
	v_mov_b32_e32 v240, v62
	s_mov_b32 m0, s21
	v_lshl_add_u64 v[66:67], s[6:7], 0, v[62:63]
	v_lshl_add_u64 v[68:69], s[6:7], 0, v[64:65]
	global_load_lds_dwordx4 v64, s[6:7]
	s_add_i32 s20, s22, 0x4000
	s_mov_b64 s[6:7], 0x80
	s_add_i32 s23, s22, 0x6000
	v_lshl_add_u64 v[56:57], v[66:67], 0, s[6:7]
	s_mov_b32 m0, s20
	s_add_u32 s0, s10, 0x11420000
	global_load_lds_dwordx4 v[56:57], off
	v_lshl_add_u64 v[56:57], v[68:69], 0, s[6:7]
	s_mov_b32 m0, s23
	s_addc_u32 s1, s11, 0
	s_add_i32 s24, s22, 0x8000
	global_load_lds_dwordx4 v[56:57], off
	s_mov_b32 m0, s24
	s_add_i32 s25, s22, 0xa000
	global_load_lds_dwordx4 v62, s[0:1]
	s_mov_b32 m0, s25
	s_mov_b64 s[4:5], 0x180
	global_load_lds_dwordx4 v64, s[0:1]
	s_add_u32 s0, s10, 0x11420080
	s_addc_u32 s1, s11, 0
	s_add_i32 s26, s22, 0xc000
	s_mov_b32 m0, s26
	s_add_i32 s27, s22, 0xe000
	global_load_lds_dwordx4 v62, s[0:1]
	s_mov_b32 m0, s27
	s_add_u32 s8, s10, 0x11c00000
	global_load_lds_dwordx4 v64, s[0:1]
	s_addc_u32 s9, s11, 0
	s_add_i32 s19, s22, 0x10000
	s_mov_b64 s[0:1], 0x100
	v_lshl_add_u64 v[56:57], v[66:67], 0, s[0:1]
	s_mov_b32 m0, s19
	s_add_i32 s13, s22, 0x12000
	s_waitcnt vmcnt(0)
	s_waitcnt vmcnt(0) lgkmcnt(0)
	s_barrier
	global_load_lds_dwordx4 v[56:57], off
	v_lshl_add_u64 v[56:57], v[68:69], 0, s[0:1]
	s_mov_b32 m0, s13
	s_add_i32 s12, s22, 0x14000
	s_add_i32 s14, s22, 0x16000
	global_load_lds_dwordx4 v[56:57], off
	v_lshl_add_u64 v[56:57], v[66:67], 0, s[4:5]
	s_mov_b32 m0, s12
	s_add_u32 s28, s10, 0x11420100
	global_load_lds_dwordx4 v[56:57], off
	v_lshl_add_u64 v[56:57], v[68:69], 0, s[4:5]
	s_mov_b32 m0, s14
	s_addc_u32 s29, s11, 0
	s_add_i32 s15, s22, 0x18000
	global_load_lds_dwordx4 v[56:57], off
	s_mov_b32 m0, s15
	s_add_i32 s16, s22, 0x1a000
	global_load_lds_dwordx4 v62, s[28:29]
	s_mov_b32 m0, s16
	v_and_b32_e32 v57, 48, v58
	global_load_lds_dwordx4 v64, s[28:29]
	s_add_u32 s28, s10, 0x11420180
	s_addc_u32 s29, s11, 0
	s_add_i32 s17, s22, 0x1c000
	s_mov_b32 m0, s17
	s_add_i32 s18, s22, 0x1e000
	global_load_lds_dwordx4 v62, s[28:29]
	s_mov_b32 m0, s18
	v_lshlrev_b32_e32 v58, 2, v58
	global_load_lds_dwordx4 v64, s[28:29]
	v_lshlrev_b32_e32 v56, 6, v59
	v_and_b32_e32 v58, 32, v58
	v_bitop3_b32 v56, v56, v58, v57 bitop3:0x36
	v_and_b32_e32 v57, 0xfffffc00, v71
	v_add3_u32 v65, 0, v56, v57
	v_mov_b32_e32 v71, v65
	ds_read_b128 v[56:59], v71
	ds_read_b128 v[80:83], v71 offset:2048
	s_waitcnt lgkmcnt(0)
	v_mfma_f32_16x16x32_bf16 v[84:87], v[56:59], v[76:79], 0
	ds_read_b128 v[56:59], v71 offset:4096
	ds_read_b128 v[88:91], v71 offset:6144
	ds_read_b128 v[96:99], v71 offset:8192
	ds_read_b128 v[100:103], v71 offset:10240
	s_waitcnt lgkmcnt(0)
	v_mfma_f32_16x16x32_bf16 v[92:95], v[56:59], v[76:79], 0
	v_lshlrev_b32_e32 v56, 9, v104
	ds_read_b128 v[104:107], v71 offset:12288
	v_lshlrev_b32_e32 v57, 9, v108
	ds_read_b128 v[108:111], v71 offset:14336
	ds_read_b128 v[112:115], v71 offset:32768
	ds_read_b128 v[116:119], v71 offset:34816
	ds_read_b128 v[120:123], v71 offset:36864
	ds_read_b128 v[124:127], v71 offset:38912
	ds_read_b128 v[128:131], v71 offset:40960
	ds_read_b128 v[132:135], v71 offset:43008
	ds_read_b128 v[136:139], v71 offset:45056
	ds_read_b128 v[140:143], v71 offset:47104
	v_mfma_f32_16x16x32_bf16 v[80:83], v[80:83], v[76:79], 0
	v_sub_u32_e32 v56, v62, v56
	v_mov_b32_e32 v241, v56
	v_sub_u32_e32 v58, v64, v57
	v_mfma_f32_16x16x32_bf16 v[88:91], v[88:91], v[76:79], 0
	v_mfma_f32_16x16x32_bf16 v[96:99], v[96:99], v[76:79], 0
	v_mfma_f32_16x16x32_bf16 v[100:103], v[100:103], v[76:79], 0
	s_waitcnt lgkmcnt(0)
	v_mfma_f32_16x16x32_bf16 v[104:107], v[104:107], v[76:79], 0
	v_mfma_f32_16x16x32_bf16 v[108:111], v[108:111], v[76:79], 0
	ds_read_b128 v[144:147], v71 offset:15360
	ds_read_b128 v[148:151], v71 offset:13312
	ds_read_b128 v[152:155], v71 offset:11264
	ds_read_b128 v[156:159], v71 offset:9216
	ds_read_b128 v[160:163], v71 offset:7168
	ds_read_b128 v[164:167], v71 offset:5120
	ds_read_b128 v[168:171], v71 offset:3072
	ds_read_b128 v[172:175], v71 offset:1024
	v_mfma_f32_16x16x32_bf16 v[112:115], v[112:115], v[76:79], 0
	v_mfma_f32_16x16x32_bf16 v[116:119], v[116:119], v[76:79], 0
	v_mfma_f32_16x16x32_bf16 v[120:123], v[120:123], v[76:79], 0
	v_mfma_f32_16x16x32_bf16 v[124:127], v[124:127], v[76:79], 0
	v_mfma_f32_16x16x32_bf16 v[128:131], v[128:131], v[76:79], 0
	v_mfma_f32_16x16x32_bf16 v[132:135], v[132:135], v[76:79], 0
	v_mfma_f32_16x16x32_bf16 v[136:139], v[136:139], v[76:79], 0
	v_mfma_f32_16x16x32_bf16 v[76:79], v[140:143], v[76:79], 0
	s_waitcnt lgkmcnt(0)
	v_mfma_f32_16x16x32_bf16 v[84:87], v[172:175], v[72:75], v[84:87]
	v_mfma_f32_16x16x32_bf16 v[80:83], v[168:171], v[72:75], v[80:83]
	v_mfma_f32_16x16x32_bf16 v[92:95], v[164:167], v[72:75], v[92:95]
	v_mfma_f32_16x16x32_bf16 v[88:91], v[160:163], v[72:75], v[88:91]
	v_mfma_f32_16x16x32_bf16 v[96:99], v[156:159], v[72:75], v[96:99]
	v_mfma_f32_16x16x32_bf16 v[100:103], v[152:155], v[72:75], v[100:103]
	ds_read_b128 v[140:143], v71 offset:33792
	ds_read_b128 v[152:155], v71 offset:35840
	ds_read_b128 v[156:159], v71 offset:37888
	ds_read_b128 v[160:163], v71 offset:39936
	v_mfma_f32_16x16x32_bf16 v[104:107], v[148:151], v[72:75], v[104:107]
	ds_read_b128 v[148:151], v71 offset:41984
	ds_read_b128 v[164:167], v71 offset:44032
	ds_read_b128 v[168:171], v71 offset:46080
	ds_read_b128 v[172:175], v71 offset:48128
	v_mfma_f32_16x16x32_bf16 v[108:111], v[144:147], v[72:75], v[108:111]
	s_waitcnt lgkmcnt(0)
	v_mfma_f32_16x16x32_bf16 v[112:115], v[140:143], v[72:75], v[112:115]
	v_mfma_f32_16x16x32_bf16 v[116:119], v[152:155], v[72:75], v[116:119]
	v_mfma_f32_16x16x32_bf16 v[120:123], v[156:159], v[72:75], v[120:123]
	v_mfma_f32_16x16x32_bf16 v[124:127], v[160:163], v[72:75], v[124:127]
	v_mfma_f32_16x16x32_bf16 v[128:131], v[148:151], v[72:75], v[128:131]
	ds_read_b128 v[140:143], v71 offset:30720
	ds_read_b128 v[144:147], v71 offset:28672
	ds_read_b128 v[148:151], v71 offset:26624
	ds_read_b128 v[152:155], v71 offset:24576
	v_mfma_f32_16x16x32_bf16 v[132:135], v[164:167], v[72:75], v[132:135]
	v_mfma_f32_16x16x32_bf16 v[136:139], v[168:171], v[72:75], v[136:139]
	ds_read_b128 v[156:159], v71 offset:22528
	ds_read_b128 v[160:163], v71 offset:20480
	ds_read_b128 v[164:167], v71 offset:18432
	ds_read_b128 v[168:171], v71 offset:16384
	v_mfma_f32_16x16x32_bf16 v[72:75], v[172:175], v[72:75], v[76:79]
	s_waitcnt lgkmcnt(0)
	v_mfma_f32_16x16x32_bf16 v[76:79], v[168:171], v[52:55], v[84:87]
	v_mfma_f32_16x16x32_bf16 v[80:83], v[164:167], v[52:55], v[80:83]
	v_mfma_f32_16x16x32_bf16 v[84:87], v[160:163], v[52:55], v[92:95]
	v_mfma_f32_16x16x32_bf16 v[88:91], v[156:159], v[52:55], v[88:91]
	v_mfma_f32_16x16x32_bf16 v[92:95], v[152:155], v[52:55], v[96:99]
	v_mfma_f32_16x16x32_bf16 v[96:99], v[148:151], v[52:55], v[100:103]
	s_nop 2
	ds_read_b128 v[100:103], v71 offset:49152
	ds_read_b128 v[148:151], v71 offset:51200
	ds_read_b128 v[152:155], v71 offset:53248
	ds_read_b128 v[156:159], v71 offset:55296
	v_mfma_f32_16x16x32_bf16 v[104:107], v[144:147], v[52:55], v[104:107]
	ds_read_b128 v[144:147], v71 offset:57344
	ds_read_b128 v[160:163], v71 offset:59392
	ds_read_b128 v[164:167], v71 offset:61440
	ds_read_b128 v[168:171], v71 offset:63488
	v_mfma_f32_16x16x32_bf16 v[108:111], v[140:143], v[52:55], v[108:111]
	s_waitcnt lgkmcnt(0)
	v_mfma_f32_16x16x32_bf16 v[100:103], v[100:103], v[52:55], v[112:115]
	v_mfma_f32_16x16x32_bf16 v[112:115], v[148:151], v[52:55], v[116:119]
	v_mfma_f32_16x16x32_bf16 v[116:119], v[152:155], v[52:55], v[120:123]
	v_mfma_f32_16x16x32_bf16 v[120:123], v[156:159], v[52:55], v[124:127]
	v_mfma_f32_16x16x32_bf16 v[124:127], v[144:147], v[52:55], v[128:131]
	v_mfma_f32_16x16x32_bf16 v[128:131], v[160:163], v[52:55], v[132:135]
	s_nop 2
	ds_read_b128 v[132:135], v71 offset:31744
	ds_read_b128 v[140:143], v71 offset:29696
	ds_read_b128 v[144:147], v71 offset:27648
	ds_read_b128 v[148:151], v71 offset:25600
	v_mfma_f32_16x16x32_bf16 v[136:139], v[164:167], v[52:55], v[136:139]
	ds_read_b128 v[152:155], v71 offset:23552
	ds_read_b128 v[156:159], v71 offset:21504
	ds_read_b128 v[160:163], v71 offset:19456
	ds_read_b128 v[164:167], v71 offset:17408
	v_mfma_f32_16x16x32_bf16 v[52:55], v[168:171], v[52:55], v[72:75]
	s_waitcnt lgkmcnt(0)
	v_mfma_f32_16x16x32_bf16 v[72:75], v[164:167], v[48:51], v[76:79]
	v_mfma_f32_16x16x32_bf16 v[76:79], v[160:163], v[48:51], v[80:83]
	v_mfma_f32_16x16x32_bf16 v[80:83], v[156:159], v[48:51], v[84:87]
	v_mfma_f32_16x16x32_bf16 v[84:87], v[152:155], v[48:51], v[88:91]
	v_mfma_f32_16x16x32_bf16 v[88:91], v[148:151], v[48:51], v[92:95]
	v_mfma_f32_16x16x32_bf16 v[92:95], v[144:147], v[48:51], v[96:99]
	s_nop 2
	ds_read_b128 v[96:99], v71 offset:50176
	ds_read_b128 v[144:147], v71 offset:52224
	ds_read_b128 v[148:151], v71 offset:54272
	ds_read_b128 v[152:155], v71 offset:56320
	v_mfma_f32_16x16x32_bf16 v[104:107], v[140:143], v[48:51], v[104:107]
	ds_read_b128 v[140:143], v71 offset:58368
	ds_read_b128 v[156:159], v71 offset:60416
	ds_read_b128 v[160:163], v71 offset:62464
	ds_read_b128 v[164:167], v71 offset:64512
	v_mfma_f32_16x16x32_bf16 v[108:111], v[132:135], v[48:51], v[108:111]
	s_waitcnt lgkmcnt(0)
	v_mfma_f32_16x16x32_bf16 v[96:99], v[96:99], v[48:51], v[100:103]
	v_mfma_f32_16x16x32_bf16 v[100:103], v[144:147], v[48:51], v[112:115]
	v_mfma_f32_16x16x32_bf16 v[112:115], v[148:151], v[48:51], v[116:119]
	v_mfma_f32_16x16x32_bf16 v[116:119], v[152:155], v[48:51], v[120:123]
	v_mfma_f32_16x16x32_bf16 v[120:123], v[140:143], v[48:51], v[124:127]
	v_mfma_f32_16x16x32_bf16 v[124:127], v[156:159], v[48:51], v[128:131]
	v_mfma_f32_16x16x32_bf16 v[128:131], v[160:163], v[48:51], v[136:139]
	v_mfma_f32_16x16x32_bf16 v[50:53], v[164:167], v[48:51], v[52:55]
	s_waitcnt vmcnt(0)
	s_waitcnt vmcnt(0)
	s_barrier
	v_add_u32_e32 v48, 0x10000, v65
	v_mov_b32_e32 v49, v48
	ds_read_b128 v[132:135], v49
	ds_read_b128 v[136:139], v49 offset:2048
	s_waitcnt lgkmcnt(0)
	v_mfma_f32_16x16x32_bf16 v[72:75], v[132:135], v[44:47], v[72:75]
	ds_read_b128 v[132:135], v49 offset:4096
	v_mfma_f32_16x16x32_bf16 v[76:79], v[136:139], v[44:47], v[76:79]
	ds_read_b128 v[136:139], v49 offset:6144
	s_waitcnt lgkmcnt(0)
	v_mfma_f32_16x16x32_bf16 v[80:83], v[132:135], v[44:47], v[80:83]
	ds_read_b128 v[132:135], v49 offset:8192
	v_mfma_f32_16x16x32_bf16 v[84:87], v[136:139], v[44:47], v[84:87]
	ds_read_b128 v[136:139], v49 offset:10240
	s_waitcnt lgkmcnt(0)
	v_mfma_f32_16x16x32_bf16 v[88:91], v[132:135], v[44:47], v[88:91]
	ds_read_b128 v[132:135], v49 offset:12288
	ds_read_b128 v[140:143], v49 offset:14336
	v_mfma_f32_16x16x32_bf16 v[92:95], v[136:139], v[44:47], v[92:95]
	ds_read_b128 v[136:139], v49 offset:32768
	ds_read_b128 v[144:147], v49 offset:34816
	ds_read_b128 v[148:151], v49 offset:36864
	ds_read_b128 v[152:155], v49 offset:38912
	s_waitcnt lgkmcnt(0)
	v_mfma_f32_16x16x32_bf16 v[104:107], v[132:135], v[44:47], v[104:107]
	ds_read_b128 v[132:135], v49 offset:40960
	ds_read_b128 v[156:159], v49 offset:43008
	ds_read_b128 v[160:163], v49 offset:45056
	ds_read_b128 v[164:167], v49 offset:47104
	v_mfma_f32_16x16x32_bf16 v[108:111], v[140:143], v[44:47], v[108:111]
	s_add_u32 s100, s10, 0x11400200
	s_addc_u32 s101, s11, 0
	s_mov_b32 m0, s22
	s_nop 0
	global_load_lds_dwordx4 v240, s[100:101]
	v_mfma_f32_16x16x32_bf16 v[96:99], v[136:139], v[44:47], v[96:99]
	v_mfma_f32_16x16x32_bf16 v[100:103], v[144:147], v[44:47], v[100:103]
	v_mfma_f32_16x16x32_bf16 v[112:115], v[148:151], v[44:47], v[112:115]
	v_mfma_f32_16x16x32_bf16 v[116:119], v[152:155], v[44:47], v[116:119]
	s_waitcnt lgkmcnt(0)
	v_mfma_f32_16x16x32_bf16 v[120:123], v[132:135], v[44:47], v[120:123]
	ds_read_b128 v[132:135], v49 offset:15360
	ds_read_b128 v[136:139], v49 offset:13312
	ds_read_b128 v[140:143], v49 offset:11264
	ds_read_b128 v[144:147], v49 offset:9216
	v_mfma_f32_16x16x32_bf16 v[124:127], v[156:159], v[44:47], v[124:127]
	v_mfma_f32_16x16x32_bf16 v[128:131], v[160:163], v[44:47], v[128:131]
	ds_read_b128 v[148:151], v49 offset:7168
	ds_read_b128 v[152:155], v49 offset:5120
	ds_read_b128 v[156:159], v49 offset:3072
	ds_read_b128 v[160:163], v49 offset:1024
	v_mfma_f32_16x16x32_bf16 v[44:47], v[164:167], v[44:47], v[50:53]
	s_add_u32 s100, s10, 0x11410200
	s_addc_u32 s101, s11, 0
	s_mov_b32 m0, s21
	s_nop 0
	global_load_lds_dwordx4 v240, s[100:101]
	s_waitcnt lgkmcnt(0)
	v_mfma_f32_16x16x32_bf16 v[50:53], v[160:163], v[40:43], v[72:75]
	v_mfma_f32_16x16x32_bf16 v[72:75], v[156:159], v[40:43], v[76:79]
	v_mfma_f32_16x16x32_bf16 v[76:79], v[152:155], v[40:43], v[80:83]
	v_mfma_f32_16x16x32_bf16 v[80:83], v[148:151], v[40:43], v[84:87]
	v_mfma_f32_16x16x32_bf16 v[84:87], v[144:147], v[40:43], v[88:91]
	v_mfma_f32_16x16x32_bf16 v[88:91], v[140:143], v[40:43], v[92:95]
	s_nop 2
	ds_read_b128 v[92:95], v49 offset:33792
	ds_read_b128 v[140:143], v49 offset:35840
	ds_read_b128 v[144:147], v49 offset:37888
	ds_read_b128 v[148:151], v49 offset:39936
	v_mfma_f32_16x16x32_bf16 v[104:107], v[136:139], v[40:43], v[104:107]
	ds_read_b128 v[136:139], v49 offset:41984
	ds_read_b128 v[152:155], v49 offset:44032
	ds_read_b128 v[156:159], v49 offset:46080
	ds_read_b128 v[160:163], v49 offset:48128
	v_mfma_f32_16x16x32_bf16 v[108:111], v[132:135], v[40:43], v[108:111]
	s_add_u32 s100, s10, 0x11400280
	s_addc_u32 s101, s11, 0
	s_mov_b32 m0, s20
	s_nop 0
	global_load_lds_dwordx4 v240, s[100:101]
	s_waitcnt lgkmcnt(0)
	v_mfma_f32_16x16x32_bf16 v[92:95], v[92:95], v[40:43], v[96:99]
	v_mfma_f32_16x16x32_bf16 v[96:99], v[140:143], v[40:43], v[100:103]
	v_mfma_f32_16x16x32_bf16 v[100:103], v[144:147], v[40:43], v[112:115]
	v_mfma_f32_16x16x32_bf16 v[112:115], v[148:151], v[40:43], v[116:119]
	v_mfma_f32_16x16x32_bf16 v[116:119], v[136:139], v[40:43], v[120:123]
	v_mfma_f32_16x16x32_bf16 v[120:123], v[152:155], v[40:43], v[124:127]
	s_nop 2
	ds_read_b128 v[124:127], v49 offset:30720
	ds_read_b128 v[132:135], v49 offset:28672
	ds_read_b128 v[136:139], v49 offset:26624
	ds_read_b128 v[140:143], v49 offset:24576
	v_mfma_f32_16x16x32_bf16 v[128:131], v[156:159], v[40:43], v[128:131]
	ds_read_b128 v[144:147], v49 offset:22528
	ds_read_b128 v[148:151], v49 offset:20480
	ds_read_b128 v[152:155], v49 offset:18432
	ds_read_b128 v[156:159], v49 offset:16384
	v_mfma_f32_16x16x32_bf16 v[40:43], v[160:163], v[40:43], v[44:47]
	s_add_u32 s100, s10, 0x11410280
	s_addc_u32 s101, s11, 0
	s_mov_b32 m0, s23
	s_nop 0
	global_load_lds_dwordx4 v240, s[100:101]
	s_waitcnt lgkmcnt(0)
	v_mfma_f32_16x16x32_bf16 v[44:47], v[156:159], v[36:39], v[50:53]
	v_mfma_f32_16x16x32_bf16 v[50:53], v[152:155], v[36:39], v[72:75]
	v_mfma_f32_16x16x32_bf16 v[72:75], v[148:151], v[36:39], v[76:79]
	v_mfma_f32_16x16x32_bf16 v[76:79], v[144:147], v[36:39], v[80:83]
	v_mfma_f32_16x16x32_bf16 v[80:83], v[140:143], v[36:39], v[84:87]
	v_mfma_f32_16x16x32_bf16 v[84:87], v[136:139], v[36:39], v[88:91]
	s_nop 2
	ds_read_b128 v[88:91], v49 offset:49152
	ds_read_b128 v[136:139], v49 offset:51200
	ds_read_b128 v[140:143], v49 offset:53248
	ds_read_b128 v[144:147], v49 offset:55296
	v_mfma_f32_16x16x32_bf16 v[104:107], v[132:135], v[36:39], v[104:107]
	ds_read_b128 v[132:135], v49 offset:57344
	ds_read_b128 v[148:151], v49 offset:59392
	ds_read_b128 v[152:155], v49 offset:61440
	ds_read_b128 v[156:159], v49 offset:63488
	v_mfma_f32_16x16x32_bf16 v[108:111], v[124:127], v[36:39], v[108:111]
	s_add_u32 s100, s10, 0x11420200
	s_addc_u32 s101, s11, 0
	s_mov_b32 m0, s24
	s_nop 0
	global_load_lds_dwordx4 v240, s[100:101]
	s_waitcnt lgkmcnt(0)
	v_mfma_f32_16x16x32_bf16 v[88:91], v[88:91], v[36:39], v[92:95]
	v_mfma_f32_16x16x32_bf16 v[92:95], v[136:139], v[36:39], v[96:99]
	v_mfma_f32_16x16x32_bf16 v[96:99], v[140:143], v[36:39], v[100:103]
	v_mfma_f32_16x16x32_bf16 v[100:103], v[144:147], v[36:39], v[112:115]
	v_mfma_f32_16x16x32_bf16 v[112:115], v[132:135], v[36:39], v[116:119]
	v_mfma_f32_16x16x32_bf16 v[116:119], v[148:151], v[36:39], v[120:123]
	s_nop 2
	ds_read_b128 v[120:123], v49 offset:31744
	ds_read_b128 v[124:127], v49 offset:29696
	ds_read_b128 v[132:135], v49 offset:27648
	ds_read_b128 v[136:139], v49 offset:25600
	v_mfma_f32_16x16x32_bf16 v[128:131], v[152:155], v[36:39], v[128:131]
	ds_read_b128 v[140:143], v49 offset:23552
	ds_read_b128 v[144:147], v49 offset:21504
	ds_read_b128 v[148:151], v49 offset:19456
	ds_read_b128 v[152:155], v49 offset:17408
	v_mfma_f32_16x16x32_bf16 v[36:39], v[156:159], v[36:39], v[40:43]
	s_add_u32 s100, s10, 0x11430200
	s_addc_u32 s101, s11, 0
	s_mov_b32 m0, s25
	s_nop 0
	global_load_lds_dwordx4 v240, s[100:101]
	s_waitcnt lgkmcnt(0)
	v_mfma_f32_16x16x32_bf16 v[40:43], v[152:155], v[32:35], v[44:47]
	v_mfma_f32_16x16x32_bf16 v[44:47], v[148:151], v[32:35], v[50:53]
	v_mfma_f32_16x16x32_bf16 v[50:53], v[144:147], v[32:35], v[72:75]
	v_mfma_f32_16x16x32_bf16 v[72:75], v[140:143], v[32:35], v[76:79]
	v_mfma_f32_16x16x32_bf16 v[76:79], v[136:139], v[32:35], v[80:83]
	v_mfma_f32_16x16x32_bf16 v[80:83], v[132:135], v[32:35], v[84:87]
	s_nop 2
	ds_read_b128 v[84:87], v49 offset:50176
	ds_read_b128 v[132:135], v49 offset:52224
	ds_read_b128 v[136:139], v49 offset:54272
	ds_read_b128 v[140:143], v49 offset:56320
	v_mfma_f32_16x16x32_bf16 v[104:107], v[124:127], v[32:35], v[104:107]
	ds_read_b128 v[124:127], v49 offset:58368
	ds_read_b128 v[144:147], v49 offset:60416
	ds_read_b128 v[148:151], v49 offset:62464
	ds_read_b128 v[152:155], v49 offset:64512
	v_mfma_f32_16x16x32_bf16 v[108:111], v[120:123], v[32:35], v[108:111]
	s_add_u32 s100, s10, 0x11420280
	s_addc_u32 s101, s11, 0
	s_mov_b32 m0, s26
	s_nop 0
	global_load_lds_dwordx4 v240, s[100:101]
	s_waitcnt lgkmcnt(0)
	v_mfma_f32_16x16x32_bf16 v[84:87], v[84:87], v[32:35], v[88:91]
	v_mfma_f32_16x16x32_bf16 v[88:91], v[132:135], v[32:35], v[92:95]
	v_mfma_f32_16x16x32_bf16 v[92:95], v[136:139], v[32:35], v[96:99]
	v_mfma_f32_16x16x32_bf16 v[96:99], v[140:143], v[32:35], v[100:103]
	v_mfma_f32_16x16x32_bf16 v[100:103], v[124:127], v[32:35], v[112:115]
	v_mfma_f32_16x16x32_bf16 v[112:115], v[144:147], v[32:35], v[116:119]
	v_mfma_f32_16x16x32_bf16 v[116:119], v[148:151], v[32:35], v[128:131]
	v_mfma_f32_16x16x32_bf16 v[32:35], v[152:155], v[32:35], v[36:39]
	s_add_u32 s100, s10, 0x11430280
	s_addc_u32 s101, s11, 0
	s_mov_b32 m0, s27
	s_nop 0
	global_load_lds_dwordx4 v240, s[100:101]
	s_nop 0
	s_waitcnt vmcnt(0)
	s_waitcnt vmcnt(0)
	s_barrier
	v_mov_b32_e32 v49, v65
	ds_read_b128 v[36:39], v49
	ds_read_b128 v[66:69], v49 offset:2048
	s_waitcnt lgkmcnt(0)
	v_mfma_f32_16x16x32_bf16 v[36:39], v[36:39], v[28:31], v[40:43]
	s_nop 2
	ds_read_b128 v[40:43], v49 offset:4096
	v_mfma_f32_16x16x32_bf16 v[44:47], v[66:69], v[28:31], v[44:47]
	ds_read_b128 v[66:69], v49 offset:6144
	s_waitcnt lgkmcnt(0)
	v_mfma_f32_16x16x32_bf16 v[40:43], v[40:43], v[28:31], v[50:53]
	s_nop 2
	ds_read_b128 v[50:53], v49 offset:8192
	v_mfma_f32_16x16x32_bf16 v[66:69], v[66:69], v[28:31], v[72:75]
	s_nop 2
	ds_read_b128 v[72:75], v49 offset:10240
	s_waitcnt lgkmcnt(0)
	v_mfma_f32_16x16x32_bf16 v[50:53], v[50:53], v[28:31], v[76:79]
	s_nop 2
	ds_read_b128 v[76:79], v49 offset:12288
	ds_read_b128 v[120:123], v49 offset:14336
	v_mfma_f32_16x16x32_bf16 v[72:75], v[72:75], v[28:31], v[80:83]
	s_nop 2
	ds_read_b128 v[80:83], v49 offset:32768
	ds_read_b128 v[124:127], v49 offset:34816
	ds_read_b128 v[128:131], v49 offset:36864
	ds_read_b128 v[132:135], v49 offset:38912
	s_waitcnt lgkmcnt(0)
	v_mfma_f32_16x16x32_bf16 v[76:79], v[76:79], v[28:31], v[104:107]
	s_nop 2
	ds_read_b128 v[104:107], v49 offset:40960
	ds_read_b128 v[136:139], v49 offset:43008
	ds_read_b128 v[140:143], v49 offset:45056
	ds_read_b128 v[144:147], v49 offset:47104
	v_mfma_f32_16x16x32_bf16 v[108:111], v[120:123], v[28:31], v[108:111]
	s_add_u32 s100, s10, 0x11400300
	s_addc_u32 s101, s11, 0
	s_mov_b32 m0, s19
	s_nop 0
	global_load_lds_dwordx4 v240, s[100:101]
	v_mfma_f32_16x16x32_bf16 v[80:83], v[80:83], v[28:31], v[84:87]
	v_mfma_f32_16x16x32_bf16 v[84:87], v[124:127], v[28:31], v[88:91]
	v_mfma_f32_16x16x32_bf16 v[88:91], v[128:131], v[28:31], v[92:95]
	v_mfma_f32_16x16x32_bf16 v[92:95], v[132:135], v[28:31], v[96:99]
	s_waitcnt lgkmcnt(0)
	v_mfma_f32_16x16x32_bf16 v[96:99], v[104:107], v[28:31], v[100:103]
	v_mfma_f32_16x16x32_bf16 v[100:103], v[136:139], v[28:31], v[112:115]
	ds_read_b128 v[104:107], v49 offset:15360
	s_nop 1
	ds_read_b128 v[112:115], v49 offset:13312
	ds_read_b128 v[120:123], v49 offset:11264
	ds_read_b128 v[124:127], v49 offset:9216
	v_mfma_f32_16x16x32_bf16 v[116:119], v[140:143], v[28:31], v[116:119]
	ds_read_b128 v[128:131], v49 offset:7168
	ds_read_b128 v[132:135], v49 offset:5120
	ds_read_b128 v[136:139], v49 offset:3072
	ds_read_b128 v[140:143], v49 offset:1024
	v_mfma_f32_16x16x32_bf16 v[28:31], v[144:147], v[28:31], v[32:35]
	s_add_u32 s100, s10, 0x11410300
	s_addc_u32 s101, s11, 0
	s_mov_b32 m0, s13
	s_nop 0
	global_load_lds_dwordx4 v240, s[100:101]
	s_waitcnt lgkmcnt(0)
	v_mfma_f32_16x16x32_bf16 v[32:35], v[140:143], v[24:27], v[36:39]
	v_mfma_f32_16x16x32_bf16 v[36:39], v[136:139], v[24:27], v[44:47]
	v_mfma_f32_16x16x32_bf16 v[40:43], v[132:135], v[24:27], v[40:43]
	v_mfma_f32_16x16x32_bf16 v[44:47], v[128:131], v[24:27], v[66:69]
	v_mfma_f32_16x16x32_bf16 v[50:53], v[124:127], v[24:27], v[50:53]
	v_mfma_f32_16x16x32_bf16 v[66:69], v[120:123], v[24:27], v[72:75]
	s_nop 2
	ds_read_b128 v[72:75], v49 offset:33792
	ds_read_b128 v[120:123], v49 offset:35840
	ds_read_b128 v[124:127], v49 offset:37888
	ds_read_b128 v[128:131], v49 offset:39936
	v_mfma_f32_16x16x32_bf16 v[76:79], v[112:115], v[24:27], v[76:79]
	ds_read_b128 v[112:115], v49 offset:41984
	ds_read_b128 v[132:135], v49 offset:44032
	ds_read_b128 v[136:139], v49 offset:46080
	ds_read_b128 v[140:143], v49 offset:48128
	v_mfma_f32_16x16x32_bf16 v[104:107], v[104:107], v[24:27], v[108:111]
	s_add_u32 s100, s10, 0x11400380
	s_addc_u32 s101, s11, 0
	s_mov_b32 m0, s12
	s_nop 0
	global_load_lds_dwordx4 v240, s[100:101]
	s_waitcnt lgkmcnt(0)
	v_mfma_f32_16x16x32_bf16 v[72:75], v[72:75], v[24:27], v[80:83]
	v_mfma_f32_16x16x32_bf16 v[80:83], v[120:123], v[24:27], v[84:87]
	v_mfma_f32_16x16x32_bf16 v[84:87], v[124:127], v[24:27], v[88:91]
	v_mfma_f32_16x16x32_bf16 v[88:91], v[128:131], v[24:27], v[92:95]
	v_mfma_f32_16x16x32_bf16 v[92:95], v[112:115], v[24:27], v[96:99]
	v_mfma_f32_16x16x32_bf16 v[96:99], v[132:135], v[24:27], v[100:103]
	s_nop 2
	ds_read_b128 v[100:103], v49 offset:30720
	ds_read_b128 v[108:111], v49 offset:28672
	ds_read_b128 v[112:115], v49 offset:26624
	ds_read_b128 v[120:123], v49 offset:24576
	v_mfma_f32_16x16x32_bf16 v[116:119], v[136:139], v[24:27], v[116:119]
	ds_read_b128 v[124:127], v49 offset:22528
	ds_read_b128 v[128:131], v49 offset:20480
	ds_read_b128 v[132:135], v49 offset:18432
	ds_read_b128 v[136:139], v49 offset:16384
	v_mfma_f32_16x16x32_bf16 v[24:27], v[140:143], v[24:27], v[28:31]
	s_add_u32 s100, s10, 0x11410380
	s_addc_u32 s101, s11, 0
	s_mov_b32 m0, s14
	s_nop 0
	global_load_lds_dwordx4 v240, s[100:101]
	s_waitcnt lgkmcnt(0)
	v_mfma_f32_16x16x32_bf16 v[28:31], v[136:139], v[20:23], v[32:35]
	v_mfma_f32_16x16x32_bf16 v[32:35], v[132:135], v[20:23], v[36:39]
	v_mfma_f32_16x16x32_bf16 v[36:39], v[128:131], v[20:23], v[40:43]
	v_mfma_f32_16x16x32_bf16 v[40:43], v[124:127], v[20:23], v[44:47]
	v_mfma_f32_16x16x32_bf16 v[44:47], v[120:123], v[20:23], v[50:53]
	v_mfma_f32_16x16x32_bf16 v[50:53], v[112:115], v[20:23], v[66:69]
	s_nop 2
	ds_read_b128 v[66:69], v49 offset:49152
	ds_read_b128 v[112:115], v49 offset:51200
	ds_read_b128 v[120:123], v49 offset:53248
	ds_read_b128 v[124:127], v49 offset:55296
	v_mfma_f32_16x16x32_bf16 v[76:79], v[108:111], v[20:23], v[76:79]
	ds_read_b128 v[108:111], v49 offset:57344
	ds_read_b128 v[128:131], v49 offset:59392
	ds_read_b128 v[132:135], v49 offset:61440
	ds_read_b128 v[136:139], v49 offset:63488
	v_mfma_f32_16x16x32_bf16 v[100:103], v[100:103], v[20:23], v[104:107]
	s_add_u32 s100, s10, 0x11420300
	s_addc_u32 s101, s11, 0
	s_mov_b32 m0, s15
	s_nop 0
	global_load_lds_dwordx4 v240, s[100:101]
	s_waitcnt lgkmcnt(0)
	v_mfma_f32_16x16x32_bf16 v[66:69], v[66:69], v[20:23], v[72:75]
	v_mfma_f32_16x16x32_bf16 v[72:75], v[112:115], v[20:23], v[80:83]
	v_mfma_f32_16x16x32_bf16 v[80:83], v[120:123], v[20:23], v[84:87]
	v_mfma_f32_16x16x32_bf16 v[84:87], v[124:127], v[20:23], v[88:91]
	v_mfma_f32_16x16x32_bf16 v[88:91], v[108:111], v[20:23], v[92:95]
	v_mfma_f32_16x16x32_bf16 v[92:95], v[128:131], v[20:23], v[96:99]
	s_nop 2
	ds_read_b128 v[96:99], v49 offset:31744
	ds_read_b128 v[104:107], v49 offset:29696
	ds_read_b128 v[108:111], v49 offset:27648
	ds_read_b128 v[112:115], v49 offset:25600
	v_mfma_f32_16x16x32_bf16 v[116:119], v[132:135], v[20:23], v[116:119]
	ds_read_b128 v[120:123], v49 offset:23552
	ds_read_b128 v[124:127], v49 offset:21504
	ds_read_b128 v[128:131], v49 offset:19456
	ds_read_b128 v[132:135], v49 offset:17408
	v_mfma_f32_16x16x32_bf16 v[20:23], v[136:139], v[20:23], v[24:27]
	s_add_u32 s100, s10, 0x11430300
	s_addc_u32 s101, s11, 0
	s_mov_b32 m0, s16
	s_nop 0
	global_load_lds_dwordx4 v240, s[100:101]
	s_waitcnt lgkmcnt(0)
	v_mfma_f32_16x16x32_bf16 v[24:27], v[132:135], v[16:19], v[28:31]
	v_mfma_f32_16x16x32_bf16 v[28:31], v[128:131], v[16:19], v[32:35]
	v_mfma_f32_16x16x32_bf16 v[32:35], v[124:127], v[16:19], v[36:39]
	v_mfma_f32_16x16x32_bf16 v[36:39], v[120:123], v[16:19], v[40:43]
	v_mfma_f32_16x16x32_bf16 v[40:43], v[112:115], v[16:19], v[44:47]
	v_mfma_f32_16x16x32_bf16 v[50:53], v[108:111], v[16:19], v[50:53]
	s_nop 1
	ds_read_b128 v[44:47], v49 offset:50176
	ds_read_b128 v[108:111], v49 offset:52224
	ds_read_b128 v[112:115], v49 offset:54272
	ds_read_b128 v[120:123], v49 offset:56320
	v_mfma_f32_16x16x32_bf16 v[76:79], v[104:107], v[16:19], v[76:79]
	ds_read_b128 v[104:107], v49 offset:58368
	ds_read_b128 v[124:127], v49 offset:60416
	ds_read_b128 v[128:131], v49 offset:62464
	ds_read_b128 v[132:135], v49 offset:64512
	v_mfma_f32_16x16x32_bf16 v[96:99], v[96:99], v[16:19], v[100:103]
	s_add_u32 s100, s10, 0x11420380
	s_addc_u32 s101, s11, 0
	s_mov_b32 m0, s17
	s_nop 0
	global_load_lds_dwordx4 v240, s[100:101]
	s_waitcnt lgkmcnt(0)
	v_mfma_f32_16x16x32_bf16 v[66:69], v[44:47], v[16:19], v[66:69]
	v_mfma_f32_16x16x32_bf16 v[72:75], v[108:111], v[16:19], v[72:75]
	v_mfma_f32_16x16x32_bf16 v[80:83], v[112:115], v[16:19], v[80:83]
	v_mfma_f32_16x16x32_bf16 v[84:87], v[120:123], v[16:19], v[84:87]
	v_mfma_f32_16x16x32_bf16 v[88:91], v[104:107], v[16:19], v[88:91]
	v_mfma_f32_16x16x32_bf16 v[92:95], v[124:127], v[16:19], v[92:95]
	v_mfma_f32_16x16x32_bf16 v[100:103], v[128:131], v[16:19], v[116:119]
	v_mfma_f32_16x16x32_bf16 v[16:19], v[132:135], v[16:19], v[20:23]
	s_add_u32 s100, s10, 0x11430380
	s_addc_u32 s101, s11, 0
	s_mov_b32 m0, s18
	s_nop 0
	global_load_lds_dwordx4 v240, s[100:101]
	s_waitcnt vmcnt(0)
	s_waitcnt vmcnt(0)
	s_barrier
	v_mov_b32_e32 v49, v48
	ds_read_b128 v[20:23], v49
	ds_read_b128 v[104:107], v49 offset:2048
	s_waitcnt lgkmcnt(0)
	v_mfma_f32_16x16x32_bf16 v[20:23], v[20:23], v[12:15], v[24:27]
	s_nop 2
	ds_read_b128 v[24:27], v49 offset:4096
	v_mfma_f32_16x16x32_bf16 v[28:31], v[104:107], v[12:15], v[28:31]
	ds_read_b128 v[104:107], v49 offset:6144
	s_waitcnt lgkmcnt(0)
	v_mfma_f32_16x16x32_bf16 v[24:27], v[24:27], v[12:15], v[32:35]
	s_nop 2
	ds_read_b128 v[32:35], v49 offset:8192
	v_mfma_f32_16x16x32_bf16 v[36:39], v[104:107], v[12:15], v[36:39]
	ds_read_b128 v[104:107], v49 offset:10240
	s_waitcnt lgkmcnt(0)
	v_mfma_f32_16x16x32_bf16 v[32:35], v[32:35], v[12:15], v[40:43]
	s_nop 2
	ds_read_b128 v[40:43], v49 offset:12288
	ds_read_b128 v[108:111], v49 offset:14336
	v_mfma_f32_16x16x32_bf16 v[50:53], v[104:107], v[12:15], v[50:53]
	ds_read_b128 v[104:107], v49 offset:32768
	ds_read_b128 v[112:115], v49 offset:34816
	ds_read_b128 v[116:119], v49 offset:36864
	ds_read_b128 v[120:123], v49 offset:38912
	s_waitcnt lgkmcnt(0)
	v_mfma_f32_16x16x32_bf16 v[40:43], v[40:43], v[12:15], v[76:79]
	s_nop 2
	ds_read_b128 v[76:79], v49 offset:40960
	ds_read_b128 v[124:127], v49 offset:43008
	ds_read_b128 v[128:131], v49 offset:45056
	ds_read_b128 v[132:135], v49 offset:47104
	v_mfma_f32_16x16x32_bf16 v[96:99], v[108:111], v[12:15], v[96:99]
	s_add_u32 s100, s10, 0x11c00000
	s_addc_u32 s101, s11, 0
	s_mov_b32 m0, s22
	s_nop 0
	global_load_lds_dwordx4 v241, s[100:101]
	v_mfma_f32_16x16x32_bf16 v[66:69], v[104:107], v[12:15], v[66:69]
	v_mfma_f32_16x16x32_bf16 v[72:75], v[112:115], v[12:15], v[72:75]
	v_mfma_f32_16x16x32_bf16 v[80:83], v[116:119], v[12:15], v[80:83]
	v_mfma_f32_16x16x32_bf16 v[84:87], v[120:123], v[12:15], v[84:87]
	s_waitcnt lgkmcnt(0)
	v_mfma_f32_16x16x32_bf16 v[76:79], v[76:79], v[12:15], v[88:91]
	v_mfma_f32_16x16x32_bf16 v[88:91], v[124:127], v[12:15], v[92:95]
	s_nop 2
	ds_read_b128 v[92:95], v49 offset:15360
	ds_read_b128 v[104:107], v49 offset:13312
	ds_read_b128 v[108:111], v49 offset:11264
	ds_read_b128 v[112:115], v49 offset:9216
	v_mfma_f32_16x16x32_bf16 v[100:103], v[128:131], v[12:15], v[100:103]
	ds_read_b128 v[116:119], v49 offset:7168
	ds_read_b128 v[120:123], v49 offset:5120
	ds_read_b128 v[124:127], v49 offset:3072
	ds_read_b128 v[128:131], v49 offset:1024
	v_mfma_f32_16x16x32_bf16 v[12:15], v[132:135], v[12:15], v[16:19]
	s_add_u32 s100, s10, 0x11c08000
	s_addc_u32 s101, s11, 0
	s_mov_b32 m0, s21
	s_nop 0
	global_load_lds_dwordx4 v241, s[100:101]
	s_waitcnt lgkmcnt(0)
	v_mfma_f32_16x16x32_bf16 v[16:19], v[128:131], v[8:11], v[20:23]
	v_mfma_f32_16x16x32_bf16 v[20:23], v[124:127], v[8:11], v[28:31]
	v_mfma_f32_16x16x32_bf16 v[24:27], v[120:123], v[8:11], v[24:27]
	v_mfma_f32_16x16x32_bf16 v[28:31], v[116:119], v[8:11], v[36:39]
	v_mfma_f32_16x16x32_bf16 v[32:35], v[112:115], v[8:11], v[32:35]
	v_mfma_f32_16x16x32_bf16 v[36:39], v[108:111], v[8:11], v[50:53]
	s_nop 2
	ds_read_b128 v[50:53], v49 offset:33792
	ds_read_b128 v[108:111], v49 offset:35840
	ds_read_b128 v[112:115], v49 offset:37888
	ds_read_b128 v[116:119], v49 offset:39936
	v_mfma_f32_16x16x32_bf16 v[40:43], v[104:107], v[8:11], v[40:43]
	ds_read_b128 v[104:107], v49 offset:41984
	ds_read_b128 v[120:123], v49 offset:44032
	ds_read_b128 v[124:127], v49 offset:46080
	ds_read_b128 v[128:131], v49 offset:48128
	v_mfma_f32_16x16x32_bf16 v[92:95], v[92:95], v[8:11], v[96:99]
	s_add_u32 s100, s10, 0x11c00080
	s_addc_u32 s101, s11, 0
	s_mov_b32 m0, s20
	s_nop 0
	global_load_lds_dwordx4 v241, s[100:101]
	s_waitcnt lgkmcnt(0)
	v_mfma_f32_16x16x32_bf16 v[50:53], v[50:53], v[8:11], v[66:69]
	v_mfma_f32_16x16x32_bf16 v[66:69], v[108:111], v[8:11], v[72:75]
	v_mfma_f32_16x16x32_bf16 v[72:75], v[112:115], v[8:11], v[80:83]
	v_mfma_f32_16x16x32_bf16 v[80:83], v[116:119], v[8:11], v[84:87]
	v_mfma_f32_16x16x32_bf16 v[76:79], v[104:107], v[8:11], v[76:79]
	v_mfma_f32_16x16x32_bf16 v[84:87], v[120:123], v[8:11], v[88:91]
	s_nop 2
	ds_read_b128 v[88:91], v49 offset:30720
	ds_read_b128 v[96:99], v49 offset:28672
	ds_read_b128 v[104:107], v49 offset:26624
	ds_read_b128 v[108:111], v49 offset:24576
	v_mfma_f32_16x16x32_bf16 v[100:103], v[124:127], v[8:11], v[100:103]
	ds_read_b128 v[112:115], v49 offset:22528
	ds_read_b128 v[116:119], v49 offset:20480
	ds_read_b128 v[120:123], v49 offset:18432
	ds_read_b128 v[124:127], v49 offset:16384
	v_mfma_f32_16x16x32_bf16 v[8:11], v[128:131], v[8:11], v[12:15]
	s_add_u32 s100, s10, 0x11c08080
	s_addc_u32 s101, s11, 0
	s_mov_b32 m0, s23
	s_nop 0
	global_load_lds_dwordx4 v241, s[100:101]
	s_waitcnt lgkmcnt(0)
	v_mfma_f32_16x16x32_bf16 v[12:15], v[124:127], v[4:7], v[16:19]
	v_mfma_f32_16x16x32_bf16 v[16:19], v[120:123], v[4:7], v[20:23]
	v_mfma_f32_16x16x32_bf16 v[20:23], v[116:119], v[4:7], v[24:27]
	v_mfma_f32_16x16x32_bf16 v[24:27], v[112:115], v[4:7], v[28:31]
	v_mfma_f32_16x16x32_bf16 v[28:31], v[108:111], v[4:7], v[32:35]
	v_mfma_f32_16x16x32_bf16 v[32:35], v[104:107], v[4:7], v[36:39]
	s_nop 2
	ds_read_b128 v[36:39], v49 offset:49152
	ds_read_b128 v[104:107], v49 offset:51200
	ds_read_b128 v[108:111], v49 offset:53248
	ds_read_b128 v[112:115], v49 offset:55296
	v_mfma_f32_16x16x32_bf16 v[96:99], v[96:99], v[4:7], v[40:43]
	s_nop 2
	ds_read_b128 v[40:43], v49 offset:57344
	ds_read_b128 v[116:119], v49 offset:59392
	ds_read_b128 v[120:123], v49 offset:61440
	ds_read_b128 v[124:127], v49 offset:63488
	v_mfma_f32_16x16x32_bf16 v[88:91], v[88:91], v[4:7], v[92:95]
	s_add_u32 s100, s10, 0x11c10000
	s_addc_u32 s101, s11, 0
	s_mov_b32 m0, s24
	s_nop 0
	global_load_lds_dwordx4 v241, s[100:101]
	s_waitcnt lgkmcnt(0)
	v_mfma_f32_16x16x32_bf16 v[50:53], v[36:39], v[4:7], v[50:53]
	v_mfma_f32_16x16x32_bf16 v[66:69], v[104:107], v[4:7], v[66:69]
	v_mfma_f32_16x16x32_bf16 v[72:75], v[108:111], v[4:7], v[72:75]
	v_mfma_f32_16x16x32_bf16 v[80:83], v[112:115], v[4:7], v[80:83]
	v_mfma_f32_16x16x32_bf16 v[76:79], v[40:43], v[4:7], v[76:79]
	ds_read_b128 v[92:95], v49 offset:31744
	ds_read_b128 v[36:39], v49 offset:29696
	ds_read_b128 v[40:43], v49 offset:27648
	ds_read_b128 v[104:107], v49 offset:25600
	v_mfma_f32_16x16x32_bf16 v[84:87], v[116:119], v[4:7], v[84:87]
	v_mfma_f32_16x16x32_bf16 v[100:103], v[120:123], v[4:7], v[100:103]
	ds_read_b128 v[108:111], v49 offset:23552
	ds_read_b128 v[112:115], v49 offset:21504
	ds_read_b128 v[116:119], v49 offset:19456
	ds_read_b128 v[120:123], v49 offset:17408
	v_mfma_f32_16x16x32_bf16 v[124:127], v[124:127], v[4:7], v[8:11]
	s_add_u32 s100, s10, 0x11c18000
	s_addc_u32 s101, s11, 0
	s_mov_b32 m0, s25
	s_nop 0
	global_load_lds_dwordx4 v241, s[100:101]
	s_waitcnt lgkmcnt(0)
	v_mfma_f32_16x16x32_bf16 v[120:123], v[120:123], v[0:3], v[12:15]
	v_mfma_f32_16x16x32_bf16 v[116:119], v[116:119], v[0:3], v[16:19]
	ds_read_b128 v[4:7], v49 offset:50176
	ds_read_b128 v[8:11], v49 offset:52224
	ds_read_b128 v[12:15], v49 offset:54272
	ds_read_b128 v[16:19], v49 offset:56320
	v_mfma_f32_16x16x32_bf16 v[36:39], v[36:39], v[0:3], v[96:99]
	s_nop 2
	ds_read_b128 v[96:99], v49 offset:58368
	ds_read_b128 v[128:131], v49 offset:60416
	ds_read_b128 v[132:135], v49 offset:62464
	ds_read_b128 v[136:139], v49 offset:64512
	v_mfma_f32_16x16x32_bf16 v[112:115], v[112:115], v[0:3], v[20:23]
	v_mfma_f32_16x16x32_bf16 v[108:111], v[108:111], v[0:3], v[24:27]
	v_mfma_f32_16x16x32_bf16 v[104:107], v[104:107], v[0:3], v[28:31]
	v_mfma_f32_16x16x32_bf16 v[40:43], v[40:43], v[0:3], v[32:35]
	v_mfma_f32_16x16x32_bf16 v[32:35], v[92:95], v[0:3], v[88:91]
	s_add_u32 s100, s10, 0x11c10080
	s_addc_u32 s101, s11, 0
	s_mov_b32 m0, s26
	s_nop 0
	global_load_lds_dwordx4 v241, s[100:101]
	s_waitcnt lgkmcnt(0)
	v_mfma_f32_16x16x32_bf16 v[28:31], v[4:7], v[0:3], v[50:53]
	v_mfma_f32_16x16x32_bf16 v[24:27], v[8:11], v[0:3], v[66:69]
	v_mfma_f32_16x16x32_bf16 v[20:23], v[12:15], v[0:3], v[72:75]
	v_mfma_f32_16x16x32_bf16 v[16:19], v[16:19], v[0:3], v[80:83]
	v_mfma_f32_16x16x32_bf16 v[12:15], v[96:99], v[0:3], v[76:79]
	v_mfma_f32_16x16x32_bf16 v[8:11], v[128:131], v[0:3], v[84:87]
	v_mfma_f32_16x16x32_bf16 v[4:7], v[132:135], v[0:3], v[100:103]
	v_mfma_f32_16x16x32_bf16 v[0:3], v[136:139], v[0:3], v[124:127]
	s_add_u32 s100, s10, 0x11c18080
	s_addc_u32 s101, s11, 0
	s_mov_b32 m0, s27
	s_nop 0
	global_load_lds_dwordx4 v241, s[100:101]
	v_max_f32_e32 v49, v123, v123
	v_max_f32_e32 v50, v122, v122
	v_max_f32_e32 v49, v50, v49
	v_max_f32_e32 v50, v117, v117
	v_max_f32_e32 v51, v116, v116
	v_max_f32_e32 v50, v51, v50
	v_max_f32_e32 v51, v119, v119
	v_max_f32_e32 v52, v118, v118
	v_max3_f32 v49, v120, v121, v49
	v_max_f32_e32 v51, v52, v51
	v_max3_f32 v49, v49, v50, v51
	v_max_f32_e32 v50, v113, v113
	v_max_f32_e32 v51, v112, v112
	v_max_f32_e32 v50, v51, v50
	v_max_f32_e32 v51, v115, v115
	v_max_f32_e32 v52, v114, v114
	v_max_f32_e32 v51, v52, v51
	v_max3_f32 v49, v49, v50, v51
	v_max_f32_e32 v50, v109, v109
	v_max_f32_e32 v51, v108, v108
	v_max_f32_e32 v50, v51, v50
	v_max_f32_e32 v51, v111, v111
	v_max_f32_e32 v52, v110, v110
	v_max_f32_e32 v51, v52, v51
	v_max3_f32 v49, v49, v50, v51
	v_max_f32_e32 v50, v105, v105
	v_max_f32_e32 v51, v104, v104
	v_max_f32_e32 v50, v51, v50
	v_max_f32_e32 v51, v107, v107
	v_max_f32_e32 v52, v106, v106
	v_max_f32_e32 v51, v52, v51
	v_max3_f32 v49, v49, v50, v51
	v_max_f32_e32 v50, v41, v41
	v_max_f32_e32 v51, v40, v40
	v_max_f32_e32 v50, v51, v50
	v_max_f32_e32 v51, v43, v43
	v_max_f32_e32 v52, v42, v42
	v_max_f32_e32 v51, v52, v51
	v_max3_f32 v49, v49, v50, v51
	v_max_f32_e32 v50, v37, v37
	v_max_f32_e32 v51, v36, v36
	v_max_f32_e32 v50, v51, v50
	v_max_f32_e32 v51, v39, v39
	v_max_f32_e32 v52, v38, v38
	v_max_f32_e32 v51, v52, v51
	v_max3_f32 v49, v49, v50, v51
	v_max_f32_e32 v50, v33, v33
	v_max_f32_e32 v51, v32, v32
	v_max_f32_e32 v50, v51, v50
	v_max_f32_e32 v51, v35, v35
	v_max_f32_e32 v52, v34, v34
	v_max_f32_e32 v51, v52, v51
	v_max3_f32 v49, v49, v50, v51
	v_max_f32_e32 v50, v29, v29
	v_max_f32_e32 v51, v28, v28
	v_max_f32_e32 v50, v51, v50
	v_max_f32_e32 v51, v31, v31
	v_max_f32_e32 v52, v30, v30
	v_max_f32_e32 v51, v52, v51
	v_max3_f32 v49, v49, v50, v51
	v_max_f32_e32 v50, v25, v25
	v_max_f32_e32 v51, v24, v24
	v_max_f32_e32 v50, v51, v50
	v_max_f32_e32 v51, v27, v27
	v_max_f32_e32 v52, v26, v26
	v_max_f32_e32 v51, v52, v51
	v_max3_f32 v49, v49, v50, v51
	v_max_f32_e32 v50, v21, v21
	v_max_f32_e32 v51, v20, v20
	v_max_f32_e32 v50, v51, v50
	v_max_f32_e32 v51, v23, v23
	v_max_f32_e32 v52, v22, v22
	v_max_f32_e32 v51, v52, v51
	v_max3_f32 v49, v49, v50, v51
	v_max_f32_e32 v50, v17, v17
	v_max_f32_e32 v51, v16, v16
	v_max_f32_e32 v50, v51, v50
	v_max_f32_e32 v51, v19, v19
	v_max_f32_e32 v52, v18, v18
	v_max_f32_e32 v51, v52, v51
	v_max3_f32 v49, v49, v50, v51
	v_max_f32_e32 v50, v13, v13
	v_max_f32_e32 v51, v12, v12
	v_max_f32_e32 v50, v51, v50
	v_max_f32_e32 v51, v15, v15
	v_max_f32_e32 v52, v14, v14
	v_max_f32_e32 v51, v52, v51
	v_max3_f32 v49, v49, v50, v51
	v_max_f32_e32 v50, v9, v9
	v_max_f32_e32 v51, v8, v8
	v_max_f32_e32 v50, v51, v50
	v_max_f32_e32 v51, v11, v11
	v_max_f32_e32 v52, v10, v10
	v_max_f32_e32 v51, v52, v51
	v_max3_f32 v49, v49, v50, v51
	v_max_f32_e32 v50, v5, v5
	v_max_f32_e32 v51, v4, v4
	v_max_f32_e32 v50, v51, v50
	v_max_f32_e32 v51, v7, v7
	v_max_f32_e32 v52, v6, v6
	v_max_f32_e32 v51, v52, v51
	v_max3_f32 v49, v49, v50, v51
	v_max_f32_e32 v50, v1, v1
	v_max_f32_e32 v51, v0, v0
	v_max_f32_e32 v50, v51, v50
	v_max_f32_e32 v51, v3, v3
	v_max_f32_e32 v52, v2, v2
	v_max_f32_e32 v51, v52, v51
	v_max3_f32 v49, v49, v50, v51
	v_mbcnt_lo_u32_b32 v50, -1, 0
	v_mbcnt_hi_u32_b32 v50, -1, v50
	v_and_b32_e32 v52, 64, v50
	v_xor_b32_e32 v51, 16, v50
	v_add_u32_e32 v52, 64, v52
	v_cmp_lt_i32_e32 vcc, v51, v52
	s_nop 1
	v_cndmask_b32_e32 v51, v50, v51, vcc
	v_lshlrev_b32_e32 v51, 2, v51
	v_mov_b32_e32 v53, v49
	s_nop 1
	v_permlane16_swap_b32_e32 v53, v49
	s_waitcnt lgkmcnt(0)
	v_max_f32_e32 v53, v53, v53
	v_max_f32_e32 v49, v49, v53
	v_xor_b32_e32 v53, 32, v50
	v_cmp_lt_i32_e32 vcc, v53, v52
	s_nop 1
	v_cndmask_b32_e32 v50, v50, v53, vcc
	v_lshlrev_b32_e32 v50, 2, v50
	v_mov_b32_e32 v52, v49
	s_nop 1
	v_permlane32_swap_b32_e32 v52, v49
	s_waitcnt lgkmcnt(0)
	v_max_f32_e32 v52, v52, v52
	v_max_f32_e32 v49, v49, v52
	v_sub_f32_e32 v52, v120, v49
	v_exp_f32_e32 v52, v52
	v_sub_f32_e32 v53, v121, v49
	v_exp_f32_e32 v53, v53
	v_sub_f32_e32 v54, v122, v49
	v_exp_f32_e32 v54, v54
	v_sub_f32_e32 v55, v123, v49
	v_exp_f32_e32 v55, v55
	v_sub_f32_e32 v59, v116, v49
	v_add_f32_e32 v57, 0, v52
	v_exp_f32_e32 v59, v59
	v_sub_f32_e32 v62, v117, v49
	v_add_f32_e32 v57, v53, v57
	v_exp_f32_e32 v62, v62
	v_sub_f32_e32 v63, v118, v49
	v_add_f32_e32 v57, v54, v57
	v_exp_f32_e32 v63, v63
	v_sub_f32_e32 v64, v119, v49
	v_add_f32_e32 v57, v55, v57
	v_exp_f32_e32 v64, v64
	v_sub_f32_e32 v66, v112, v49
	v_add_f32_e32 v57, v59, v57
	v_exp_f32_e32 v66, v66
	v_sub_f32_e32 v67, v113, v49
	v_add_f32_e32 v57, v62, v57
	v_exp_f32_e32 v67, v67
	v_sub_f32_e32 v68, v114, v49
	v_add_f32_e32 v57, v63, v57
	v_exp_f32_e32 v68, v68
	v_sub_f32_e32 v69, v115, v49
	v_add_f32_e32 v57, v64, v57
	v_exp_f32_e32 v69, v69
	v_sub_f32_e32 v71, v108, v49
	v_add_f32_e32 v57, v66, v57
	v_exp_f32_e32 v71, v71
	v_sub_f32_e32 v72, v109, v49
	v_add_f32_e32 v57, v67, v57
	v_exp_f32_e32 v72, v72
	v_sub_f32_e32 v73, v110, v49
	v_add_f32_e32 v57, v68, v57
	v_exp_f32_e32 v73, v73
	v_sub_f32_e32 v74, v111, v49
	v_add_f32_e32 v57, v69, v57
	v_exp_f32_e32 v74, v74
	v_sub_f32_e32 v75, v104, v49
	v_add_f32_e32 v57, v71, v57
	v_exp_f32_e32 v75, v75
	v_sub_f32_e32 v76, v105, v49
	v_add_f32_e32 v57, v72, v57
	v_exp_f32_e32 v76, v76
	v_sub_f32_e32 v77, v106, v49
	v_add_f32_e32 v57, v73, v57
	v_exp_f32_e32 v77, v77
	v_sub_f32_e32 v78, v107, v49
	v_add_f32_e32 v57, v74, v57
	v_exp_f32_e32 v78, v78
	v_sub_f32_e32 v40, v40, v49
	v_add_f32_e32 v57, v75, v57
	v_exp_f32_e32 v40, v40
	v_sub_f32_e32 v41, v41, v49
	v_add_f32_e32 v57, v76, v57
	v_exp_f32_e32 v41, v41
	v_sub_f32_e32 v42, v42, v49
	v_add_f32_e32 v57, v77, v57
	v_exp_f32_e32 v42, v42
	v_sub_f32_e32 v43, v43, v49
	v_add_f32_e32 v57, v78, v57
	v_exp_f32_e32 v43, v43
	v_sub_f32_e32 v36, v36, v49
	v_add_f32_e32 v57, v40, v57
	v_exp_f32_e32 v36, v36
	v_sub_f32_e32 v37, v37, v49
	v_add_f32_e32 v57, v41, v57
	v_exp_f32_e32 v37, v37
	v_sub_f32_e32 v38, v38, v49
	v_add_f32_e32 v57, v42, v57
	v_exp_f32_e32 v38, v38
	v_sub_f32_e32 v39, v39, v49
	v_add_f32_e32 v57, v43, v57
	v_exp_f32_e32 v39, v39
	v_sub_f32_e32 v32, v32, v49
	v_add_f32_e32 v57, v36, v57
	v_exp_f32_e32 v32, v32
	v_sub_f32_e32 v33, v33, v49
	v_add_f32_e32 v57, v37, v57
	v_exp_f32_e32 v33, v33
	v_sub_f32_e32 v34, v34, v49
	v_add_f32_e32 v57, v38, v57
	v_exp_f32_e32 v34, v34
	v_sub_f32_e32 v35, v35, v49
	v_add_f32_e32 v57, v39, v57
	v_exp_f32_e32 v35, v35
	v_sub_f32_e32 v28, v28, v49
	v_add_f32_e32 v57, v32, v57
	v_exp_f32_e32 v79, v28
	v_sub_f32_e32 v28, v29, v49
	v_add_f32_e32 v57, v33, v57
	v_exp_f32_e32 v80, v28
	v_sub_f32_e32 v28, v30, v49
	v_add_f32_e32 v57, v34, v57
	v_exp_f32_e32 v81, v28
	v_sub_f32_e32 v28, v31, v49
	v_add_f32_e32 v57, v35, v57
	v_exp_f32_e32 v82, v28
	v_sub_f32_e32 v24, v24, v49
	v_add_f32_e32 v28, v79, v57
	v_exp_f32_e32 v57, v24
	v_sub_f32_e32 v24, v25, v49
	v_add_f32_e32 v28, v80, v28
	v_exp_f32_e32 v83, v24
	v_sub_f32_e32 v24, v26, v49
	v_add_f32_e32 v28, v81, v28
	v_exp_f32_e32 v84, v24
	v_sub_f32_e32 v24, v27, v49
	v_add_f32_e32 v28, v82, v28
	v_exp_f32_e32 v85, v24
	v_sub_f32_e32 v20, v20, v49
	v_add_f32_e32 v24, v57, v28
	v_exp_f32_e32 v86, v20
	v_sub_f32_e32 v20, v21, v49
	v_add_f32_e32 v24, v83, v24
	v_exp_f32_e32 v87, v20
	v_sub_f32_e32 v20, v22, v49
	v_add_f32_e32 v24, v84, v24
	v_exp_f32_e32 v88, v20
	v_sub_f32_e32 v20, v23, v49
	v_add_f32_e32 v24, v85, v24
	v_exp_f32_e32 v89, v20
	v_sub_f32_e32 v16, v16, v49
	v_add_f32_e32 v20, v86, v24
	v_exp_f32_e32 v90, v16
	v_sub_f32_e32 v16, v17, v49
	v_add_f32_e32 v20, v87, v20
	v_exp_f32_e32 v91, v16
	v_sub_f32_e32 v16, v18, v49
	v_add_f32_e32 v20, v88, v20
	v_exp_f32_e32 v92, v16
	v_sub_f32_e32 v16, v19, v49
	v_add_f32_e32 v20, v89, v20
	v_exp_f32_e32 v93, v16
	v_sub_f32_e32 v12, v12, v49
	v_add_f32_e32 v16, v90, v20
	v_exp_f32_e32 v94, v12
	v_sub_f32_e32 v12, v13, v49
	v_add_f32_e32 v16, v91, v16
	v_exp_f32_e32 v95, v12
	v_sub_f32_e32 v12, v14, v49
	v_add_f32_e32 v16, v92, v16
	v_exp_f32_e32 v96, v12
	v_sub_f32_e32 v12, v15, v49
	v_add_f32_e32 v16, v93, v16
	v_exp_f32_e32 v97, v12
	v_sub_f32_e32 v8, v8, v49
	v_add_f32_e32 v12, v94, v16
	v_exp_f32_e32 v98, v8
	v_sub_f32_e32 v8, v9, v49
	v_add_f32_e32 v12, v95, v12
	v_exp_f32_e32 v99, v8
	v_sub_f32_e32 v8, v10, v49
	v_add_f32_e32 v12, v96, v12
	v_exp_f32_e32 v100, v8
	v_sub_f32_e32 v8, v11, v49
	v_add_f32_e32 v12, v97, v12
	v_exp_f32_e32 v11, v8
	v_sub_f32_e32 v4, v4, v49
	v_add_f32_e32 v8, v98, v12
	v_exp_f32_e32 v101, v4
	v_sub_f32_e32 v4, v5, v49
	v_add_f32_e32 v8, v99, v8
	v_exp_f32_e32 v102, v4
	v_sub_f32_e32 v4, v6, v49
	v_add_f32_e32 v8, v100, v8
	v_exp_f32_e32 v103, v4
	v_sub_f32_e32 v4, v7, v49
	v_add_f32_e32 v8, v11, v8
	v_exp_f32_e32 v104, v4
	v_sub_f32_e32 v0, v0, v49
	v_add_f32_e32 v4, v101, v8
	v_exp_f32_e32 v105, v0
	v_sub_f32_e32 v0, v1, v49
	v_add_f32_e32 v4, v102, v4
	v_exp_f32_e32 v106, v0
	v_sub_f32_e32 v0, v2, v49
	v_add_f32_e32 v4, v103, v4
	v_exp_f32_e32 v107, v0
	v_sub_f32_e32 v0, v3, v49
	v_add_f32_e32 v4, v104, v4
	v_exp_f32_e32 v3, v0
	v_add_f32_e32 v0, v105, v4
	v_add_f32_e32 v0, v106, v0
	v_add_f32_e32 v0, v107, v0
	v_add_f32_e32 v0, v3, v0
	v_mov_b32_e32 v1, v0
	s_nop 1
	v_permlane16_swap_b32_e32 v1, v0
	v_cvt_pk_bf16_f32 v28, v52, v53
	v_cvt_pk_bf16_f32 v29, v54, v55
	v_cvt_pk_bf16_f32 v30, v59, v62
	v_cvt_pk_bf16_f32 v31, v63, v64
	s_waitcnt lgkmcnt(0)
	v_add_f32_e32 v0, v0, v1
	v_mov_b32_e32 v1, v0
	s_nop 1
	v_permlane32_swap_b32_e32 v1, v0
	v_cvt_pk_bf16_f32 v20, v66, v67
	v_cvt_pk_bf16_f32 v21, v68, v69
	v_cvt_pk_bf16_f32 v22, v71, v72
	v_cvt_pk_bf16_f32 v23, v73, v74
	s_waitcnt lgkmcnt(0)
	v_add_f32_e32 v49, v0, v1
	v_cvt_pk_bf16_f32 v24, v75, v76
	v_cvt_pk_bf16_f32 v25, v77, v78
	v_cvt_pk_bf16_f32 v26, v40, v41
	v_cvt_pk_bf16_f32 v27, v42, v43
	v_cvt_pk_bf16_f32 v16, v36, v37
	v_cvt_pk_bf16_f32 v17, v38, v39
	v_cvt_pk_bf16_f32 v18, v32, v33
	v_cvt_pk_bf16_f32 v19, v34, v35
	v_cvt_pk_bf16_f32 v12, v79, v80
	v_cvt_pk_bf16_f32 v13, v81, v82
	v_cvt_pk_bf16_f32 v14, v57, v83
	v_cvt_pk_bf16_f32 v15, v84, v85
	v_cvt_pk_bf16_f32 v4, v86, v87
	v_cvt_pk_bf16_f32 v5, v88, v89
	v_cvt_pk_bf16_f32 v6, v90, v91
	v_cvt_pk_bf16_f32 v7, v92, v93
	v_cvt_pk_bf16_f32 v8, v94, v95
	v_cvt_pk_bf16_f32 v9, v96, v97
	v_cvt_pk_bf16_f32 v10, v98, v99
	v_cvt_pk_bf16_f32 v11, v100, v11
	v_cvt_pk_bf16_f32 v0, v101, v102
	v_cvt_pk_bf16_f32 v1, v103, v104
	v_cvt_pk_bf16_f32 v2, v105, v106
	v_cvt_pk_bf16_f32 v3, v107, v3
	s_waitcnt vmcnt(0)
	s_waitcnt vmcnt(0)
	s_barrier
	v_mov_b32_e32 v64, v65
	v_div_scale_f32 v62, vcc, 1.0, v49, 1.0
	v_lshlrev_b32_e32 v54, 2, v70
	v_ashrrev_i32_e32 v55, 31, v54
	ds_read_b128 v[32:35], v64
	ds_read_b128 v[36:39], v64 offset:2048
	v_div_scale_f32 v57, s[0:1], v49, v49, 1.0
	v_rcp_f32_e32 v59, v57
	s_waitcnt lgkmcnt(0)
	v_mfma_f32_16x16x32_bf16 v[44:47], v[32:35], v[28:31], 0
	v_fma_f32 v40, -v57, v59, 1.0
	v_fmac_f32_e32 v59, v40, v59
	ds_read_b128 v[40:43], v64 offset:4096
	ds_read_b128 v[32:35], v64 offset:6144
	v_mul_f32_e32 v63, v62, v59
	v_fma_f32 v66, -v57, v63, v62
	v_fmac_f32_e32 v63, v66, v59
	v_mfma_f32_16x16x32_bf16 v[50:53], v[36:39], v[28:31], 0
	v_fma_f32 v36, -v57, v63, v62
	ds_read_b128 v[66:69], v64 offset:8192
	ds_read_b128 v[70:73], v64 offset:10240
	v_div_fmas_f32 v36, v36, v59, v63
	s_waitcnt lgkmcnt(0)
	v_mfma_f32_16x16x32_bf16 v[74:77], v[32:35], v[28:31], 0
	v_lshl_add_u64 v[34:35], v[54:55], 1, v[60:61]
	ds_read_b128 v[60:63], v64 offset:12288
	ds_read_b128 v[78:81], v64 offset:14336
	ds_read_b128 v[82:85], v64 offset:32768
	ds_read_b128 v[86:89], v64 offset:34816
	ds_read_b128 v[90:93], v64 offset:36864
	ds_read_b128 v[94:97], v64 offset:38912
	ds_read_b128 v[98:101], v64 offset:40960
	ds_read_b128 v[102:105], v64 offset:43008
	ds_read_b128 v[106:109], v64 offset:45056
	ds_read_b128 v[110:113], v64 offset:47104
	s_mov_b64 s[0:1], 0x1000000
	v_mfma_f32_16x16x32_bf16 v[38:41], v[40:43], v[28:31], 0
	v_div_fixup_f32 v36, v36, v49, 1.0
	v_lshl_add_u64 v[32:33], v[34:35], 0, s[0:1]
	v_mfma_f32_16x16x32_bf16 v[66:69], v[66:69], v[28:31], 0
	v_mfma_f32_16x16x32_bf16 v[70:73], v[70:73], v[28:31], 0
	s_waitcnt lgkmcnt(0)
	v_mfma_f32_16x16x32_bf16 v[60:63], v[60:63], v[28:31], 0
	v_mfma_f32_16x16x32_bf16 v[78:81], v[78:81], v[28:31], 0
	s_add_u32 s100, s10, 0x11c00100
	s_addc_u32 s101, s11, 0
	s_mov_b32 m0, s19
	s_nop 0
	global_load_lds_dwordx4 v241, s[100:101]
	ds_read_b128 v[114:117], v64 offset:30720
	ds_read_b128 v[118:121], v64 offset:28672
	ds_read_b128 v[122:125], v64 offset:26624
	ds_read_b128 v[126:129], v64 offset:24576
	ds_read_b128 v[130:133], v64 offset:22528
	ds_read_b128 v[134:137], v64 offset:20480
	ds_read_b128 v[138:141], v64 offset:18432
	ds_read_b128 v[142:145], v64 offset:16384
	v_mfma_f32_16x16x32_bf16 v[82:85], v[82:85], v[28:31], 0
	v_mfma_f32_16x16x32_bf16 v[86:89], v[86:89], v[28:31], 0
	v_mfma_f32_16x16x32_bf16 v[90:93], v[90:93], v[28:31], 0
	v_mfma_f32_16x16x32_bf16 v[94:97], v[94:97], v[28:31], 0
	v_mfma_f32_16x16x32_bf16 v[98:101], v[98:101], v[28:31], 0
	v_mfma_f32_16x16x32_bf16 v[102:105], v[102:105], v[28:31], 0
	v_mfma_f32_16x16x32_bf16 v[106:109], v[106:109], v[28:31], 0
	v_mfma_f32_16x16x32_bf16 v[110:113], v[110:113], v[28:31], 0
	s_add_u32 s100, s10, 0x11c08100
	s_addc_u32 s101, s11, 0
	s_mov_b32 m0, s13
	s_nop 0
	global_load_lds_dwordx4 v241, s[100:101]
	s_waitcnt lgkmcnt(0)
	v_mfma_f32_16x16x32_bf16 v[42:45], v[142:145], v[24:27], v[44:47]
	v_mfma_f32_16x16x32_bf16 v[50:53], v[138:141], v[24:27], v[50:53]
	v_mfma_f32_16x16x32_bf16 v[38:41], v[134:137], v[24:27], v[38:41]
	v_mfma_f32_16x16x32_bf16 v[74:77], v[130:133], v[24:27], v[74:77]
	v_mfma_f32_16x16x32_bf16 v[66:69], v[126:129], v[24:27], v[66:69]
	v_mfma_f32_16x16x32_bf16 v[70:73], v[122:125], v[24:27], v[70:73]
	ds_read_b128 v[122:125], v64 offset:49152
	ds_read_b128 v[126:129], v64 offset:51200
	ds_read_b128 v[130:133], v64 offset:53248
	ds_read_b128 v[134:137], v64 offset:55296
	v_mfma_f32_16x16x32_bf16 v[60:63], v[118:121], v[24:27], v[60:63]
	ds_read_b128 v[118:121], v64 offset:57344
	ds_read_b128 v[138:141], v64 offset:59392
	ds_read_b128 v[142:145], v64 offset:61440
	ds_read_b128 v[146:149], v64 offset:63488
	v_mfma_f32_16x16x32_bf16 v[78:81], v[114:117], v[24:27], v[78:81]
	s_add_u32 s100, s10, 0x11c00180
	s_addc_u32 s101, s11, 0
	s_mov_b32 m0, s12
	s_nop 0
	global_load_lds_dwordx4 v241, s[100:101]
	s_waitcnt lgkmcnt(0)
	v_mfma_f32_16x16x32_bf16 v[82:85], v[122:125], v[24:27], v[82:85]
	v_mfma_f32_16x16x32_bf16 v[86:89], v[126:129], v[24:27], v[86:89]
	v_mfma_f32_16x16x32_bf16 v[90:93], v[130:133], v[24:27], v[90:93]
	v_mfma_f32_16x16x32_bf16 v[94:97], v[134:137], v[24:27], v[94:97]
	v_mfma_f32_16x16x32_bf16 v[98:101], v[118:121], v[24:27], v[98:101]
	ds_read_b128 v[114:117], v64 offset:15360
	ds_read_b128 v[118:121], v64 offset:13312
	ds_read_b128 v[122:125], v64 offset:11264
	ds_read_b128 v[126:129], v64 offset:9216
	v_mfma_f32_16x16x32_bf16 v[102:105], v[138:141], v[24:27], v[102:105]
	v_mfma_f32_16x16x32_bf16 v[106:109], v[142:145], v[24:27], v[106:109]
	ds_read_b128 v[130:133], v64 offset:7168
	ds_read_b128 v[134:137], v64 offset:5120
	ds_read_b128 v[138:141], v64 offset:3072
	ds_read_b128 v[142:145], v64 offset:1024
	v_mfma_f32_16x16x32_bf16 v[110:113], v[146:149], v[24:27], v[110:113]
	s_add_u32 s100, s10, 0x11c08180
	s_addc_u32 s101, s11, 0
	s_mov_b32 m0, s14
	s_nop 0
	global_load_lds_dwordx4 v241, s[100:101]
	s_waitcnt lgkmcnt(0)
	v_mfma_f32_16x16x32_bf16 v[42:45], v[142:145], v[20:23], v[42:45]
	v_mfma_f32_16x16x32_bf16 v[50:53], v[138:141], v[20:23], v[50:53]
	v_mfma_f32_16x16x32_bf16 v[38:41], v[134:137], v[20:23], v[38:41]
	v_mfma_f32_16x16x32_bf16 v[74:77], v[130:133], v[20:23], v[74:77]
	v_mfma_f32_16x16x32_bf16 v[66:69], v[126:129], v[20:23], v[66:69]
	v_mfma_f32_16x16x32_bf16 v[70:73], v[122:125], v[20:23], v[70:73]
	ds_read_b128 v[122:125], v64 offset:33792
	ds_read_b128 v[126:129], v64 offset:35840
	ds_read_b128 v[130:133], v64 offset:37888
	ds_read_b128 v[134:137], v64 offset:39936
	v_mfma_f32_16x16x32_bf16 v[60:63], v[118:121], v[20:23], v[60:63]
	ds_read_b128 v[118:121], v64 offset:41984
	ds_read_b128 v[138:141], v64 offset:44032
	ds_read_b128 v[142:145], v64 offset:46080
	ds_read_b128 v[146:149], v64 offset:48128
	v_mfma_f32_16x16x32_bf16 v[78:81], v[114:117], v[20:23], v[78:81]
	s_add_u32 s100, s10, 0x11c10100
	s_addc_u32 s101, s11, 0
	s_mov_b32 m0, s15
	s_nop 0
	global_load_lds_dwordx4 v241, s[100:101]
	s_waitcnt lgkmcnt(0)
	v_mfma_f32_16x16x32_bf16 v[82:85], v[122:125], v[20:23], v[82:85]
	v_mfma_f32_16x16x32_bf16 v[86:89], v[126:129], v[20:23], v[86:89]
	v_mfma_f32_16x16x32_bf16 v[90:93], v[130:133], v[20:23], v[90:93]
	v_mfma_f32_16x16x32_bf16 v[94:97], v[134:137], v[20:23], v[94:97]
	v_mfma_f32_16x16x32_bf16 v[98:101], v[118:121], v[20:23], v[98:101]
	ds_read_b128 v[114:117], v64 offset:31744
	ds_read_b128 v[118:121], v64 offset:29696
	ds_read_b128 v[122:125], v64 offset:27648
	ds_read_b128 v[126:129], v64 offset:25600
	v_mfma_f32_16x16x32_bf16 v[102:105], v[138:141], v[20:23], v[102:105]
	v_mfma_f32_16x16x32_bf16 v[106:109], v[142:145], v[20:23], v[106:109]
	ds_read_b128 v[130:133], v64 offset:23552
	ds_read_b128 v[134:137], v64 offset:21504
	ds_read_b128 v[138:141], v64 offset:19456
	ds_read_b128 v[142:145], v64 offset:17408
	v_mfma_f32_16x16x32_bf16 v[110:113], v[146:149], v[20:23], v[110:113]
	s_add_u32 s100, s10, 0x11c18100
	s_addc_u32 s101, s11, 0
	s_mov_b32 m0, s16
	s_nop 0
	global_load_lds_dwordx4 v241, s[100:101]
	s_waitcnt lgkmcnt(0)
	v_mfma_f32_16x16x32_bf16 v[42:45], v[142:145], v[16:19], v[42:45]
	v_mfma_f32_16x16x32_bf16 v[50:53], v[138:141], v[16:19], v[50:53]
	v_mfma_f32_16x16x32_bf16 v[38:41], v[134:137], v[16:19], v[38:41]
	v_mfma_f32_16x16x32_bf16 v[74:77], v[130:133], v[16:19], v[74:77]
	v_mfma_f32_16x16x32_bf16 v[66:69], v[126:129], v[16:19], v[66:69]
	v_mfma_f32_16x16x32_bf16 v[70:73], v[122:125], v[16:19], v[70:73]
	ds_read_b128 v[122:125], v64 offset:50176
	ds_read_b128 v[126:129], v64 offset:52224
	ds_read_b128 v[130:133], v64 offset:54272
	ds_read_b128 v[134:137], v64 offset:56320
	v_mfma_f32_16x16x32_bf16 v[60:63], v[118:121], v[16:19], v[60:63]
	ds_read_b128 v[118:121], v64 offset:58368
	ds_read_b128 v[138:141], v64 offset:60416
	ds_read_b128 v[142:145], v64 offset:62464
	ds_read_b128 v[146:149], v64 offset:64512
	v_mfma_f32_16x16x32_bf16 v[78:81], v[114:117], v[16:19], v[78:81]
	s_add_u32 s100, s10, 0x11c10180
	s_addc_u32 s101, s11, 0
	s_mov_b32 m0, s17
	s_nop 0
	global_load_lds_dwordx4 v241, s[100:101]
	s_waitcnt lgkmcnt(0)
	v_mfma_f32_16x16x32_bf16 v[82:85], v[122:125], v[16:19], v[82:85]
	v_mfma_f32_16x16x32_bf16 v[86:89], v[126:129], v[16:19], v[86:89]
	v_mfma_f32_16x16x32_bf16 v[90:93], v[130:133], v[16:19], v[90:93]
	v_mfma_f32_16x16x32_bf16 v[94:97], v[134:137], v[16:19], v[94:97]
	v_mfma_f32_16x16x32_bf16 v[98:101], v[118:121], v[16:19], v[98:101]
	v_mfma_f32_16x16x32_bf16 v[102:105], v[138:141], v[16:19], v[102:105]
	v_mfma_f32_16x16x32_bf16 v[106:109], v[142:145], v[16:19], v[106:109]
	v_mfma_f32_16x16x32_bf16 v[110:113], v[146:149], v[16:19], v[110:113]
	s_add_u32 s100, s10, 0x11c18180
	s_addc_u32 s101, s11, 0
	s_mov_b32 m0, s18
	s_nop 0
	global_load_lds_dwordx4 v241, s[100:101]
	s_waitcnt vmcnt(0)
	s_waitcnt vmcnt(0)
	s_barrier
	v_mov_b32_e32 v37, v48
	ds_read_b128 v[114:117], v37
	ds_read_b128 v[118:121], v37 offset:2048
	s_waitcnt lgkmcnt(0)
	v_mfma_f32_16x16x32_bf16 v[42:45], v[114:117], v[12:15], v[42:45]
	ds_read_b128 v[114:117], v37 offset:4096
	v_mfma_f32_16x16x32_bf16 v[50:53], v[118:121], v[12:15], v[50:53]
	ds_read_b128 v[118:121], v37 offset:6144
	s_waitcnt lgkmcnt(0)
	v_mfma_f32_16x16x32_bf16 v[38:41], v[114:117], v[12:15], v[38:41]
	ds_read_b128 v[114:117], v37 offset:8192
	v_mfma_f32_16x16x32_bf16 v[74:77], v[118:121], v[12:15], v[74:77]
	ds_read_b128 v[118:121], v37 offset:10240
	s_waitcnt lgkmcnt(0)
	v_mfma_f32_16x16x32_bf16 v[66:69], v[114:117], v[12:15], v[66:69]
	ds_read_b128 v[114:117], v37 offset:12288
	ds_read_b128 v[122:125], v37 offset:14336
	v_mfma_f32_16x16x32_bf16 v[70:73], v[118:121], v[12:15], v[70:73]
	ds_read_b128 v[118:121], v37 offset:32768
	ds_read_b128 v[126:129], v37 offset:34816
	ds_read_b128 v[130:133], v37 offset:36864
	ds_read_b128 v[134:137], v37 offset:38912
	s_waitcnt lgkmcnt(0)
	v_mfma_f32_16x16x32_bf16 v[60:63], v[114:117], v[12:15], v[60:63]
	ds_read_b128 v[114:117], v37 offset:40960
	ds_read_b128 v[138:141], v37 offset:43008
	ds_read_b128 v[142:145], v37 offset:45056
	ds_read_b128 v[146:149], v37 offset:47104
	v_mfma_f32_16x16x32_bf16 v[78:81], v[122:125], v[12:15], v[78:81]
	s_add_u32 s100, s10, 0x11c20000
	s_addc_u32 s101, s11, 0
	s_mov_b32 m0, s22
	s_nop 0
	global_load_lds_dwordx4 v241, s[100:101]
	v_mfma_f32_16x16x32_bf16 v[82:85], v[118:121], v[12:15], v[82:85]
	v_mfma_f32_16x16x32_bf16 v[86:89], v[126:129], v[12:15], v[86:89]
	v_mfma_f32_16x16x32_bf16 v[90:93], v[130:133], v[12:15], v[90:93]
	v_mfma_f32_16x16x32_bf16 v[94:97], v[134:137], v[12:15], v[94:97]
	s_waitcnt lgkmcnt(0)
	v_mfma_f32_16x16x32_bf16 v[98:101], v[114:117], v[12:15], v[98:101]
	ds_read_b128 v[114:117], v37 offset:30720
	ds_read_b128 v[118:121], v37 offset:28672
	ds_read_b128 v[122:125], v37 offset:26624
	ds_read_b128 v[126:129], v37 offset:24576
	v_mfma_f32_16x16x32_bf16 v[102:105], v[138:141], v[12:15], v[102:105]
	v_mfma_f32_16x16x32_bf16 v[106:109], v[142:145], v[12:15], v[106:109]
	ds_read_b128 v[130:133], v37 offset:22528
	ds_read_b128 v[134:137], v37 offset:20480
	ds_read_b128 v[138:141], v37 offset:18432
	ds_read_b128 v[142:145], v37 offset:16384
	v_mfma_f32_16x16x32_bf16 v[110:113], v[146:149], v[12:15], v[110:113]
	s_add_u32 s100, s10, 0x11c28000
	s_addc_u32 s101, s11, 0
	s_mov_b32 m0, s21
	s_nop 0
	global_load_lds_dwordx4 v241, s[100:101]
	s_waitcnt lgkmcnt(0)
	v_mfma_f32_16x16x32_bf16 v[42:45], v[142:145], v[8:11], v[42:45]
	v_mfma_f32_16x16x32_bf16 v[50:53], v[138:141], v[8:11], v[50:53]
	v_mfma_f32_16x16x32_bf16 v[38:41], v[134:137], v[8:11], v[38:41]
	v_mfma_f32_16x16x32_bf16 v[74:77], v[130:133], v[8:11], v[74:77]
	v_mfma_f32_16x16x32_bf16 v[66:69], v[126:129], v[8:11], v[66:69]
	v_mfma_f32_16x16x32_bf16 v[70:73], v[122:125], v[8:11], v[70:73]
	ds_read_b128 v[122:125], v37 offset:49152
	ds_read_b128 v[126:129], v37 offset:51200
	ds_read_b128 v[130:133], v37 offset:53248
	ds_read_b128 v[134:137], v37 offset:55296
	v_mfma_f32_16x16x32_bf16 v[60:63], v[118:121], v[8:11], v[60:63]
	ds_read_b128 v[118:121], v37 offset:57344
	ds_read_b128 v[138:141], v37 offset:59392
	ds_read_b128 v[142:145], v37 offset:61440
	ds_read_b128 v[146:149], v37 offset:63488
	v_mfma_f32_16x16x32_bf16 v[78:81], v[114:117], v[8:11], v[78:81]
	s_add_u32 s100, s10, 0x11c20080
	s_addc_u32 s101, s11, 0
	s_mov_b32 m0, s20
	s_nop 0
	global_load_lds_dwordx4 v241, s[100:101]
	s_waitcnt lgkmcnt(0)
	v_mfma_f32_16x16x32_bf16 v[82:85], v[122:125], v[8:11], v[82:85]
	v_mfma_f32_16x16x32_bf16 v[86:89], v[126:129], v[8:11], v[86:89]
	v_mfma_f32_16x16x32_bf16 v[90:93], v[130:133], v[8:11], v[90:93]
	v_mfma_f32_16x16x32_bf16 v[94:97], v[134:137], v[8:11], v[94:97]
	v_mfma_f32_16x16x32_bf16 v[98:101], v[118:121], v[8:11], v[98:101]
	ds_read_b128 v[114:117], v37 offset:15360
	ds_read_b128 v[118:121], v37 offset:13312
	ds_read_b128 v[122:125], v37 offset:11264
	ds_read_b128 v[126:129], v37 offset:9216
	v_mfma_f32_16x16x32_bf16 v[102:105], v[138:141], v[8:11], v[102:105]
	v_mfma_f32_16x16x32_bf16 v[106:109], v[142:145], v[8:11], v[106:109]
	ds_read_b128 v[130:133], v37 offset:7168
	ds_read_b128 v[134:137], v37 offset:5120
	ds_read_b128 v[138:141], v37 offset:3072
	ds_read_b128 v[142:145], v37 offset:1024
	v_mfma_f32_16x16x32_bf16 v[110:113], v[146:149], v[8:11], v[110:113]
	s_add_u32 s100, s10, 0x11c28080
	s_addc_u32 s101, s11, 0
	s_mov_b32 m0, s23
	s_nop 0
	global_load_lds_dwordx4 v241, s[100:101]
	s_waitcnt lgkmcnt(0)
	v_mfma_f32_16x16x32_bf16 v[42:45], v[142:145], v[4:7], v[42:45]
	v_mfma_f32_16x16x32_bf16 v[50:53], v[138:141], v[4:7], v[50:53]
	v_mfma_f32_16x16x32_bf16 v[38:41], v[134:137], v[4:7], v[38:41]
	v_mfma_f32_16x16x32_bf16 v[74:77], v[130:133], v[4:7], v[74:77]
	v_mfma_f32_16x16x32_bf16 v[66:69], v[126:129], v[4:7], v[66:69]
	v_mfma_f32_16x16x32_bf16 v[70:73], v[122:125], v[4:7], v[70:73]
	ds_read_b128 v[122:125], v37 offset:33792
	ds_read_b128 v[126:129], v37 offset:35840
	ds_read_b128 v[130:133], v37 offset:37888
	ds_read_b128 v[134:137], v37 offset:39936
	v_mfma_f32_16x16x32_bf16 v[60:63], v[118:121], v[4:7], v[60:63]
	ds_read_b128 v[118:121], v37 offset:41984
	ds_read_b128 v[138:141], v37 offset:44032
	ds_read_b128 v[142:145], v37 offset:46080
	ds_read_b128 v[146:149], v37 offset:48128
	v_mfma_f32_16x16x32_bf16 v[78:81], v[114:117], v[4:7], v[78:81]
	s_add_u32 s100, s10, 0x11c30000
	s_addc_u32 s101, s11, 0
	s_mov_b32 m0, s24
	s_nop 0
	global_load_lds_dwordx4 v241, s[100:101]
	s_waitcnt lgkmcnt(0)
	v_mfma_f32_16x16x32_bf16 v[82:85], v[122:125], v[4:7], v[82:85]
	v_mfma_f32_16x16x32_bf16 v[86:89], v[126:129], v[4:7], v[86:89]
	v_mfma_f32_16x16x32_bf16 v[90:93], v[130:133], v[4:7], v[90:93]
	v_mfma_f32_16x16x32_bf16 v[94:97], v[134:137], v[4:7], v[94:97]
	v_mfma_f32_16x16x32_bf16 v[98:101], v[118:121], v[4:7], v[98:101]
	ds_read_b128 v[114:117], v37 offset:31744
	ds_read_b128 v[118:121], v37 offset:29696
	ds_read_b128 v[122:125], v37 offset:27648
	ds_read_b128 v[126:129], v37 offset:25600
	v_mfma_f32_16x16x32_bf16 v[102:105], v[138:141], v[4:7], v[102:105]
	v_mfma_f32_16x16x32_bf16 v[106:109], v[142:145], v[4:7], v[106:109]
	ds_read_b128 v[130:133], v37 offset:23552
	ds_read_b128 v[134:137], v37 offset:21504
	ds_read_b128 v[138:141], v37 offset:19456
	ds_read_b128 v[142:145], v37 offset:17408
	v_mfma_f32_16x16x32_bf16 v[110:113], v[146:149], v[4:7], v[110:113]
	s_add_u32 s100, s10, 0x11c38000
	s_addc_u32 s101, s11, 0
	s_mov_b32 m0, s25
	s_nop 0
	global_load_lds_dwordx4 v241, s[100:101]
	s_waitcnt lgkmcnt(0)
	v_mfma_f32_16x16x32_bf16 v[42:45], v[142:145], v[0:3], v[42:45]
	v_mfma_f32_16x16x32_bf16 v[50:53], v[138:141], v[0:3], v[50:53]
	v_mfma_f32_16x16x32_bf16 v[38:41], v[134:137], v[0:3], v[38:41]
	v_mfma_f32_16x16x32_bf16 v[74:77], v[130:133], v[0:3], v[74:77]
	v_mfma_f32_16x16x32_bf16 v[66:69], v[126:129], v[0:3], v[66:69]
	v_mfma_f32_16x16x32_bf16 v[70:73], v[122:125], v[0:3], v[70:73]
	ds_read_b128 v[122:125], v37 offset:50176
	ds_read_b128 v[126:129], v37 offset:52224
	ds_read_b128 v[130:133], v37 offset:54272
	ds_read_b128 v[134:137], v37 offset:56320
	v_mfma_f32_16x16x32_bf16 v[60:63], v[118:121], v[0:3], v[60:63]
	ds_read_b128 v[118:121], v37 offset:58368
	ds_read_b128 v[138:141], v37 offset:60416
	ds_read_b128 v[142:145], v37 offset:62464
	ds_read_b128 v[146:149], v37 offset:64512
	v_mfma_f32_16x16x32_bf16 v[78:81], v[114:117], v[0:3], v[78:81]
	s_add_u32 s100, s10, 0x11c30080
	s_addc_u32 s101, s11, 0
	s_mov_b32 m0, s26
	s_nop 0
	global_load_lds_dwordx4 v241, s[100:101]
	s_waitcnt lgkmcnt(0)
	v_mfma_f32_16x16x32_bf16 v[82:85], v[122:125], v[0:3], v[82:85]
	v_mfma_f32_16x16x32_bf16 v[86:89], v[126:129], v[0:3], v[86:89]
	v_mfma_f32_16x16x32_bf16 v[90:93], v[130:133], v[0:3], v[90:93]
	v_mfma_f32_16x16x32_bf16 v[94:97], v[134:137], v[0:3], v[94:97]
	v_mfma_f32_16x16x32_bf16 v[98:101], v[118:121], v[0:3], v[98:101]
	v_mfma_f32_16x16x32_bf16 v[102:105], v[138:141], v[0:3], v[102:105]
	v_mfma_f32_16x16x32_bf16 v[106:109], v[142:145], v[0:3], v[106:109]
	v_mfma_f32_16x16x32_bf16 v[110:113], v[146:149], v[0:3], v[110:113]
	s_add_u32 s100, s10, 0x11c38080
	s_addc_u32 s101, s11, 0
	s_mov_b32 m0, s27
	s_nop 0
	global_load_lds_dwordx4 v241, s[100:101]
	s_mov_b32 s0, 0x1000000
	v_add_co_u32_e32 v34, vcc, s0, v34
	v_mul_f32_e32 v37, v36, v42
	v_mul_f32_e32 v42, v36, v43
	v_mul_f32_e32 v43, v36, v45
	v_addc_co_u32_e32 v35, vcc, 0, v35, vcc
	v_cvt_pk_bf16_f32 v42, v37, v42
	v_mul_f32_e32 v37, v36, v44
	v_cvt_pk_bf16_f32 v43, v37, v43
	global_store_dwordx2 v[34:35], v[42:43], off
	v_mul_f32_e32 v34, v36, v50
	v_mul_f32_e32 v35, v36, v51
	v_cvt_pk_bf16_f32 v34, v34, v35
	v_mul_f32_e32 v35, v36, v52
	v_mul_f32_e32 v37, v36, v53
	v_cvt_pk_bf16_f32 v35, v35, v37
	global_store_dwordx2 v[32:33], v[34:35], off offset:32
	v_mul_f32_e32 v34, v36, v38
	v_mul_f32_e32 v35, v36, v39
	v_cvt_pk_bf16_f32 v34, v34, v35
	v_mul_f32_e32 v35, v36, v40
	v_mul_f32_e32 v37, v36, v41
	v_cvt_pk_bf16_f32 v35, v35, v37
	global_store_dwordx2 v[32:33], v[34:35], off offset:64
	v_mul_f32_e32 v34, v36, v74
	v_mul_f32_e32 v35, v36, v75
	v_cvt_pk_bf16_f32 v34, v34, v35
	v_mul_f32_e32 v35, v36, v76
	v_mul_f32_e32 v37, v36, v77
	v_cvt_pk_bf16_f32 v35, v35, v37
	global_store_dwordx2 v[32:33], v[34:35], off offset:96
	v_mul_f32_e32 v34, v36, v66
	v_mul_f32_e32 v35, v36, v67
	v_cvt_pk_bf16_f32 v34, v34, v35
	v_mul_f32_e32 v35, v36, v68
	v_mul_f32_e32 v37, v36, v69
	v_cvt_pk_bf16_f32 v35, v35, v37
	global_store_dwordx2 v[32:33], v[34:35], off offset:128
	v_mul_f32_e32 v34, v36, v70
	v_mul_f32_e32 v35, v36, v71
	v_cvt_pk_bf16_f32 v34, v34, v35
	v_mul_f32_e32 v35, v36, v72
	v_mul_f32_e32 v37, v36, v73
	v_cvt_pk_bf16_f32 v35, v35, v37
	global_store_dwordx2 v[32:33], v[34:35], off offset:160
	v_mul_f32_e32 v34, v36, v60
	v_mul_f32_e32 v35, v36, v61
	v_cvt_pk_bf16_f32 v34, v34, v35
	v_mul_f32_e32 v35, v36, v62
	v_mul_f32_e32 v37, v36, v63
	v_cvt_pk_bf16_f32 v35, v35, v37
	global_store_dwordx2 v[32:33], v[34:35], off offset:192
	v_mul_f32_e32 v34, v36, v78
	v_mul_f32_e32 v35, v36, v79
	v_cvt_pk_bf16_f32 v34, v34, v35
	v_mul_f32_e32 v35, v36, v80
	v_mul_f32_e32 v37, v36, v81
	v_cvt_pk_bf16_f32 v35, v35, v37
	global_store_dwordx2 v[32:33], v[34:35], off offset:224
	v_mul_f32_e32 v34, v36, v82
	v_mul_f32_e32 v35, v36, v83
	v_cvt_pk_bf16_f32 v34, v34, v35
	v_mul_f32_e32 v35, v36, v84
	v_mul_f32_e32 v37, v36, v85
	v_cvt_pk_bf16_f32 v35, v35, v37
	global_store_dwordx2 v[32:33], v[34:35], off offset:256
	v_mul_f32_e32 v34, v36, v86
	v_mul_f32_e32 v35, v36, v87
	v_cvt_pk_bf16_f32 v34, v34, v35
	v_mul_f32_e32 v35, v36, v88
	v_mul_f32_e32 v37, v36, v89
	v_cvt_pk_bf16_f32 v35, v35, v37
	global_store_dwordx2 v[32:33], v[34:35], off offset:288
	v_mul_f32_e32 v34, v36, v90
	v_mul_f32_e32 v35, v36, v91
	v_cvt_pk_bf16_f32 v34, v34, v35
	v_mul_f32_e32 v35, v36, v92
	v_mul_f32_e32 v37, v36, v93
	v_cvt_pk_bf16_f32 v35, v35, v37
	global_store_dwordx2 v[32:33], v[34:35], off offset:320
	v_mul_f32_e32 v34, v36, v94
	v_mul_f32_e32 v35, v36, v95
	v_cvt_pk_bf16_f32 v34, v34, v35
	v_mul_f32_e32 v35, v36, v96
	v_mul_f32_e32 v37, v36, v97
	v_cvt_pk_bf16_f32 v35, v35, v37
	global_store_dwordx2 v[32:33], v[34:35], off offset:352
	v_mul_f32_e32 v34, v36, v98
	v_mul_f32_e32 v35, v36, v99
	v_cvt_pk_bf16_f32 v34, v34, v35
	v_mul_f32_e32 v35, v36, v100
	v_mul_f32_e32 v37, v36, v101
	v_cvt_pk_bf16_f32 v35, v35, v37
	global_store_dwordx2 v[32:33], v[34:35], off offset:384
	v_mul_f32_e32 v34, v36, v102
	v_mul_f32_e32 v35, v36, v103
	v_cvt_pk_bf16_f32 v34, v34, v35
	v_mul_f32_e32 v35, v36, v104
	v_mul_f32_e32 v37, v36, v105
	v_cvt_pk_bf16_f32 v35, v35, v37
	global_store_dwordx2 v[32:33], v[34:35], off offset:416
	v_mul_f32_e32 v34, v36, v106
	v_mul_f32_e32 v35, v36, v107
	v_cvt_pk_bf16_f32 v34, v34, v35
	v_mul_f32_e32 v35, v36, v108
	v_mul_f32_e32 v37, v36, v109
	v_cvt_pk_bf16_f32 v35, v35, v37
	global_store_dwordx2 v[32:33], v[34:35], off offset:448
	v_mul_f32_e32 v34, v36, v110
	v_mul_f32_e32 v35, v36, v111
	v_cvt_pk_bf16_f32 v34, v34, v35
	v_mul_f32_e32 v35, v36, v112
	v_mul_f32_e32 v37, v36, v113
	v_cvt_pk_bf16_f32 v35, v35, v37
	global_store_dwordx2 v[32:33], v[34:35], off offset:480
	s_waitcnt vmcnt(0)
	s_waitcnt vmcnt(0)
	s_barrier
	ds_read_b128 v[38:41], v65
	ds_read_b128 v[42:45], v65 offset:2048
	ds_read_b128 v[50:53], v65 offset:4096
	ds_read_b128 v[54:57], v65 offset:6144
	ds_read_b128 v[58:61], v65 offset:8192
	ds_read_b128 v[66:69], v65 offset:10240
	ds_read_b128 v[70:73], v65 offset:12288
	ds_read_b128 v[74:77], v65 offset:14336
	ds_read_b128 v[78:81], v65 offset:32768
	ds_read_b128 v[82:85], v65 offset:34816
	ds_read_b128 v[86:89], v65 offset:36864
	ds_read_b128 v[90:93], v65 offset:38912
	ds_read_b128 v[94:97], v65 offset:40960
	ds_read_b128 v[98:101], v65 offset:43008
	ds_read_b128 v[102:105], v65 offset:45056
	ds_read_b128 v[106:109], v65 offset:47104
	s_waitcnt lgkmcnt(0)
	v_mfma_f32_16x16x32_bf16 v[38:41], v[38:41], v[28:31], 0
	v_mfma_f32_16x16x32_bf16 v[42:45], v[42:45], v[28:31], 0
	v_mfma_f32_16x16x32_bf16 v[50:53], v[50:53], v[28:31], 0
	v_mfma_f32_16x16x32_bf16 v[54:57], v[54:57], v[28:31], 0
	v_mfma_f32_16x16x32_bf16 v[58:61], v[58:61], v[28:31], 0
	v_mfma_f32_16x16x32_bf16 v[66:69], v[66:69], v[28:31], 0
	v_mfma_f32_16x16x32_bf16 v[70:73], v[70:73], v[28:31], 0
	v_mfma_f32_16x16x32_bf16 v[74:77], v[74:77], v[28:31], 0
	s_add_u32 s100, s10, 0x11c20100
	s_addc_u32 s101, s11, 0
	s_mov_b32 m0, s19
	s_nop 0
	global_load_lds_dwordx4 v241, s[100:101]
	ds_read_b128 v[110:113], v65 offset:30720
	ds_read_b128 v[114:117], v65 offset:28672
	ds_read_b128 v[118:121], v65 offset:26624
	ds_read_b128 v[122:125], v65 offset:24576
	ds_read_b128 v[126:129], v65 offset:22528
	ds_read_b128 v[130:133], v65 offset:20480
	ds_read_b128 v[134:137], v65 offset:18432
	ds_read_b128 v[138:141], v65 offset:16384
	v_mfma_f32_16x16x32_bf16 v[78:81], v[78:81], v[28:31], 0
	v_mfma_f32_16x16x32_bf16 v[82:85], v[82:85], v[28:31], 0
	v_mfma_f32_16x16x32_bf16 v[86:89], v[86:89], v[28:31], 0
	v_mfma_f32_16x16x32_bf16 v[90:93], v[90:93], v[28:31], 0
	v_mfma_f32_16x16x32_bf16 v[94:97], v[94:97], v[28:31], 0
	v_mfma_f32_16x16x32_bf16 v[98:101], v[98:101], v[28:31], 0
	v_mfma_f32_16x16x32_bf16 v[102:105], v[102:105], v[28:31], 0
	v_mfma_f32_16x16x32_bf16 v[28:31], v[106:109], v[28:31], 0
	s_add_u32 s100, s10, 0x11c28100
	s_addc_u32 s101, s11, 0
	s_mov_b32 m0, s13
	s_nop 0
	global_load_lds_dwordx4 v241, s[100:101]
	s_waitcnt lgkmcnt(0)
	v_mfma_f32_16x16x32_bf16 v[38:41], v[138:141], v[24:27], v[38:41]
	v_mfma_f32_16x16x32_bf16 v[42:45], v[134:137], v[24:27], v[42:45]
	v_mfma_f32_16x16x32_bf16 v[50:53], v[130:133], v[24:27], v[50:53]
	v_mfma_f32_16x16x32_bf16 v[54:57], v[126:129], v[24:27], v[54:57]
	v_mfma_f32_16x16x32_bf16 v[58:61], v[122:125], v[24:27], v[58:61]
	v_mfma_f32_16x16x32_bf16 v[66:69], v[118:121], v[24:27], v[66:69]
	ds_read_b128 v[106:109], v65 offset:49152
	ds_read_b128 v[118:121], v65 offset:51200
	ds_read_b128 v[122:125], v65 offset:53248
	ds_read_b128 v[126:129], v65 offset:55296
	v_mfma_f32_16x16x32_bf16 v[70:73], v[114:117], v[24:27], v[70:73]
	ds_read_b128 v[114:117], v65 offset:57344
	ds_read_b128 v[130:133], v65 offset:59392
	ds_read_b128 v[134:137], v65 offset:61440
	ds_read_b128 v[138:141], v65 offset:63488
	v_mfma_f32_16x16x32_bf16 v[74:77], v[110:113], v[24:27], v[74:77]
	s_add_u32 s100, s10, 0x11c20180
	s_addc_u32 s101, s11, 0
	s_mov_b32 m0, s12
	s_nop 0
	global_load_lds_dwordx4 v241, s[100:101]
	s_waitcnt lgkmcnt(0)
	v_mfma_f32_16x16x32_bf16 v[78:81], v[106:109], v[24:27], v[78:81]
	v_mfma_f32_16x16x32_bf16 v[82:85], v[118:121], v[24:27], v[82:85]
	v_mfma_f32_16x16x32_bf16 v[86:89], v[122:125], v[24:27], v[86:89]
	v_mfma_f32_16x16x32_bf16 v[90:93], v[126:129], v[24:27], v[90:93]
	v_mfma_f32_16x16x32_bf16 v[94:97], v[114:117], v[24:27], v[94:97]
	ds_read_b128 v[106:109], v65 offset:15360
	ds_read_b128 v[110:113], v65 offset:13312
	ds_read_b128 v[114:117], v65 offset:11264
	ds_read_b128 v[118:121], v65 offset:9216
	v_mfma_f32_16x16x32_bf16 v[98:101], v[130:133], v[24:27], v[98:101]
	v_mfma_f32_16x16x32_bf16 v[102:105], v[134:137], v[24:27], v[102:105]
	ds_read_b128 v[122:125], v65 offset:7168
	ds_read_b128 v[126:129], v65 offset:5120
	ds_read_b128 v[130:133], v65 offset:3072
	ds_read_b128 v[134:137], v65 offset:1024
	v_mfma_f32_16x16x32_bf16 v[24:27], v[138:141], v[24:27], v[28:31]
	s_add_u32 s100, s10, 0x11c28180
	s_addc_u32 s101, s11, 0
	s_mov_b32 m0, s14
	s_nop 0
	global_load_lds_dwordx4 v241, s[100:101]
	s_waitcnt lgkmcnt(0)
	v_mfma_f32_16x16x32_bf16 v[28:31], v[134:137], v[20:23], v[38:41]
	v_mfma_f32_16x16x32_bf16 v[38:41], v[130:133], v[20:23], v[42:45]
	v_mfma_f32_16x16x32_bf16 v[42:45], v[126:129], v[20:23], v[50:53]
	v_mfma_f32_16x16x32_bf16 v[50:53], v[122:125], v[20:23], v[54:57]
	v_mfma_f32_16x16x32_bf16 v[54:57], v[118:121], v[20:23], v[58:61]
	v_mfma_f32_16x16x32_bf16 v[58:61], v[114:117], v[20:23], v[66:69]
	s_nop 2
	ds_read_b128 v[66:69], v65 offset:33792
	ds_read_b128 v[114:117], v65 offset:35840
	ds_read_b128 v[118:121], v65 offset:37888
	ds_read_b128 v[122:125], v65 offset:39936
	v_mfma_f32_16x16x32_bf16 v[70:73], v[110:113], v[20:23], v[70:73]
	ds_read_b128 v[110:113], v65 offset:41984
	ds_read_b128 v[126:129], v65 offset:44032
	ds_read_b128 v[130:133], v65 offset:46080
	ds_read_b128 v[134:137], v65 offset:48128
	v_mfma_f32_16x16x32_bf16 v[74:77], v[106:109], v[20:23], v[74:77]
	s_add_u32 s100, s10, 0x11c30100
	s_addc_u32 s101, s11, 0
	s_mov_b32 m0, s15
	s_nop 0
	global_load_lds_dwordx4 v241, s[100:101]
	s_waitcnt lgkmcnt(0)
	v_mfma_f32_16x16x32_bf16 v[66:69], v[66:69], v[20:23], v[78:81]
	v_mfma_f32_16x16x32_bf16 v[78:81], v[114:117], v[20:23], v[82:85]
	v_mfma_f32_16x16x32_bf16 v[82:85], v[118:121], v[20:23], v[86:89]
	v_mfma_f32_16x16x32_bf16 v[86:89], v[122:125], v[20:23], v[90:93]
	v_mfma_f32_16x16x32_bf16 v[90:93], v[110:113], v[20:23], v[94:97]
	v_mfma_f32_16x16x32_bf16 v[94:97], v[126:129], v[20:23], v[98:101]
	s_nop 2
	ds_read_b128 v[98:101], v65 offset:31744
	ds_read_b128 v[106:109], v65 offset:29696
	ds_read_b128 v[110:113], v65 offset:27648
	ds_read_b128 v[114:117], v65 offset:25600
	v_mfma_f32_16x16x32_bf16 v[102:105], v[130:133], v[20:23], v[102:105]
	ds_read_b128 v[118:121], v65 offset:23552
	ds_read_b128 v[122:125], v65 offset:21504
	ds_read_b128 v[126:129], v65 offset:19456
	ds_read_b128 v[130:133], v65 offset:17408
	v_mfma_f32_16x16x32_bf16 v[20:23], v[134:137], v[20:23], v[24:27]
	s_add_u32 s100, s10, 0x11c38100
	s_addc_u32 s101, s11, 0
	s_mov_b32 m0, s16
	s_nop 0
	global_load_lds_dwordx4 v241, s[100:101]
	s_waitcnt lgkmcnt(0)
	v_mfma_f32_16x16x32_bf16 v[24:27], v[130:133], v[16:19], v[28:31]
	v_mfma_f32_16x16x32_bf16 v[28:31], v[126:129], v[16:19], v[38:41]
	v_mfma_f32_16x16x32_bf16 v[38:41], v[122:125], v[16:19], v[42:45]
	v_mfma_f32_16x16x32_bf16 v[42:45], v[118:121], v[16:19], v[50:53]
	v_mfma_f32_16x16x32_bf16 v[50:53], v[114:117], v[16:19], v[54:57]
	v_mfma_f32_16x16x32_bf16 v[54:57], v[110:113], v[16:19], v[58:61]
	s_nop 2
	ds_read_b128 v[58:61], v65 offset:50176
	ds_read_b128 v[110:113], v65 offset:52224
	ds_read_b128 v[114:117], v65 offset:54272
	ds_read_b128 v[118:121], v65 offset:56320
	v_mfma_f32_16x16x32_bf16 v[70:73], v[106:109], v[16:19], v[70:73]
	ds_read_b128 v[106:109], v65 offset:58368
	ds_read_b128 v[122:125], v65 offset:60416
	ds_read_b128 v[126:129], v65 offset:62464
	ds_read_b128 v[62:65], v65 offset:64512
	v_mfma_f32_16x16x32_bf16 v[74:77], v[98:101], v[16:19], v[74:77]
	s_add_u32 s100, s10, 0x11c30180
	s_addc_u32 s101, s11, 0
	s_mov_b32 m0, s17
	s_nop 0
	global_load_lds_dwordx4 v241, s[100:101]
	s_waitcnt lgkmcnt(0)
	v_mfma_f32_16x16x32_bf16 v[58:61], v[58:61], v[16:19], v[66:69]
	v_mfma_f32_16x16x32_bf16 v[66:69], v[110:113], v[16:19], v[78:81]
	v_mfma_f32_16x16x32_bf16 v[78:81], v[114:117], v[16:19], v[82:85]
	v_mfma_f32_16x16x32_bf16 v[82:85], v[118:121], v[16:19], v[86:89]
	v_mfma_f32_16x16x32_bf16 v[86:89], v[106:109], v[16:19], v[90:93]
	v_mfma_f32_16x16x32_bf16 v[90:93], v[122:125], v[16:19], v[94:97]
	v_mfma_f32_16x16x32_bf16 v[94:97], v[126:129], v[16:19], v[102:105]
	v_mfma_f32_16x16x32_bf16 v[16:19], v[62:65], v[16:19], v[20:23]
	s_add_u32 s100, s10, 0x11c38180
	s_addc_u32 s101, s11, 0
	s_mov_b32 m0, s18
	s_nop 0
	global_load_lds_dwordx4 v241, s[100:101]
	s_waitcnt vmcnt(0)
	s_waitcnt vmcnt(0)
	s_barrier
	s_nop 0
	ds_read_b128 v[20:23], v48
	ds_read_b128 v[62:65], v48 offset:2048
	s_waitcnt lgkmcnt(1)
	v_mfma_f32_16x16x32_bf16 v[20:23], v[20:23], v[12:15], v[24:27]
	s_nop 2
	ds_read_b128 v[24:27], v48 offset:4096
	s_waitcnt lgkmcnt(1)
	v_mfma_f32_16x16x32_bf16 v[28:31], v[62:65], v[12:15], v[28:31]
	ds_read_b128 v[62:65], v48 offset:6144
	s_waitcnt lgkmcnt(1)
	v_mfma_f32_16x16x32_bf16 v[24:27], v[24:27], v[12:15], v[38:41]
	s_nop 2
	ds_read_b128 v[38:41], v48 offset:8192
	s_waitcnt lgkmcnt(1)
	v_mfma_f32_16x16x32_bf16 v[42:45], v[62:65], v[12:15], v[42:45]
	ds_read_b128 v[62:65], v48 offset:10240
	s_waitcnt lgkmcnt(1)
	v_mfma_f32_16x16x32_bf16 v[38:41], v[38:41], v[12:15], v[50:53]
	s_nop 2
	ds_read_b128 v[50:53], v48 offset:12288
	ds_read_b128 v[98:101], v48 offset:14336
	s_waitcnt lgkmcnt(2)
	v_mfma_f32_16x16x32_bf16 v[54:57], v[62:65], v[12:15], v[54:57]
	ds_read_b128 v[62:65], v48 offset:32768
	ds_read_b128 v[102:105], v48 offset:34816
	ds_read_b128 v[106:109], v48 offset:36864
	ds_read_b128 v[110:113], v48 offset:38912
	s_waitcnt lgkmcnt(5)
	v_mfma_f32_16x16x32_bf16 v[50:53], v[50:53], v[12:15], v[70:73]
	s_nop 2
	ds_read_b128 v[70:73], v48 offset:40960
	ds_read_b128 v[114:117], v48 offset:43008
	ds_read_b128 v[118:121], v48 offset:45056
	ds_read_b128 v[122:125], v48 offset:47104
	s_waitcnt lgkmcnt(8)
	v_mfma_f32_16x16x32_bf16 v[74:77], v[98:101], v[12:15], v[74:77]
	s_waitcnt lgkmcnt(7)
	v_mfma_f32_16x16x32_bf16 v[58:61], v[62:65], v[12:15], v[58:61]
	s_waitcnt lgkmcnt(6)
	v_mfma_f32_16x16x32_bf16 v[62:65], v[102:105], v[12:15], v[66:69]
	s_waitcnt lgkmcnt(5)
	v_mfma_f32_16x16x32_bf16 v[66:69], v[106:109], v[12:15], v[78:81]
	s_waitcnt lgkmcnt(4)
	v_mfma_f32_16x16x32_bf16 v[78:81], v[110:113], v[12:15], v[82:85]
	s_waitcnt lgkmcnt(3)
	v_mfma_f32_16x16x32_bf16 v[70:73], v[70:73], v[12:15], v[86:89]
	s_waitcnt lgkmcnt(2)
	v_mfma_f32_16x16x32_bf16 v[82:85], v[114:117], v[12:15], v[90:93]
	s_nop 0
	ds_read_b128 v[86:89], v48 offset:30720
	s_nop 0
	ds_read_b128 v[90:93], v48 offset:28672
	ds_read_b128 v[98:101], v48 offset:26624
	ds_read_b128 v[102:105], v48 offset:24576
	s_waitcnt lgkmcnt(5)
	v_mfma_f32_16x16x32_bf16 v[94:97], v[118:121], v[12:15], v[94:97]
	ds_read_b128 v[106:109], v48 offset:22528
	ds_read_b128 v[110:113], v48 offset:20480
	ds_read_b128 v[114:117], v48 offset:18432
	ds_read_b128 v[118:121], v48 offset:16384
	s_waitcnt lgkmcnt(8)
	v_mfma_f32_16x16x32_bf16 v[12:15], v[122:125], v[12:15], v[16:19]
	s_waitcnt lgkmcnt(0)
	v_mfma_f32_16x16x32_bf16 v[16:19], v[118:121], v[8:11], v[20:23]
	v_mfma_f32_16x16x32_bf16 v[20:23], v[114:117], v[8:11], v[28:31]
	v_mfma_f32_16x16x32_bf16 v[24:27], v[110:113], v[8:11], v[24:27]
	v_mfma_f32_16x16x32_bf16 v[28:31], v[106:109], v[8:11], v[42:45]
	v_mfma_f32_16x16x32_bf16 v[38:41], v[102:105], v[8:11], v[38:41]
	v_mfma_f32_16x16x32_bf16 v[42:45], v[98:101], v[8:11], v[54:57]
	s_nop 2
	ds_read_b128 v[54:57], v48 offset:49152
	ds_read_b128 v[98:101], v48 offset:51200
	ds_read_b128 v[102:105], v48 offset:53248
	ds_read_b128 v[106:109], v48 offset:55296
	v_mfma_f32_16x16x32_bf16 v[50:53], v[90:93], v[8:11], v[50:53]
	ds_read_b128 v[90:93], v48 offset:57344
	ds_read_b128 v[110:113], v48 offset:59392
	ds_read_b128 v[114:117], v48 offset:61440
	ds_read_b128 v[118:121], v48 offset:63488
	v_mfma_f32_16x16x32_bf16 v[74:77], v[86:89], v[8:11], v[74:77]
	s_waitcnt lgkmcnt(7)
	v_mfma_f32_16x16x32_bf16 v[54:57], v[54:57], v[8:11], v[58:61]
	s_waitcnt lgkmcnt(6)
	v_mfma_f32_16x16x32_bf16 v[58:61], v[98:101], v[8:11], v[62:65]
	s_waitcnt lgkmcnt(5)
	v_mfma_f32_16x16x32_bf16 v[62:65], v[102:105], v[8:11], v[66:69]
	s_waitcnt lgkmcnt(4)
	v_mfma_f32_16x16x32_bf16 v[66:69], v[106:109], v[8:11], v[78:81]
	s_waitcnt lgkmcnt(3)
	v_mfma_f32_16x16x32_bf16 v[70:73], v[90:93], v[8:11], v[70:73]
	s_waitcnt lgkmcnt(2)
	v_mfma_f32_16x16x32_bf16 v[78:81], v[110:113], v[8:11], v[82:85]
	s_nop 2
	ds_read_b128 v[82:85], v48 offset:15360
	ds_read_b128 v[86:89], v48 offset:13312
	ds_read_b128 v[90:93], v48 offset:11264
	ds_read_b128 v[98:101], v48 offset:9216
	s_waitcnt lgkmcnt(5)
	v_mfma_f32_16x16x32_bf16 v[94:97], v[114:117], v[8:11], v[94:97]
	ds_read_b128 v[102:105], v48 offset:7168
	ds_read_b128 v[106:109], v48 offset:5120
	ds_read_b128 v[110:113], v48 offset:3072
	ds_read_b128 v[114:117], v48 offset:1024
	s_waitcnt lgkmcnt(8)
	v_mfma_f32_16x16x32_bf16 v[8:11], v[118:121], v[8:11], v[12:15]
	s_waitcnt lgkmcnt(0)
	v_mfma_f32_16x16x32_bf16 v[12:15], v[114:117], v[4:7], v[16:19]
	v_mfma_f32_16x16x32_bf16 v[16:19], v[110:113], v[4:7], v[20:23]
	v_mfma_f32_16x16x32_bf16 v[20:23], v[106:109], v[4:7], v[24:27]
	v_mfma_f32_16x16x32_bf16 v[24:27], v[102:105], v[4:7], v[28:31]
	v_mfma_f32_16x16x32_bf16 v[28:31], v[98:101], v[4:7], v[38:41]
	v_mfma_f32_16x16x32_bf16 v[38:41], v[90:93], v[4:7], v[42:45]
	s_nop 2
	ds_read_b128 v[42:45], v48 offset:33792
	ds_read_b128 v[90:93], v48 offset:35840
	ds_read_b128 v[98:101], v48 offset:37888
	ds_read_b128 v[102:105], v48 offset:39936
	v_mfma_f32_16x16x32_bf16 v[50:53], v[86:89], v[4:7], v[50:53]
	ds_read_b128 v[86:89], v48 offset:41984
	ds_read_b128 v[106:109], v48 offset:44032
	ds_read_b128 v[110:113], v48 offset:46080
	ds_read_b128 v[114:117], v48 offset:48128
	v_mfma_f32_16x16x32_bf16 v[74:77], v[82:85], v[4:7], v[74:77]
	s_waitcnt lgkmcnt(7)
	v_mfma_f32_16x16x32_bf16 v[42:45], v[42:45], v[4:7], v[54:57]
	s_waitcnt lgkmcnt(6)
	v_mfma_f32_16x16x32_bf16 v[54:57], v[90:93], v[4:7], v[58:61]
	s_waitcnt lgkmcnt(5)
	v_mfma_f32_16x16x32_bf16 v[58:61], v[98:101], v[4:7], v[62:65]
	s_waitcnt lgkmcnt(4)
	v_mfma_f32_16x16x32_bf16 v[62:65], v[102:105], v[4:7], v[66:69]
	s_waitcnt lgkmcnt(3)
	v_mfma_f32_16x16x32_bf16 v[66:69], v[86:89], v[4:7], v[70:73]
	s_waitcnt lgkmcnt(2)
	v_mfma_f32_16x16x32_bf16 v[70:73], v[106:109], v[4:7], v[78:81]
	s_nop 2
	ds_read_b128 v[78:81], v48 offset:31744
	ds_read_b128 v[82:85], v48 offset:29696
	ds_read_b128 v[86:89], v48 offset:27648
	ds_read_b128 v[90:93], v48 offset:25600
	s_waitcnt lgkmcnt(5)
	v_mfma_f32_16x16x32_bf16 v[94:97], v[110:113], v[4:7], v[94:97]
	ds_read_b128 v[98:101], v48 offset:23552
	ds_read_b128 v[102:105], v48 offset:21504
	ds_read_b128 v[106:109], v48 offset:19456
	ds_read_b128 v[110:113], v48 offset:17408
	s_waitcnt lgkmcnt(8)
	v_mfma_f32_16x16x32_bf16 v[4:7], v[114:117], v[4:7], v[8:11]
	s_waitcnt lgkmcnt(0)
	v_mfma_f32_16x16x32_bf16 v[8:11], v[110:113], v[0:3], v[12:15]
	v_mfma_f32_16x16x32_bf16 v[12:15], v[106:109], v[0:3], v[16:19]
	v_mfma_f32_16x16x32_bf16 v[16:19], v[102:105], v[0:3], v[20:23]
	v_mfma_f32_16x16x32_bf16 v[20:23], v[98:101], v[0:3], v[24:27]
	v_mfma_f32_16x16x32_bf16 v[24:27], v[90:93], v[0:3], v[28:31]
	v_mfma_f32_16x16x32_bf16 v[28:31], v[86:89], v[0:3], v[38:41]
	s_nop 2
	ds_read_b128 v[38:41], v48 offset:50176
	ds_read_b128 v[86:89], v48 offset:52224
	ds_read_b128 v[90:93], v48 offset:54272
	ds_read_b128 v[98:101], v48 offset:56320
	v_mfma_f32_16x16x32_bf16 v[50:53], v[82:85], v[0:3], v[50:53]
	ds_read_b128 v[82:85], v48 offset:58368
	ds_read_b128 v[102:105], v48 offset:60416
	ds_read_b128 v[106:109], v48 offset:62464
	ds_read_b128 v[46:49], v48 offset:64512
	v_mfma_f32_16x16x32_bf16 v[74:77], v[78:81], v[0:3], v[74:77]
	s_waitcnt lgkmcnt(7)
	v_mfma_f32_16x16x32_bf16 v[38:41], v[38:41], v[0:3], v[42:45]
	s_waitcnt lgkmcnt(6)
	v_mfma_f32_16x16x32_bf16 v[42:45], v[86:89], v[0:3], v[54:57]
	s_waitcnt lgkmcnt(5)
	v_mfma_f32_16x16x32_bf16 v[54:57], v[90:93], v[0:3], v[58:61]
	s_waitcnt lgkmcnt(4)
	v_mfma_f32_16x16x32_bf16 v[58:61], v[98:101], v[0:3], v[62:65]
	s_waitcnt lgkmcnt(3)
	v_mfma_f32_16x16x32_bf16 v[62:65], v[82:85], v[0:3], v[66:69]
	s_waitcnt lgkmcnt(2)
	v_mfma_f32_16x16x32_bf16 v[66:69], v[102:105], v[0:3], v[70:73]
	s_waitcnt lgkmcnt(1)
	v_mfma_f32_16x16x32_bf16 v[70:73], v[106:109], v[0:3], v[94:97]
	s_waitcnt lgkmcnt(0)
	v_mfma_f32_16x16x32_bf16 v[0:3], v[46:49], v[0:3], v[4:7]
	s_nop 2
	v_mul_f32_e32 v4, v36, v8
	v_mul_f32_e32 v5, v36, v9
	v_cvt_pk_bf16_f32 v4, v4, v5
	v_mul_f32_e32 v5, v36, v10
	v_mul_f32_e32 v6, v36, v11
	v_cvt_pk_bf16_f32 v5, v5, v6
	global_store_dwordx2 v[32:33], v[4:5], off offset:512
	v_mul_f32_e32 v4, v36, v12
	v_mul_f32_e32 v5, v36, v13
	v_cvt_pk_bf16_f32 v4, v4, v5
	v_mul_f32_e32 v5, v36, v14
	v_mul_f32_e32 v6, v36, v15
	v_cvt_pk_bf16_f32 v5, v5, v6
	global_store_dwordx2 v[32:33], v[4:5], off offset:544
	v_mul_f32_e32 v4, v36, v16
	v_mul_f32_e32 v5, v36, v17
	v_cvt_pk_bf16_f32 v4, v4, v5
	v_mul_f32_e32 v5, v36, v18
	v_mul_f32_e32 v6, v36, v19
	v_cvt_pk_bf16_f32 v5, v5, v6
	global_store_dwordx2 v[32:33], v[4:5], off offset:576
	v_mul_f32_e32 v4, v36, v20
	v_mul_f32_e32 v5, v36, v21
	v_cvt_pk_bf16_f32 v4, v4, v5
	v_mul_f32_e32 v5, v36, v22
	v_mul_f32_e32 v6, v36, v23
	v_cvt_pk_bf16_f32 v5, v5, v6
	global_store_dwordx2 v[32:33], v[4:5], off offset:608
	v_mul_f32_e32 v4, v36, v24
	v_mul_f32_e32 v5, v36, v25
	v_cvt_pk_bf16_f32 v4, v4, v5
	v_mul_f32_e32 v5, v36, v26
	v_mul_f32_e32 v6, v36, v27
	v_cvt_pk_bf16_f32 v5, v5, v6
	global_store_dwordx2 v[32:33], v[4:5], off offset:640
	v_mul_f32_e32 v4, v36, v28
	v_mul_f32_e32 v5, v36, v29
	v_cvt_pk_bf16_f32 v4, v4, v5
	v_mul_f32_e32 v5, v36, v30
	v_mul_f32_e32 v6, v36, v31
	v_cvt_pk_bf16_f32 v5, v5, v6
	global_store_dwordx2 v[32:33], v[4:5], off offset:672
	v_mul_f32_e32 v4, v36, v50
	v_mul_f32_e32 v5, v36, v51
	v_cvt_pk_bf16_f32 v4, v4, v5
	v_mul_f32_e32 v5, v36, v52
	v_mul_f32_e32 v6, v36, v53
	v_cvt_pk_bf16_f32 v5, v5, v6
	global_store_dwordx2 v[32:33], v[4:5], off offset:704
	v_mul_f32_e32 v4, v36, v74
	v_mul_f32_e32 v5, v36, v75
	v_cvt_pk_bf16_f32 v4, v4, v5
	v_mul_f32_e32 v5, v36, v76
	v_mul_f32_e32 v6, v36, v77
	v_cvt_pk_bf16_f32 v5, v5, v6
	global_store_dwordx2 v[32:33], v[4:5], off offset:736
	v_mul_f32_e32 v4, v36, v38
	v_mul_f32_e32 v5, v36, v39
	v_cvt_pk_bf16_f32 v4, v4, v5
	v_mul_f32_e32 v5, v36, v40
	v_mul_f32_e32 v6, v36, v41
	v_cvt_pk_bf16_f32 v5, v5, v6
	global_store_dwordx2 v[32:33], v[4:5], off offset:768
	v_mul_f32_e32 v4, v36, v42
	v_mul_f32_e32 v5, v36, v43
	v_cvt_pk_bf16_f32 v4, v4, v5
	v_mul_f32_e32 v5, v36, v44
	v_mul_f32_e32 v6, v36, v45
	v_cvt_pk_bf16_f32 v5, v5, v6
	global_store_dwordx2 v[32:33], v[4:5], off offset:800
	v_mul_f32_e32 v4, v36, v54
	v_mul_f32_e32 v5, v36, v55
	v_cvt_pk_bf16_f32 v4, v4, v5
	v_mul_f32_e32 v5, v36, v56
	v_mul_f32_e32 v6, v36, v57
	v_cvt_pk_bf16_f32 v5, v5, v6
	global_store_dwordx2 v[32:33], v[4:5], off offset:832
	v_mul_f32_e32 v4, v36, v58
	v_mul_f32_e32 v5, v36, v59
	v_cvt_pk_bf16_f32 v4, v4, v5
	v_mul_f32_e32 v5, v36, v60
	v_mul_f32_e32 v6, v36, v61
	v_cvt_pk_bf16_f32 v5, v5, v6
	global_store_dwordx2 v[32:33], v[4:5], off offset:864
	v_mul_f32_e32 v4, v36, v62
	v_mul_f32_e32 v5, v36, v63
	v_cvt_pk_bf16_f32 v4, v4, v5
	v_mul_f32_e32 v5, v36, v64
	v_mul_f32_e32 v6, v36, v65
	v_cvt_pk_bf16_f32 v5, v5, v6
	global_store_dwordx2 v[32:33], v[4:5], off offset:896
	v_mul_f32_e32 v4, v36, v66
	v_mul_f32_e32 v5, v36, v67
	v_cvt_pk_bf16_f32 v4, v4, v5
	v_mul_f32_e32 v5, v36, v68
	v_mul_f32_e32 v6, v36, v69
	v_cvt_pk_bf16_f32 v5, v5, v6
	global_store_dwordx2 v[32:33], v[4:5], off offset:928
	v_mul_f32_e32 v4, v36, v70
	v_mul_f32_e32 v5, v36, v71
	v_cvt_pk_bf16_f32 v4, v4, v5
	v_mul_f32_e32 v5, v36, v72
	v_mul_f32_e32 v0, v36, v0
	v_mul_f32_e32 v1, v36, v1
	v_mul_f32_e32 v6, v36, v73
	v_cvt_pk_bf16_f32 v5, v5, v6
	global_store_dwordx2 v[32:33], v[4:5], off offset:960
	v_cvt_pk_bf16_f32 v0, v0, v1
	v_mul_f32_e32 v1, v36, v2
	v_mul_f32_e32 v2, v36, v3
	v_cvt_pk_bf16_f32 v1, v1, v2
	global_store_dwordx2 v[32:33], v[0:1], off offset:992
	s_waitcnt vmcnt(0)
	s_barrier

.LBB0_957:
	s_mov_b32 s0, s38
	s_lshl_b32 s0, s0, 8
	v_mov_b32_e32 v120, v229
	v_mov_b32_e32 v132, v228
	s_add_i32 s0, s0, s44
	s_nop 0
	v_add_u32_e32 v226, s0, v120
	s_lshl_b32 s0, s20, 8
	s_or_b32 s0, s0, s45
	v_lshl_add_u32 v196, v132, 3, s0
	v_ashrrev_i32_e32 v197, 31, v196
	v_lshlrev_b64 v[244:245], 1, v[196:197]
	v_ashrrev_i32_e32 v227, 31, v226
	v_lshl_add_u64 v[120:121], s[14:15], 0, v[244:245]
	v_lshlrev_b64 v[246:247], 12, v[226:227]
	v_lshl_add_u64 v[122:123], v[120:121], 0, v[246:247]
	global_load_dwordx4 v[236:239], v[122:123], off
	global_load_dwordx4 v[240:243], v[122:123], off offset:256
	v_add_u32_e32 v222, 16, v226
	v_add_u32_e32 v218, 32, v226
	v_add_u32_e32 v214, 48, v226
	v_add_u32_e32 v210, 0x80, v226
	v_add_u32_e32 v206, 0x90, v226
	v_add_u32_e32 v202, 0xa0, v226
	v_add_u32_e32 v198, 0xb0, v226
	v_ashrrev_i32_e32 v223, 31, v222
	v_ashrrev_i32_e32 v219, 31, v218
	v_ashrrev_i32_e32 v215, 31, v214
	v_ashrrev_i32_e32 v211, 31, v210
	v_ashrrev_i32_e32 v207, 31, v206
	v_ashrrev_i32_e32 v203, 31, v202
	v_ashrrev_i32_e32 v199, 31, v198
	v_lshlrev_b64 v[224:225], 12, v[222:223]
	v_lshlrev_b64 v[220:221], 12, v[218:219]
	v_lshlrev_b64 v[216:217], 12, v[214:215]
	v_lshlrev_b64 v[212:213], 12, v[210:211]
	v_lshlrev_b64 v[208:209], 12, v[206:207]
	v_lshlrev_b64 v[204:205], 12, v[202:203]
	v_lshlrev_b64 v[200:201], 12, v[198:199]
	v_cmp_eq_u32_e32 vcc, 0, v132
	v_lshl_add_u64 v[122:123], v[120:121], 0, v[224:225]
	v_lshl_add_u64 v[132:133], v[120:121], 0, v[220:221]
	v_lshl_add_u64 v[134:135], v[120:121], 0, v[216:217]
	v_lshl_add_u64 v[136:137], v[120:121], 0, v[212:213]
	v_lshl_add_u64 v[138:139], v[120:121], 0, v[208:209]
	v_lshl_add_u64 v[248:249], v[120:121], 0, v[204:205]
	v_lshl_add_u64 v[120:121], v[120:121], 0, v[200:201]
	global_load_dwordx4 v[180:183], v[122:123], off
	global_load_dwordx4 v[176:179], v[122:123], off offset:256
	global_load_dwordx4 v[172:175], v[132:133], off
	global_load_dwordx4 v[168:171], v[132:133], off offset:256
	global_load_dwordx4 v[164:167], v[134:135], off
	global_load_dwordx4 v[160:163], v[134:135], off offset:256
	global_load_dwordx4 v[156:159], v[136:137], off
	global_load_dwordx4 v[152:155], v[136:137], off offset:256
	global_load_dwordx4 v[148:151], v[138:139], off
	global_load_dwordx4 v[144:147], v[138:139], off offset:256
	global_load_dwordx4 v[140:143], v[248:249], off
	s_nop 0
	global_load_dwordx4 v[136:139], v[248:249], off offset:256
	global_load_dwordx4 v[132:135], v[120:121], off
	s_nop 0
	global_load_dwordx4 v[120:123], v[120:121], off offset:256
	s_lshl_b32 s0, s20, 2
	s_ashr_i32 s1, s0, 31
	s_waitcnt vmcnt(0)
	v_lshlrev_b32_e32 v248, 16, v236
	v_and_b32_e32 v236, 0xffff0000, v236
	v_lshlrev_b32_e32 v250, 16, v238
	v_lshlrev_b32_e32 v251, 16, v239
	v_and_b32_e32 v239, 0xffff0000, v239
	v_add_f32_e32 v129, v129, v236
	v_add_f32_e32 v128, v128, v248
	v_add_f32_e32 v236, v124, v250
	v_add_f32_e32 v127, v127, v239
	v_mul_f32_e32 v239, v129, v129
	v_cvt_pk_bf16_f32 v124, v128, v129
	v_lshlrev_b32_e32 v129, 16, v240
	v_add_f32_e32 v116, v116, v129
	v_and_b32_e32 v129, 0xffff0000, v240
	v_lshlrev_b32_e32 v249, 16, v237
	v_and_b32_e32 v237, 0xffff0000, v237
	v_add_f32_e32 v117, v117, v129
	v_lshlrev_b32_e32 v129, 16, v241
	v_add_f32_e32 v131, v131, v237
	v_add_f32_e32 v118, v118, v129
	v_and_b32_e32 v129, 0xffff0000, v241
	v_and_b32_e32 v238, 0xffff0000, v238
	v_add_f32_e32 v130, v130, v249
	v_mul_f32_e32 v248, v131, v131
	v_add_f32_e32 v119, v119, v129
	v_lshlrev_b32_e32 v129, 16, v242
	v_add_f32_e32 v237, v125, v238
	v_cvt_pk_bf16_f32 v125, v130, v131
	v_fmac_f32_e32 v248, v130, v130
	v_add_f32_e32 v130, v112, v129
	v_and_b32_e32 v112, 0xffff0000, v242
	v_mul_f32_e32 v249, v237, v237
	v_add_f32_e32 v131, v113, v112
	v_lshlrev_b32_e32 v112, 16, v243
	v_add_f32_e32 v238, v126, v251
	v_cvt_pk_bf16_f32 v126, v236, v237
	v_fmac_f32_e32 v249, v236, v236
	v_add_f32_e32 v236, v114, v112
	v_and_b32_e32 v112, 0xffff0000, v243
	v_add_f32_e32 v237, v115, v112
	v_mul_f32_e32 v112, v117, v117
	v_mul_f32_e32 v113, v119, v119
	v_fmac_f32_e32 v112, v116, v116
	v_fmac_f32_e32 v113, v118, v118
	v_add_f32_e32 v112, v112, v113
	v_mul_f32_e32 v113, v131, v131
	v_fmac_f32_e32 v239, v128, v128
	v_fmac_f32_e32 v113, v130, v130
	v_mul_f32_e32 v250, v127, v127
	v_add_f32_e32 v128, v239, v248
	v_add_f32_e32 v112, v113, v112
	v_mul_f32_e32 v113, v237, v237
	v_fmac_f32_e32 v250, v238, v238
	v_add_f32_e32 v128, v249, v128
	v_fmac_f32_e32 v113, v236, v236
	v_add_f32_e32 v128, v250, v128
	v_add_f32_e32 v112, v113, v112
	v_and_b32_e32 v114, 64, v233
	v_cvt_pk_bf16_f32 v127, v238, v127
	v_add_f32_e32 v113, v128, v112
	v_xor_b32_e32 v112, 16, v233
	v_add_u32_e32 v238, 64, v114
	v_cmp_lt_i32_e64 s[2:3], v112, v238
	v_lshl_add_u64 v[114:115], s[14:15], 0, v[246:247]
	v_lshl_add_u64 v[128:129], v[114:115], 0, v[244:245]
	v_cndmask_b32_e64 v112, v233, v112, s[2:3]
	v_lshlrev_b32_e32 v112, 2, v112
	v_mov_b32_e32 v239, v113
	s_nop 1
	v_permlane16_swap_b32_e32 v239, v113
	global_store_dwordx4 v[128:129], v[124:127], off
	v_cvt_pk_bf16_f32 v116, v116, v117
	v_cvt_pk_bf16_f32 v117, v118, v119
	v_cvt_pk_bf16_f32 v118, v130, v131
	s_waitcnt lgkmcnt(0)
	v_add_f32_e32 v114, v113, v239
	v_xor_b32_e32 v113, 32, v233
	v_cmp_lt_i32_e64 s[2:3], v113, v238
	v_cvt_pk_bf16_f32 v119, v236, v237
	global_store_dwordx4 v[128:129], v[116:119], off offset:256
	s_nop 0
	v_cndmask_b32_e64 v113, v233, v113, s[2:3]
	v_lshlrev_b32_e32 v113, 2, v113
	v_mov_b32_e32 v115, v114
	s_nop 1
	v_permlane32_swap_b32_e32 v115, v114
	s_and_saveexec_b64 s[2:3], vcc
	s_cbranch_execz .LBB0_959
	v_lshlrev_b64 v[116:117], 8, v[226:227]
	v_lshl_add_u64 v[116:117], s[16:17], 0, v[116:117]
	v_lshl_add_u64 v[116:117], s[0:1], 2, v[116:117]
	s_lshl_b32 s20, s43, 2
	v_lshl_add_u64 v[116:117], v[116:117], 0, s[20:21]
	s_waitcnt lgkmcnt(0)
	v_add_f32_e32 v114, v114, v115
	global_store_dword v[116:117], v114, off

.LBB0_1529:
	s_mov_b32 s0, s40
	s_lshl_b32 s1, s22, 7
	v_mov_b32_e32 v154, v182
	v_mov_b32_e32 v160, v183
	s_or_b32 s1, s1, s48
	s_lshl_b32 s0, s0, 8
	v_lshl_add_u32 v152, v160, 2, s1
	v_ashrrev_i32_e32 v153, 31, v152
	v_lshlrev_b64 v[80:81], 2, v[152:153]
	v_lshl_add_u64 v[82:83], s[12:13], 0, v[80:81]
	v_lshl_add_u64 v[84:85], s[26:27], 0, v[80:81]
	global_load_dwordx4 v[100:103], v[84:85], off
	global_load_dwordx4 v[92:95], v[82:83], off
	s_nop 0
	global_load_dwordx4 v[80:83], v[82:83], off offset:256
	s_nop 0
	global_load_dwordx4 v[84:87], v[84:85], off offset:256
	s_add_i32 s0, s0, s45
	v_add_u32_e32 v156, s0, v154
	v_lshlrev_b64 v[190:191], 1, v[152:153]
	v_ashrrev_i32_e32 v157, 31, v156
	v_lshl_add_u64 v[154:155], s[16:17], 0, v[190:191]
	v_lshlrev_b64 v[192:193], 12, v[156:157]
	v_lshl_add_u64 v[158:159], v[154:155], 0, v[192:193]
	global_load_dwordx2 v[194:195], v[158:159], off
	global_load_dwordx2 v[196:197], v[158:159], off offset:128
	v_add_u32_e32 v172, 16, v156
	v_add_u32_e32 v166, 32, v156
	v_add_u32_e32 v158, 48, v156
	v_ashrrev_i32_e32 v173, 31, v172
	v_ashrrev_i32_e32 v167, 31, v166
	v_ashrrev_i32_e32 v159, 31, v158
	v_lshlrev_b64 v[176:177], 12, v[172:173]
	v_lshlrev_b64 v[168:169], 12, v[166:167]
	v_cmp_eq_u32_e32 vcc, 0, v160
	v_lshlrev_b64 v[160:161], 12, v[158:159]
	v_lshl_add_u64 v[162:163], v[154:155], 0, v[176:177]
	v_lshl_add_u64 v[164:165], v[154:155], 0, v[168:169]
	v_lshl_add_u64 v[198:199], v[154:155], 0, v[160:161]
	global_load_dwordx2 v[180:181], v[162:163], off
	global_load_dwordx2 v[178:179], v[162:163], off offset:128
	global_load_dwordx2 v[174:175], v[164:165], off
	global_load_dwordx2 v[170:171], v[164:165], off offset:128
	s_nop 0
	global_load_dwordx2 v[164:165], v[198:199], off
	global_load_dwordx2 v[162:163], v[198:199], off offset:128
	s_lshl_b32 s0, s22, 2
	s_ashr_i32 s1, s0, 31
	s_waitcnt vmcnt(0)
	v_add_f32_e32 v141, v141, v101
	v_add_f32_e32 v143, v143, v103
	v_add_f32_e32 v140, v140, v100
	v_add_f32_e32 v142, v142, v102
	v_add_f32_e32 v132, v132, v84
	v_mul_f32_e32 v141, 0xbfb8aa3b, v141
	v_mul_f32_e32 v143, 0xbfb8aa3b, v143
	v_mul_f32_e32 v140, 0xbfb8aa3b, v140
	v_mul_f32_e32 v142, 0xbfb8aa3b, v142
	v_mul_f32_e32 v132, 0xbfb8aa3b, v132
	v_exp_f32_e32 v141, v141
	v_exp_f32_e32 v143, v143
	v_exp_f32_e32 v140, v140
	v_exp_f32_e32 v142, v142
	v_exp_f32_e32 v132, v132
	v_add_f32_e32 v141, 1.0, v141
	v_add_f32_e32 v143, 1.0, v143
	v_add_f32_e32 v140, 1.0, v140
	v_add_f32_e32 v142, 1.0, v142
	v_add_f32_e32 v132, 1.0, v132
	v_rcp_f32_e32 v141, v141
	v_rcp_f32_e32 v143, v143
	v_add_f32_e32 v133, v133, v85
	v_rcp_f32_e32 v140, v140
	v_rcp_f32_e32 v142, v142
	v_rcp_f32_e32 v132, v132
	v_mul_f32_e32 v133, 0xbfb8aa3b, v133
	v_add_f32_e32 v137, v137, v93
	v_add_f32_e32 v139, v139, v95
	v_lshlrev_b32_e32 v189, 16, v194
	v_and_b32_e32 v194, 0xffff0000, v194
	v_lshlrev_b32_e32 v198, 16, v195
	v_and_b32_e32 v195, 0xffff0000, v195
	v_exp_f32_e32 v133, v133
	v_add_f32_e32 v136, v136, v92
	v_add_f32_e32 v138, v138, v94
	v_add_f32_e32 v128, v128, v80
	v_lshlrev_b32_e32 v199, 16, v196
	v_fmac_f32_e32 v194, v137, v141
	v_fmac_f32_e32 v195, v139, v143
	v_fmac_f32_e32 v189, v136, v140
	v_fmac_f32_e32 v198, v138, v142
	v_fmac_f32_e32 v199, v128, v132
	v_mul_f32_e32 v128, v194, v194
	v_mul_f32_e32 v132, v195, v195
	v_add_f32_e32 v134, v134, v86
	v_fmac_f32_e32 v128, v189, v189
	v_fmac_f32_e32 v132, v198, v198
	v_add_f32_e32 v133, 1.0, v133
	v_add_f32_e32 v128, v128, v132
	v_mul_f32_e32 v132, 0xbfb8aa3b, v134
	v_add_f32_e32 v134, v135, v87
	v_rcp_f32_e32 v133, v133
	v_exp_f32_e32 v132, v132
	v_mul_f32_e32 v134, 0xbfb8aa3b, v134
	v_exp_f32_e32 v134, v134
	v_add_f32_e32 v129, v129, v81
	v_and_b32_e32 v196, 0xffff0000, v196
	v_fmac_f32_e32 v196, v129, v133
	v_add_f32_e32 v129, 1.0, v132
	v_rcp_f32_e32 v129, v129
	v_add_f32_e32 v132, 1.0, v134
	v_rcp_f32_e32 v132, v132
	v_lshlrev_b32_e32 v200, 16, v197
	v_add_f32_e32 v130, v130, v82
	v_and_b32_e32 v197, 0xffff0000, v197
	v_fmac_f32_e32 v200, v130, v129
	v_add_f32_e32 v129, v131, v83
	v_fmac_f32_e32 v197, v129, v132
	v_mul_f32_e32 v129, v196, v196
	v_mul_f32_e32 v130, v197, v197
	v_fmac_f32_e32 v129, v199, v199
	v_fmac_f32_e32 v130, v200, v200
	v_add_f32_e32 v129, v129, v130
	v_and_b32_e32 v130, 64, v188
	v_add_f32_e32 v129, v128, v129
	v_xor_b32_e32 v128, 16, v188
	v_add_u32_e32 v136, 64, v130
	v_cmp_lt_i32_e64 s[2:3], v128, v136
	v_lshl_add_u64 v[130:131], s[16:17], 0, v[192:193]
	v_lshl_add_u64 v[134:135], v[130:131], 0, v[190:191]
	v_cndmask_b32_e64 v128, v188, v128, s[2:3]
	v_lshlrev_b32_e32 v128, 2, v128
	v_mov_b32_e32 v137, v129
	s_nop 1
	v_permlane16_swap_b32_e32 v137, v129
	v_cvt_pk_bf16_f32 v132, v189, v194
	v_cvt_pk_bf16_f32 v133, v198, v195
	global_store_dwordx2 v[134:135], v[132:133], off
	v_cvt_pk_bf16_f32 v132, v199, v196
	s_waitcnt lgkmcnt(0)
	v_add_f32_e32 v130, v129, v137
	v_xor_b32_e32 v129, 32, v188
	v_cmp_lt_i32_e64 s[2:3], v129, v136
	v_cvt_pk_bf16_f32 v133, v200, v197
	global_store_dwordx2 v[134:135], v[132:133], off offset:128
	s_nop 0
	v_cndmask_b32_e64 v129, v188, v129, s[2:3]
	v_lshlrev_b32_e32 v129, 2, v129
	v_mov_b32_e32 v131, v130
	s_nop 1
	v_permlane32_swap_b32_e32 v131, v130
	s_and_saveexec_b64 s[2:3], vcc
	s_cbranch_execz .LBB0_1531
	s_waitcnt lgkmcnt(0)
	v_add_f32_e32 v132, v130, v131
	v_lshlrev_b64 v[130:131], 8, v[156:157]
	v_lshl_add_u64 v[130:131], s[18:19], 0, v[130:131]
	v_lshl_add_u64 v[130:131], s[0:1], 2, v[130:131]
	s_lshl_b32 s22, s44, 2
	v_lshl_add_u64 v[130:131], v[130:131], 0, s[22:23]
	global_store_dword v[130:131], v132, off
.LBB0_1531:
	s_or_b64 exec, exec, s[2:3]
	v_add_f32_e32 v124, v124, v100
	v_mul_f32_e32 v124, 0xbfb8aa3b, v124
	v_exp_f32_e32 v124, v124
	v_add_f32_e32 v125, v125, v101
	v_mul_f32_e32 v125, 0xbfb8aa3b, v125
	v_exp_f32_e32 v125, v125
	v_add_f32_e32 v124, 1.0, v124
	v_rcp_f32_e32 v124, v124
	v_lshlrev_b32_e32 v130, 16, v180
	v_add_f32_e32 v120, v120, v92
	s_waitcnt lgkmcnt(0)
	v_and_b32_e32 v131, 0xffff0000, v180
	v_fmac_f32_e32 v130, v120, v124
	v_add_f32_e32 v124, v126, v102
	v_add_f32_e32 v120, 1.0, v125
	v_mul_f32_e32 v124, 0xbfb8aa3b, v124
	v_add_f32_e32 v125, v127, v103
	v_rcp_f32_e32 v120, v120
	v_exp_f32_e32 v124, v124
	v_mul_f32_e32 v125, 0xbfb8aa3b, v125
	v_exp_f32_e32 v125, v125
	v_add_f32_e32 v121, v121, v93
	v_add_f32_e32 v116, v116, v84
	v_fmac_f32_e32 v131, v121, v120
	v_add_f32_e32 v120, 1.0, v124
	v_mul_f32_e32 v116, 0xbfb8aa3b, v116
	v_rcp_f32_e32 v120, v120
	v_add_f32_e32 v121, 1.0, v125
	v_exp_f32_e32 v116, v116
	v_rcp_f32_e32 v121, v121
	v_lshlrev_b32_e32 v132, 16, v181
	v_add_f32_e32 v122, v122, v94
	v_and_b32_e32 v133, 0xffff0000, v181
	v_fmac_f32_e32 v132, v122, v120
	v_add_f32_e32 v120, v123, v95
	v_add_f32_e32 v116, 1.0, v116
	v_add_f32_e32 v117, v117, v85
	v_fmac_f32_e32 v133, v120, v121
	v_rcp_f32_e32 v116, v116
	v_mul_f32_e32 v117, 0xbfb8aa3b, v117
	v_mul_f32_e32 v120, v131, v131
	v_mul_f32_e32 v121, v133, v133
	v_exp_f32_e32 v117, v117
	v_fmac_f32_e32 v120, v130, v130
	v_fmac_f32_e32 v121, v132, v132
	v_add_f32_e32 v120, v120, v121
	v_lshlrev_b32_e32 v121, 16, v178
	v_add_f32_e32 v112, v112, v80
	v_fmac_f32_e32 v121, v112, v116
	v_add_f32_e32 v116, v118, v86
	v_add_f32_e32 v112, 1.0, v117
	v_mul_f32_e32 v116, 0xbfb8aa3b, v116
	v_add_f32_e32 v117, v119, v87
	v_rcp_f32_e32 v112, v112
	v_exp_f32_e32 v116, v116
	v_mul_f32_e32 v117, 0xbfb8aa3b, v117
	v_exp_f32_e32 v117, v117
	v_and_b32_e32 v122, 0xffff0000, v178
	v_add_f32_e32 v113, v113, v81
	v_fmac_f32_e32 v122, v113, v112
	v_add_f32_e32 v112, 1.0, v116
	v_rcp_f32_e32 v112, v112
	v_add_f32_e32 v113, 1.0, v117
	v_rcp_f32_e32 v113, v113
	v_lshlrev_b32_e32 v123, 16, v179
	v_add_f32_e32 v114, v114, v82
	v_and_b32_e32 v124, 0xffff0000, v179
	v_fmac_f32_e32 v123, v114, v112
	v_add_f32_e32 v112, v115, v83
	v_fmac_f32_e32 v124, v112, v113
	v_mul_f32_e32 v112, v122, v122
	v_mul_f32_e32 v113, v124, v124
	v_fmac_f32_e32 v112, v121, v121
	v_fmac_f32_e32 v113, v123, v123
	v_add_f32_e32 v112, v112, v113
	v_add_f32_e32 v118, v120, v112
	v_mov_b32_e32 v119, v118
	s_nop 1
	v_permlane16_swap_b32_e32 v119, v118
	v_lshl_add_u64 v[112:113], s[16:17], 0, v[176:177]
	v_lshl_add_u64 v[116:117], v[152:153], 1, v[112:113]
	v_cvt_pk_bf16_f32 v114, v130, v131
	v_cvt_pk_bf16_f32 v115, v132, v133
	s_waitcnt lgkmcnt(0)
	v_add_f32_e32 v112, v118, v119
	v_mov_b32_e32 v113, v112
	s_nop 1
	v_permlane32_swap_b32_e32 v113, v112
	global_store_dwordx2 v[116:117], v[114:115], off
	v_cvt_pk_bf16_f32 v114, v121, v122
	v_cvt_pk_bf16_f32 v115, v123, v124
	global_store_dwordx2 v[116:117], v[114:115], off offset:128
	s_and_saveexec_b64 s[2:3], vcc
	s_cbranch_execz .LBB0_1533
	s_waitcnt lgkmcnt(0)
	v_add_f32_e32 v114, v112, v113
	v_lshlrev_b64 v[112:113], 8, v[172:173]
	v_lshl_add_u64 v[112:113], s[18:19], 0, v[112:113]
	v_lshl_add_u64 v[112:113], s[0:1], 2, v[112:113]
	s_lshl_b32 s22, s44, 2
	v_lshl_add_u64 v[112:113], v[112:113], 0, s[22:23]
	global_store_dword v[112:113], v114, off
.LBB0_1533:
	s_or_b64 exec, exec, s[2:3]
	v_add_f32_e32 v108, v108, v100
	v_mul_f32_e32 v108, 0xbfb8aa3b, v108
	v_exp_f32_e32 v108, v108
	v_add_f32_e32 v109, v109, v101
	v_mul_f32_e32 v109, 0xbfb8aa3b, v109
	v_exp_f32_e32 v109, v109
	v_add_f32_e32 v108, 1.0, v108
	v_rcp_f32_e32 v108, v108
	v_lshlrev_b32_e32 v112, 16, v174
	v_add_f32_e32 v104, v104, v92
	s_waitcnt lgkmcnt(0)
	v_and_b32_e32 v113, 0xffff0000, v174
	v_fmac_f32_e32 v112, v104, v108
	v_add_f32_e32 v108, v110, v102
	v_add_f32_e32 v104, 1.0, v109
	v_mul_f32_e32 v108, 0xbfb8aa3b, v108
	v_add_f32_e32 v109, v111, v103
	v_rcp_f32_e32 v104, v104
	v_exp_f32_e32 v108, v108
	v_mul_f32_e32 v109, 0xbfb8aa3b, v109
	v_exp_f32_e32 v109, v109
	v_add_f32_e32 v105, v105, v93
	v_add_f32_e32 v96, v96, v84
	v_fmac_f32_e32 v113, v105, v104
	v_add_f32_e32 v104, 1.0, v108
	v_mul_f32_e32 v96, 0xbfb8aa3b, v96
	v_rcp_f32_e32 v104, v104
	v_add_f32_e32 v105, 1.0, v109
	v_exp_f32_e32 v96, v96
	v_rcp_f32_e32 v105, v105
	v_lshlrev_b32_e32 v114, 16, v175
	v_add_f32_e32 v106, v106, v94
	v_and_b32_e32 v115, 0xffff0000, v175
	v_fmac_f32_e32 v114, v106, v104
	v_add_f32_e32 v104, v107, v95
	v_add_f32_e32 v96, 1.0, v96
	v_add_f32_e32 v97, v97, v85
	v_fmac_f32_e32 v115, v104, v105
	v_rcp_f32_e32 v96, v96
	v_mul_f32_e32 v97, 0xbfb8aa3b, v97
	v_mul_f32_e32 v104, v113, v113
	v_mul_f32_e32 v105, v115, v115
	v_exp_f32_e32 v97, v97
	v_fmac_f32_e32 v104, v112, v112
	v_fmac_f32_e32 v105, v114, v114
	v_add_f32_e32 v104, v104, v105
	v_lshlrev_b32_e32 v105, 16, v170
	v_add_f32_e32 v88, v88, v80
	v_fmac_f32_e32 v105, v88, v96
	v_add_f32_e32 v96, v98, v86
	v_add_f32_e32 v88, 1.0, v97
	v_mul_f32_e32 v96, 0xbfb8aa3b, v96
	v_add_f32_e32 v97, v99, v87
	v_rcp_f32_e32 v88, v88
	v_exp_f32_e32 v96, v96
	v_mul_f32_e32 v97, 0xbfb8aa3b, v97
	v_exp_f32_e32 v97, v97
	v_and_b32_e32 v106, 0xffff0000, v170
	v_add_f32_e32 v89, v89, v81
	v_fmac_f32_e32 v106, v89, v88
	v_add_f32_e32 v88, 1.0, v96
	v_rcp_f32_e32 v88, v88
	v_add_f32_e32 v89, 1.0, v97
	v_rcp_f32_e32 v89, v89
	v_lshlrev_b32_e32 v107, 16, v171
	v_add_f32_e32 v90, v90, v82
	v_and_b32_e32 v108, 0xffff0000, v171
	v_fmac_f32_e32 v107, v90, v88
	v_add_f32_e32 v88, v91, v83
	v_fmac_f32_e32 v108, v88, v89
	v_mul_f32_e32 v88, v106, v106
	v_mul_f32_e32 v89, v108, v108
	v_fmac_f32_e32 v88, v105, v105
	v_fmac_f32_e32 v89, v107, v107
	v_add_f32_e32 v88, v88, v89
	v_add_f32_e32 v98, v104, v88
	v_mov_b32_e32 v99, v98
	s_nop 1
	v_permlane16_swap_b32_e32 v99, v98
	v_lshl_add_u64 v[88:89], s[16:17], 0, v[168:169]
	v_lshl_add_u64 v[96:97], v[152:153], 1, v[88:89]
	v_cvt_pk_bf16_f32 v90, v112, v113
	v_cvt_pk_bf16_f32 v91, v114, v115
	s_waitcnt lgkmcnt(0)
	v_add_f32_e32 v88, v98, v99
	v_mov_b32_e32 v89, v88
	s_nop 1
	v_permlane32_swap_b32_e32 v89, v88
	global_store_dwordx2 v[96:97], v[90:91], off
	v_cvt_pk_bf16_f32 v90, v105, v106
	v_cvt_pk_bf16_f32 v91, v107, v108
	global_store_dwordx2 v[96:97], v[90:91], off offset:128
	s_and_saveexec_b64 s[2:3], vcc
	s_cbranch_execz .LBB0_1535
	s_waitcnt lgkmcnt(0)
	v_add_f32_e32 v90, v88, v89
	v_lshlrev_b64 v[88:89], 8, v[166:167]
	v_lshl_add_u64 v[88:89], s[18:19], 0, v[88:89]
	v_lshl_add_u64 v[88:89], s[0:1], 2, v[88:89]
	s_lshl_b32 s22, s44, 2
	v_lshl_add_u64 v[88:89], v[88:89], 0, s[22:23]
	global_store_dword v[88:89], v90, off
.LBB0_1535:
	s_or_b64 exec, exec, s[2:3]
	v_add_f32_e32 v76, v76, v100
	v_mul_f32_e32 v76, 0xbfb8aa3b, v76
	v_exp_f32_e32 v76, v76
	v_add_f32_e32 v77, v77, v101
	v_mul_f32_e32 v77, 0xbfb8aa3b, v77
	v_exp_f32_e32 v77, v77
	v_add_f32_e32 v76, 1.0, v76
	v_rcp_f32_e32 v76, v76
	v_lshlrev_b32_e32 v88, 16, v164
	v_add_f32_e32 v72, v72, v92
	s_waitcnt lgkmcnt(0)
	v_and_b32_e32 v89, 0xffff0000, v164
	v_fmac_f32_e32 v88, v72, v76
	v_add_f32_e32 v76, v78, v102
	v_add_f32_e32 v72, 1.0, v77
	v_mul_f32_e32 v76, 0xbfb8aa3b, v76
	v_add_f32_e32 v77, v79, v103
	v_rcp_f32_e32 v72, v72
	v_exp_f32_e32 v76, v76
	v_mul_f32_e32 v77, 0xbfb8aa3b, v77
	v_exp_f32_e32 v77, v77
	v_add_f32_e32 v73, v73, v93
	v_add_f32_e32 v68, v68, v84
	v_fmac_f32_e32 v89, v73, v72
	v_add_f32_e32 v72, 1.0, v76
	v_mul_f32_e32 v68, 0xbfb8aa3b, v68
	v_rcp_f32_e32 v72, v72
	v_add_f32_e32 v73, 1.0, v77
	v_exp_f32_e32 v68, v68
	v_rcp_f32_e32 v73, v73
	v_lshlrev_b32_e32 v90, 16, v165
	v_add_f32_e32 v74, v74, v94
	v_and_b32_e32 v91, 0xffff0000, v165
	v_fmac_f32_e32 v90, v74, v72
	v_add_f32_e32 v72, v75, v95
	v_add_f32_e32 v68, 1.0, v68
	v_add_f32_e32 v69, v69, v85
	v_fmac_f32_e32 v91, v72, v73
	v_rcp_f32_e32 v68, v68
	v_mul_f32_e32 v69, 0xbfb8aa3b, v69
	v_mul_f32_e32 v72, v89, v89
	v_mul_f32_e32 v73, v91, v91
	v_exp_f32_e32 v69, v69
	v_fmac_f32_e32 v72, v88, v88
	v_fmac_f32_e32 v73, v90, v90
	v_add_f32_e32 v72, v72, v73
	v_lshlrev_b32_e32 v73, 16, v162
	v_add_f32_e32 v64, v64, v80
	v_fmac_f32_e32 v73, v64, v68
	v_add_f32_e32 v68, v70, v86
	v_add_f32_e32 v64, 1.0, v69
	v_mul_f32_e32 v68, 0xbfb8aa3b, v68
	v_add_f32_e32 v69, v71, v87
	v_rcp_f32_e32 v64, v64
	v_exp_f32_e32 v68, v68
	v_mul_f32_e32 v69, 0xbfb8aa3b, v69
	v_exp_f32_e32 v69, v69
	v_and_b32_e32 v74, 0xffff0000, v162
	v_add_f32_e32 v65, v65, v81
	v_fmac_f32_e32 v74, v65, v64
	v_add_f32_e32 v64, 1.0, v68
	v_rcp_f32_e32 v64, v64
	v_add_f32_e32 v65, 1.0, v69
	v_rcp_f32_e32 v65, v65
	v_lshlrev_b32_e32 v75, 16, v163
	v_add_f32_e32 v66, v66, v82
	v_and_b32_e32 v76, 0xffff0000, v163
	v_fmac_f32_e32 v75, v66, v64
	v_add_f32_e32 v64, v67, v83
	v_fmac_f32_e32 v76, v64, v65
	v_mul_f32_e32 v64, v74, v74
	v_mul_f32_e32 v65, v76, v76
	v_fmac_f32_e32 v64, v73, v73
	v_fmac_f32_e32 v65, v75, v75
	v_add_f32_e32 v64, v64, v65
	v_add_f32_e32 v70, v72, v64
	v_mov_b32_e32 v71, v70
	s_nop 1
	v_permlane16_swap_b32_e32 v71, v70
	v_lshl_add_u64 v[64:65], s[16:17], 0, v[160:161]
	v_lshl_add_u64 v[68:69], v[152:153], 1, v[64:65]
	v_cvt_pk_bf16_f32 v66, v88, v89
	v_cvt_pk_bf16_f32 v67, v90, v91
	s_waitcnt lgkmcnt(0)
	v_add_f32_e32 v64, v70, v71
	v_mov_b32_e32 v65, v64
	s_nop 1
	v_permlane32_swap_b32_e32 v65, v64
	global_store_dwordx2 v[68:69], v[66:67], off
	v_cvt_pk_bf16_f32 v66, v73, v74
	v_cvt_pk_bf16_f32 v67, v75, v76
	global_store_dwordx2 v[68:69], v[66:67], off offset:128
	s_and_saveexec_b64 s[2:3], vcc
	s_cbranch_execz .LBB0_1537
	s_waitcnt lgkmcnt(0)
	v_add_f32_e32 v66, v64, v65
	v_lshlrev_b64 v[64:65], 8, v[158:159]
	v_lshl_add_u64 v[64:65], s[18:19], 0, v[64:65]
	v_lshl_add_u64 v[64:65], s[0:1], 2, v[64:65]
	s_lshl_b32 s22, s44, 2
	v_lshl_add_u64 v[64:65], v[64:65], 0, s[22:23]
	global_store_dword v[64:65], v66, off
.LBB0_1537:
	s_or_b64 exec, exec, s[2:3]
	v_add_u32_e32 v78, 0x80, v156
	v_ashrrev_i32_e32 v79, 31, v78
	v_lshlrev_b64 v[90:91], 12, v[78:79]
	s_waitcnt lgkmcnt(0)
	v_lshl_add_u64 v[64:65], v[154:155], 0, v[90:91]
	global_load_dwordx2 v[96:97], v[64:65], off
	global_load_dwordx2 v[98:99], v[64:65], off offset:128
	v_add_u32_e32 v70, 0x90, v156
	v_add_u32_e32 v66, 0xa0, v156
	v_add_u32_e32 v64, 0xb0, v156
	v_ashrrev_i32_e32 v71, 31, v70
	v_ashrrev_i32_e32 v67, 31, v66
	v_add_f32_e32 v110, v62, v102
	v_add_f32_e32 v112, v63, v103
	v_ashrrev_i32_e32 v65, 31, v64
	v_lshlrev_b64 v[74:75], 12, v[70:71]
	v_lshlrev_b64 v[62:63], 12, v[66:67]
	v_add_f32_e32 v106, v60, v100
	v_add_f32_e32 v107, v56, v92
	v_add_f32_e32 v108, v61, v101
	v_add_f32_e32 v109, v57, v93
	v_add_f32_e32 v111, v58, v94
	v_add_f32_e32 v113, v59, v95
	v_lshlrev_b64 v[56:57], 12, v[64:65]
	v_lshl_add_u64 v[58:59], v[154:155], 0, v[74:75]
	v_lshl_add_u64 v[60:61], v[154:155], 0, v[62:63]
	v_lshl_add_u64 v[104:105], v[154:155], 0, v[56:57]
	global_load_dwordx2 v[88:89], v[58:59], off
	global_load_dwordx2 v[76:77], v[58:59], off offset:128
	global_load_dwordx2 v[72:73], v[60:61], off
	global_load_dwordx2 v[68:69], v[60:61], off offset:128
	s_nop 0
	global_load_dwordx2 v[60:61], v[104:105], off
	global_load_dwordx2 v[58:59], v[104:105], off offset:128
	v_add_f32_e32 v52, v52, v84
	v_add_f32_e32 v53, v53, v85
	v_mul_f32_e32 v105, 0xbfb8aa3b, v108
	v_mul_f32_e32 v108, 0xbfb8aa3b, v112
	v_mul_f32_e32 v104, 0xbfb8aa3b, v106
	v_mul_f32_e32 v106, 0xbfb8aa3b, v110
	v_mul_f32_e32 v52, 0xbfb8aa3b, v52
	v_mul_f32_e32 v53, 0xbfb8aa3b, v53
	v_exp_f32_e32 v105, v105
	v_exp_f32_e32 v108, v108
	v_exp_f32_e32 v104, v104
	v_exp_f32_e32 v106, v106
	v_exp_f32_e32 v52, v52
	v_exp_f32_e32 v53, v53
	v_add_f32_e32 v105, 1.0, v105
	v_add_f32_e32 v108, 1.0, v108
	v_add_f32_e32 v54, v54, v86
	v_add_f32_e32 v104, 1.0, v104
	v_add_f32_e32 v106, 1.0, v106
	v_add_f32_e32 v52, 1.0, v52
	v_add_f32_e32 v53, 1.0, v53
	v_rcp_f32_e32 v105, v105
	v_rcp_f32_e32 v108, v108
	v_add_f32_e32 v55, v55, v87
	v_mul_f32_e32 v54, 0xbfb8aa3b, v54
	v_rcp_f32_e32 v104, v104
	v_rcp_f32_e32 v106, v106
	v_rcp_f32_e32 v52, v52
	v_rcp_f32_e32 v53, v53
	v_mul_f32_e32 v55, 0xbfb8aa3b, v55
	v_exp_f32_e32 v54, v54
	v_exp_f32_e32 v55, v55
	v_add_f32_e32 v48, v48, v80
	v_add_f32_e32 v49, v49, v81
	v_add_f32_e32 v54, 1.0, v54
	v_rcp_f32_e32 v54, v54
	v_add_f32_e32 v50, v50, v82
	s_waitcnt vmcnt(7)
	v_lshlrev_b32_e32 v110, 16, v96
	v_and_b32_e32 v96, 0xffff0000, v96
	v_lshlrev_b32_e32 v112, 16, v97
	v_and_b32_e32 v97, 0xffff0000, v97
	s_waitcnt vmcnt(6)
	v_lshlrev_b32_e32 v114, 16, v98
	v_and_b32_e32 v98, 0xffff0000, v98
	v_fmac_f32_e32 v96, v109, v105
	v_fmac_f32_e32 v97, v113, v108
	v_fmac_f32_e32 v110, v107, v104
	v_fmac_f32_e32 v112, v111, v106
	v_fmac_f32_e32 v114, v48, v52
	v_fmac_f32_e32 v98, v49, v53
	v_mul_f32_e32 v48, v96, v96
	v_mul_f32_e32 v49, v97, v97
	v_fmac_f32_e32 v48, v110, v110
	v_fmac_f32_e32 v49, v112, v112
	v_add_f32_e32 v48, v48, v49
	v_add_f32_e32 v49, 1.0, v55
	v_rcp_f32_e32 v49, v49
	v_lshlrev_b32_e32 v115, 16, v99
	v_and_b32_e32 v99, 0xffff0000, v99
	v_fmac_f32_e32 v115, v50, v54
	v_add_f32_e32 v50, v51, v83
	v_fmac_f32_e32 v99, v50, v49
	v_mul_f32_e32 v49, v98, v98
	v_mul_f32_e32 v50, v99, v99
	v_fmac_f32_e32 v49, v114, v114
	v_fmac_f32_e32 v50, v115, v115
	v_add_f32_e32 v49, v49, v50
	v_add_f32_e32 v54, v48, v49
	v_mov_b32_e32 v55, v54
	s_nop 1
	v_permlane16_swap_b32_e32 v55, v54
	v_lshl_add_u64 v[48:49], s[16:17], 0, v[90:91]
	v_lshl_add_u64 v[52:53], v[152:153], 1, v[48:49]
	v_cvt_pk_bf16_f32 v50, v110, v96
	v_cvt_pk_bf16_f32 v51, v112, v97
	s_waitcnt lgkmcnt(0)
	v_add_f32_e32 v48, v54, v55
	v_mov_b32_e32 v49, v48
	s_nop 1
	v_permlane32_swap_b32_e32 v49, v48
	global_store_dwordx2 v[52:53], v[50:51], off
	v_cvt_pk_bf16_f32 v50, v114, v98
	v_cvt_pk_bf16_f32 v51, v115, v99
	global_store_dwordx2 v[52:53], v[50:51], off offset:128
	s_and_saveexec_b64 s[2:3], vcc
	s_cbranch_execz .LBB0_1539
	s_waitcnt lgkmcnt(0)
	v_add_f32_e32 v50, v48, v49
	v_lshlrev_b64 v[48:49], 8, v[78:79]
	v_lshl_add_u64 v[48:49], s[18:19], 0, v[48:49]
	v_lshl_add_u64 v[48:49], s[0:1], 2, v[48:49]
	s_lshl_b32 s22, s44, 2
	v_lshl_add_u64 v[48:49], v[48:49], 0, s[22:23]
	global_store_dword v[48:49], v50, off
.LBB0_1539:
	s_or_b64 exec, exec, s[2:3]
	v_add_f32_e32 v44, v44, v100
	v_mul_f32_e32 v44, 0xbfb8aa3b, v44
	v_exp_f32_e32 v44, v44
	v_add_f32_e32 v45, v45, v101
	v_mul_f32_e32 v45, 0xbfb8aa3b, v45
	v_exp_f32_e32 v45, v45
	v_add_f32_e32 v44, 1.0, v44
	v_rcp_f32_e32 v44, v44
	s_waitcnt vmcnt(7)
	v_lshlrev_b32_e32 v48, 16, v88
	v_add_f32_e32 v40, v40, v92
	s_waitcnt lgkmcnt(0)
	v_and_b32_e32 v49, 0xffff0000, v88
	v_fmac_f32_e32 v48, v40, v44
	v_add_f32_e32 v44, v46, v102
	v_add_f32_e32 v40, 1.0, v45
	v_mul_f32_e32 v44, 0xbfb8aa3b, v44
	v_add_f32_e32 v45, v47, v103
	v_rcp_f32_e32 v40, v40
	v_exp_f32_e32 v44, v44
	v_mul_f32_e32 v45, 0xbfb8aa3b, v45
	v_exp_f32_e32 v45, v45
	v_add_f32_e32 v41, v41, v93
	v_add_f32_e32 v36, v36, v84
	v_fmac_f32_e32 v49, v41, v40
	v_add_f32_e32 v40, 1.0, v44
	v_mul_f32_e32 v36, 0xbfb8aa3b, v36
	v_rcp_f32_e32 v40, v40
	v_add_f32_e32 v41, 1.0, v45
	v_exp_f32_e32 v36, v36
	v_rcp_f32_e32 v41, v41
	v_lshlrev_b32_e32 v50, 16, v89
	v_add_f32_e32 v42, v42, v94
	v_and_b32_e32 v51, 0xffff0000, v89
	v_fmac_f32_e32 v50, v42, v40
	v_add_f32_e32 v40, v43, v95
	v_add_f32_e32 v36, 1.0, v36
	v_add_f32_e32 v37, v37, v85
	v_fmac_f32_e32 v51, v40, v41
	v_rcp_f32_e32 v36, v36
	v_mul_f32_e32 v37, 0xbfb8aa3b, v37
	v_mul_f32_e32 v40, v49, v49
	v_mul_f32_e32 v41, v51, v51
	v_exp_f32_e32 v37, v37
	v_fmac_f32_e32 v40, v48, v48
	v_fmac_f32_e32 v41, v50, v50
	v_add_f32_e32 v40, v40, v41
	s_waitcnt vmcnt(6)
	v_lshlrev_b32_e32 v41, 16, v76
	v_add_f32_e32 v32, v32, v80
	v_fmac_f32_e32 v41, v32, v36
	v_add_f32_e32 v36, v38, v86
	v_add_f32_e32 v32, 1.0, v37
	v_mul_f32_e32 v36, 0xbfb8aa3b, v36
	v_add_f32_e32 v37, v39, v87
	v_rcp_f32_e32 v32, v32
	v_exp_f32_e32 v36, v36
	v_mul_f32_e32 v37, 0xbfb8aa3b, v37
	v_exp_f32_e32 v37, v37
	v_and_b32_e32 v42, 0xffff0000, v76
	v_add_f32_e32 v33, v33, v81
	v_fmac_f32_e32 v42, v33, v32
	v_add_f32_e32 v32, 1.0, v36
	v_rcp_f32_e32 v32, v32
	v_add_f32_e32 v33, 1.0, v37
	v_rcp_f32_e32 v33, v33
	v_lshlrev_b32_e32 v43, 16, v77
	v_add_f32_e32 v34, v34, v82
	v_and_b32_e32 v44, 0xffff0000, v77
	v_fmac_f32_e32 v43, v34, v32
	v_add_f32_e32 v32, v35, v83
	v_fmac_f32_e32 v44, v32, v33
	v_mul_f32_e32 v32, v42, v42
	v_mul_f32_e32 v33, v44, v44
	v_fmac_f32_e32 v32, v41, v41
	v_fmac_f32_e32 v33, v43, v43
	v_add_f32_e32 v32, v32, v33
	v_add_f32_e32 v38, v40, v32
	v_mov_b32_e32 v39, v38
	s_nop 1
	v_permlane16_swap_b32_e32 v39, v38
	v_lshl_add_u64 v[32:33], s[16:17], 0, v[74:75]
	v_lshl_add_u64 v[36:37], v[152:153], 1, v[32:33]
	v_cvt_pk_bf16_f32 v34, v48, v49
	v_cvt_pk_bf16_f32 v35, v50, v51
	s_waitcnt lgkmcnt(0)
	v_add_f32_e32 v32, v38, v39
	v_mov_b32_e32 v33, v32
	s_nop 1
	v_permlane32_swap_b32_e32 v33, v32
	global_store_dwordx2 v[36:37], v[34:35], off
	v_cvt_pk_bf16_f32 v34, v41, v42
	v_cvt_pk_bf16_f32 v35, v43, v44
	global_store_dwordx2 v[36:37], v[34:35], off offset:128
	s_and_saveexec_b64 s[2:3], vcc
	s_cbranch_execz .LBB0_1541
	s_waitcnt lgkmcnt(0)
	v_add_f32_e32 v34, v32, v33
	v_lshlrev_b64 v[32:33], 8, v[70:71]
	v_lshl_add_u64 v[32:33], s[18:19], 0, v[32:33]
	v_lshl_add_u64 v[32:33], s[0:1], 2, v[32:33]
	s_lshl_b32 s22, s44, 2
	v_lshl_add_u64 v[32:33], v[32:33], 0, s[22:23]
	global_store_dword v[32:33], v34, off
.LBB0_1541:
	s_or_b64 exec, exec, s[2:3]
	v_add_f32_e32 v28, v28, v100
	v_mul_f32_e32 v28, 0xbfb8aa3b, v28
	v_exp_f32_e32 v28, v28
	v_add_f32_e32 v29, v29, v101
	v_mul_f32_e32 v29, 0xbfb8aa3b, v29
	v_exp_f32_e32 v29, v29
	v_add_f32_e32 v28, 1.0, v28
	v_rcp_f32_e32 v28, v28
	s_waitcnt vmcnt(7)
	v_lshlrev_b32_e32 v32, 16, v72
	v_add_f32_e32 v24, v24, v92
	s_waitcnt lgkmcnt(0)
	v_and_b32_e32 v33, 0xffff0000, v72
	v_fmac_f32_e32 v32, v24, v28
	v_add_f32_e32 v28, v30, v102
	v_add_f32_e32 v24, 1.0, v29
	v_mul_f32_e32 v28, 0xbfb8aa3b, v28
	v_add_f32_e32 v29, v31, v103
	v_rcp_f32_e32 v24, v24
	v_exp_f32_e32 v28, v28
	v_mul_f32_e32 v29, 0xbfb8aa3b, v29
	v_exp_f32_e32 v29, v29
	v_add_f32_e32 v25, v25, v93
	v_add_f32_e32 v20, v20, v84
	v_fmac_f32_e32 v33, v25, v24
	v_add_f32_e32 v24, 1.0, v28
	v_mul_f32_e32 v20, 0xbfb8aa3b, v20
	v_rcp_f32_e32 v24, v24
	v_add_f32_e32 v25, 1.0, v29
	v_exp_f32_e32 v20, v20
	v_rcp_f32_e32 v25, v25
	v_lshlrev_b32_e32 v34, 16, v73
	v_add_f32_e32 v26, v26, v94
	v_and_b32_e32 v35, 0xffff0000, v73
	v_fmac_f32_e32 v34, v26, v24
	v_add_f32_e32 v24, v27, v95
	v_add_f32_e32 v20, 1.0, v20
	v_add_f32_e32 v21, v21, v85
	v_fmac_f32_e32 v35, v24, v25
	v_rcp_f32_e32 v20, v20
	v_mul_f32_e32 v21, 0xbfb8aa3b, v21
	v_mul_f32_e32 v24, v33, v33
	v_mul_f32_e32 v25, v35, v35
	v_exp_f32_e32 v21, v21
	v_fmac_f32_e32 v24, v32, v32
	v_fmac_f32_e32 v25, v34, v34
	v_add_f32_e32 v24, v24, v25
	s_waitcnt vmcnt(6)
	v_lshlrev_b32_e32 v25, 16, v68
	v_add_f32_e32 v16, v16, v80
	v_fmac_f32_e32 v25, v16, v20
	v_add_f32_e32 v20, v22, v86
	v_add_f32_e32 v16, 1.0, v21
	v_mul_f32_e32 v20, 0xbfb8aa3b, v20
	v_add_f32_e32 v21, v23, v87
	v_rcp_f32_e32 v16, v16
	v_exp_f32_e32 v20, v20
	v_mul_f32_e32 v21, 0xbfb8aa3b, v21
	v_exp_f32_e32 v21, v21
	v_and_b32_e32 v26, 0xffff0000, v68
	v_add_f32_e32 v17, v17, v81
	v_fmac_f32_e32 v26, v17, v16
	v_add_f32_e32 v16, 1.0, v20
	v_rcp_f32_e32 v16, v16
	v_add_f32_e32 v17, 1.0, v21
	v_rcp_f32_e32 v17, v17
	v_lshlrev_b32_e32 v27, 16, v69
	v_add_f32_e32 v18, v18, v82
	v_and_b32_e32 v28, 0xffff0000, v69
	v_fmac_f32_e32 v27, v18, v16
	v_add_f32_e32 v16, v19, v83
	v_fmac_f32_e32 v28, v16, v17
	v_mul_f32_e32 v16, v26, v26
	v_mul_f32_e32 v17, v28, v28
	v_fmac_f32_e32 v16, v25, v25
	v_fmac_f32_e32 v17, v27, v27
	v_add_f32_e32 v16, v16, v17
	v_add_f32_e32 v22, v24, v16
	v_mov_b32_e32 v23, v22
	s_nop 1
	v_permlane16_swap_b32_e32 v23, v22
	v_lshl_add_u64 v[16:17], s[16:17], 0, v[62:63]
	v_lshl_add_u64 v[20:21], v[152:153], 1, v[16:17]
	v_cvt_pk_bf16_f32 v18, v32, v33
	v_cvt_pk_bf16_f32 v19, v34, v35
	s_waitcnt lgkmcnt(0)
	v_add_f32_e32 v16, v22, v23
	v_mov_b32_e32 v17, v16
	s_nop 1
	v_permlane32_swap_b32_e32 v17, v16
	global_store_dwordx2 v[20:21], v[18:19], off
	v_cvt_pk_bf16_f32 v18, v25, v26
	v_cvt_pk_bf16_f32 v19, v27, v28
	global_store_dwordx2 v[20:21], v[18:19], off offset:128
	s_and_saveexec_b64 s[2:3], vcc
	s_cbranch_execz .LBB0_1543
	s_waitcnt lgkmcnt(0)
	v_add_f32_e32 v18, v16, v17
	v_lshlrev_b64 v[16:17], 8, v[66:67]
	v_lshl_add_u64 v[16:17], s[18:19], 0, v[16:17]
	v_lshl_add_u64 v[16:17], s[0:1], 2, v[16:17]
	s_lshl_b32 s22, s44, 2
	v_lshl_add_u64 v[16:17], v[16:17], 0, s[22:23]
	global_store_dword v[16:17], v18, off
.LBB0_1543:
	s_or_b64 exec, exec, s[2:3]
	v_add_f32_e32 v12, v12, v100
	v_mul_f32_e32 v12, 0xbfb8aa3b, v12
	v_exp_f32_e32 v12, v12
	v_add_f32_e32 v13, v13, v101
	v_mul_f32_e32 v13, 0xbfb8aa3b, v13
	v_exp_f32_e32 v13, v13
	v_add_f32_e32 v12, 1.0, v12
	v_rcp_f32_e32 v12, v12
	s_waitcnt vmcnt(7)
	v_lshlrev_b32_e32 v16, 16, v60
	v_add_f32_e32 v8, v8, v92
	s_waitcnt lgkmcnt(0)
	v_and_b32_e32 v17, 0xffff0000, v60
	v_fmac_f32_e32 v16, v8, v12
	v_add_f32_e32 v12, v14, v102
	v_add_f32_e32 v8, 1.0, v13
	v_mul_f32_e32 v12, 0xbfb8aa3b, v12
	v_add_f32_e32 v13, v15, v103
	v_rcp_f32_e32 v8, v8
	v_exp_f32_e32 v12, v12
	v_mul_f32_e32 v13, 0xbfb8aa3b, v13
	v_exp_f32_e32 v13, v13
	v_add_f32_e32 v9, v9, v93
	v_add_f32_e32 v4, v4, v84
	v_fmac_f32_e32 v17, v9, v8
	v_add_f32_e32 v8, 1.0, v12
	v_mul_f32_e32 v4, 0xbfb8aa3b, v4
	v_rcp_f32_e32 v8, v8
	v_add_f32_e32 v9, 1.0, v13
	v_exp_f32_e32 v4, v4
	v_rcp_f32_e32 v9, v9
	v_lshlrev_b32_e32 v18, 16, v61
	v_add_f32_e32 v10, v10, v94
	v_and_b32_e32 v19, 0xffff0000, v61
	v_fmac_f32_e32 v18, v10, v8
	v_add_f32_e32 v8, v11, v95
	v_add_f32_e32 v4, 1.0, v4
	v_add_f32_e32 v5, v5, v85
	v_fmac_f32_e32 v19, v8, v9
	v_rcp_f32_e32 v4, v4
	v_mul_f32_e32 v5, 0xbfb8aa3b, v5
	v_mul_f32_e32 v8, v17, v17
	v_mul_f32_e32 v9, v19, v19
	v_exp_f32_e32 v5, v5
	v_fmac_f32_e32 v8, v16, v16
	v_fmac_f32_e32 v9, v18, v18
	v_add_f32_e32 v8, v8, v9
	s_waitcnt vmcnt(6)
	v_lshlrev_b32_e32 v9, 16, v58
	v_add_f32_e32 v0, v0, v80
	v_fmac_f32_e32 v9, v0, v4
	v_add_f32_e32 v4, v6, v86
	v_add_f32_e32 v0, 1.0, v5
	v_mul_f32_e32 v4, 0xbfb8aa3b, v4
	v_add_f32_e32 v5, v7, v87
	v_rcp_f32_e32 v0, v0
	v_exp_f32_e32 v4, v4
	v_mul_f32_e32 v5, 0xbfb8aa3b, v5
	v_exp_f32_e32 v5, v5
	v_and_b32_e32 v10, 0xffff0000, v58
	v_add_f32_e32 v1, v1, v81
	v_fmac_f32_e32 v10, v1, v0
	v_add_f32_e32 v0, 1.0, v4
	v_rcp_f32_e32 v0, v0
	v_add_f32_e32 v1, 1.0, v5
	v_rcp_f32_e32 v1, v1
	v_lshlrev_b32_e32 v11, 16, v59
	v_add_f32_e32 v2, v2, v82
	v_and_b32_e32 v12, 0xffff0000, v59
	v_fmac_f32_e32 v11, v2, v0
	v_add_f32_e32 v0, v3, v83
	v_fmac_f32_e32 v12, v0, v1
	v_mul_f32_e32 v0, v10, v10
	v_mul_f32_e32 v1, v12, v12
	v_fmac_f32_e32 v0, v9, v9
	v_fmac_f32_e32 v1, v11, v11
	v_add_f32_e32 v0, v0, v1
	v_add_f32_e32 v6, v8, v0
	v_mov_b32_e32 v7, v6
	s_nop 1
	v_permlane16_swap_b32_e32 v7, v6
	v_lshl_add_u64 v[0:1], s[16:17], 0, v[56:57]
	v_lshl_add_u64 v[4:5], v[152:153], 1, v[0:1]
	v_cvt_pk_bf16_f32 v2, v16, v17
	v_cvt_pk_bf16_f32 v3, v18, v19
	s_waitcnt lgkmcnt(0)
	v_add_f32_e32 v0, v6, v7
	v_mov_b32_e32 v1, v0
	s_nop 1
	v_permlane32_swap_b32_e32 v1, v0
	global_store_dwordx2 v[4:5], v[2:3], off
	v_cvt_pk_bf16_f32 v2, v9, v10
	v_cvt_pk_bf16_f32 v3, v11, v12
	global_store_dwordx2 v[4:5], v[2:3], off offset:128
	s_and_saveexec_b64 s[2:3], vcc
	s_cbranch_execz .LBB0_1545
	s_waitcnt lgkmcnt(0)
	v_add_f32_e32 v2, v0, v1
	v_lshlrev_b64 v[0:1], 8, v[64:65]
	v_lshl_add_u64 v[0:1], s[18:19], 0, v[0:1]
	v_lshl_add_u64 v[0:1], s[0:1], 2, v[0:1]
	s_lshl_b32 s22, s44, 2
	v_lshl_add_u64 v[0:1], v[0:1], 0, s[22:23]
	global_store_dword v[0:1], v2, off

.LBB0_1739:
.LBB0_1740:
	s_add_i32 s0, 0, 0x23f94
	s_waitcnt vmcnt(0)
	v_mov_b32_e32 v0, s0
	v_mbcnt_lo_u32_b32 v58, -1, 0
	v_mbcnt_hi_u32_b32 v58, -1, v58
	ds_read_b32 v0, v0
	v_lshlrev_b32_e32 v71, 4, v58
	v_and_b32_e32 v59, 15, v58
	s_mov_b32 s1, 0
	v_ashrrev_i32_e32 v70, 4, v58
	s_waitcnt lgkmcnt(0)
	v_readfirstlane_b32 s0, v0
	s_and_b32 s4, s0, 7
	s_mul_i32 s5, s4, 0x1400000
	s_add_u32 s5, s94, s5
	s_addc_u32 s6, s95, 0
	s_lshl_b32 s4, s4, 22
	s_sub_u32 s4, 0, s4
	s_subb_u32 s7, 0, 0
	s_add_u32 s4, s5, s4
	s_addc_u32 s5, s6, s7
	s_lshl_b32 s8, s88, 10
	v_add_u32_e32 v0, s8, v71
	v_ashrrev_i32_e32 v1, 31, v0
	v_lshrrev_b32_e32 v1, 22, v1
	v_add_u32_e32 v1, v0, v1
	v_ashrrev_i32_e32 v1, 10, v1
	v_mul_i32_i24_e32 v2, 0x400, v1
	v_sub_u32_e32 v2, v0, v2
	v_lshrrev_b32_e32 v3, 4, v2
	v_bitop3_b32 v2, v3, v2, 32 bitop3:0x6c
	v_ashrrev_i32_e32 v4, 31, v2
	v_lshrrev_b32_e32 v4, 26, v4
	v_lshlrev_b32_e32 v3, 3, v1
	v_add_u32_e32 v4, v2, v4
	v_and_b32_e32 v3, -16, v3
	v_ashrrev_i32_e32 v5, 6, v4
	v_add_u32_e32 v104, v5, v3
	v_and_b32_e32 v3, 0xc0, v4
	v_lshlrev_b32_e32 v1, 5, v1
	v_sub_u32_e32 v2, v2, v3
	v_mov_b32_e32 v3, 1
	v_and_b32_e32 v1, 32, v1
	v_ashrrev_i16_sdwa v2, v3, sext(v2) dst_sel:DWORD dst_unused:UNUSED_PAD src0_sel:DWORD src1_sel:BYTE_0
	v_add_u32_sdwa v1, v1, sext(v2) dst_sel:DWORD dst_unused:UNUSED_PAD src0_sel:DWORD src1_sel:WORD_0
	v_lshlrev_b32_e32 v2, 10, v104
	v_add_u32_e32 v0, 0x2000, v0
	v_lshl_add_u32 v62, v1, 1, v2
	v_ashrrev_i32_e32 v1, 31, v0
	v_lshrrev_b32_e32 v1, 22, v1
	v_add_u32_e32 v1, v0, v1
	v_ashrrev_i32_e32 v1, 10, v1
	v_mul_i32_i24_e32 v2, 0x400, v1
	v_sub_u32_e32 v0, v0, v2
	v_lshrrev_b32_e32 v2, 4, v0
	s_lshl_b32 s6, s0, 3
	v_bitop3_b32 v0, v2, v0, 32 bitop3:0x6c
	s_and_b32 s6, s6, 56
	s_ashr_i32 s7, s0, 5
	v_ashrrev_i32_e32 v4, 31, v0
	s_add_i32 s9, s6, s7
	v_lshrrev_b32_e32 v4, 26, v4
	s_ashr_i32 s12, s9, 5
	v_lshlrev_b32_e32 v2, 3, v1
	v_add_u32_e32 v4, v0, v4
	s_bfe_u32 s0, s0, 0x20003
	s_lshl_b32 s6, s12, 2
	v_and_b32_e32 v2, -16, v2
	v_ashrrev_i32_e32 v5, 6, v4
	s_or_b32 s6, s6, s0
	v_add_u32_e32 v108, v5, v2
	v_and_b32_e32 v2, 0xffc0, v4
	s_ashr_i32 s7, s6, 31
	v_sub_u32_e32 v0, v0, v2
	s_lshl_b64 s[6:7], s[6:7], 18
	v_lshrrev_b16_e32 v2, 7, v0
	s_add_u32 s10, s94, s6
	v_and_b32_e32 v2, 1, v2
	s_addc_u32 s11, s95, s7
	v_lshlrev_b32_e32 v1, 5, v1
	v_add_u16_e32 v0, v0, v2
	s_add_u32 s6, s10, 0x11600000
	v_and_b32_e32 v1, 32, v1
	v_ashrrev_i16_sdwa v0, v3, sext(v0) dst_sel:DWORD dst_unused:UNUSED_PAD src0_sel:DWORD src1_sel:BYTE_0
	s_addc_u32 s7, s11, 0
	s_lshl_b32 s9, s9, 7
	v_add_u32_sdwa v0, v1, sext(v0) dst_sel:DWORD dst_unused:UNUSED_PAD src0_sel:DWORD src1_sel:WORD_0
	v_lshlrev_b32_e32 v1, 10, v108
	s_lshl_b32 s12, s12, 12
	s_and_b32 s9, s9, 0xf80
	v_lshl_add_u32 v64, v0, 1, v1
	v_lshl_or_b32 v1, s88, 4, v59
	s_or_b32 s9, s12, s9
	v_add_u32_e32 v2, s9, v1
	v_ashrrev_i32_e32 v3, 31, v2
	v_lshlrev_b64 v[2:3], 12, v[2:3]
	s_lshl_b32 s0, s0, 10
	v_lshl_add_u64 v[2:3], s[4:5], 0, v[2:3]
	v_lshlrev_b32_e32 v0, 3, v70
	v_lshl_add_u64 v[2:3], v[2:3], 0, s[0:1]
	s_mov_b64 s[0:1], 0x13000000
	v_ashrrev_i32_e32 v1, 31, v0
	v_lshl_add_u64 v[60:61], v[2:3], 0, s[0:1]
	v_lshl_add_u64 v[0:1], v[0:1], 1, v[60:61]
	s_mov_b64 s[0:1], 0xc00000
	v_lshl_add_u64 v[2:3], v[0:1], 0, s[0:1]
	s_mov_b32 s0, 0xc00000
	v_add_co_u32_e32 v0, vcc, s0, v0
	s_add_i32 s22, s8, 0
	s_nop 0
	v_addc_co_u32_e32 v1, vcc, 0, v1, vcc
	v_mov_b32_e32 v63, 0
	s_mov_b32 m0, s22
	s_add_i32 s21, s22, 0x2000
	global_load_dwordx4 v[72:75], v[2:3], off offset:64
	global_load_dwordx4 v[52:55], v[2:3], off offset:128
	global_load_dwordx4 v[48:51], v[2:3], off offset:192
	global_load_dwordx4 v[44:47], v[2:3], off offset:256
	global_load_dwordx4 v[40:43], v[2:3], off offset:320
	global_load_dwordx4 v[36:39], v[2:3], off offset:384
	global_load_dwordx4 v[32:35], v[2:3], off offset:448
	global_load_dwordx4 v[28:31], v[2:3], off offset:512
	global_load_dwordx4 v[24:27], v[2:3], off offset:576
	global_load_dwordx4 v[20:23], v[2:3], off offset:640
	global_load_dwordx4 v[16:19], v[2:3], off offset:704
	global_load_dwordx4 v[12:15], v[2:3], off offset:768
	global_load_dwordx4 v[8:11], v[2:3], off offset:832
	global_load_dwordx4 v[4:7], v[2:3], off offset:896
	global_load_dwordx4 v[76:79], v[0:1], off
	s_nop 0
	global_load_dwordx4 v[0:3], v[2:3], off offset:960
	v_mov_b32_e32 v65, v63
	global_load_lds_dwordx4 v62, s[6:7]
	v_mov_b32_e32 v240, v62
	s_mov_b32 m0, s21
	v_lshl_add_u64 v[66:67], s[6:7], 0, v[62:63]
	v_lshl_add_u64 v[68:69], s[6:7], 0, v[64:65]
	global_load_lds_dwordx4 v64, s[6:7]
	s_add_i32 s20, s22, 0x4000
	s_mov_b64 s[6:7], 0x80
	s_add_i32 s23, s22, 0x6000
	v_lshl_add_u64 v[56:57], v[66:67], 0, s[6:7]
	s_mov_b32 m0, s20
	s_add_u32 s0, s10, 0x11620000
	global_load_lds_dwordx4 v[56:57], off
	v_lshl_add_u64 v[56:57], v[68:69], 0, s[6:7]
	s_mov_b32 m0, s23
	s_addc_u32 s1, s11, 0
	s_add_i32 s24, s22, 0x8000
	global_load_lds_dwordx4 v[56:57], off
	s_mov_b32 m0, s24
	s_add_i32 s25, s22, 0xa000
	global_load_lds_dwordx4 v62, s[0:1]
	s_mov_b32 m0, s25
	s_mov_b64 s[4:5], 0x180
	global_load_lds_dwordx4 v64, s[0:1]
	s_add_u32 s0, s10, 0x11620080
	s_addc_u32 s1, s11, 0
	s_add_i32 s26, s22, 0xc000
	s_mov_b32 m0, s26
	s_add_i32 s27, s22, 0xe000
	global_load_lds_dwordx4 v62, s[0:1]
	s_mov_b32 m0, s27
	s_add_u32 s8, s10, 0x11e00000
	global_load_lds_dwordx4 v64, s[0:1]
	s_addc_u32 s9, s11, 0
	s_add_i32 s19, s22, 0x10000
	s_mov_b64 s[0:1], 0x100
	v_lshl_add_u64 v[56:57], v[66:67], 0, s[0:1]
	s_mov_b32 m0, s19
	s_add_i32 s13, s22, 0x12000
	s_waitcnt vmcnt(0)
	s_waitcnt vmcnt(0) lgkmcnt(0)
	s_barrier
	global_load_lds_dwordx4 v[56:57], off
	v_lshl_add_u64 v[56:57], v[68:69], 0, s[0:1]
	s_mov_b32 m0, s13
	s_add_i32 s12, s22, 0x14000
	s_add_i32 s14, s22, 0x16000
	global_load_lds_dwordx4 v[56:57], off
	v_lshl_add_u64 v[56:57], v[66:67], 0, s[4:5]
	s_mov_b32 m0, s12
	s_add_u32 s28, s10, 0x11620100
	global_load_lds_dwordx4 v[56:57], off
	v_lshl_add_u64 v[56:57], v[68:69], 0, s[4:5]
	s_mov_b32 m0, s14
	s_addc_u32 s29, s11, 0
	s_add_i32 s15, s22, 0x18000
	global_load_lds_dwordx4 v[56:57], off
	s_mov_b32 m0, s15
	s_add_i32 s16, s22, 0x1a000
	global_load_lds_dwordx4 v62, s[28:29]
	s_mov_b32 m0, s16
	v_and_b32_e32 v57, 48, v58
	global_load_lds_dwordx4 v64, s[28:29]
	s_add_u32 s28, s10, 0x11620180
	s_addc_u32 s29, s11, 0
	s_add_i32 s17, s22, 0x1c000
	s_mov_b32 m0, s17
	s_add_i32 s18, s22, 0x1e000
	global_load_lds_dwordx4 v62, s[28:29]
	s_mov_b32 m0, s18
	v_lshlrev_b32_e32 v58, 2, v58
	global_load_lds_dwordx4 v64, s[28:29]
	v_lshlrev_b32_e32 v56, 6, v59
	v_and_b32_e32 v58, 32, v58
	v_bitop3_b32 v56, v56, v58, v57 bitop3:0x36
	v_and_b32_e32 v57, 0xfffffc00, v71
	v_add3_u32 v65, 0, v56, v57
	v_mov_b32_e32 v71, v65
	ds_read_b128 v[56:59], v71
	ds_read_b128 v[80:83], v71 offset:2048
	s_waitcnt lgkmcnt(0)
	v_mfma_f32_16x16x32_bf16 v[84:87], v[56:59], v[76:79], 0
	ds_read_b128 v[56:59], v71 offset:4096
	ds_read_b128 v[88:91], v71 offset:6144
	ds_read_b128 v[96:99], v71 offset:8192
	ds_read_b128 v[100:103], v71 offset:10240
	s_waitcnt lgkmcnt(0)
	v_mfma_f32_16x16x32_bf16 v[92:95], v[56:59], v[76:79], 0
	v_lshlrev_b32_e32 v56, 9, v104
	ds_read_b128 v[104:107], v71 offset:12288
	v_lshlrev_b32_e32 v57, 9, v108
	ds_read_b128 v[108:111], v71 offset:14336
	ds_read_b128 v[112:115], v71 offset:32768
	ds_read_b128 v[116:119], v71 offset:34816
	ds_read_b128 v[120:123], v71 offset:36864
	ds_read_b128 v[124:127], v71 offset:38912
	ds_read_b128 v[128:131], v71 offset:40960
	ds_read_b128 v[132:135], v71 offset:43008
	ds_read_b128 v[136:139], v71 offset:45056
	ds_read_b128 v[140:143], v71 offset:47104
	v_mfma_f32_16x16x32_bf16 v[80:83], v[80:83], v[76:79], 0
	v_sub_u32_e32 v56, v62, v56
	v_mov_b32_e32 v241, v56
	v_sub_u32_e32 v58, v64, v57
	v_mfma_f32_16x16x32_bf16 v[88:91], v[88:91], v[76:79], 0
	v_mfma_f32_16x16x32_bf16 v[96:99], v[96:99], v[76:79], 0
	v_mfma_f32_16x16x32_bf16 v[100:103], v[100:103], v[76:79], 0
	s_waitcnt lgkmcnt(0)
	v_mfma_f32_16x16x32_bf16 v[104:107], v[104:107], v[76:79], 0
	v_mfma_f32_16x16x32_bf16 v[108:111], v[108:111], v[76:79], 0
	ds_read_b128 v[144:147], v71 offset:15360
	ds_read_b128 v[148:151], v71 offset:13312
	ds_read_b128 v[152:155], v71 offset:11264
	ds_read_b128 v[156:159], v71 offset:9216
	ds_read_b128 v[160:163], v71 offset:7168
	ds_read_b128 v[164:167], v71 offset:5120
	ds_read_b128 v[168:171], v71 offset:3072
	ds_read_b128 v[172:175], v71 offset:1024
	v_mfma_f32_16x16x32_bf16 v[112:115], v[112:115], v[76:79], 0
	v_mfma_f32_16x16x32_bf16 v[116:119], v[116:119], v[76:79], 0
	v_mfma_f32_16x16x32_bf16 v[120:123], v[120:123], v[76:79], 0
	v_mfma_f32_16x16x32_bf16 v[124:127], v[124:127], v[76:79], 0
	v_mfma_f32_16x16x32_bf16 v[128:131], v[128:131], v[76:79], 0
	v_mfma_f32_16x16x32_bf16 v[132:135], v[132:135], v[76:79], 0
	v_mfma_f32_16x16x32_bf16 v[136:139], v[136:139], v[76:79], 0
	v_mfma_f32_16x16x32_bf16 v[76:79], v[140:143], v[76:79], 0
	s_waitcnt lgkmcnt(0)
	v_mfma_f32_16x16x32_bf16 v[84:87], v[172:175], v[72:75], v[84:87]
	v_mfma_f32_16x16x32_bf16 v[80:83], v[168:171], v[72:75], v[80:83]
	v_mfma_f32_16x16x32_bf16 v[92:95], v[164:167], v[72:75], v[92:95]
	v_mfma_f32_16x16x32_bf16 v[88:91], v[160:163], v[72:75], v[88:91]
	v_mfma_f32_16x16x32_bf16 v[96:99], v[156:159], v[72:75], v[96:99]
	v_mfma_f32_16x16x32_bf16 v[100:103], v[152:155], v[72:75], v[100:103]
	ds_read_b128 v[140:143], v71 offset:33792
	ds_read_b128 v[152:155], v71 offset:35840
	ds_read_b128 v[156:159], v71 offset:37888
	ds_read_b128 v[160:163], v71 offset:39936
	v_mfma_f32_16x16x32_bf16 v[104:107], v[148:151], v[72:75], v[104:107]
	ds_read_b128 v[148:151], v71 offset:41984
	ds_read_b128 v[164:167], v71 offset:44032
	ds_read_b128 v[168:171], v71 offset:46080
	ds_read_b128 v[172:175], v71 offset:48128
	v_mfma_f32_16x16x32_bf16 v[108:111], v[144:147], v[72:75], v[108:111]
	s_waitcnt lgkmcnt(0)
	v_mfma_f32_16x16x32_bf16 v[112:115], v[140:143], v[72:75], v[112:115]
	v_mfma_f32_16x16x32_bf16 v[116:119], v[152:155], v[72:75], v[116:119]
	v_mfma_f32_16x16x32_bf16 v[120:123], v[156:159], v[72:75], v[120:123]
	v_mfma_f32_16x16x32_bf16 v[124:127], v[160:163], v[72:75], v[124:127]
	v_mfma_f32_16x16x32_bf16 v[128:131], v[148:151], v[72:75], v[128:131]
	ds_read_b128 v[140:143], v71 offset:30720
	ds_read_b128 v[144:147], v71 offset:28672
	ds_read_b128 v[148:151], v71 offset:26624
	ds_read_b128 v[152:155], v71 offset:24576
	v_mfma_f32_16x16x32_bf16 v[132:135], v[164:167], v[72:75], v[132:135]
	v_mfma_f32_16x16x32_bf16 v[136:139], v[168:171], v[72:75], v[136:139]
	ds_read_b128 v[156:159], v71 offset:22528
	ds_read_b128 v[160:163], v71 offset:20480
	ds_read_b128 v[164:167], v71 offset:18432
	ds_read_b128 v[168:171], v71 offset:16384
	v_mfma_f32_16x16x32_bf16 v[72:75], v[172:175], v[72:75], v[76:79]
	s_waitcnt lgkmcnt(0)
	v_mfma_f32_16x16x32_bf16 v[76:79], v[168:171], v[52:55], v[84:87]
	v_mfma_f32_16x16x32_bf16 v[80:83], v[164:167], v[52:55], v[80:83]
	v_mfma_f32_16x16x32_bf16 v[84:87], v[160:163], v[52:55], v[92:95]
	v_mfma_f32_16x16x32_bf16 v[88:91], v[156:159], v[52:55], v[88:91]
	v_mfma_f32_16x16x32_bf16 v[92:95], v[152:155], v[52:55], v[96:99]
	v_mfma_f32_16x16x32_bf16 v[96:99], v[148:151], v[52:55], v[100:103]
	s_nop 2
	ds_read_b128 v[100:103], v71 offset:49152
	ds_read_b128 v[148:151], v71 offset:51200
	ds_read_b128 v[152:155], v71 offset:53248
	ds_read_b128 v[156:159], v71 offset:55296
	v_mfma_f32_16x16x32_bf16 v[104:107], v[144:147], v[52:55], v[104:107]
	ds_read_b128 v[144:147], v71 offset:57344
	ds_read_b128 v[160:163], v71 offset:59392
	ds_read_b128 v[164:167], v71 offset:61440
	ds_read_b128 v[168:171], v71 offset:63488
	v_mfma_f32_16x16x32_bf16 v[108:111], v[140:143], v[52:55], v[108:111]
	s_waitcnt lgkmcnt(0)
	v_mfma_f32_16x16x32_bf16 v[100:103], v[100:103], v[52:55], v[112:115]
	v_mfma_f32_16x16x32_bf16 v[112:115], v[148:151], v[52:55], v[116:119]
	v_mfma_f32_16x16x32_bf16 v[116:119], v[152:155], v[52:55], v[120:123]
	v_mfma_f32_16x16x32_bf16 v[120:123], v[156:159], v[52:55], v[124:127]
	v_mfma_f32_16x16x32_bf16 v[124:127], v[144:147], v[52:55], v[128:131]
	v_mfma_f32_16x16x32_bf16 v[128:131], v[160:163], v[52:55], v[132:135]
	s_nop 2
	ds_read_b128 v[132:135], v71 offset:31744
	ds_read_b128 v[140:143], v71 offset:29696
	ds_read_b128 v[144:147], v71 offset:27648
	ds_read_b128 v[148:151], v71 offset:25600
	v_mfma_f32_16x16x32_bf16 v[136:139], v[164:167], v[52:55], v[136:139]
	ds_read_b128 v[152:155], v71 offset:23552
	ds_read_b128 v[156:159], v71 offset:21504
	ds_read_b128 v[160:163], v71 offset:19456
	ds_read_b128 v[164:167], v71 offset:17408
	v_mfma_f32_16x16x32_bf16 v[52:55], v[168:171], v[52:55], v[72:75]
	s_waitcnt lgkmcnt(0)
	v_mfma_f32_16x16x32_bf16 v[72:75], v[164:167], v[48:51], v[76:79]
	v_mfma_f32_16x16x32_bf16 v[76:79], v[160:163], v[48:51], v[80:83]
	v_mfma_f32_16x16x32_bf16 v[80:83], v[156:159], v[48:51], v[84:87]
	v_mfma_f32_16x16x32_bf16 v[84:87], v[152:155], v[48:51], v[88:91]
	v_mfma_f32_16x16x32_bf16 v[88:91], v[148:151], v[48:51], v[92:95]
	v_mfma_f32_16x16x32_bf16 v[92:95], v[144:147], v[48:51], v[96:99]
	s_nop 2
	ds_read_b128 v[96:99], v71 offset:50176
	ds_read_b128 v[144:147], v71 offset:52224
	ds_read_b128 v[148:151], v71 offset:54272
	ds_read_b128 v[152:155], v71 offset:56320
	v_mfma_f32_16x16x32_bf16 v[104:107], v[140:143], v[48:51], v[104:107]
	ds_read_b128 v[140:143], v71 offset:58368
	ds_read_b128 v[156:159], v71 offset:60416
	ds_read_b128 v[160:163], v71 offset:62464
	ds_read_b128 v[164:167], v71 offset:64512
	v_mfma_f32_16x16x32_bf16 v[108:111], v[132:135], v[48:51], v[108:111]
	s_waitcnt lgkmcnt(0)
	v_mfma_f32_16x16x32_bf16 v[96:99], v[96:99], v[48:51], v[100:103]
	v_mfma_f32_16x16x32_bf16 v[100:103], v[144:147], v[48:51], v[112:115]
	v_mfma_f32_16x16x32_bf16 v[112:115], v[148:151], v[48:51], v[116:119]
	v_mfma_f32_16x16x32_bf16 v[116:119], v[152:155], v[48:51], v[120:123]
	v_mfma_f32_16x16x32_bf16 v[120:123], v[140:143], v[48:51], v[124:127]
	v_mfma_f32_16x16x32_bf16 v[124:127], v[156:159], v[48:51], v[128:131]
	v_mfma_f32_16x16x32_bf16 v[128:131], v[160:163], v[48:51], v[136:139]
	v_mfma_f32_16x16x32_bf16 v[50:53], v[164:167], v[48:51], v[52:55]
	s_waitcnt vmcnt(0)
	s_waitcnt vmcnt(0)
	s_barrier
	v_add_u32_e32 v48, 0x10000, v65
	v_mov_b32_e32 v49, v48
	ds_read_b128 v[132:135], v49
	ds_read_b128 v[136:139], v49 offset:2048
	s_waitcnt lgkmcnt(0)
	v_mfma_f32_16x16x32_bf16 v[72:75], v[132:135], v[44:47], v[72:75]
	ds_read_b128 v[132:135], v49 offset:4096
	v_mfma_f32_16x16x32_bf16 v[76:79], v[136:139], v[44:47], v[76:79]
	ds_read_b128 v[136:139], v49 offset:6144
	s_waitcnt lgkmcnt(0)
	v_mfma_f32_16x16x32_bf16 v[80:83], v[132:135], v[44:47], v[80:83]
	ds_read_b128 v[132:135], v49 offset:8192
	v_mfma_f32_16x16x32_bf16 v[84:87], v[136:139], v[44:47], v[84:87]
	ds_read_b128 v[136:139], v49 offset:10240
	s_waitcnt lgkmcnt(0)
	v_mfma_f32_16x16x32_bf16 v[88:91], v[132:135], v[44:47], v[88:91]
	ds_read_b128 v[132:135], v49 offset:12288
	ds_read_b128 v[140:143], v49 offset:14336
	v_mfma_f32_16x16x32_bf16 v[92:95], v[136:139], v[44:47], v[92:95]
	ds_read_b128 v[136:139], v49 offset:32768
	ds_read_b128 v[144:147], v49 offset:34816
	ds_read_b128 v[148:151], v49 offset:36864
	ds_read_b128 v[152:155], v49 offset:38912
	s_waitcnt lgkmcnt(0)
	v_mfma_f32_16x16x32_bf16 v[104:107], v[132:135], v[44:47], v[104:107]
	ds_read_b128 v[132:135], v49 offset:40960
	ds_read_b128 v[156:159], v49 offset:43008
	ds_read_b128 v[160:163], v49 offset:45056
	ds_read_b128 v[164:167], v49 offset:47104
	v_mfma_f32_16x16x32_bf16 v[108:111], v[140:143], v[44:47], v[108:111]
	s_add_u32 s100, s10, 0x11600200
	s_addc_u32 s101, s11, 0
	s_mov_b32 m0, s22
	s_nop 0
	global_load_lds_dwordx4 v240, s[100:101]
	v_mfma_f32_16x16x32_bf16 v[96:99], v[136:139], v[44:47], v[96:99]
	v_mfma_f32_16x16x32_bf16 v[100:103], v[144:147], v[44:47], v[100:103]
	v_mfma_f32_16x16x32_bf16 v[112:115], v[148:151], v[44:47], v[112:115]
	v_mfma_f32_16x16x32_bf16 v[116:119], v[152:155], v[44:47], v[116:119]
	s_waitcnt lgkmcnt(0)
	v_mfma_f32_16x16x32_bf16 v[120:123], v[132:135], v[44:47], v[120:123]
	ds_read_b128 v[132:135], v49 offset:15360
	ds_read_b128 v[136:139], v49 offset:13312
	ds_read_b128 v[140:143], v49 offset:11264
	ds_read_b128 v[144:147], v49 offset:9216
	v_mfma_f32_16x16x32_bf16 v[124:127], v[156:159], v[44:47], v[124:127]
	v_mfma_f32_16x16x32_bf16 v[128:131], v[160:163], v[44:47], v[128:131]
	ds_read_b128 v[148:151], v49 offset:7168
	ds_read_b128 v[152:155], v49 offset:5120
	ds_read_b128 v[156:159], v49 offset:3072
	ds_read_b128 v[160:163], v49 offset:1024
	v_mfma_f32_16x16x32_bf16 v[44:47], v[164:167], v[44:47], v[50:53]
	s_add_u32 s100, s10, 0x11610200
	s_addc_u32 s101, s11, 0
	s_mov_b32 m0, s21
	s_nop 0
	global_load_lds_dwordx4 v240, s[100:101]
	s_waitcnt lgkmcnt(0)
	v_mfma_f32_16x16x32_bf16 v[50:53], v[160:163], v[40:43], v[72:75]
	v_mfma_f32_16x16x32_bf16 v[72:75], v[156:159], v[40:43], v[76:79]
	v_mfma_f32_16x16x32_bf16 v[76:79], v[152:155], v[40:43], v[80:83]
	v_mfma_f32_16x16x32_bf16 v[80:83], v[148:151], v[40:43], v[84:87]
	v_mfma_f32_16x16x32_bf16 v[84:87], v[144:147], v[40:43], v[88:91]
	v_mfma_f32_16x16x32_bf16 v[88:91], v[140:143], v[40:43], v[92:95]
	s_nop 2
	ds_read_b128 v[92:95], v49 offset:33792
	ds_read_b128 v[140:143], v49 offset:35840
	ds_read_b128 v[144:147], v49 offset:37888
	ds_read_b128 v[148:151], v49 offset:39936
	v_mfma_f32_16x16x32_bf16 v[104:107], v[136:139], v[40:43], v[104:107]
	ds_read_b128 v[136:139], v49 offset:41984
	ds_read_b128 v[152:155], v49 offset:44032
	ds_read_b128 v[156:159], v49 offset:46080
	ds_read_b128 v[160:163], v49 offset:48128
	v_mfma_f32_16x16x32_bf16 v[108:111], v[132:135], v[40:43], v[108:111]
	s_add_u32 s100, s10, 0x11600280
	s_addc_u32 s101, s11, 0
	s_mov_b32 m0, s20
	s_nop 0
	global_load_lds_dwordx4 v240, s[100:101]
	s_waitcnt lgkmcnt(0)
	v_mfma_f32_16x16x32_bf16 v[92:95], v[92:95], v[40:43], v[96:99]
	v_mfma_f32_16x16x32_bf16 v[96:99], v[140:143], v[40:43], v[100:103]
	v_mfma_f32_16x16x32_bf16 v[100:103], v[144:147], v[40:43], v[112:115]
	v_mfma_f32_16x16x32_bf16 v[112:115], v[148:151], v[40:43], v[116:119]
	v_mfma_f32_16x16x32_bf16 v[116:119], v[136:139], v[40:43], v[120:123]
	v_mfma_f32_16x16x32_bf16 v[120:123], v[152:155], v[40:43], v[124:127]
	s_nop 2
	ds_read_b128 v[124:127], v49 offset:30720
	ds_read_b128 v[132:135], v49 offset:28672
	ds_read_b128 v[136:139], v49 offset:26624
	ds_read_b128 v[140:143], v49 offset:24576
	v_mfma_f32_16x16x32_bf16 v[128:131], v[156:159], v[40:43], v[128:131]
	ds_read_b128 v[144:147], v49 offset:22528
	ds_read_b128 v[148:151], v49 offset:20480
	ds_read_b128 v[152:155], v49 offset:18432
	ds_read_b128 v[156:159], v49 offset:16384
	v_mfma_f32_16x16x32_bf16 v[40:43], v[160:163], v[40:43], v[44:47]
	s_add_u32 s100, s10, 0x11610280
	s_addc_u32 s101, s11, 0
	s_mov_b32 m0, s23
	s_nop 0
	global_load_lds_dwordx4 v240, s[100:101]
	s_waitcnt lgkmcnt(0)
	v_mfma_f32_16x16x32_bf16 v[44:47], v[156:159], v[36:39], v[50:53]
	v_mfma_f32_16x16x32_bf16 v[50:53], v[152:155], v[36:39], v[72:75]
	v_mfma_f32_16x16x32_bf16 v[72:75], v[148:151], v[36:39], v[76:79]
	v_mfma_f32_16x16x32_bf16 v[76:79], v[144:147], v[36:39], v[80:83]
	v_mfma_f32_16x16x32_bf16 v[80:83], v[140:143], v[36:39], v[84:87]
	v_mfma_f32_16x16x32_bf16 v[84:87], v[136:139], v[36:39], v[88:91]
	s_nop 2
	ds_read_b128 v[88:91], v49 offset:49152
	ds_read_b128 v[136:139], v49 offset:51200
	ds_read_b128 v[140:143], v49 offset:53248
	ds_read_b128 v[144:147], v49 offset:55296
	v_mfma_f32_16x16x32_bf16 v[104:107], v[132:135], v[36:39], v[104:107]
	ds_read_b128 v[132:135], v49 offset:57344
	ds_read_b128 v[148:151], v49 offset:59392
	ds_read_b128 v[152:155], v49 offset:61440
	ds_read_b128 v[156:159], v49 offset:63488
	v_mfma_f32_16x16x32_bf16 v[108:111], v[124:127], v[36:39], v[108:111]
	s_add_u32 s100, s10, 0x11620200
	s_addc_u32 s101, s11, 0
	s_mov_b32 m0, s24
	s_nop 0
	global_load_lds_dwordx4 v240, s[100:101]
	s_waitcnt lgkmcnt(0)
	v_mfma_f32_16x16x32_bf16 v[88:91], v[88:91], v[36:39], v[92:95]
	v_mfma_f32_16x16x32_bf16 v[92:95], v[136:139], v[36:39], v[96:99]
	v_mfma_f32_16x16x32_bf16 v[96:99], v[140:143], v[36:39], v[100:103]
	v_mfma_f32_16x16x32_bf16 v[100:103], v[144:147], v[36:39], v[112:115]
	v_mfma_f32_16x16x32_bf16 v[112:115], v[132:135], v[36:39], v[116:119]
	v_mfma_f32_16x16x32_bf16 v[116:119], v[148:151], v[36:39], v[120:123]
	s_nop 2
	ds_read_b128 v[120:123], v49 offset:31744
	ds_read_b128 v[124:127], v49 offset:29696
	ds_read_b128 v[132:135], v49 offset:27648
	ds_read_b128 v[136:139], v49 offset:25600
	v_mfma_f32_16x16x32_bf16 v[128:131], v[152:155], v[36:39], v[128:131]
	ds_read_b128 v[140:143], v49 offset:23552
	ds_read_b128 v[144:147], v49 offset:21504
	ds_read_b128 v[148:151], v49 offset:19456
	ds_read_b128 v[152:155], v49 offset:17408
	v_mfma_f32_16x16x32_bf16 v[36:39], v[156:159], v[36:39], v[40:43]
	s_add_u32 s100, s10, 0x11630200
	s_addc_u32 s101, s11, 0
	s_mov_b32 m0, s25
	s_nop 0
	global_load_lds_dwordx4 v240, s[100:101]
	s_waitcnt lgkmcnt(0)
	v_mfma_f32_16x16x32_bf16 v[40:43], v[152:155], v[32:35], v[44:47]
	v_mfma_f32_16x16x32_bf16 v[44:47], v[148:151], v[32:35], v[50:53]
	v_mfma_f32_16x16x32_bf16 v[50:53], v[144:147], v[32:35], v[72:75]
	v_mfma_f32_16x16x32_bf16 v[72:75], v[140:143], v[32:35], v[76:79]
	v_mfma_f32_16x16x32_bf16 v[76:79], v[136:139], v[32:35], v[80:83]
	v_mfma_f32_16x16x32_bf16 v[80:83], v[132:135], v[32:35], v[84:87]
	s_nop 2
	ds_read_b128 v[84:87], v49 offset:50176
	ds_read_b128 v[132:135], v49 offset:52224
	ds_read_b128 v[136:139], v49 offset:54272
	ds_read_b128 v[140:143], v49 offset:56320
	v_mfma_f32_16x16x32_bf16 v[104:107], v[124:127], v[32:35], v[104:107]
	ds_read_b128 v[124:127], v49 offset:58368
	ds_read_b128 v[144:147], v49 offset:60416
	ds_read_b128 v[148:151], v49 offset:62464
	ds_read_b128 v[152:155], v49 offset:64512
	v_mfma_f32_16x16x32_bf16 v[108:111], v[120:123], v[32:35], v[108:111]
	s_add_u32 s100, s10, 0x11620280
	s_addc_u32 s101, s11, 0
	s_mov_b32 m0, s26
	s_nop 0
	global_load_lds_dwordx4 v240, s[100:101]
	s_waitcnt lgkmcnt(0)
	v_mfma_f32_16x16x32_bf16 v[84:87], v[84:87], v[32:35], v[88:91]
	v_mfma_f32_16x16x32_bf16 v[88:91], v[132:135], v[32:35], v[92:95]
	v_mfma_f32_16x16x32_bf16 v[92:95], v[136:139], v[32:35], v[96:99]
	v_mfma_f32_16x16x32_bf16 v[96:99], v[140:143], v[32:35], v[100:103]
	v_mfma_f32_16x16x32_bf16 v[100:103], v[124:127], v[32:35], v[112:115]
	v_mfma_f32_16x16x32_bf16 v[112:115], v[144:147], v[32:35], v[116:119]
	v_mfma_f32_16x16x32_bf16 v[116:119], v[148:151], v[32:35], v[128:131]
	v_mfma_f32_16x16x32_bf16 v[32:35], v[152:155], v[32:35], v[36:39]
	s_add_u32 s100, s10, 0x11630280
	s_addc_u32 s101, s11, 0
	s_mov_b32 m0, s27
	s_nop 0
	global_load_lds_dwordx4 v240, s[100:101]
	s_nop 0
	s_waitcnt vmcnt(0)
	s_waitcnt vmcnt(0)
	s_barrier
	v_mov_b32_e32 v49, v65
	ds_read_b128 v[36:39], v49
	ds_read_b128 v[66:69], v49 offset:2048
	s_waitcnt lgkmcnt(0)
	v_mfma_f32_16x16x32_bf16 v[36:39], v[36:39], v[28:31], v[40:43]
	s_nop 2
	ds_read_b128 v[40:43], v49 offset:4096
	v_mfma_f32_16x16x32_bf16 v[44:47], v[66:69], v[28:31], v[44:47]
	ds_read_b128 v[66:69], v49 offset:6144
	s_waitcnt lgkmcnt(0)
	v_mfma_f32_16x16x32_bf16 v[40:43], v[40:43], v[28:31], v[50:53]
	s_nop 2
	ds_read_b128 v[50:53], v49 offset:8192
	v_mfma_f32_16x16x32_bf16 v[66:69], v[66:69], v[28:31], v[72:75]
	s_nop 2
	ds_read_b128 v[72:75], v49 offset:10240
	s_waitcnt lgkmcnt(0)
	v_mfma_f32_16x16x32_bf16 v[50:53], v[50:53], v[28:31], v[76:79]
	s_nop 2
	ds_read_b128 v[76:79], v49 offset:12288
	ds_read_b128 v[120:123], v49 offset:14336
	v_mfma_f32_16x16x32_bf16 v[72:75], v[72:75], v[28:31], v[80:83]
	s_nop 2
	ds_read_b128 v[80:83], v49 offset:32768
	ds_read_b128 v[124:127], v49 offset:34816
	ds_read_b128 v[128:131], v49 offset:36864
	ds_read_b128 v[132:135], v49 offset:38912
	s_waitcnt lgkmcnt(0)
	v_mfma_f32_16x16x32_bf16 v[76:79], v[76:79], v[28:31], v[104:107]
	s_nop 2
	ds_read_b128 v[104:107], v49 offset:40960
	ds_read_b128 v[136:139], v49 offset:43008
	ds_read_b128 v[140:143], v49 offset:45056
	ds_read_b128 v[144:147], v49 offset:47104
	v_mfma_f32_16x16x32_bf16 v[108:111], v[120:123], v[28:31], v[108:111]
	s_add_u32 s100, s10, 0x11600300
	s_addc_u32 s101, s11, 0
	s_mov_b32 m0, s19
	s_nop 0
	global_load_lds_dwordx4 v240, s[100:101]
	v_mfma_f32_16x16x32_bf16 v[80:83], v[80:83], v[28:31], v[84:87]
	v_mfma_f32_16x16x32_bf16 v[84:87], v[124:127], v[28:31], v[88:91]
	v_mfma_f32_16x16x32_bf16 v[88:91], v[128:131], v[28:31], v[92:95]
	v_mfma_f32_16x16x32_bf16 v[92:95], v[132:135], v[28:31], v[96:99]
	s_waitcnt lgkmcnt(0)
	v_mfma_f32_16x16x32_bf16 v[96:99], v[104:107], v[28:31], v[100:103]
	v_mfma_f32_16x16x32_bf16 v[100:103], v[136:139], v[28:31], v[112:115]
	ds_read_b128 v[104:107], v49 offset:15360
	s_nop 1
	ds_read_b128 v[112:115], v49 offset:13312
	ds_read_b128 v[120:123], v49 offset:11264
	ds_read_b128 v[124:127], v49 offset:9216
	v_mfma_f32_16x16x32_bf16 v[116:119], v[140:143], v[28:31], v[116:119]
	ds_read_b128 v[128:131], v49 offset:7168
	ds_read_b128 v[132:135], v49 offset:5120
	ds_read_b128 v[136:139], v49 offset:3072
	ds_read_b128 v[140:143], v49 offset:1024
	v_mfma_f32_16x16x32_bf16 v[28:31], v[144:147], v[28:31], v[32:35]
	s_add_u32 s100, s10, 0x11610300
	s_addc_u32 s101, s11, 0
	s_mov_b32 m0, s13
	s_nop 0
	global_load_lds_dwordx4 v240, s[100:101]
	s_waitcnt lgkmcnt(0)
	v_mfma_f32_16x16x32_bf16 v[32:35], v[140:143], v[24:27], v[36:39]
	v_mfma_f32_16x16x32_bf16 v[36:39], v[136:139], v[24:27], v[44:47]
	v_mfma_f32_16x16x32_bf16 v[40:43], v[132:135], v[24:27], v[40:43]
	v_mfma_f32_16x16x32_bf16 v[44:47], v[128:131], v[24:27], v[66:69]
	v_mfma_f32_16x16x32_bf16 v[50:53], v[124:127], v[24:27], v[50:53]
	v_mfma_f32_16x16x32_bf16 v[66:69], v[120:123], v[24:27], v[72:75]
	s_nop 2
	ds_read_b128 v[72:75], v49 offset:33792
	ds_read_b128 v[120:123], v49 offset:35840
	ds_read_b128 v[124:127], v49 offset:37888
	ds_read_b128 v[128:131], v49 offset:39936
	v_mfma_f32_16x16x32_bf16 v[76:79], v[112:115], v[24:27], v[76:79]
	ds_read_b128 v[112:115], v49 offset:41984
	ds_read_b128 v[132:135], v49 offset:44032
	ds_read_b128 v[136:139], v49 offset:46080
	ds_read_b128 v[140:143], v49 offset:48128
	v_mfma_f32_16x16x32_bf16 v[104:107], v[104:107], v[24:27], v[108:111]
	s_add_u32 s100, s10, 0x11600380
	s_addc_u32 s101, s11, 0
	s_mov_b32 m0, s12
	s_nop 0
	global_load_lds_dwordx4 v240, s[100:101]
	s_waitcnt lgkmcnt(0)
	v_mfma_f32_16x16x32_bf16 v[72:75], v[72:75], v[24:27], v[80:83]
	v_mfma_f32_16x16x32_bf16 v[80:83], v[120:123], v[24:27], v[84:87]
	v_mfma_f32_16x16x32_bf16 v[84:87], v[124:127], v[24:27], v[88:91]
	v_mfma_f32_16x16x32_bf16 v[88:91], v[128:131], v[24:27], v[92:95]
	v_mfma_f32_16x16x32_bf16 v[92:95], v[112:115], v[24:27], v[96:99]
	v_mfma_f32_16x16x32_bf16 v[96:99], v[132:135], v[24:27], v[100:103]
	s_nop 2
	ds_read_b128 v[100:103], v49 offset:30720
	ds_read_b128 v[108:111], v49 offset:28672
	ds_read_b128 v[112:115], v49 offset:26624
	ds_read_b128 v[120:123], v49 offset:24576
	v_mfma_f32_16x16x32_bf16 v[116:119], v[136:139], v[24:27], v[116:119]
	ds_read_b128 v[124:127], v49 offset:22528
	ds_read_b128 v[128:131], v49 offset:20480
	ds_read_b128 v[132:135], v49 offset:18432
	ds_read_b128 v[136:139], v49 offset:16384
	v_mfma_f32_16x16x32_bf16 v[24:27], v[140:143], v[24:27], v[28:31]
	s_add_u32 s100, s10, 0x11610380
	s_addc_u32 s101, s11, 0
	s_mov_b32 m0, s14
	s_nop 0
	global_load_lds_dwordx4 v240, s[100:101]
	s_waitcnt lgkmcnt(0)
	v_mfma_f32_16x16x32_bf16 v[28:31], v[136:139], v[20:23], v[32:35]
	v_mfma_f32_16x16x32_bf16 v[32:35], v[132:135], v[20:23], v[36:39]
	v_mfma_f32_16x16x32_bf16 v[36:39], v[128:131], v[20:23], v[40:43]
	v_mfma_f32_16x16x32_bf16 v[40:43], v[124:127], v[20:23], v[44:47]
	v_mfma_f32_16x16x32_bf16 v[44:47], v[120:123], v[20:23], v[50:53]
	v_mfma_f32_16x16x32_bf16 v[50:53], v[112:115], v[20:23], v[66:69]
	s_nop 2
	ds_read_b128 v[66:69], v49 offset:49152
	ds_read_b128 v[112:115], v49 offset:51200
	ds_read_b128 v[120:123], v49 offset:53248
	ds_read_b128 v[124:127], v49 offset:55296
	v_mfma_f32_16x16x32_bf16 v[76:79], v[108:111], v[20:23], v[76:79]
	ds_read_b128 v[108:111], v49 offset:57344
	ds_read_b128 v[128:131], v49 offset:59392
	ds_read_b128 v[132:135], v49 offset:61440
	ds_read_b128 v[136:139], v49 offset:63488
	v_mfma_f32_16x16x32_bf16 v[100:103], v[100:103], v[20:23], v[104:107]
	s_add_u32 s100, s10, 0x11620300
	s_addc_u32 s101, s11, 0
	s_mov_b32 m0, s15
	s_nop 0
	global_load_lds_dwordx4 v240, s[100:101]
	s_waitcnt lgkmcnt(0)
	v_mfma_f32_16x16x32_bf16 v[66:69], v[66:69], v[20:23], v[72:75]
	v_mfma_f32_16x16x32_bf16 v[72:75], v[112:115], v[20:23], v[80:83]
	v_mfma_f32_16x16x32_bf16 v[80:83], v[120:123], v[20:23], v[84:87]
	v_mfma_f32_16x16x32_bf16 v[84:87], v[124:127], v[20:23], v[88:91]
	v_mfma_f32_16x16x32_bf16 v[88:91], v[108:111], v[20:23], v[92:95]
	v_mfma_f32_16x16x32_bf16 v[92:95], v[128:131], v[20:23], v[96:99]
	s_nop 2
	ds_read_b128 v[96:99], v49 offset:31744
	ds_read_b128 v[104:107], v49 offset:29696
	ds_read_b128 v[108:111], v49 offset:27648
	ds_read_b128 v[112:115], v49 offset:25600
	v_mfma_f32_16x16x32_bf16 v[116:119], v[132:135], v[20:23], v[116:119]
	ds_read_b128 v[120:123], v49 offset:23552
	ds_read_b128 v[124:127], v49 offset:21504
	ds_read_b128 v[128:131], v49 offset:19456
	ds_read_b128 v[132:135], v49 offset:17408
	v_mfma_f32_16x16x32_bf16 v[20:23], v[136:139], v[20:23], v[24:27]
	s_add_u32 s100, s10, 0x11630300
	s_addc_u32 s101, s11, 0
	s_mov_b32 m0, s16
	s_nop 0
	global_load_lds_dwordx4 v240, s[100:101]
	s_waitcnt lgkmcnt(0)
	v_mfma_f32_16x16x32_bf16 v[24:27], v[132:135], v[16:19], v[28:31]
	v_mfma_f32_16x16x32_bf16 v[28:31], v[128:131], v[16:19], v[32:35]
	v_mfma_f32_16x16x32_bf16 v[32:35], v[124:127], v[16:19], v[36:39]
	v_mfma_f32_16x16x32_bf16 v[36:39], v[120:123], v[16:19], v[40:43]
	v_mfma_f32_16x16x32_bf16 v[40:43], v[112:115], v[16:19], v[44:47]
	v_mfma_f32_16x16x32_bf16 v[50:53], v[108:111], v[16:19], v[50:53]
	s_nop 1
	ds_read_b128 v[44:47], v49 offset:50176
	ds_read_b128 v[108:111], v49 offset:52224
	ds_read_b128 v[112:115], v49 offset:54272
	ds_read_b128 v[120:123], v49 offset:56320
	v_mfma_f32_16x16x32_bf16 v[76:79], v[104:107], v[16:19], v[76:79]
	ds_read_b128 v[104:107], v49 offset:58368
	ds_read_b128 v[124:127], v49 offset:60416
	ds_read_b128 v[128:131], v49 offset:62464
	ds_read_b128 v[132:135], v49 offset:64512
	v_mfma_f32_16x16x32_bf16 v[96:99], v[96:99], v[16:19], v[100:103]
	s_add_u32 s100, s10, 0x11620380
	s_addc_u32 s101, s11, 0
	s_mov_b32 m0, s17
	s_nop 0
	global_load_lds_dwordx4 v240, s[100:101]
	s_waitcnt lgkmcnt(0)
	v_mfma_f32_16x16x32_bf16 v[66:69], v[44:47], v[16:19], v[66:69]
	v_mfma_f32_16x16x32_bf16 v[72:75], v[108:111], v[16:19], v[72:75]
	v_mfma_f32_16x16x32_bf16 v[80:83], v[112:115], v[16:19], v[80:83]
	v_mfma_f32_16x16x32_bf16 v[84:87], v[120:123], v[16:19], v[84:87]
	v_mfma_f32_16x16x32_bf16 v[88:91], v[104:107], v[16:19], v[88:91]
	v_mfma_f32_16x16x32_bf16 v[92:95], v[124:127], v[16:19], v[92:95]
	v_mfma_f32_16x16x32_bf16 v[100:103], v[128:131], v[16:19], v[116:119]
	v_mfma_f32_16x16x32_bf16 v[16:19], v[132:135], v[16:19], v[20:23]
	s_add_u32 s100, s10, 0x11630380
	s_addc_u32 s101, s11, 0
	s_mov_b32 m0, s18
	s_nop 0
	global_load_lds_dwordx4 v240, s[100:101]
	s_waitcnt vmcnt(0)
	s_waitcnt vmcnt(0)
	s_barrier
	v_mov_b32_e32 v49, v48
	ds_read_b128 v[20:23], v49
	ds_read_b128 v[104:107], v49 offset:2048
	s_waitcnt lgkmcnt(0)
	v_mfma_f32_16x16x32_bf16 v[20:23], v[20:23], v[12:15], v[24:27]
	s_nop 2
	ds_read_b128 v[24:27], v49 offset:4096
	v_mfma_f32_16x16x32_bf16 v[28:31], v[104:107], v[12:15], v[28:31]
	ds_read_b128 v[104:107], v49 offset:6144
	s_waitcnt lgkmcnt(0)
	v_mfma_f32_16x16x32_bf16 v[24:27], v[24:27], v[12:15], v[32:35]
	s_nop 2
	ds_read_b128 v[32:35], v49 offset:8192
	v_mfma_f32_16x16x32_bf16 v[36:39], v[104:107], v[12:15], v[36:39]
	ds_read_b128 v[104:107], v49 offset:10240
	s_waitcnt lgkmcnt(0)
	v_mfma_f32_16x16x32_bf16 v[32:35], v[32:35], v[12:15], v[40:43]
	s_nop 2
	ds_read_b128 v[40:43], v49 offset:12288
	ds_read_b128 v[108:111], v49 offset:14336
	v_mfma_f32_16x16x32_bf16 v[50:53], v[104:107], v[12:15], v[50:53]
	ds_read_b128 v[104:107], v49 offset:32768
	ds_read_b128 v[112:115], v49 offset:34816
	ds_read_b128 v[116:119], v49 offset:36864
	ds_read_b128 v[120:123], v49 offset:38912
	s_waitcnt lgkmcnt(0)
	v_mfma_f32_16x16x32_bf16 v[40:43], v[40:43], v[12:15], v[76:79]
	s_nop 2
	ds_read_b128 v[76:79], v49 offset:40960
	ds_read_b128 v[124:127], v49 offset:43008
	ds_read_b128 v[128:131], v49 offset:45056
	ds_read_b128 v[132:135], v49 offset:47104
	v_mfma_f32_16x16x32_bf16 v[96:99], v[108:111], v[12:15], v[96:99]
	s_add_u32 s100, s10, 0x11e00000
	s_addc_u32 s101, s11, 0
	s_mov_b32 m0, s22
	s_nop 0
	global_load_lds_dwordx4 v241, s[100:101]
	v_mfma_f32_16x16x32_bf16 v[66:69], v[104:107], v[12:15], v[66:69]
	v_mfma_f32_16x16x32_bf16 v[72:75], v[112:115], v[12:15], v[72:75]
	v_mfma_f32_16x16x32_bf16 v[80:83], v[116:119], v[12:15], v[80:83]
	v_mfma_f32_16x16x32_bf16 v[84:87], v[120:123], v[12:15], v[84:87]
	s_waitcnt lgkmcnt(0)
	v_mfma_f32_16x16x32_bf16 v[76:79], v[76:79], v[12:15], v[88:91]
	v_mfma_f32_16x16x32_bf16 v[88:91], v[124:127], v[12:15], v[92:95]
	s_nop 2
	ds_read_b128 v[92:95], v49 offset:15360
	ds_read_b128 v[104:107], v49 offset:13312
	ds_read_b128 v[108:111], v49 offset:11264
	ds_read_b128 v[112:115], v49 offset:9216
	v_mfma_f32_16x16x32_bf16 v[100:103], v[128:131], v[12:15], v[100:103]
	ds_read_b128 v[116:119], v49 offset:7168
	ds_read_b128 v[120:123], v49 offset:5120
	ds_read_b128 v[124:127], v49 offset:3072
	ds_read_b128 v[128:131], v49 offset:1024
	v_mfma_f32_16x16x32_bf16 v[12:15], v[132:135], v[12:15], v[16:19]
	s_add_u32 s100, s10, 0x11e08000
	s_addc_u32 s101, s11, 0
	s_mov_b32 m0, s21
	s_nop 0
	global_load_lds_dwordx4 v241, s[100:101]
	s_waitcnt lgkmcnt(0)
	v_mfma_f32_16x16x32_bf16 v[16:19], v[128:131], v[8:11], v[20:23]
	v_mfma_f32_16x16x32_bf16 v[20:23], v[124:127], v[8:11], v[28:31]
	v_mfma_f32_16x16x32_bf16 v[24:27], v[120:123], v[8:11], v[24:27]
	v_mfma_f32_16x16x32_bf16 v[28:31], v[116:119], v[8:11], v[36:39]
	v_mfma_f32_16x16x32_bf16 v[32:35], v[112:115], v[8:11], v[32:35]
	v_mfma_f32_16x16x32_bf16 v[36:39], v[108:111], v[8:11], v[50:53]
	s_nop 2
	ds_read_b128 v[50:53], v49 offset:33792
	ds_read_b128 v[108:111], v49 offset:35840
	ds_read_b128 v[112:115], v49 offset:37888
	ds_read_b128 v[116:119], v49 offset:39936
	v_mfma_f32_16x16x32_bf16 v[40:43], v[104:107], v[8:11], v[40:43]
	ds_read_b128 v[104:107], v49 offset:41984
	ds_read_b128 v[120:123], v49 offset:44032
	ds_read_b128 v[124:127], v49 offset:46080
	ds_read_b128 v[128:131], v49 offset:48128
	v_mfma_f32_16x16x32_bf16 v[92:95], v[92:95], v[8:11], v[96:99]
	s_add_u32 s100, s10, 0x11e00080
	s_addc_u32 s101, s11, 0
	s_mov_b32 m0, s20
	s_nop 0
	global_load_lds_dwordx4 v241, s[100:101]
	s_waitcnt lgkmcnt(0)
	v_mfma_f32_16x16x32_bf16 v[50:53], v[50:53], v[8:11], v[66:69]
	v_mfma_f32_16x16x32_bf16 v[66:69], v[108:111], v[8:11], v[72:75]
	v_mfma_f32_16x16x32_bf16 v[72:75], v[112:115], v[8:11], v[80:83]
	v_mfma_f32_16x16x32_bf16 v[80:83], v[116:119], v[8:11], v[84:87]
	v_mfma_f32_16x16x32_bf16 v[76:79], v[104:107], v[8:11], v[76:79]
	v_mfma_f32_16x16x32_bf16 v[84:87], v[120:123], v[8:11], v[88:91]
	s_nop 2
	ds_read_b128 v[88:91], v49 offset:30720
	ds_read_b128 v[96:99], v49 offset:28672
	ds_read_b128 v[104:107], v49 offset:26624
	ds_read_b128 v[108:111], v49 offset:24576
	v_mfma_f32_16x16x32_bf16 v[100:103], v[124:127], v[8:11], v[100:103]
	ds_read_b128 v[112:115], v49 offset:22528
	ds_read_b128 v[116:119], v49 offset:20480
	ds_read_b128 v[120:123], v49 offset:18432
	ds_read_b128 v[124:127], v49 offset:16384
	v_mfma_f32_16x16x32_bf16 v[8:11], v[128:131], v[8:11], v[12:15]
	s_add_u32 s100, s10, 0x11e08080
	s_addc_u32 s101, s11, 0
	s_mov_b32 m0, s23
	s_nop 0
	global_load_lds_dwordx4 v241, s[100:101]
	s_waitcnt lgkmcnt(0)
	v_mfma_f32_16x16x32_bf16 v[12:15], v[124:127], v[4:7], v[16:19]
	v_mfma_f32_16x16x32_bf16 v[16:19], v[120:123], v[4:7], v[20:23]
	v_mfma_f32_16x16x32_bf16 v[20:23], v[116:119], v[4:7], v[24:27]
	v_mfma_f32_16x16x32_bf16 v[24:27], v[112:115], v[4:7], v[28:31]
	v_mfma_f32_16x16x32_bf16 v[28:31], v[108:111], v[4:7], v[32:35]
	v_mfma_f32_16x16x32_bf16 v[32:35], v[104:107], v[4:7], v[36:39]
	s_nop 2
	ds_read_b128 v[36:39], v49 offset:49152
	ds_read_b128 v[104:107], v49 offset:51200
	ds_read_b128 v[108:111], v49 offset:53248
	ds_read_b128 v[112:115], v49 offset:55296
	v_mfma_f32_16x16x32_bf16 v[96:99], v[96:99], v[4:7], v[40:43]
	s_nop 2
	ds_read_b128 v[40:43], v49 offset:57344
	ds_read_b128 v[116:119], v49 offset:59392
	ds_read_b128 v[120:123], v49 offset:61440
	ds_read_b128 v[124:127], v49 offset:63488
	v_mfma_f32_16x16x32_bf16 v[88:91], v[88:91], v[4:7], v[92:95]
	s_add_u32 s100, s10, 0x11e10000
	s_addc_u32 s101, s11, 0
	s_mov_b32 m0, s24
	s_nop 0
	global_load_lds_dwordx4 v241, s[100:101]
	s_waitcnt lgkmcnt(0)
	v_mfma_f32_16x16x32_bf16 v[50:53], v[36:39], v[4:7], v[50:53]
	v_mfma_f32_16x16x32_bf16 v[66:69], v[104:107], v[4:7], v[66:69]
	v_mfma_f32_16x16x32_bf16 v[72:75], v[108:111], v[4:7], v[72:75]
	v_mfma_f32_16x16x32_bf16 v[80:83], v[112:115], v[4:7], v[80:83]
	v_mfma_f32_16x16x32_bf16 v[76:79], v[40:43], v[4:7], v[76:79]
	ds_read_b128 v[92:95], v49 offset:31744
	ds_read_b128 v[36:39], v49 offset:29696
	ds_read_b128 v[40:43], v49 offset:27648
	ds_read_b128 v[104:107], v49 offset:25600
	v_mfma_f32_16x16x32_bf16 v[84:87], v[116:119], v[4:7], v[84:87]
	v_mfma_f32_16x16x32_bf16 v[100:103], v[120:123], v[4:7], v[100:103]
	ds_read_b128 v[108:111], v49 offset:23552
	ds_read_b128 v[112:115], v49 offset:21504
	ds_read_b128 v[116:119], v49 offset:19456
	ds_read_b128 v[120:123], v49 offset:17408
	v_mfma_f32_16x16x32_bf16 v[124:127], v[124:127], v[4:7], v[8:11]
	s_add_u32 s100, s10, 0x11e18000
	s_addc_u32 s101, s11, 0
	s_mov_b32 m0, s25
	s_nop 0
	global_load_lds_dwordx4 v241, s[100:101]
	s_waitcnt lgkmcnt(0)
	v_mfma_f32_16x16x32_bf16 v[120:123], v[120:123], v[0:3], v[12:15]
	v_mfma_f32_16x16x32_bf16 v[116:119], v[116:119], v[0:3], v[16:19]
	ds_read_b128 v[4:7], v49 offset:50176
	ds_read_b128 v[8:11], v49 offset:52224
	ds_read_b128 v[12:15], v49 offset:54272
	ds_read_b128 v[16:19], v49 offset:56320
	v_mfma_f32_16x16x32_bf16 v[36:39], v[36:39], v[0:3], v[96:99]
	s_nop 2
	ds_read_b128 v[96:99], v49 offset:58368
	ds_read_b128 v[128:131], v49 offset:60416
	ds_read_b128 v[132:135], v49 offset:62464
	ds_read_b128 v[136:139], v49 offset:64512
	v_mfma_f32_16x16x32_bf16 v[112:115], v[112:115], v[0:3], v[20:23]
	v_mfma_f32_16x16x32_bf16 v[108:111], v[108:111], v[0:3], v[24:27]
	v_mfma_f32_16x16x32_bf16 v[104:107], v[104:107], v[0:3], v[28:31]
	v_mfma_f32_16x16x32_bf16 v[40:43], v[40:43], v[0:3], v[32:35]
	v_mfma_f32_16x16x32_bf16 v[32:35], v[92:95], v[0:3], v[88:91]
	s_add_u32 s100, s10, 0x11e10080
	s_addc_u32 s101, s11, 0
	s_mov_b32 m0, s26
	s_nop 0
	global_load_lds_dwordx4 v241, s[100:101]
	s_waitcnt lgkmcnt(0)
	v_mfma_f32_16x16x32_bf16 v[28:31], v[4:7], v[0:3], v[50:53]
	v_mfma_f32_16x16x32_bf16 v[24:27], v[8:11], v[0:3], v[66:69]
	v_mfma_f32_16x16x32_bf16 v[20:23], v[12:15], v[0:3], v[72:75]
	v_mfma_f32_16x16x32_bf16 v[16:19], v[16:19], v[0:3], v[80:83]
	v_mfma_f32_16x16x32_bf16 v[12:15], v[96:99], v[0:3], v[76:79]
	v_mfma_f32_16x16x32_bf16 v[8:11], v[128:131], v[0:3], v[84:87]
	v_mfma_f32_16x16x32_bf16 v[4:7], v[132:135], v[0:3], v[100:103]
	v_mfma_f32_16x16x32_bf16 v[0:3], v[136:139], v[0:3], v[124:127]
	s_add_u32 s100, s10, 0x11e18080
	s_addc_u32 s101, s11, 0
	s_mov_b32 m0, s27
	s_nop 0
	global_load_lds_dwordx4 v241, s[100:101]
	v_max_f32_e32 v49, v123, v123
	v_max_f32_e32 v50, v122, v122
	v_max_f32_e32 v49, v50, v49
	v_max_f32_e32 v50, v117, v117
	v_max_f32_e32 v51, v116, v116
	v_max_f32_e32 v50, v51, v50
	v_max_f32_e32 v51, v119, v119
	v_max_f32_e32 v52, v118, v118
	v_max3_f32 v49, v120, v121, v49
	v_max_f32_e32 v51, v52, v51
	v_max3_f32 v49, v49, v50, v51
	v_max_f32_e32 v50, v113, v113
	v_max_f32_e32 v51, v112, v112
	v_max_f32_e32 v50, v51, v50
	v_max_f32_e32 v51, v115, v115
	v_max_f32_e32 v52, v114, v114
	v_max_f32_e32 v51, v52, v51
	v_max3_f32 v49, v49, v50, v51
	v_max_f32_e32 v50, v109, v109
	v_max_f32_e32 v51, v108, v108
	v_max_f32_e32 v50, v51, v50
	v_max_f32_e32 v51, v111, v111
	v_max_f32_e32 v52, v110, v110
	v_max_f32_e32 v51, v52, v51
	v_max3_f32 v49, v49, v50, v51
	v_max_f32_e32 v50, v105, v105
	v_max_f32_e32 v51, v104, v104
	v_max_f32_e32 v50, v51, v50
	v_max_f32_e32 v51, v107, v107
	v_max_f32_e32 v52, v106, v106
	v_max_f32_e32 v51, v52, v51
	v_max3_f32 v49, v49, v50, v51
	v_max_f32_e32 v50, v41, v41
	v_max_f32_e32 v51, v40, v40
	v_max_f32_e32 v50, v51, v50
	v_max_f32_e32 v51, v43, v43
	v_max_f32_e32 v52, v42, v42
	v_max_f32_e32 v51, v52, v51
	v_max3_f32 v49, v49, v50, v51
	v_max_f32_e32 v50, v37, v37
	v_max_f32_e32 v51, v36, v36
	v_max_f32_e32 v50, v51, v50
	v_max_f32_e32 v51, v39, v39
	v_max_f32_e32 v52, v38, v38
	v_max_f32_e32 v51, v52, v51
	v_max3_f32 v49, v49, v50, v51
	v_max_f32_e32 v50, v33, v33
	v_max_f32_e32 v51, v32, v32
	v_max_f32_e32 v50, v51, v50
	v_max_f32_e32 v51, v35, v35
	v_max_f32_e32 v52, v34, v34
	v_max_f32_e32 v51, v52, v51
	v_max3_f32 v49, v49, v50, v51
	v_max_f32_e32 v50, v29, v29
	v_max_f32_e32 v51, v28, v28
	v_max_f32_e32 v50, v51, v50
	v_max_f32_e32 v51, v31, v31
	v_max_f32_e32 v52, v30, v30
	v_max_f32_e32 v51, v52, v51
	v_max3_f32 v49, v49, v50, v51
	v_max_f32_e32 v50, v25, v25
	v_max_f32_e32 v51, v24, v24
	v_max_f32_e32 v50, v51, v50
	v_max_f32_e32 v51, v27, v27
	v_max_f32_e32 v52, v26, v26
	v_max_f32_e32 v51, v52, v51
	v_max3_f32 v49, v49, v50, v51
	v_max_f32_e32 v50, v21, v21
	v_max_f32_e32 v51, v20, v20
	v_max_f32_e32 v50, v51, v50
	v_max_f32_e32 v51, v23, v23
	v_max_f32_e32 v52, v22, v22
	v_max_f32_e32 v51, v52, v51
	v_max3_f32 v49, v49, v50, v51
	v_max_f32_e32 v50, v17, v17
	v_max_f32_e32 v51, v16, v16
	v_max_f32_e32 v50, v51, v50
	v_max_f32_e32 v51, v19, v19
	v_max_f32_e32 v52, v18, v18
	v_max_f32_e32 v51, v52, v51
	v_max3_f32 v49, v49, v50, v51
	v_max_f32_e32 v50, v13, v13
	v_max_f32_e32 v51, v12, v12
	v_max_f32_e32 v50, v51, v50
	v_max_f32_e32 v51, v15, v15
	v_max_f32_e32 v52, v14, v14
	v_max_f32_e32 v51, v52, v51
	v_max3_f32 v49, v49, v50, v51
	v_max_f32_e32 v50, v9, v9
	v_max_f32_e32 v51, v8, v8
	v_max_f32_e32 v50, v51, v50
	v_max_f32_e32 v51, v11, v11
	v_max_f32_e32 v52, v10, v10
	v_max_f32_e32 v51, v52, v51
	v_max3_f32 v49, v49, v50, v51
	v_max_f32_e32 v50, v5, v5
	v_max_f32_e32 v51, v4, v4
	v_max_f32_e32 v50, v51, v50
	v_max_f32_e32 v51, v7, v7
	v_max_f32_e32 v52, v6, v6
	v_max_f32_e32 v51, v52, v51
	v_max3_f32 v49, v49, v50, v51
	v_max_f32_e32 v50, v1, v1
	v_max_f32_e32 v51, v0, v0
	v_max_f32_e32 v50, v51, v50
	v_max_f32_e32 v51, v3, v3
	v_max_f32_e32 v52, v2, v2
	v_max_f32_e32 v51, v52, v51
	v_max3_f32 v49, v49, v50, v51
	v_mbcnt_lo_u32_b32 v50, -1, 0
	v_mbcnt_hi_u32_b32 v50, -1, v50
	v_and_b32_e32 v52, 64, v50
	v_xor_b32_e32 v51, 16, v50
	v_add_u32_e32 v52, 64, v52
	v_cmp_lt_i32_e32 vcc, v51, v52
	s_nop 1
	v_cndmask_b32_e32 v51, v50, v51, vcc
	v_lshlrev_b32_e32 v51, 2, v51
	v_mov_b32_e32 v53, v49
	s_nop 1
	v_permlane16_swap_b32_e32 v53, v49
	s_waitcnt lgkmcnt(0)
	v_max_f32_e32 v53, v53, v53
	v_max_f32_e32 v49, v49, v53
	v_xor_b32_e32 v53, 32, v50
	v_cmp_lt_i32_e32 vcc, v53, v52
	s_nop 1
	v_cndmask_b32_e32 v50, v50, v53, vcc
	v_lshlrev_b32_e32 v50, 2, v50
	v_mov_b32_e32 v52, v49
	s_nop 1
	v_permlane32_swap_b32_e32 v52, v49
	s_waitcnt lgkmcnt(0)
	v_max_f32_e32 v52, v52, v52
	v_max_f32_e32 v49, v49, v52
	v_sub_f32_e32 v52, v120, v49
	v_exp_f32_e32 v52, v52
	v_sub_f32_e32 v53, v121, v49
	v_exp_f32_e32 v53, v53
	v_sub_f32_e32 v54, v122, v49
	v_exp_f32_e32 v54, v54
	v_sub_f32_e32 v55, v123, v49
	v_exp_f32_e32 v55, v55
	v_sub_f32_e32 v59, v116, v49
	v_add_f32_e32 v57, 0, v52
	v_exp_f32_e32 v59, v59
	v_sub_f32_e32 v62, v117, v49
	v_add_f32_e32 v57, v53, v57
	v_exp_f32_e32 v62, v62
	v_sub_f32_e32 v63, v118, v49
	v_add_f32_e32 v57, v54, v57
	v_exp_f32_e32 v63, v63
	v_sub_f32_e32 v64, v119, v49
	v_add_f32_e32 v57, v55, v57
	v_exp_f32_e32 v64, v64
	v_sub_f32_e32 v66, v112, v49
	v_add_f32_e32 v57, v59, v57
	v_exp_f32_e32 v66, v66
	v_sub_f32_e32 v67, v113, v49
	v_add_f32_e32 v57, v62, v57
	v_exp_f32_e32 v67, v67
	v_sub_f32_e32 v68, v114, v49
	v_add_f32_e32 v57, v63, v57
	v_exp_f32_e32 v68, v68
	v_sub_f32_e32 v69, v115, v49
	v_add_f32_e32 v57, v64, v57
	v_exp_f32_e32 v69, v69
	v_sub_f32_e32 v71, v108, v49
	v_add_f32_e32 v57, v66, v57
	v_exp_f32_e32 v71, v71
	v_sub_f32_e32 v72, v109, v49
	v_add_f32_e32 v57, v67, v57
	v_exp_f32_e32 v72, v72
	v_sub_f32_e32 v73, v110, v49
	v_add_f32_e32 v57, v68, v57
	v_exp_f32_e32 v73, v73
	v_sub_f32_e32 v74, v111, v49
	v_add_f32_e32 v57, v69, v57
	v_exp_f32_e32 v74, v74
	v_sub_f32_e32 v75, v104, v49
	v_add_f32_e32 v57, v71, v57
	v_exp_f32_e32 v75, v75
	v_sub_f32_e32 v76, v105, v49
	v_add_f32_e32 v57, v72, v57
	v_exp_f32_e32 v76, v76
	v_sub_f32_e32 v77, v106, v49
	v_add_f32_e32 v57, v73, v57
	v_exp_f32_e32 v77, v77
	v_sub_f32_e32 v78, v107, v49
	v_add_f32_e32 v57, v74, v57
	v_exp_f32_e32 v78, v78
	v_sub_f32_e32 v40, v40, v49
	v_add_f32_e32 v57, v75, v57
	v_exp_f32_e32 v40, v40
	v_sub_f32_e32 v41, v41, v49
	v_add_f32_e32 v57, v76, v57
	v_exp_f32_e32 v41, v41
	v_sub_f32_e32 v42, v42, v49
	v_add_f32_e32 v57, v77, v57
	v_exp_f32_e32 v42, v42
	v_sub_f32_e32 v43, v43, v49
	v_add_f32_e32 v57, v78, v57
	v_exp_f32_e32 v43, v43
	v_sub_f32_e32 v36, v36, v49
	v_add_f32_e32 v57, v40, v57
	v_exp_f32_e32 v36, v36
	v_sub_f32_e32 v37, v37, v49
	v_add_f32_e32 v57, v41, v57
	v_exp_f32_e32 v37, v37
	v_sub_f32_e32 v38, v38, v49
	v_add_f32_e32 v57, v42, v57
	v_exp_f32_e32 v38, v38
	v_sub_f32_e32 v39, v39, v49
	v_add_f32_e32 v57, v43, v57
	v_exp_f32_e32 v39, v39
	v_sub_f32_e32 v32, v32, v49
	v_add_f32_e32 v57, v36, v57
	v_exp_f32_e32 v32, v32
	v_sub_f32_e32 v33, v33, v49
	v_add_f32_e32 v57, v37, v57
	v_exp_f32_e32 v33, v33
	v_sub_f32_e32 v34, v34, v49
	v_add_f32_e32 v57, v38, v57
	v_exp_f32_e32 v34, v34
	v_sub_f32_e32 v35, v35, v49
	v_add_f32_e32 v57, v39, v57
	v_exp_f32_e32 v35, v35
	v_sub_f32_e32 v28, v28, v49
	v_add_f32_e32 v57, v32, v57
	v_exp_f32_e32 v79, v28
	v_sub_f32_e32 v28, v29, v49
	v_add_f32_e32 v57, v33, v57
	v_exp_f32_e32 v80, v28
	v_sub_f32_e32 v28, v30, v49
	v_add_f32_e32 v57, v34, v57
	v_exp_f32_e32 v81, v28
	v_sub_f32_e32 v28, v31, v49
	v_add_f32_e32 v57, v35, v57
	v_exp_f32_e32 v82, v28
	v_sub_f32_e32 v24, v24, v49
	v_add_f32_e32 v28, v79, v57
	v_exp_f32_e32 v57, v24
	v_sub_f32_e32 v24, v25, v49
	v_add_f32_e32 v28, v80, v28
	v_exp_f32_e32 v83, v24
	v_sub_f32_e32 v24, v26, v49
	v_add_f32_e32 v28, v81, v28
	v_exp_f32_e32 v84, v24
	v_sub_f32_e32 v24, v27, v49
	v_add_f32_e32 v28, v82, v28
	v_exp_f32_e32 v85, v24
	v_sub_f32_e32 v20, v20, v49
	v_add_f32_e32 v24, v57, v28
	v_exp_f32_e32 v86, v20
	v_sub_f32_e32 v20, v21, v49
	v_add_f32_e32 v24, v83, v24
	v_exp_f32_e32 v87, v20
	v_sub_f32_e32 v20, v22, v49
	v_add_f32_e32 v24, v84, v24
	v_exp_f32_e32 v88, v20
	v_sub_f32_e32 v20, v23, v49
	v_add_f32_e32 v24, v85, v24
	v_exp_f32_e32 v89, v20
	v_sub_f32_e32 v16, v16, v49
	v_add_f32_e32 v20, v86, v24
	v_exp_f32_e32 v90, v16
	v_sub_f32_e32 v16, v17, v49
	v_add_f32_e32 v20, v87, v20
	v_exp_f32_e32 v91, v16
	v_sub_f32_e32 v16, v18, v49
	v_add_f32_e32 v20, v88, v20
	v_exp_f32_e32 v92, v16
	v_sub_f32_e32 v16, v19, v49
	v_add_f32_e32 v20, v89, v20
	v_exp_f32_e32 v93, v16
	v_sub_f32_e32 v12, v12, v49
	v_add_f32_e32 v16, v90, v20
	v_exp_f32_e32 v94, v12
	v_sub_f32_e32 v12, v13, v49
	v_add_f32_e32 v16, v91, v16
	v_exp_f32_e32 v95, v12
	v_sub_f32_e32 v12, v14, v49
	v_add_f32_e32 v16, v92, v16
	v_exp_f32_e32 v96, v12
	v_sub_f32_e32 v12, v15, v49
	v_add_f32_e32 v16, v93, v16
	v_exp_f32_e32 v97, v12
	v_sub_f32_e32 v8, v8, v49
	v_add_f32_e32 v12, v94, v16
	v_exp_f32_e32 v98, v8
	v_sub_f32_e32 v8, v9, v49
	v_add_f32_e32 v12, v95, v12
	v_exp_f32_e32 v99, v8
	v_sub_f32_e32 v8, v10, v49
	v_add_f32_e32 v12, v96, v12
	v_exp_f32_e32 v100, v8
	v_sub_f32_e32 v8, v11, v49
	v_add_f32_e32 v12, v97, v12
	v_exp_f32_e32 v11, v8
	v_sub_f32_e32 v4, v4, v49
	v_add_f32_e32 v8, v98, v12
	v_exp_f32_e32 v101, v4
	v_sub_f32_e32 v4, v5, v49
	v_add_f32_e32 v8, v99, v8
	v_exp_f32_e32 v102, v4
	v_sub_f32_e32 v4, v6, v49
	v_add_f32_e32 v8, v100, v8
	v_exp_f32_e32 v103, v4
	v_sub_f32_e32 v4, v7, v49
	v_add_f32_e32 v8, v11, v8
	v_exp_f32_e32 v104, v4
	v_sub_f32_e32 v0, v0, v49
	v_add_f32_e32 v4, v101, v8
	v_exp_f32_e32 v105, v0
	v_sub_f32_e32 v0, v1, v49
	v_add_f32_e32 v4, v102, v4
	v_exp_f32_e32 v106, v0
	v_sub_f32_e32 v0, v2, v49
	v_add_f32_e32 v4, v103, v4
	v_exp_f32_e32 v107, v0
	v_sub_f32_e32 v0, v3, v49
	v_add_f32_e32 v4, v104, v4
	v_exp_f32_e32 v3, v0
	v_add_f32_e32 v0, v105, v4
	v_add_f32_e32 v0, v106, v0
	v_add_f32_e32 v0, v107, v0
	v_add_f32_e32 v0, v3, v0
	v_mov_b32_e32 v1, v0
	s_nop 1
	v_permlane16_swap_b32_e32 v1, v0
	v_cvt_pk_bf16_f32 v28, v52, v53
	v_cvt_pk_bf16_f32 v29, v54, v55
	v_cvt_pk_bf16_f32 v30, v59, v62
	v_cvt_pk_bf16_f32 v31, v63, v64
	s_waitcnt lgkmcnt(0)
	v_add_f32_e32 v0, v0, v1
	v_mov_b32_e32 v1, v0
	s_nop 1
	v_permlane32_swap_b32_e32 v1, v0
	v_cvt_pk_bf16_f32 v20, v66, v67
	v_cvt_pk_bf16_f32 v21, v68, v69
	v_cvt_pk_bf16_f32 v22, v71, v72
	v_cvt_pk_bf16_f32 v23, v73, v74
	s_waitcnt lgkmcnt(0)
	v_add_f32_e32 v49, v0, v1
	v_cvt_pk_bf16_f32 v24, v75, v76
	v_cvt_pk_bf16_f32 v25, v77, v78
	v_cvt_pk_bf16_f32 v26, v40, v41
	v_cvt_pk_bf16_f32 v27, v42, v43
	v_cvt_pk_bf16_f32 v16, v36, v37
	v_cvt_pk_bf16_f32 v17, v38, v39
	v_cvt_pk_bf16_f32 v18, v32, v33
	v_cvt_pk_bf16_f32 v19, v34, v35
	v_cvt_pk_bf16_f32 v12, v79, v80
	v_cvt_pk_bf16_f32 v13, v81, v82
	v_cvt_pk_bf16_f32 v14, v57, v83
	v_cvt_pk_bf16_f32 v15, v84, v85
	v_cvt_pk_bf16_f32 v4, v86, v87
	v_cvt_pk_bf16_f32 v5, v88, v89
	v_cvt_pk_bf16_f32 v6, v90, v91
	v_cvt_pk_bf16_f32 v7, v92, v93
	v_cvt_pk_bf16_f32 v8, v94, v95
	v_cvt_pk_bf16_f32 v9, v96, v97
	v_cvt_pk_bf16_f32 v10, v98, v99
	v_cvt_pk_bf16_f32 v11, v100, v11
	v_cvt_pk_bf16_f32 v0, v101, v102
	v_cvt_pk_bf16_f32 v1, v103, v104
	v_cvt_pk_bf16_f32 v2, v105, v106
	v_cvt_pk_bf16_f32 v3, v107, v3
	s_waitcnt vmcnt(0)
	s_waitcnt vmcnt(0)
	s_barrier
	v_mov_b32_e32 v64, v65
	v_div_scale_f32 v62, vcc, 1.0, v49, 1.0
	v_lshlrev_b32_e32 v54, 2, v70
	v_ashrrev_i32_e32 v55, 31, v54
	ds_read_b128 v[32:35], v64
	ds_read_b128 v[36:39], v64 offset:2048
	v_div_scale_f32 v57, s[0:1], v49, v49, 1.0
	v_rcp_f32_e32 v59, v57
	s_waitcnt lgkmcnt(0)
	v_mfma_f32_16x16x32_bf16 v[44:47], v[32:35], v[28:31], 0
	v_fma_f32 v40, -v57, v59, 1.0
	v_fmac_f32_e32 v59, v40, v59
	ds_read_b128 v[40:43], v64 offset:4096
	ds_read_b128 v[32:35], v64 offset:6144
	v_mul_f32_e32 v63, v62, v59
	v_fma_f32 v66, -v57, v63, v62
	v_fmac_f32_e32 v63, v66, v59
	v_mfma_f32_16x16x32_bf16 v[50:53], v[36:39], v[28:31], 0
	v_fma_f32 v36, -v57, v63, v62
	ds_read_b128 v[66:69], v64 offset:8192
	ds_read_b128 v[70:73], v64 offset:10240
	v_div_fmas_f32 v36, v36, v59, v63
	s_waitcnt lgkmcnt(0)
	v_mfma_f32_16x16x32_bf16 v[74:77], v[32:35], v[28:31], 0
	v_lshl_add_u64 v[34:35], v[54:55], 1, v[60:61]
	ds_read_b128 v[60:63], v64 offset:12288
	ds_read_b128 v[78:81], v64 offset:14336
	ds_read_b128 v[82:85], v64 offset:32768
	ds_read_b128 v[86:89], v64 offset:34816
	ds_read_b128 v[90:93], v64 offset:36864
	ds_read_b128 v[94:97], v64 offset:38912
	ds_read_b128 v[98:101], v64 offset:40960
	ds_read_b128 v[102:105], v64 offset:43008
	ds_read_b128 v[106:109], v64 offset:45056
	ds_read_b128 v[110:113], v64 offset:47104
	s_mov_b64 s[0:1], 0x1000000
	v_mfma_f32_16x16x32_bf16 v[38:41], v[40:43], v[28:31], 0
	v_div_fixup_f32 v36, v36, v49, 1.0
	v_lshl_add_u64 v[32:33], v[34:35], 0, s[0:1]
	v_mfma_f32_16x16x32_bf16 v[66:69], v[66:69], v[28:31], 0
	v_mfma_f32_16x16x32_bf16 v[70:73], v[70:73], v[28:31], 0
	s_waitcnt lgkmcnt(0)
	v_mfma_f32_16x16x32_bf16 v[60:63], v[60:63], v[28:31], 0
	v_mfma_f32_16x16x32_bf16 v[78:81], v[78:81], v[28:31], 0
	s_add_u32 s100, s10, 0x11e00100
	s_addc_u32 s101, s11, 0
	s_mov_b32 m0, s19
	s_nop 0
	global_load_lds_dwordx4 v241, s[100:101]
	ds_read_b128 v[114:117], v64 offset:30720
	ds_read_b128 v[118:121], v64 offset:28672
	ds_read_b128 v[122:125], v64 offset:26624
	ds_read_b128 v[126:129], v64 offset:24576
	ds_read_b128 v[130:133], v64 offset:22528
	ds_read_b128 v[134:137], v64 offset:20480
	ds_read_b128 v[138:141], v64 offset:18432
	ds_read_b128 v[142:145], v64 offset:16384
	v_mfma_f32_16x16x32_bf16 v[82:85], v[82:85], v[28:31], 0
	v_mfma_f32_16x16x32_bf16 v[86:89], v[86:89], v[28:31], 0
	v_mfma_f32_16x16x32_bf16 v[90:93], v[90:93], v[28:31], 0
	v_mfma_f32_16x16x32_bf16 v[94:97], v[94:97], v[28:31], 0
	v_mfma_f32_16x16x32_bf16 v[98:101], v[98:101], v[28:31], 0
	v_mfma_f32_16x16x32_bf16 v[102:105], v[102:105], v[28:31], 0
	v_mfma_f32_16x16x32_bf16 v[106:109], v[106:109], v[28:31], 0
	v_mfma_f32_16x16x32_bf16 v[110:113], v[110:113], v[28:31], 0
	s_add_u32 s100, s10, 0x11e08100
	s_addc_u32 s101, s11, 0
	s_mov_b32 m0, s13
	s_nop 0
	global_load_lds_dwordx4 v241, s[100:101]
	s_waitcnt lgkmcnt(0)
	v_mfma_f32_16x16x32_bf16 v[42:45], v[142:145], v[24:27], v[44:47]
	v_mfma_f32_16x16x32_bf16 v[50:53], v[138:141], v[24:27], v[50:53]
	v_mfma_f32_16x16x32_bf16 v[38:41], v[134:137], v[24:27], v[38:41]
	v_mfma_f32_16x16x32_bf16 v[74:77], v[130:133], v[24:27], v[74:77]
	v_mfma_f32_16x16x32_bf16 v[66:69], v[126:129], v[24:27], v[66:69]
	v_mfma_f32_16x16x32_bf16 v[70:73], v[122:125], v[24:27], v[70:73]
	ds_read_b128 v[122:125], v64 offset:49152
	ds_read_b128 v[126:129], v64 offset:51200
	ds_read_b128 v[130:133], v64 offset:53248
	ds_read_b128 v[134:137], v64 offset:55296
	v_mfma_f32_16x16x32_bf16 v[60:63], v[118:121], v[24:27], v[60:63]
	ds_read_b128 v[118:121], v64 offset:57344
	ds_read_b128 v[138:141], v64 offset:59392
	ds_read_b128 v[142:145], v64 offset:61440
	ds_read_b128 v[146:149], v64 offset:63488
	v_mfma_f32_16x16x32_bf16 v[78:81], v[114:117], v[24:27], v[78:81]
	s_add_u32 s100, s10, 0x11e00180
	s_addc_u32 s101, s11, 0
	s_mov_b32 m0, s12
	s_nop 0
	global_load_lds_dwordx4 v241, s[100:101]
	s_waitcnt lgkmcnt(0)
	v_mfma_f32_16x16x32_bf16 v[82:85], v[122:125], v[24:27], v[82:85]
	v_mfma_f32_16x16x32_bf16 v[86:89], v[126:129], v[24:27], v[86:89]
	v_mfma_f32_16x16x32_bf16 v[90:93], v[130:133], v[24:27], v[90:93]
	v_mfma_f32_16x16x32_bf16 v[94:97], v[134:137], v[24:27], v[94:97]
	v_mfma_f32_16x16x32_bf16 v[98:101], v[118:121], v[24:27], v[98:101]
	ds_read_b128 v[114:117], v64 offset:15360
	ds_read_b128 v[118:121], v64 offset:13312
	ds_read_b128 v[122:125], v64 offset:11264
	ds_read_b128 v[126:129], v64 offset:9216
	v_mfma_f32_16x16x32_bf16 v[102:105], v[138:141], v[24:27], v[102:105]
	v_mfma_f32_16x16x32_bf16 v[106:109], v[142:145], v[24:27], v[106:109]
	ds_read_b128 v[130:133], v64 offset:7168
	ds_read_b128 v[134:137], v64 offset:5120
	ds_read_b128 v[138:141], v64 offset:3072
	ds_read_b128 v[142:145], v64 offset:1024
	v_mfma_f32_16x16x32_bf16 v[110:113], v[146:149], v[24:27], v[110:113]
	s_add_u32 s100, s10, 0x11e08180
	s_addc_u32 s101, s11, 0
	s_mov_b32 m0, s14
	s_nop 0
	global_load_lds_dwordx4 v241, s[100:101]
	s_waitcnt lgkmcnt(0)
	v_mfma_f32_16x16x32_bf16 v[42:45], v[142:145], v[20:23], v[42:45]
	v_mfma_f32_16x16x32_bf16 v[50:53], v[138:141], v[20:23], v[50:53]
	v_mfma_f32_16x16x32_bf16 v[38:41], v[134:137], v[20:23], v[38:41]
	v_mfma_f32_16x16x32_bf16 v[74:77], v[130:133], v[20:23], v[74:77]
	v_mfma_f32_16x16x32_bf16 v[66:69], v[126:129], v[20:23], v[66:69]
	v_mfma_f32_16x16x32_bf16 v[70:73], v[122:125], v[20:23], v[70:73]
	ds_read_b128 v[122:125], v64 offset:33792
	ds_read_b128 v[126:129], v64 offset:35840
	ds_read_b128 v[130:133], v64 offset:37888
	ds_read_b128 v[134:137], v64 offset:39936
	v_mfma_f32_16x16x32_bf16 v[60:63], v[118:121], v[20:23], v[60:63]
	ds_read_b128 v[118:121], v64 offset:41984
	ds_read_b128 v[138:141], v64 offset:44032
	ds_read_b128 v[142:145], v64 offset:46080
	ds_read_b128 v[146:149], v64 offset:48128
	v_mfma_f32_16x16x32_bf16 v[78:81], v[114:117], v[20:23], v[78:81]
	s_add_u32 s100, s10, 0x11e10100
	s_addc_u32 s101, s11, 0
	s_mov_b32 m0, s15
	s_nop 0
	global_load_lds_dwordx4 v241, s[100:101]
	s_waitcnt lgkmcnt(0)
	v_mfma_f32_16x16x32_bf16 v[82:85], v[122:125], v[20:23], v[82:85]
	v_mfma_f32_16x16x32_bf16 v[86:89], v[126:129], v[20:23], v[86:89]
	v_mfma_f32_16x16x32_bf16 v[90:93], v[130:133], v[20:23], v[90:93]
	v_mfma_f32_16x16x32_bf16 v[94:97], v[134:137], v[20:23], v[94:97]
	v_mfma_f32_16x16x32_bf16 v[98:101], v[118:121], v[20:23], v[98:101]
	ds_read_b128 v[114:117], v64 offset:31744
	ds_read_b128 v[118:121], v64 offset:29696
	ds_read_b128 v[122:125], v64 offset:27648
	ds_read_b128 v[126:129], v64 offset:25600
	v_mfma_f32_16x16x32_bf16 v[102:105], v[138:141], v[20:23], v[102:105]
	v_mfma_f32_16x16x32_bf16 v[106:109], v[142:145], v[20:23], v[106:109]
	ds_read_b128 v[130:133], v64 offset:23552
	ds_read_b128 v[134:137], v64 offset:21504
	ds_read_b128 v[138:141], v64 offset:19456
	ds_read_b128 v[142:145], v64 offset:17408
	v_mfma_f32_16x16x32_bf16 v[110:113], v[146:149], v[20:23], v[110:113]
	s_add_u32 s100, s10, 0x11e18100
	s_addc_u32 s101, s11, 0
	s_mov_b32 m0, s16
	s_nop 0
	global_load_lds_dwordx4 v241, s[100:101]
	s_waitcnt lgkmcnt(0)
	v_mfma_f32_16x16x32_bf16 v[42:45], v[142:145], v[16:19], v[42:45]
	v_mfma_f32_16x16x32_bf16 v[50:53], v[138:141], v[16:19], v[50:53]
	v_mfma_f32_16x16x32_bf16 v[38:41], v[134:137], v[16:19], v[38:41]
	v_mfma_f32_16x16x32_bf16 v[74:77], v[130:133], v[16:19], v[74:77]
	v_mfma_f32_16x16x32_bf16 v[66:69], v[126:129], v[16:19], v[66:69]
	v_mfma_f32_16x16x32_bf16 v[70:73], v[122:125], v[16:19], v[70:73]
	ds_read_b128 v[122:125], v64 offset:50176
	ds_read_b128 v[126:129], v64 offset:52224
	ds_read_b128 v[130:133], v64 offset:54272
	ds_read_b128 v[134:137], v64 offset:56320
	v_mfma_f32_16x16x32_bf16 v[60:63], v[118:121], v[16:19], v[60:63]
	ds_read_b128 v[118:121], v64 offset:58368
	ds_read_b128 v[138:141], v64 offset:60416
	ds_read_b128 v[142:145], v64 offset:62464
	ds_read_b128 v[146:149], v64 offset:64512
	v_mfma_f32_16x16x32_bf16 v[78:81], v[114:117], v[16:19], v[78:81]
	s_add_u32 s100, s10, 0x11e10180
	s_addc_u32 s101, s11, 0
	s_mov_b32 m0, s17
	s_nop 0
	global_load_lds_dwordx4 v241, s[100:101]
	s_waitcnt lgkmcnt(0)
	v_mfma_f32_16x16x32_bf16 v[82:85], v[122:125], v[16:19], v[82:85]
	v_mfma_f32_16x16x32_bf16 v[86:89], v[126:129], v[16:19], v[86:89]
	v_mfma_f32_16x16x32_bf16 v[90:93], v[130:133], v[16:19], v[90:93]
	v_mfma_f32_16x16x32_bf16 v[94:97], v[134:137], v[16:19], v[94:97]
	v_mfma_f32_16x16x32_bf16 v[98:101], v[118:121], v[16:19], v[98:101]
	v_mfma_f32_16x16x32_bf16 v[102:105], v[138:141], v[16:19], v[102:105]
	v_mfma_f32_16x16x32_bf16 v[106:109], v[142:145], v[16:19], v[106:109]
	v_mfma_f32_16x16x32_bf16 v[110:113], v[146:149], v[16:19], v[110:113]
	s_add_u32 s100, s10, 0x11e18180
	s_addc_u32 s101, s11, 0
	s_mov_b32 m0, s18
	s_nop 0
	global_load_lds_dwordx4 v241, s[100:101]
	s_waitcnt vmcnt(0)
	s_waitcnt vmcnt(0)
	s_barrier
	v_mov_b32_e32 v37, v48
	ds_read_b128 v[114:117], v37
	ds_read_b128 v[118:121], v37 offset:2048
	s_waitcnt lgkmcnt(0)
	v_mfma_f32_16x16x32_bf16 v[42:45], v[114:117], v[12:15], v[42:45]
	ds_read_b128 v[114:117], v37 offset:4096
	v_mfma_f32_16x16x32_bf16 v[50:53], v[118:121], v[12:15], v[50:53]
	ds_read_b128 v[118:121], v37 offset:6144
	s_waitcnt lgkmcnt(0)
	v_mfma_f32_16x16x32_bf16 v[38:41], v[114:117], v[12:15], v[38:41]
	ds_read_b128 v[114:117], v37 offset:8192
	v_mfma_f32_16x16x32_bf16 v[74:77], v[118:121], v[12:15], v[74:77]
	ds_read_b128 v[118:121], v37 offset:10240
	s_waitcnt lgkmcnt(0)
	v_mfma_f32_16x16x32_bf16 v[66:69], v[114:117], v[12:15], v[66:69]
	ds_read_b128 v[114:117], v37 offset:12288
	ds_read_b128 v[122:125], v37 offset:14336
	v_mfma_f32_16x16x32_bf16 v[70:73], v[118:121], v[12:15], v[70:73]
	ds_read_b128 v[118:121], v37 offset:32768
	ds_read_b128 v[126:129], v37 offset:34816
	ds_read_b128 v[130:133], v37 offset:36864
	ds_read_b128 v[134:137], v37 offset:38912
	s_waitcnt lgkmcnt(0)
	v_mfma_f32_16x16x32_bf16 v[60:63], v[114:117], v[12:15], v[60:63]
	ds_read_b128 v[114:117], v37 offset:40960
	ds_read_b128 v[138:141], v37 offset:43008
	ds_read_b128 v[142:145], v37 offset:45056
	ds_read_b128 v[146:149], v37 offset:47104
	v_mfma_f32_16x16x32_bf16 v[78:81], v[122:125], v[12:15], v[78:81]
	s_add_u32 s100, s10, 0x11e20000
	s_addc_u32 s101, s11, 0
	s_mov_b32 m0, s22
	s_nop 0
	global_load_lds_dwordx4 v241, s[100:101]
	v_mfma_f32_16x16x32_bf16 v[82:85], v[118:121], v[12:15], v[82:85]
	v_mfma_f32_16x16x32_bf16 v[86:89], v[126:129], v[12:15], v[86:89]
	v_mfma_f32_16x16x32_bf16 v[90:93], v[130:133], v[12:15], v[90:93]
	v_mfma_f32_16x16x32_bf16 v[94:97], v[134:137], v[12:15], v[94:97]
	s_waitcnt lgkmcnt(0)
	v_mfma_f32_16x16x32_bf16 v[98:101], v[114:117], v[12:15], v[98:101]
	ds_read_b128 v[114:117], v37 offset:30720
	ds_read_b128 v[118:121], v37 offset:28672
	ds_read_b128 v[122:125], v37 offset:26624
	ds_read_b128 v[126:129], v37 offset:24576
	v_mfma_f32_16x16x32_bf16 v[102:105], v[138:141], v[12:15], v[102:105]
	v_mfma_f32_16x16x32_bf16 v[106:109], v[142:145], v[12:15], v[106:109]
	ds_read_b128 v[130:133], v37 offset:22528
	ds_read_b128 v[134:137], v37 offset:20480
	ds_read_b128 v[138:141], v37 offset:18432
	ds_read_b128 v[142:145], v37 offset:16384
	v_mfma_f32_16x16x32_bf16 v[110:113], v[146:149], v[12:15], v[110:113]
	s_add_u32 s100, s10, 0x11e28000
	s_addc_u32 s101, s11, 0
	s_mov_b32 m0, s21
	s_nop 0
	global_load_lds_dwordx4 v241, s[100:101]
	s_waitcnt lgkmcnt(0)
	v_mfma_f32_16x16x32_bf16 v[42:45], v[142:145], v[8:11], v[42:45]
	v_mfma_f32_16x16x32_bf16 v[50:53], v[138:141], v[8:11], v[50:53]
	v_mfma_f32_16x16x32_bf16 v[38:41], v[134:137], v[8:11], v[38:41]
	v_mfma_f32_16x16x32_bf16 v[74:77], v[130:133], v[8:11], v[74:77]
	v_mfma_f32_16x16x32_bf16 v[66:69], v[126:129], v[8:11], v[66:69]
	v_mfma_f32_16x16x32_bf16 v[70:73], v[122:125], v[8:11], v[70:73]
	ds_read_b128 v[122:125], v37 offset:49152
	ds_read_b128 v[126:129], v37 offset:51200
	ds_read_b128 v[130:133], v37 offset:53248
	ds_read_b128 v[134:137], v37 offset:55296
	v_mfma_f32_16x16x32_bf16 v[60:63], v[118:121], v[8:11], v[60:63]
	ds_read_b128 v[118:121], v37 offset:57344
	ds_read_b128 v[138:141], v37 offset:59392
	ds_read_b128 v[142:145], v37 offset:61440
	ds_read_b128 v[146:149], v37 offset:63488
	v_mfma_f32_16x16x32_bf16 v[78:81], v[114:117], v[8:11], v[78:81]
	s_add_u32 s100, s10, 0x11e20080
	s_addc_u32 s101, s11, 0
	s_mov_b32 m0, s20
	s_nop 0
	global_load_lds_dwordx4 v241, s[100:101]
	s_waitcnt lgkmcnt(0)
	v_mfma_f32_16x16x32_bf16 v[82:85], v[122:125], v[8:11], v[82:85]
	v_mfma_f32_16x16x32_bf16 v[86:89], v[126:129], v[8:11], v[86:89]
	v_mfma_f32_16x16x32_bf16 v[90:93], v[130:133], v[8:11], v[90:93]
	v_mfma_f32_16x16x32_bf16 v[94:97], v[134:137], v[8:11], v[94:97]
	v_mfma_f32_16x16x32_bf16 v[98:101], v[118:121], v[8:11], v[98:101]
	ds_read_b128 v[114:117], v37 offset:15360
	ds_read_b128 v[118:121], v37 offset:13312
	ds_read_b128 v[122:125], v37 offset:11264
	ds_read_b128 v[126:129], v37 offset:9216
	v_mfma_f32_16x16x32_bf16 v[102:105], v[138:141], v[8:11], v[102:105]
	v_mfma_f32_16x16x32_bf16 v[106:109], v[142:145], v[8:11], v[106:109]
	ds_read_b128 v[130:133], v37 offset:7168
	ds_read_b128 v[134:137], v37 offset:5120
	ds_read_b128 v[138:141], v37 offset:3072
	ds_read_b128 v[142:145], v37 offset:1024
	v_mfma_f32_16x16x32_bf16 v[110:113], v[146:149], v[8:11], v[110:113]
	s_add_u32 s100, s10, 0x11e28080
	s_addc_u32 s101, s11, 0
	s_mov_b32 m0, s23
	s_nop 0
	global_load_lds_dwordx4 v241, s[100:101]
	s_waitcnt lgkmcnt(0)
	v_mfma_f32_16x16x32_bf16 v[42:45], v[142:145], v[4:7], v[42:45]
	v_mfma_f32_16x16x32_bf16 v[50:53], v[138:141], v[4:7], v[50:53]
	v_mfma_f32_16x16x32_bf16 v[38:41], v[134:137], v[4:7], v[38:41]
	v_mfma_f32_16x16x32_bf16 v[74:77], v[130:133], v[4:7], v[74:77]
	v_mfma_f32_16x16x32_bf16 v[66:69], v[126:129], v[4:7], v[66:69]
	v_mfma_f32_16x16x32_bf16 v[70:73], v[122:125], v[4:7], v[70:73]
	ds_read_b128 v[122:125], v37 offset:33792
	ds_read_b128 v[126:129], v37 offset:35840
	ds_read_b128 v[130:133], v37 offset:37888
	ds_read_b128 v[134:137], v37 offset:39936
	v_mfma_f32_16x16x32_bf16 v[60:63], v[118:121], v[4:7], v[60:63]
	ds_read_b128 v[118:121], v37 offset:41984
	ds_read_b128 v[138:141], v37 offset:44032
	ds_read_b128 v[142:145], v37 offset:46080
	ds_read_b128 v[146:149], v37 offset:48128
	v_mfma_f32_16x16x32_bf16 v[78:81], v[114:117], v[4:7], v[78:81]
	s_add_u32 s100, s10, 0x11e30000
	s_addc_u32 s101, s11, 0
	s_mov_b32 m0, s24
	s_nop 0
	global_load_lds_dwordx4 v241, s[100:101]
	s_waitcnt lgkmcnt(0)
	v_mfma_f32_16x16x32_bf16 v[82:85], v[122:125], v[4:7], v[82:85]
	v_mfma_f32_16x16x32_bf16 v[86:89], v[126:129], v[4:7], v[86:89]
	v_mfma_f32_16x16x32_bf16 v[90:93], v[130:133], v[4:7], v[90:93]
	v_mfma_f32_16x16x32_bf16 v[94:97], v[134:137], v[4:7], v[94:97]
	v_mfma_f32_16x16x32_bf16 v[98:101], v[118:121], v[4:7], v[98:101]
	ds_read_b128 v[114:117], v37 offset:31744
	ds_read_b128 v[118:121], v37 offset:29696
	ds_read_b128 v[122:125], v37 offset:27648
	ds_read_b128 v[126:129], v37 offset:25600
	v_mfma_f32_16x16x32_bf16 v[102:105], v[138:141], v[4:7], v[102:105]
	v_mfma_f32_16x16x32_bf16 v[106:109], v[142:145], v[4:7], v[106:109]
	ds_read_b128 v[130:133], v37 offset:23552
	ds_read_b128 v[134:137], v37 offset:21504
	ds_read_b128 v[138:141], v37 offset:19456
	ds_read_b128 v[142:145], v37 offset:17408
	v_mfma_f32_16x16x32_bf16 v[110:113], v[146:149], v[4:7], v[110:113]
	s_add_u32 s100, s10, 0x11e38000
	s_addc_u32 s101, s11, 0
	s_mov_b32 m0, s25
	s_nop 0
	global_load_lds_dwordx4 v241, s[100:101]
	s_waitcnt lgkmcnt(0)
	v_mfma_f32_16x16x32_bf16 v[42:45], v[142:145], v[0:3], v[42:45]
	v_mfma_f32_16x16x32_bf16 v[50:53], v[138:141], v[0:3], v[50:53]
	v_mfma_f32_16x16x32_bf16 v[38:41], v[134:137], v[0:3], v[38:41]
	v_mfma_f32_16x16x32_bf16 v[74:77], v[130:133], v[0:3], v[74:77]
	v_mfma_f32_16x16x32_bf16 v[66:69], v[126:129], v[0:3], v[66:69]
	v_mfma_f32_16x16x32_bf16 v[70:73], v[122:125], v[0:3], v[70:73]
	ds_read_b128 v[122:125], v37 offset:50176
	ds_read_b128 v[126:129], v37 offset:52224
	ds_read_b128 v[130:133], v37 offset:54272
	ds_read_b128 v[134:137], v37 offset:56320
	v_mfma_f32_16x16x32_bf16 v[60:63], v[118:121], v[0:3], v[60:63]
	ds_read_b128 v[118:121], v37 offset:58368
	ds_read_b128 v[138:141], v37 offset:60416
	ds_read_b128 v[142:145], v37 offset:62464
	ds_read_b128 v[146:149], v37 offset:64512
	v_mfma_f32_16x16x32_bf16 v[78:81], v[114:117], v[0:3], v[78:81]
	s_add_u32 s100, s10, 0x11e30080
	s_addc_u32 s101, s11, 0
	s_mov_b32 m0, s26
	s_nop 0
	global_load_lds_dwordx4 v241, s[100:101]
	s_waitcnt lgkmcnt(0)
	v_mfma_f32_16x16x32_bf16 v[82:85], v[122:125], v[0:3], v[82:85]
	v_mfma_f32_16x16x32_bf16 v[86:89], v[126:129], v[0:3], v[86:89]
	v_mfma_f32_16x16x32_bf16 v[90:93], v[130:133], v[0:3], v[90:93]
	v_mfma_f32_16x16x32_bf16 v[94:97], v[134:137], v[0:3], v[94:97]
	v_mfma_f32_16x16x32_bf16 v[98:101], v[118:121], v[0:3], v[98:101]
	v_mfma_f32_16x16x32_bf16 v[102:105], v[138:141], v[0:3], v[102:105]
	v_mfma_f32_16x16x32_bf16 v[106:109], v[142:145], v[0:3], v[106:109]
	v_mfma_f32_16x16x32_bf16 v[110:113], v[146:149], v[0:3], v[110:113]
	s_add_u32 s100, s10, 0x11e38080
	s_addc_u32 s101, s11, 0
	s_mov_b32 m0, s27
	s_nop 0
	global_load_lds_dwordx4 v241, s[100:101]
	s_mov_b32 s0, 0x1000000
	v_add_co_u32_e32 v34, vcc, s0, v34
	v_mul_f32_e32 v37, v36, v42
	v_mul_f32_e32 v42, v36, v43
	v_mul_f32_e32 v43, v36, v45
	v_addc_co_u32_e32 v35, vcc, 0, v35, vcc
	v_cvt_pk_bf16_f32 v42, v37, v42
	v_mul_f32_e32 v37, v36, v44
	v_cvt_pk_bf16_f32 v43, v37, v43
	global_store_dwordx2 v[34:35], v[42:43], off
	v_mul_f32_e32 v34, v36, v50
	v_mul_f32_e32 v35, v36, v51
	v_cvt_pk_bf16_f32 v34, v34, v35
	v_mul_f32_e32 v35, v36, v52
	v_mul_f32_e32 v37, v36, v53
	v_cvt_pk_bf16_f32 v35, v35, v37
	global_store_dwordx2 v[32:33], v[34:35], off offset:32
	v_mul_f32_e32 v34, v36, v38
	v_mul_f32_e32 v35, v36, v39
	v_cvt_pk_bf16_f32 v34, v34, v35
	v_mul_f32_e32 v35, v36, v40
	v_mul_f32_e32 v37, v36, v41
	v_cvt_pk_bf16_f32 v35, v35, v37
	global_store_dwordx2 v[32:33], v[34:35], off offset:64
	v_mul_f32_e32 v34, v36, v74
	v_mul_f32_e32 v35, v36, v75
	v_cvt_pk_bf16_f32 v34, v34, v35
	v_mul_f32_e32 v35, v36, v76
	v_mul_f32_e32 v37, v36, v77
	v_cvt_pk_bf16_f32 v35, v35, v37
	global_store_dwordx2 v[32:33], v[34:35], off offset:96
	v_mul_f32_e32 v34, v36, v66
	v_mul_f32_e32 v35, v36, v67
	v_cvt_pk_bf16_f32 v34, v34, v35
	v_mul_f32_e32 v35, v36, v68
	v_mul_f32_e32 v37, v36, v69
	v_cvt_pk_bf16_f32 v35, v35, v37
	global_store_dwordx2 v[32:33], v[34:35], off offset:128
	v_mul_f32_e32 v34, v36, v70
	v_mul_f32_e32 v35, v36, v71
	v_cvt_pk_bf16_f32 v34, v34, v35
	v_mul_f32_e32 v35, v36, v72
	v_mul_f32_e32 v37, v36, v73
	v_cvt_pk_bf16_f32 v35, v35, v37
	global_store_dwordx2 v[32:33], v[34:35], off offset:160
	v_mul_f32_e32 v34, v36, v60
	v_mul_f32_e32 v35, v36, v61
	v_cvt_pk_bf16_f32 v34, v34, v35
	v_mul_f32_e32 v35, v36, v62
	v_mul_f32_e32 v37, v36, v63
	v_cvt_pk_bf16_f32 v35, v35, v37
	global_store_dwordx2 v[32:33], v[34:35], off offset:192
	v_mul_f32_e32 v34, v36, v78
	v_mul_f32_e32 v35, v36, v79
	v_cvt_pk_bf16_f32 v34, v34, v35
	v_mul_f32_e32 v35, v36, v80
	v_mul_f32_e32 v37, v36, v81
	v_cvt_pk_bf16_f32 v35, v35, v37
	global_store_dwordx2 v[32:33], v[34:35], off offset:224
	v_mul_f32_e32 v34, v36, v82
	v_mul_f32_e32 v35, v36, v83
	v_cvt_pk_bf16_f32 v34, v34, v35
	v_mul_f32_e32 v35, v36, v84
	v_mul_f32_e32 v37, v36, v85
	v_cvt_pk_bf16_f32 v35, v35, v37
	global_store_dwordx2 v[32:33], v[34:35], off offset:256
	v_mul_f32_e32 v34, v36, v86
	v_mul_f32_e32 v35, v36, v87
	v_cvt_pk_bf16_f32 v34, v34, v35
	v_mul_f32_e32 v35, v36, v88
	v_mul_f32_e32 v37, v36, v89
	v_cvt_pk_bf16_f32 v35, v35, v37
	global_store_dwordx2 v[32:33], v[34:35], off offset:288
	v_mul_f32_e32 v34, v36, v90
	v_mul_f32_e32 v35, v36, v91
	v_cvt_pk_bf16_f32 v34, v34, v35
	v_mul_f32_e32 v35, v36, v92
	v_mul_f32_e32 v37, v36, v93
	v_cvt_pk_bf16_f32 v35, v35, v37
	global_store_dwordx2 v[32:33], v[34:35], off offset:320
	v_mul_f32_e32 v34, v36, v94
	v_mul_f32_e32 v35, v36, v95
	v_cvt_pk_bf16_f32 v34, v34, v35
	v_mul_f32_e32 v35, v36, v96
	v_mul_f32_e32 v37, v36, v97
	v_cvt_pk_bf16_f32 v35, v35, v37
	global_store_dwordx2 v[32:33], v[34:35], off offset:352
	v_mul_f32_e32 v34, v36, v98
	v_mul_f32_e32 v35, v36, v99
	v_cvt_pk_bf16_f32 v34, v34, v35
	v_mul_f32_e32 v35, v36, v100
	v_mul_f32_e32 v37, v36, v101
	v_cvt_pk_bf16_f32 v35, v35, v37
	global_store_dwordx2 v[32:33], v[34:35], off offset:384
	v_mul_f32_e32 v34, v36, v102
	v_mul_f32_e32 v35, v36, v103
	v_cvt_pk_bf16_f32 v34, v34, v35
	v_mul_f32_e32 v35, v36, v104
	v_mul_f32_e32 v37, v36, v105
	v_cvt_pk_bf16_f32 v35, v35, v37
	global_store_dwordx2 v[32:33], v[34:35], off offset:416
	v_mul_f32_e32 v34, v36, v106
	v_mul_f32_e32 v35, v36, v107
	v_cvt_pk_bf16_f32 v34, v34, v35
	v_mul_f32_e32 v35, v36, v108
	v_mul_f32_e32 v37, v36, v109
	v_cvt_pk_bf16_f32 v35, v35, v37
	global_store_dwordx2 v[32:33], v[34:35], off offset:448
	v_mul_f32_e32 v34, v36, v110
	v_mul_f32_e32 v35, v36, v111
	v_cvt_pk_bf16_f32 v34, v34, v35
	v_mul_f32_e32 v35, v36, v112
	v_mul_f32_e32 v37, v36, v113
	v_cvt_pk_bf16_f32 v35, v35, v37
	global_store_dwordx2 v[32:33], v[34:35], off offset:480
	s_waitcnt vmcnt(0)
	s_waitcnt vmcnt(0)
	s_barrier
	ds_read_b128 v[38:41], v65
	ds_read_b128 v[42:45], v65 offset:2048
	ds_read_b128 v[50:53], v65 offset:4096
	ds_read_b128 v[54:57], v65 offset:6144
	ds_read_b128 v[58:61], v65 offset:8192
	ds_read_b128 v[66:69], v65 offset:10240
	ds_read_b128 v[70:73], v65 offset:12288
	ds_read_b128 v[74:77], v65 offset:14336
	ds_read_b128 v[78:81], v65 offset:32768
	ds_read_b128 v[82:85], v65 offset:34816
	ds_read_b128 v[86:89], v65 offset:36864
	ds_read_b128 v[90:93], v65 offset:38912
	ds_read_b128 v[94:97], v65 offset:40960
	ds_read_b128 v[98:101], v65 offset:43008
	ds_read_b128 v[102:105], v65 offset:45056
	ds_read_b128 v[106:109], v65 offset:47104
	s_waitcnt lgkmcnt(0)
	v_mfma_f32_16x16x32_bf16 v[38:41], v[38:41], v[28:31], 0
	v_mfma_f32_16x16x32_bf16 v[42:45], v[42:45], v[28:31], 0
	v_mfma_f32_16x16x32_bf16 v[50:53], v[50:53], v[28:31], 0
	v_mfma_f32_16x16x32_bf16 v[54:57], v[54:57], v[28:31], 0
	v_mfma_f32_16x16x32_bf16 v[58:61], v[58:61], v[28:31], 0
	v_mfma_f32_16x16x32_bf16 v[66:69], v[66:69], v[28:31], 0
	v_mfma_f32_16x16x32_bf16 v[70:73], v[70:73], v[28:31], 0
	v_mfma_f32_16x16x32_bf16 v[74:77], v[74:77], v[28:31], 0
	s_add_u32 s100, s10, 0x11e20100
	s_addc_u32 s101, s11, 0
	s_mov_b32 m0, s19
	s_nop 0
	global_load_lds_dwordx4 v241, s[100:101]
	ds_read_b128 v[110:113], v65 offset:30720
	ds_read_b128 v[114:117], v65 offset:28672
	ds_read_b128 v[118:121], v65 offset:26624
	ds_read_b128 v[122:125], v65 offset:24576
	ds_read_b128 v[126:129], v65 offset:22528
	ds_read_b128 v[130:133], v65 offset:20480
	ds_read_b128 v[134:137], v65 offset:18432
	ds_read_b128 v[138:141], v65 offset:16384
	v_mfma_f32_16x16x32_bf16 v[78:81], v[78:81], v[28:31], 0
	v_mfma_f32_16x16x32_bf16 v[82:85], v[82:85], v[28:31], 0
	v_mfma_f32_16x16x32_bf16 v[86:89], v[86:89], v[28:31], 0
	v_mfma_f32_16x16x32_bf16 v[90:93], v[90:93], v[28:31], 0
	v_mfma_f32_16x16x32_bf16 v[94:97], v[94:97], v[28:31], 0
	v_mfma_f32_16x16x32_bf16 v[98:101], v[98:101], v[28:31], 0
	v_mfma_f32_16x16x32_bf16 v[102:105], v[102:105], v[28:31], 0
	v_mfma_f32_16x16x32_bf16 v[28:31], v[106:109], v[28:31], 0
	s_add_u32 s100, s10, 0x11e28100
	s_addc_u32 s101, s11, 0
	s_mov_b32 m0, s13
	s_nop 0
	global_load_lds_dwordx4 v241, s[100:101]
	s_waitcnt lgkmcnt(0)
	v_mfma_f32_16x16x32_bf16 v[38:41], v[138:141], v[24:27], v[38:41]
	v_mfma_f32_16x16x32_bf16 v[42:45], v[134:137], v[24:27], v[42:45]
	v_mfma_f32_16x16x32_bf16 v[50:53], v[130:133], v[24:27], v[50:53]
	v_mfma_f32_16x16x32_bf16 v[54:57], v[126:129], v[24:27], v[54:57]
	v_mfma_f32_16x16x32_bf16 v[58:61], v[122:125], v[24:27], v[58:61]
	v_mfma_f32_16x16x32_bf16 v[66:69], v[118:121], v[24:27], v[66:69]
	ds_read_b128 v[106:109], v65 offset:49152
	ds_read_b128 v[118:121], v65 offset:51200
	ds_read_b128 v[122:125], v65 offset:53248
	ds_read_b128 v[126:129], v65 offset:55296
	v_mfma_f32_16x16x32_bf16 v[70:73], v[114:117], v[24:27], v[70:73]
	ds_read_b128 v[114:117], v65 offset:57344
	ds_read_b128 v[130:133], v65 offset:59392
	ds_read_b128 v[134:137], v65 offset:61440
	ds_read_b128 v[138:141], v65 offset:63488
	v_mfma_f32_16x16x32_bf16 v[74:77], v[110:113], v[24:27], v[74:77]
	s_add_u32 s100, s10, 0x11e20180
	s_addc_u32 s101, s11, 0
	s_mov_b32 m0, s12
	s_nop 0
	global_load_lds_dwordx4 v241, s[100:101]
	s_waitcnt lgkmcnt(0)
	v_mfma_f32_16x16x32_bf16 v[78:81], v[106:109], v[24:27], v[78:81]
	v_mfma_f32_16x16x32_bf16 v[82:85], v[118:121], v[24:27], v[82:85]
	v_mfma_f32_16x16x32_bf16 v[86:89], v[122:125], v[24:27], v[86:89]
	v_mfma_f32_16x16x32_bf16 v[90:93], v[126:129], v[24:27], v[90:93]
	v_mfma_f32_16x16x32_bf16 v[94:97], v[114:117], v[24:27], v[94:97]
	ds_read_b128 v[106:109], v65 offset:15360
	ds_read_b128 v[110:113], v65 offset:13312
	ds_read_b128 v[114:117], v65 offset:11264
	ds_read_b128 v[118:121], v65 offset:9216
	v_mfma_f32_16x16x32_bf16 v[98:101], v[130:133], v[24:27], v[98:101]
	v_mfma_f32_16x16x32_bf16 v[102:105], v[134:137], v[24:27], v[102:105]
	ds_read_b128 v[122:125], v65 offset:7168
	ds_read_b128 v[126:129], v65 offset:5120
	ds_read_b128 v[130:133], v65 offset:3072
	ds_read_b128 v[134:137], v65 offset:1024
	v_mfma_f32_16x16x32_bf16 v[24:27], v[138:141], v[24:27], v[28:31]
	s_add_u32 s100, s10, 0x11e28180
	s_addc_u32 s101, s11, 0
	s_mov_b32 m0, s14
	s_nop 0
	global_load_lds_dwordx4 v241, s[100:101]
	s_waitcnt lgkmcnt(0)
	v_mfma_f32_16x16x32_bf16 v[28:31], v[134:137], v[20:23], v[38:41]
	v_mfma_f32_16x16x32_bf16 v[38:41], v[130:133], v[20:23], v[42:45]
	v_mfma_f32_16x16x32_bf16 v[42:45], v[126:129], v[20:23], v[50:53]
	v_mfma_f32_16x16x32_bf16 v[50:53], v[122:125], v[20:23], v[54:57]
	v_mfma_f32_16x16x32_bf16 v[54:57], v[118:121], v[20:23], v[58:61]
	v_mfma_f32_16x16x32_bf16 v[58:61], v[114:117], v[20:23], v[66:69]
	s_nop 2
	ds_read_b128 v[66:69], v65 offset:33792
	ds_read_b128 v[114:117], v65 offset:35840
	ds_read_b128 v[118:121], v65 offset:37888
	ds_read_b128 v[122:125], v65 offset:39936
	v_mfma_f32_16x16x32_bf16 v[70:73], v[110:113], v[20:23], v[70:73]
	ds_read_b128 v[110:113], v65 offset:41984
	ds_read_b128 v[126:129], v65 offset:44032
	ds_read_b128 v[130:133], v65 offset:46080
	ds_read_b128 v[134:137], v65 offset:48128
	v_mfma_f32_16x16x32_bf16 v[74:77], v[106:109], v[20:23], v[74:77]
	s_add_u32 s100, s10, 0x11e30100
	s_addc_u32 s101, s11, 0
	s_mov_b32 m0, s15
	s_nop 0
	global_load_lds_dwordx4 v241, s[100:101]
	s_waitcnt lgkmcnt(0)
	v_mfma_f32_16x16x32_bf16 v[66:69], v[66:69], v[20:23], v[78:81]
	v_mfma_f32_16x16x32_bf16 v[78:81], v[114:117], v[20:23], v[82:85]
	v_mfma_f32_16x16x32_bf16 v[82:85], v[118:121], v[20:23], v[86:89]
	v_mfma_f32_16x16x32_bf16 v[86:89], v[122:125], v[20:23], v[90:93]
	v_mfma_f32_16x16x32_bf16 v[90:93], v[110:113], v[20:23], v[94:97]
	v_mfma_f32_16x16x32_bf16 v[94:97], v[126:129], v[20:23], v[98:101]
	s_nop 2
	ds_read_b128 v[98:101], v65 offset:31744
	ds_read_b128 v[106:109], v65 offset:29696
	ds_read_b128 v[110:113], v65 offset:27648
	ds_read_b128 v[114:117], v65 offset:25600
	v_mfma_f32_16x16x32_bf16 v[102:105], v[130:133], v[20:23], v[102:105]
	ds_read_b128 v[118:121], v65 offset:23552
	ds_read_b128 v[122:125], v65 offset:21504
	ds_read_b128 v[126:129], v65 offset:19456
	ds_read_b128 v[130:133], v65 offset:17408
	v_mfma_f32_16x16x32_bf16 v[20:23], v[134:137], v[20:23], v[24:27]
	s_add_u32 s100, s10, 0x11e38100
	s_addc_u32 s101, s11, 0
	s_mov_b32 m0, s16
	s_nop 0
	global_load_lds_dwordx4 v241, s[100:101]
	s_waitcnt lgkmcnt(0)
	v_mfma_f32_16x16x32_bf16 v[24:27], v[130:133], v[16:19], v[28:31]
	v_mfma_f32_16x16x32_bf16 v[28:31], v[126:129], v[16:19], v[38:41]
	v_mfma_f32_16x16x32_bf16 v[38:41], v[122:125], v[16:19], v[42:45]
	v_mfma_f32_16x16x32_bf16 v[42:45], v[118:121], v[16:19], v[50:53]
	v_mfma_f32_16x16x32_bf16 v[50:53], v[114:117], v[16:19], v[54:57]
	v_mfma_f32_16x16x32_bf16 v[54:57], v[110:113], v[16:19], v[58:61]
	s_nop 2
	ds_read_b128 v[58:61], v65 offset:50176
	ds_read_b128 v[110:113], v65 offset:52224
	ds_read_b128 v[114:117], v65 offset:54272
	ds_read_b128 v[118:121], v65 offset:56320
	v_mfma_f32_16x16x32_bf16 v[70:73], v[106:109], v[16:19], v[70:73]
	ds_read_b128 v[106:109], v65 offset:58368
	ds_read_b128 v[122:125], v65 offset:60416
	ds_read_b128 v[126:129], v65 offset:62464
	ds_read_b128 v[62:65], v65 offset:64512
	v_mfma_f32_16x16x32_bf16 v[74:77], v[98:101], v[16:19], v[74:77]
	s_add_u32 s100, s10, 0x11e30180
	s_addc_u32 s101, s11, 0
	s_mov_b32 m0, s17
	s_nop 0
	global_load_lds_dwordx4 v241, s[100:101]
	s_waitcnt lgkmcnt(0)
	v_mfma_f32_16x16x32_bf16 v[58:61], v[58:61], v[16:19], v[66:69]
	v_mfma_f32_16x16x32_bf16 v[66:69], v[110:113], v[16:19], v[78:81]
	v_mfma_f32_16x16x32_bf16 v[78:81], v[114:117], v[16:19], v[82:85]
	v_mfma_f32_16x16x32_bf16 v[82:85], v[118:121], v[16:19], v[86:89]
	v_mfma_f32_16x16x32_bf16 v[86:89], v[106:109], v[16:19], v[90:93]
	v_mfma_f32_16x16x32_bf16 v[90:93], v[122:125], v[16:19], v[94:97]
	v_mfma_f32_16x16x32_bf16 v[94:97], v[126:129], v[16:19], v[102:105]
	v_mfma_f32_16x16x32_bf16 v[16:19], v[62:65], v[16:19], v[20:23]
	s_add_u32 s100, s10, 0x11e38180
	s_addc_u32 s101, s11, 0
	s_mov_b32 m0, s18
	s_nop 0
	global_load_lds_dwordx4 v241, s[100:101]
	s_waitcnt vmcnt(0)
	s_waitcnt vmcnt(0)
	s_barrier
	s_nop 0
	ds_read_b128 v[20:23], v48
	ds_read_b128 v[62:65], v48 offset:2048
	s_waitcnt lgkmcnt(1)
	v_mfma_f32_16x16x32_bf16 v[20:23], v[20:23], v[12:15], v[24:27]
	s_nop 2
	ds_read_b128 v[24:27], v48 offset:4096
	s_waitcnt lgkmcnt(1)
	v_mfma_f32_16x16x32_bf16 v[28:31], v[62:65], v[12:15], v[28:31]
	ds_read_b128 v[62:65], v48 offset:6144
	s_waitcnt lgkmcnt(1)
	v_mfma_f32_16x16x32_bf16 v[24:27], v[24:27], v[12:15], v[38:41]
	s_nop 2
	ds_read_b128 v[38:41], v48 offset:8192
	s_waitcnt lgkmcnt(1)
	v_mfma_f32_16x16x32_bf16 v[42:45], v[62:65], v[12:15], v[42:45]
	ds_read_b128 v[62:65], v48 offset:10240
	s_waitcnt lgkmcnt(1)
	v_mfma_f32_16x16x32_bf16 v[38:41], v[38:41], v[12:15], v[50:53]
	s_nop 2
	ds_read_b128 v[50:53], v48 offset:12288
	ds_read_b128 v[98:101], v48 offset:14336
	s_waitcnt lgkmcnt(2)
	v_mfma_f32_16x16x32_bf16 v[54:57], v[62:65], v[12:15], v[54:57]
	ds_read_b128 v[62:65], v48 offset:32768
	ds_read_b128 v[102:105], v48 offset:34816
	ds_read_b128 v[106:109], v48 offset:36864
	ds_read_b128 v[110:113], v48 offset:38912
	s_waitcnt lgkmcnt(5)
	v_mfma_f32_16x16x32_bf16 v[50:53], v[50:53], v[12:15], v[70:73]
	s_nop 2
	ds_read_b128 v[70:73], v48 offset:40960
	ds_read_b128 v[114:117], v48 offset:43008
	ds_read_b128 v[118:121], v48 offset:45056
	ds_read_b128 v[122:125], v48 offset:47104
	s_waitcnt lgkmcnt(8)
	v_mfma_f32_16x16x32_bf16 v[74:77], v[98:101], v[12:15], v[74:77]
	s_waitcnt lgkmcnt(7)
	v_mfma_f32_16x16x32_bf16 v[58:61], v[62:65], v[12:15], v[58:61]
	s_waitcnt lgkmcnt(6)
	v_mfma_f32_16x16x32_bf16 v[62:65], v[102:105], v[12:15], v[66:69]
	s_waitcnt lgkmcnt(5)
	v_mfma_f32_16x16x32_bf16 v[66:69], v[106:109], v[12:15], v[78:81]
	s_waitcnt lgkmcnt(4)
	v_mfma_f32_16x16x32_bf16 v[78:81], v[110:113], v[12:15], v[82:85]
	s_waitcnt lgkmcnt(3)
	v_mfma_f32_16x16x32_bf16 v[70:73], v[70:73], v[12:15], v[86:89]
	s_waitcnt lgkmcnt(2)
	v_mfma_f32_16x16x32_bf16 v[82:85], v[114:117], v[12:15], v[90:93]
	s_nop 0
	ds_read_b128 v[86:89], v48 offset:30720
	s_nop 0
	ds_read_b128 v[90:93], v48 offset:28672
	ds_read_b128 v[98:101], v48 offset:26624
	ds_read_b128 v[102:105], v48 offset:24576
	s_waitcnt lgkmcnt(5)
	v_mfma_f32_16x16x32_bf16 v[94:97], v[118:121], v[12:15], v[94:97]
	ds_read_b128 v[106:109], v48 offset:22528
	ds_read_b128 v[110:113], v48 offset:20480
	ds_read_b128 v[114:117], v48 offset:18432
	ds_read_b128 v[118:121], v48 offset:16384
	s_waitcnt lgkmcnt(8)
	v_mfma_f32_16x16x32_bf16 v[12:15], v[122:125], v[12:15], v[16:19]
	s_waitcnt lgkmcnt(0)
	v_mfma_f32_16x16x32_bf16 v[16:19], v[118:121], v[8:11], v[20:23]
	v_mfma_f32_16x16x32_bf16 v[20:23], v[114:117], v[8:11], v[28:31]
	v_mfma_f32_16x16x32_bf16 v[24:27], v[110:113], v[8:11], v[24:27]
	v_mfma_f32_16x16x32_bf16 v[28:31], v[106:109], v[8:11], v[42:45]
	v_mfma_f32_16x16x32_bf16 v[38:41], v[102:105], v[8:11], v[38:41]
	v_mfma_f32_16x16x32_bf16 v[42:45], v[98:101], v[8:11], v[54:57]
	s_nop 2
	ds_read_b128 v[54:57], v48 offset:49152
	ds_read_b128 v[98:101], v48 offset:51200
	ds_read_b128 v[102:105], v48 offset:53248
	ds_read_b128 v[106:109], v48 offset:55296
	v_mfma_f32_16x16x32_bf16 v[50:53], v[90:93], v[8:11], v[50:53]
	ds_read_b128 v[90:93], v48 offset:57344
	ds_read_b128 v[110:113], v48 offset:59392
	ds_read_b128 v[114:117], v48 offset:61440
	ds_read_b128 v[118:121], v48 offset:63488
	v_mfma_f32_16x16x32_bf16 v[74:77], v[86:89], v[8:11], v[74:77]
	s_waitcnt lgkmcnt(7)
	v_mfma_f32_16x16x32_bf16 v[54:57], v[54:57], v[8:11], v[58:61]
	s_waitcnt lgkmcnt(6)
	v_mfma_f32_16x16x32_bf16 v[58:61], v[98:101], v[8:11], v[62:65]
	s_waitcnt lgkmcnt(5)
	v_mfma_f32_16x16x32_bf16 v[62:65], v[102:105], v[8:11], v[66:69]
	s_waitcnt lgkmcnt(4)
	v_mfma_f32_16x16x32_bf16 v[66:69], v[106:109], v[8:11], v[78:81]
	s_waitcnt lgkmcnt(3)
	v_mfma_f32_16x16x32_bf16 v[70:73], v[90:93], v[8:11], v[70:73]
	s_waitcnt lgkmcnt(2)
	v_mfma_f32_16x16x32_bf16 v[78:81], v[110:113], v[8:11], v[82:85]
	s_nop 2
	ds_read_b128 v[82:85], v48 offset:15360
	ds_read_b128 v[86:89], v48 offset:13312
	ds_read_b128 v[90:93], v48 offset:11264
	ds_read_b128 v[98:101], v48 offset:9216
	s_waitcnt lgkmcnt(5)
	v_mfma_f32_16x16x32_bf16 v[94:97], v[114:117], v[8:11], v[94:97]
	ds_read_b128 v[102:105], v48 offset:7168
	ds_read_b128 v[106:109], v48 offset:5120
	ds_read_b128 v[110:113], v48 offset:3072
	ds_read_b128 v[114:117], v48 offset:1024
	s_waitcnt lgkmcnt(8)
	v_mfma_f32_16x16x32_bf16 v[8:11], v[118:121], v[8:11], v[12:15]
	s_waitcnt lgkmcnt(0)
	v_mfma_f32_16x16x32_bf16 v[12:15], v[114:117], v[4:7], v[16:19]
	v_mfma_f32_16x16x32_bf16 v[16:19], v[110:113], v[4:7], v[20:23]
	v_mfma_f32_16x16x32_bf16 v[20:23], v[106:109], v[4:7], v[24:27]
	v_mfma_f32_16x16x32_bf16 v[24:27], v[102:105], v[4:7], v[28:31]
	v_mfma_f32_16x16x32_bf16 v[28:31], v[98:101], v[4:7], v[38:41]
	v_mfma_f32_16x16x32_bf16 v[38:41], v[90:93], v[4:7], v[42:45]
	s_nop 2
	ds_read_b128 v[42:45], v48 offset:33792
	ds_read_b128 v[90:93], v48 offset:35840
	ds_read_b128 v[98:101], v48 offset:37888
	ds_read_b128 v[102:105], v48 offset:39936
	v_mfma_f32_16x16x32_bf16 v[50:53], v[86:89], v[4:7], v[50:53]
	ds_read_b128 v[86:89], v48 offset:41984
	ds_read_b128 v[106:109], v48 offset:44032
	ds_read_b128 v[110:113], v48 offset:46080
	ds_read_b128 v[114:117], v48 offset:48128
	v_mfma_f32_16x16x32_bf16 v[74:77], v[82:85], v[4:7], v[74:77]
	s_waitcnt lgkmcnt(7)
	v_mfma_f32_16x16x32_bf16 v[42:45], v[42:45], v[4:7], v[54:57]
	s_waitcnt lgkmcnt(6)
	v_mfma_f32_16x16x32_bf16 v[54:57], v[90:93], v[4:7], v[58:61]
	s_waitcnt lgkmcnt(5)
	v_mfma_f32_16x16x32_bf16 v[58:61], v[98:101], v[4:7], v[62:65]
	s_waitcnt lgkmcnt(4)
	v_mfma_f32_16x16x32_bf16 v[62:65], v[102:105], v[4:7], v[66:69]
	s_waitcnt lgkmcnt(3)
	v_mfma_f32_16x16x32_bf16 v[66:69], v[86:89], v[4:7], v[70:73]
	s_waitcnt lgkmcnt(2)
	v_mfma_f32_16x16x32_bf16 v[70:73], v[106:109], v[4:7], v[78:81]
	s_nop 2
	ds_read_b128 v[78:81], v48 offset:31744
	ds_read_b128 v[82:85], v48 offset:29696
	ds_read_b128 v[86:89], v48 offset:27648
	ds_read_b128 v[90:93], v48 offset:25600
	s_waitcnt lgkmcnt(5)
	v_mfma_f32_16x16x32_bf16 v[94:97], v[110:113], v[4:7], v[94:97]
	ds_read_b128 v[98:101], v48 offset:23552
	ds_read_b128 v[102:105], v48 offset:21504
	ds_read_b128 v[106:109], v48 offset:19456
	ds_read_b128 v[110:113], v48 offset:17408
	s_waitcnt lgkmcnt(8)
	v_mfma_f32_16x16x32_bf16 v[4:7], v[114:117], v[4:7], v[8:11]
	s_waitcnt lgkmcnt(0)
	v_mfma_f32_16x16x32_bf16 v[8:11], v[110:113], v[0:3], v[12:15]
	v_mfma_f32_16x16x32_bf16 v[12:15], v[106:109], v[0:3], v[16:19]
	v_mfma_f32_16x16x32_bf16 v[16:19], v[102:105], v[0:3], v[20:23]
	v_mfma_f32_16x16x32_bf16 v[20:23], v[98:101], v[0:3], v[24:27]
	v_mfma_f32_16x16x32_bf16 v[24:27], v[90:93], v[0:3], v[28:31]
	v_mfma_f32_16x16x32_bf16 v[28:31], v[86:89], v[0:3], v[38:41]
	s_nop 2
	ds_read_b128 v[38:41], v48 offset:50176
	ds_read_b128 v[86:89], v48 offset:52224
	ds_read_b128 v[90:93], v48 offset:54272
	ds_read_b128 v[98:101], v48 offset:56320
	v_mfma_f32_16x16x32_bf16 v[50:53], v[82:85], v[0:3], v[50:53]
	ds_read_b128 v[82:85], v48 offset:58368
	ds_read_b128 v[102:105], v48 offset:60416
	ds_read_b128 v[106:109], v48 offset:62464
	ds_read_b128 v[46:49], v48 offset:64512
	v_mfma_f32_16x16x32_bf16 v[74:77], v[78:81], v[0:3], v[74:77]
	s_waitcnt lgkmcnt(7)
	v_mfma_f32_16x16x32_bf16 v[38:41], v[38:41], v[0:3], v[42:45]
	s_waitcnt lgkmcnt(6)
	v_mfma_f32_16x16x32_bf16 v[42:45], v[86:89], v[0:3], v[54:57]
	s_waitcnt lgkmcnt(5)
	v_mfma_f32_16x16x32_bf16 v[54:57], v[90:93], v[0:3], v[58:61]
	s_waitcnt lgkmcnt(4)
	v_mfma_f32_16x16x32_bf16 v[58:61], v[98:101], v[0:3], v[62:65]
	s_waitcnt lgkmcnt(3)
	v_mfma_f32_16x16x32_bf16 v[62:65], v[82:85], v[0:3], v[66:69]
	s_waitcnt lgkmcnt(2)
	v_mfma_f32_16x16x32_bf16 v[66:69], v[102:105], v[0:3], v[70:73]
	s_waitcnt lgkmcnt(1)
	v_mfma_f32_16x16x32_bf16 v[70:73], v[106:109], v[0:3], v[94:97]
	s_waitcnt lgkmcnt(0)
	v_mfma_f32_16x16x32_bf16 v[0:3], v[46:49], v[0:3], v[4:7]
	s_nop 2
	v_mul_f32_e32 v4, v36, v8
	v_mul_f32_e32 v5, v36, v9
	v_cvt_pk_bf16_f32 v4, v4, v5
	v_mul_f32_e32 v5, v36, v10
	v_mul_f32_e32 v6, v36, v11
	v_cvt_pk_bf16_f32 v5, v5, v6
	global_store_dwordx2 v[32:33], v[4:5], off offset:512
	v_mul_f32_e32 v4, v36, v12
	v_mul_f32_e32 v5, v36, v13
	v_cvt_pk_bf16_f32 v4, v4, v5
	v_mul_f32_e32 v5, v36, v14
	v_mul_f32_e32 v6, v36, v15
	v_cvt_pk_bf16_f32 v5, v5, v6
	global_store_dwordx2 v[32:33], v[4:5], off offset:544
	v_mul_f32_e32 v4, v36, v16
	v_mul_f32_e32 v5, v36, v17
	v_cvt_pk_bf16_f32 v4, v4, v5
	v_mul_f32_e32 v5, v36, v18
	v_mul_f32_e32 v6, v36, v19
	v_cvt_pk_bf16_f32 v5, v5, v6
	global_store_dwordx2 v[32:33], v[4:5], off offset:576
	v_mul_f32_e32 v4, v36, v20
	v_mul_f32_e32 v5, v36, v21
	v_cvt_pk_bf16_f32 v4, v4, v5
	v_mul_f32_e32 v5, v36, v22
	v_mul_f32_e32 v6, v36, v23
	v_cvt_pk_bf16_f32 v5, v5, v6
	global_store_dwordx2 v[32:33], v[4:5], off offset:608
	v_mul_f32_e32 v4, v36, v24
	v_mul_f32_e32 v5, v36, v25
	v_cvt_pk_bf16_f32 v4, v4, v5
	v_mul_f32_e32 v5, v36, v26
	v_mul_f32_e32 v6, v36, v27
	v_cvt_pk_bf16_f32 v5, v5, v6
	global_store_dwordx2 v[32:33], v[4:5], off offset:640
	v_mul_f32_e32 v4, v36, v28
	v_mul_f32_e32 v5, v36, v29
	v_cvt_pk_bf16_f32 v4, v4, v5
	v_mul_f32_e32 v5, v36, v30
	v_mul_f32_e32 v6, v36, v31
	v_cvt_pk_bf16_f32 v5, v5, v6
	global_store_dwordx2 v[32:33], v[4:5], off offset:672
	v_mul_f32_e32 v4, v36, v50
	v_mul_f32_e32 v5, v36, v51
	v_cvt_pk_bf16_f32 v4, v4, v5
	v_mul_f32_e32 v5, v36, v52
	v_mul_f32_e32 v6, v36, v53
	v_cvt_pk_bf16_f32 v5, v5, v6
	global_store_dwordx2 v[32:33], v[4:5], off offset:704
	v_mul_f32_e32 v4, v36, v74
	v_mul_f32_e32 v5, v36, v75
	v_cvt_pk_bf16_f32 v4, v4, v5
	v_mul_f32_e32 v5, v36, v76
	v_mul_f32_e32 v6, v36, v77
	v_cvt_pk_bf16_f32 v5, v5, v6
	global_store_dwordx2 v[32:33], v[4:5], off offset:736
	v_mul_f32_e32 v4, v36, v38
	v_mul_f32_e32 v5, v36, v39
	v_cvt_pk_bf16_f32 v4, v4, v5
	v_mul_f32_e32 v5, v36, v40
	v_mul_f32_e32 v6, v36, v41
	v_cvt_pk_bf16_f32 v5, v5, v6
	global_store_dwordx2 v[32:33], v[4:5], off offset:768
	v_mul_f32_e32 v4, v36, v42
	v_mul_f32_e32 v5, v36, v43
	v_cvt_pk_bf16_f32 v4, v4, v5
	v_mul_f32_e32 v5, v36, v44
	v_mul_f32_e32 v6, v36, v45
	v_cvt_pk_bf16_f32 v5, v5, v6
	global_store_dwordx2 v[32:33], v[4:5], off offset:800
	v_mul_f32_e32 v4, v36, v54
	v_mul_f32_e32 v5, v36, v55
	v_cvt_pk_bf16_f32 v4, v4, v5
	v_mul_f32_e32 v5, v36, v56
	v_mul_f32_e32 v6, v36, v57
	v_cvt_pk_bf16_f32 v5, v5, v6
	global_store_dwordx2 v[32:33], v[4:5], off offset:832
	v_mul_f32_e32 v4, v36, v58
	v_mul_f32_e32 v5, v36, v59
	v_cvt_pk_bf16_f32 v4, v4, v5
	v_mul_f32_e32 v5, v36, v60
	v_mul_f32_e32 v6, v36, v61
	v_cvt_pk_bf16_f32 v5, v5, v6
	global_store_dwordx2 v[32:33], v[4:5], off offset:864
	v_mul_f32_e32 v4, v36, v62
	v_mul_f32_e32 v5, v36, v63
	v_cvt_pk_bf16_f32 v4, v4, v5
	v_mul_f32_e32 v5, v36, v64
	v_mul_f32_e32 v6, v36, v65
	v_cvt_pk_bf16_f32 v5, v5, v6
	global_store_dwordx2 v[32:33], v[4:5], off offset:896
	v_mul_f32_e32 v4, v36, v66
	v_mul_f32_e32 v5, v36, v67
	v_cvt_pk_bf16_f32 v4, v4, v5
	v_mul_f32_e32 v5, v36, v68
	v_mul_f32_e32 v6, v36, v69
	v_cvt_pk_bf16_f32 v5, v5, v6
	global_store_dwordx2 v[32:33], v[4:5], off offset:928
	v_mul_f32_e32 v4, v36, v70
	v_mul_f32_e32 v5, v36, v71
	v_cvt_pk_bf16_f32 v4, v4, v5
	v_mul_f32_e32 v5, v36, v72
	v_mul_f32_e32 v0, v36, v0
	v_mul_f32_e32 v1, v36, v1
	v_mul_f32_e32 v6, v36, v73
	v_cvt_pk_bf16_f32 v5, v5, v6
	global_store_dwordx2 v[32:33], v[4:5], off offset:960
	v_cvt_pk_bf16_f32 v0, v0, v1
	v_mul_f32_e32 v1, v36, v2
	v_mul_f32_e32 v2, v36, v3
	v_cvt_pk_bf16_f32 v1, v1, v2
	global_store_dwordx2 v[32:33], v[0:1], off offset:992
	s_waitcnt vmcnt(0)
	s_barrier

.LBB0_2072:
	s_add_u32 s6, s94, 0x12000000
	s_addc_u32 s7, s95, 0
	s_lshl_b32 s8, s34, 8
	s_add_i32 s8, s8, s42
	v_ashrrev_i32_e32 v128, 1, v201
	s_lshl_b32 s1, s29, 5
	v_or_b32_e32 v198, s8, v144
	s_lshl_b32 s8, s0, 8
	v_and_b32_e32 v200, -8, v128
	s_or_b32 s1, s8, s1
	v_add_u32_e32 v202, s1, v200
	v_ashrrev_i32_e32 v203, 31, v202
	v_lshl_add_u64 v[128:129], v[202:203], 1, s[94:95]
	s_mov_b64 s[8:9], 0xf200000
	v_mov_b32_e32 v199, 0
	v_lshl_add_u64 v[128:129], v[128:129], 0, s[8:9]
	v_lshlrev_b64 v[130:131], 12, v[198:199]
	v_lshl_add_u64 v[130:131], v[128:129], 0, v[130:131]
	s_waitcnt vmcnt(0)
	s_barrier
	global_load_dwordx4 v[208:211], v[130:131], off
	global_load_dwordx4 v[212:215], v[130:131], off offset:256
	v_mov_b32_e32 v197, v199
	v_mov_b32_e32 v195, v199
	v_mov_b32_e32 v193, v199
	v_mov_b32_e32 v191, v199
	v_mov_b32_e32 v189, v199
	v_mov_b32_e32 v187, v199
	v_mov_b32_e32 v185, v199
	v_or_b32_e32 v196, 16, v198
	v_or_b32_e32 v194, 32, v198
	v_or_b32_e32 v192, 48, v198
	v_add_u32_e32 v190, 0x80, v198
	v_add_u32_e32 v188, 0x90, v198
	v_add_u32_e32 v186, 0xa0, v198
	v_add_u32_e32 v184, 0xb0, v198
	v_lshlrev_b64 v[130:131], 12, v[196:197]
	v_lshlrev_b64 v[132:133], 12, v[194:195]
	v_lshlrev_b64 v[134:135], 12, v[192:193]
	v_lshlrev_b64 v[136:137], 12, v[190:191]
	v_lshlrev_b64 v[138:139], 12, v[188:189]
	v_lshlrev_b64 v[140:141], 12, v[186:187]
	v_lshlrev_b64 v[142:143], 12, v[184:185]
	v_lshl_add_u64 v[130:131], v[128:129], 0, v[130:131]
	v_lshl_add_u64 v[132:133], v[128:129], 0, v[132:133]
	v_lshl_add_u64 v[134:135], v[128:129], 0, v[134:135]
	v_lshl_add_u64 v[136:137], v[128:129], 0, v[136:137]
	v_lshl_add_u64 v[138:139], v[128:129], 0, v[138:139]
	v_lshl_add_u64 v[204:205], v[128:129], 0, v[140:141]
	v_lshl_add_u64 v[128:129], v[128:129], 0, v[142:143]
	global_load_dwordx4 v[180:183], v[130:131], off
	global_load_dwordx4 v[176:179], v[130:131], off offset:256
	global_load_dwordx4 v[172:175], v[132:133], off
	global_load_dwordx4 v[168:171], v[132:133], off offset:256
	global_load_dwordx4 v[164:167], v[134:135], off
	global_load_dwordx4 v[160:163], v[134:135], off offset:256
	global_load_dwordx4 v[156:159], v[136:137], off
	global_load_dwordx4 v[152:155], v[136:137], off offset:256
	global_load_dwordx4 v[148:151], v[138:139], off
	global_load_dwordx4 v[144:147], v[138:139], off offset:256
	global_load_dwordx4 v[140:143], v[204:205], off
	s_nop 0
	global_load_dwordx4 v[136:139], v[204:205], off offset:256
	global_load_dwordx4 v[132:135], v[128:129], off
	s_nop 0
	global_load_dwordx4 v[128:131], v[128:129], off offset:256
	v_mbcnt_lo_u32_b32 v204, -1, 0
	v_mbcnt_hi_u32_b32 v207, -1, v204
	v_and_b32_e32 v205, 64, v207
	v_xor_b32_e32 v204, 16, v207
	v_add_u32_e32 v222, 64, v205
	v_cmp_lt_i32_e32 vcc, v204, v222
	s_lshl_b32 s0, s0, 2
	s_mov_b32 s9, 0
	v_cndmask_b32_e32 v204, v207, v204, vcc
	v_lshlrev_b32_e32 v206, 2, v204
	s_ashr_i32 s1, s0, 31
	s_waitcnt vmcnt(0)
	v_lshlrev_b32_e32 v204, 16, v208
	v_lshlrev_b32_e32 v218, 16, v212
	v_and_b32_e32 v219, 0xffff0000, v212
	v_lshlrev_b32_e32 v212, 16, v213
	v_and_b32_e32 v213, 0xffff0000, v213
	v_and_b32_e32 v205, 0xffff0000, v208
	v_lshlrev_b32_e32 v208, 16, v209
	v_and_b32_e32 v209, 0xffff0000, v209
	v_pk_add_f32 v[118:119], v[118:119], v[212:213]
	v_lshlrev_b32_e32 v212, 16, v214
	v_and_b32_e32 v213, 0xffff0000, v214
	v_lshlrev_b32_e32 v216, 16, v210
	v_and_b32_e32 v217, 0xffff0000, v210
	v_pk_add_f32 v[124:125], v[124:125], v[204:205]
	v_pk_add_f32 v[126:127], v[126:127], v[208:209]
	v_pk_add_f32 v[116:117], v[116:117], v[218:219]
	v_pk_add_f32 v[112:113], v[112:113], v[212:213]
	v_lshlrev_b32_e32 v212, 16, v215
	v_and_b32_e32 v213, 0xffff0000, v215
	v_lshlrev_b32_e32 v210, 16, v211
	v_and_b32_e32 v211, 0xffff0000, v211
	v_pk_add_f32 v[120:121], v[120:121], v[216:217]
	v_pk_mul_f32 v[204:205], v[124:125], v[124:125]
	v_pk_mul_f32 v[208:209], v[126:127], v[126:127]
	v_pk_add_f32 v[114:115], v[114:115], v[212:213]
	v_pk_mul_f32 v[212:213], v[116:117], v[116:117]
	v_pk_mul_f32 v[214:215], v[118:119], v[118:119]
	v_pk_add_f32 v[122:123], v[122:123], v[210:211]
	v_pk_mul_f32 v[210:211], v[120:121], v[120:121]
	v_pk_mul_f32 v[218:219], v[112:113], v[112:113]
	v_add_f32_e32 v214, v214, v215
	v_add_f32_e32 v212, v212, v213
	v_add_f32_e32 v208, v208, v209
	v_add_f32_e32 v204, v204, v205
	v_pk_mul_f32 v[216:217], v[122:123], v[122:123]
	v_pk_mul_f32 v[220:221], v[114:115], v[114:115]
	v_add_f32_e32 v212, v212, v214
	v_add_f32_e32 v213, v218, v219
	v_add_f32_e32 v204, v204, v208
	v_add_f32_e32 v205, v210, v211
	v_add_f32_e32 v220, v220, v221
	v_add_f32_e32 v212, v213, v212
	v_add_f32_e32 v213, v216, v217
	v_add_f32_e32 v204, v205, v204
	v_add_f32_e32 v212, v220, v212
	v_add_f32_e32 v204, v213, v204
	v_add_f32_e32 v204, v204, v212
	v_mov_b32_e32 v205, v204
	s_nop 1
	v_permlane16_swap_b32_e32 v205, v204
	v_xor_b32_e32 v208, 32, v207
	v_cmp_lt_i32_e32 vcc, v208, v222
	s_nop 1
	v_cndmask_b32_e32 v207, v207, v208, vcc
	v_lshlrev_b32_e32 v207, 2, v207
	s_waitcnt lgkmcnt(0)
	v_add_f32_e32 v208, v204, v205
	v_mov_b32_e32 v209, v208
	s_nop 1
	v_permlane32_swap_b32_e32 v209, v208
	v_cmp_gt_u32_e32 vcc, 16, v201
	v_lshlrev_b64 v[204:205], 8, v[198:199]
	s_and_saveexec_b64 s[10:11], vcc
	s_cbranch_execz .LBB0_2074
	s_waitcnt lgkmcnt(0)
	v_add_f32_e32 v210, v208, v209
	v_lshl_add_u64 v[208:209], s[6:7], 0, v[204:205]
	v_lshl_add_u64 v[208:209], s[0:1], 2, v[208:209]
	s_lshl_b32 s8, s29, 2
	v_lshl_add_u64 v[208:209], v[208:209], 0, s[8:9]
	global_store_dword v[208:209], v210, off
.LBB0_2074:
	s_or_b64 exec, exec, s[10:11]
	v_lshlrev_b32_e32 v212, 16, v176
	v_and_b32_e32 v213, 0xffff0000, v176
	v_lshlrev_b32_e32 v176, 16, v177
	v_and_b32_e32 v177, 0xffff0000, v177
	v_lshlrev_b32_e32 v208, 16, v180
	s_waitcnt lgkmcnt(0)
	v_and_b32_e32 v209, 0xffff0000, v180
	v_lshlrev_b32_e32 v180, 16, v181
	v_and_b32_e32 v181, 0xffff0000, v181
	v_pk_add_f32 v[102:103], v[102:103], v[176:177]
	v_lshlrev_b32_e32 v176, 16, v178
	v_and_b32_e32 v177, 0xffff0000, v178
	v_pk_add_f32 v[110:111], v[110:111], v[180:181]
	v_lshlrev_b32_e32 v180, 16, v182
	v_and_b32_e32 v181, 0xffff0000, v182
	v_pk_add_f32 v[100:101], v[100:101], v[212:213]
	v_pk_add_f32 v[96:97], v[96:97], v[176:177]
	v_lshlrev_b32_e32 v176, 16, v179
	v_and_b32_e32 v177, 0xffff0000, v179
	v_pk_add_f32 v[108:109], v[108:109], v[208:209]
	v_pk_add_f32 v[104:105], v[104:105], v[180:181]
	v_lshlrev_b32_e32 v180, 16, v183
	v_and_b32_e32 v181, 0xffff0000, v183
	v_pk_add_f32 v[176:177], v[98:99], v[176:177]
	v_pk_mul_f32 v[98:99], v[100:101], v[100:101]
	v_pk_mul_f32 v[178:179], v[102:103], v[102:103]
	v_pk_add_f32 v[106:107], v[106:107], v[180:181]
	v_pk_mul_f32 v[180:181], v[108:109], v[108:109]
	v_pk_mul_f32 v[182:183], v[110:111], v[110:111]
	v_add_f32_e32 v178, v178, v179
	v_add_f32_e32 v98, v98, v99
	v_pk_mul_f32 v[208:209], v[104:105], v[104:105]
	v_pk_mul_f32 v[212:213], v[96:97], v[96:97]
	v_add_f32_e32 v98, v98, v178
	v_add_f32_e32 v178, v182, v183
	v_add_f32_e32 v179, v180, v181
	v_pk_mul_f32 v[210:211], v[106:107], v[106:107]
	v_pk_mul_f32 v[214:215], v[176:177], v[176:177]
	v_add_f32_e32 v99, v212, v213
	v_add_f32_e32 v178, v179, v178
	v_add_f32_e32 v179, v208, v209
	v_add_f32_e32 v214, v214, v215
	v_add_f32_e32 v98, v99, v98
	v_add_f32_e32 v99, v210, v211
	v_add_f32_e32 v178, v179, v178
	v_add_f32_e32 v98, v214, v98
	v_add_f32_e32 v99, v99, v178
	v_add_f32_e32 v98, v99, v98
	v_mov_b32_e32 v99, v98
	s_nop 1
	v_permlane16_swap_b32_e32 v99, v98
	v_lshlrev_b64 v[178:179], 8, v[196:197]
	s_waitcnt lgkmcnt(0)
	v_add_f32_e32 v98, v98, v99
	v_mov_b32_e32 v99, v98
	s_nop 1
	v_permlane32_swap_b32_e32 v99, v98
	s_and_saveexec_b64 s[8:9], vcc
	s_cbranch_execz .LBB0_2076
	s_waitcnt lgkmcnt(0)
	v_add_f32_e32 v180, v98, v99
	v_lshl_add_u64 v[98:99], s[6:7], 0, v[178:179]
	v_lshl_add_u64 v[98:99], s[0:1], 2, v[98:99]
	s_lshl_b32 s10, s29, 2
	s_mov_b32 s11, 0
	v_lshl_add_u64 v[98:99], v[98:99], 0, s[10:11]
	global_store_dword v[98:99], v180, off
.LBB0_2076:
	s_or_b64 exec, exec, s[8:9]
	v_lshlrev_b32_e32 v98, 16, v172
	s_waitcnt lgkmcnt(0)
	v_and_b32_e32 v99, 0xffff0000, v172
	v_lshlrev_b32_e32 v182, 16, v168
	v_and_b32_e32 v183, 0xffff0000, v168
	v_lshlrev_b32_e32 v168, 16, v169
	v_and_b32_e32 v169, 0xffff0000, v169
	v_pk_add_f32 v[92:93], v[92:93], v[98:99]
	v_lshlrev_b32_e32 v98, 16, v173
	v_and_b32_e32 v99, 0xffff0000, v173
	v_pk_add_f32 v[86:87], v[86:87], v[168:169]
	v_lshlrev_b32_e32 v168, 16, v170
	v_and_b32_e32 v169, 0xffff0000, v170
	v_pk_add_f32 v[94:95], v[94:95], v[98:99]
	v_lshlrev_b32_e32 v98, 16, v174
	v_and_b32_e32 v99, 0xffff0000, v174
	v_pk_add_f32 v[84:85], v[84:85], v[182:183]
	v_pk_add_f32 v[80:81], v[80:81], v[168:169]
	v_lshlrev_b32_e32 v168, 16, v171
	v_and_b32_e32 v169, 0xffff0000, v171
	v_pk_add_f32 v[88:89], v[88:89], v[98:99]
	v_lshlrev_b32_e32 v98, 16, v175
	v_and_b32_e32 v99, 0xffff0000, v175
	v_pk_add_f32 v[168:169], v[82:83], v[168:169]
	v_pk_mul_f32 v[82:83], v[84:85], v[84:85]
	v_pk_mul_f32 v[170:171], v[86:87], v[86:87]
	v_pk_add_f32 v[90:91], v[90:91], v[98:99]
	v_pk_mul_f32 v[98:99], v[92:93], v[92:93]
	v_pk_mul_f32 v[172:173], v[94:95], v[94:95]
	v_add_f32_e32 v170, v170, v171
	v_add_f32_e32 v82, v82, v83
	v_pk_mul_f32 v[174:175], v[88:89], v[88:89]
	v_pk_mul_f32 v[182:183], v[80:81], v[80:81]
	v_add_f32_e32 v82, v82, v170
	v_add_f32_e32 v170, v172, v173
	v_add_f32_e32 v98, v98, v99
	v_pk_mul_f32 v[180:181], v[90:91], v[90:91]
	v_pk_mul_f32 v[208:209], v[168:169], v[168:169]
	v_add_f32_e32 v83, v182, v183
	v_add_f32_e32 v98, v98, v170
	v_add_f32_e32 v99, v174, v175
	v_add_f32_e32 v208, v208, v209
	v_add_f32_e32 v82, v83, v82
	v_add_f32_e32 v83, v180, v181
	v_add_f32_e32 v98, v99, v98
	v_add_f32_e32 v82, v208, v82
	v_add_f32_e32 v83, v83, v98
	v_add_f32_e32 v82, v83, v82
	v_mov_b32_e32 v83, v82
	s_nop 1
	v_permlane16_swap_b32_e32 v83, v82
	v_lshlrev_b64 v[170:171], 8, v[194:195]
	s_waitcnt lgkmcnt(0)
	v_add_f32_e32 v82, v82, v83
	v_mov_b32_e32 v83, v82
	s_nop 1
	v_permlane32_swap_b32_e32 v83, v82
	s_and_saveexec_b64 s[8:9], vcc
	s_cbranch_execz .LBB0_2078
	s_waitcnt lgkmcnt(0)
	v_add_f32_e32 v98, v82, v83
	v_lshl_add_u64 v[82:83], s[6:7], 0, v[170:171]
	v_lshl_add_u64 v[82:83], s[0:1], 2, v[82:83]
	s_lshl_b32 s10, s29, 2
	s_mov_b32 s11, 0
	v_lshl_add_u64 v[82:83], v[82:83], 0, s[10:11]
	global_store_dword v[82:83], v98, off
.LBB0_2078:
	s_or_b64 exec, exec, s[8:9]
	v_lshlrev_b32_e32 v82, 16, v164
	s_waitcnt lgkmcnt(0)
	v_and_b32_e32 v83, 0xffff0000, v164
	v_pk_add_f32 v[76:77], v[76:77], v[82:83]
	v_lshlrev_b32_e32 v82, 16, v165
	v_and_b32_e32 v83, 0xffff0000, v165
	v_lshlrev_b32_e32 v172, 16, v160
	v_and_b32_e32 v173, 0xffff0000, v160
	v_lshlrev_b32_e32 v160, 16, v161
	v_and_b32_e32 v161, 0xffff0000, v161
	v_pk_add_f32 v[78:79], v[78:79], v[82:83]
	v_lshlrev_b32_e32 v82, 16, v166
	v_and_b32_e32 v83, 0xffff0000, v166
	v_pk_add_f32 v[70:71], v[70:71], v[160:161]
	v_lshlrev_b32_e32 v160, 16, v162
	v_and_b32_e32 v161, 0xffff0000, v162
	v_pk_add_f32 v[72:73], v[72:73], v[82:83]
	v_lshlrev_b32_e32 v82, 16, v167
	v_and_b32_e32 v83, 0xffff0000, v167
	v_pk_add_f32 v[68:69], v[68:69], v[172:173]
	v_pk_add_f32 v[64:65], v[64:65], v[160:161]
	v_lshlrev_b32_e32 v160, 16, v163
	v_and_b32_e32 v161, 0xffff0000, v163
	v_pk_add_f32 v[74:75], v[74:75], v[82:83]
	v_pk_mul_f32 v[82:83], v[76:77], v[76:77]
	v_pk_mul_f32 v[98:99], v[78:79], v[78:79]
	v_pk_add_f32 v[160:161], v[66:67], v[160:161]
	v_pk_mul_f32 v[66:67], v[68:69], v[68:69]
	v_pk_mul_f32 v[162:163], v[70:71], v[70:71]
	v_pk_mul_f32 v[164:165], v[72:73], v[72:73]
	v_pk_mul_f32 v[172:173], v[64:65], v[64:65]
	v_add_f32_e32 v162, v162, v163
	v_add_f32_e32 v66, v66, v67
	v_add_f32_e32 v98, v98, v99
	v_add_f32_e32 v82, v82, v83
	v_pk_mul_f32 v[166:167], v[74:75], v[74:75]
	v_pk_mul_f32 v[174:175], v[160:161], v[160:161]
	v_add_f32_e32 v66, v66, v162
	v_add_f32_e32 v67, v172, v173
	v_add_f32_e32 v82, v82, v98
	v_add_f32_e32 v83, v164, v165
	v_add_f32_e32 v174, v174, v175
	v_add_f32_e32 v66, v67, v66
	v_add_f32_e32 v67, v166, v167
	v_add_f32_e32 v82, v83, v82
	v_add_f32_e32 v66, v174, v66
	v_add_f32_e32 v67, v67, v82
	v_add_f32_e32 v66, v67, v66
	v_mov_b32_e32 v67, v66
	s_nop 1
	v_permlane16_swap_b32_e32 v67, v66
	v_lshlrev_b64 v[162:163], 8, v[192:193]
	s_waitcnt lgkmcnt(0)
	v_add_f32_e32 v66, v66, v67
	v_mov_b32_e32 v67, v66
	s_nop 1
	v_permlane32_swap_b32_e32 v67, v66
	s_and_saveexec_b64 s[8:9], vcc
	s_cbranch_execz .LBB0_2080
	s_waitcnt lgkmcnt(0)
	v_add_f32_e32 v82, v66, v67
	v_lshl_add_u64 v[66:67], s[6:7], 0, v[162:163]
	v_lshl_add_u64 v[66:67], s[0:1], 2, v[66:67]
	s_lshl_b32 s10, s29, 2
	s_mov_b32 s11, 0
	v_lshl_add_u64 v[66:67], v[66:67], 0, s[10:11]
	global_store_dword v[66:67], v82, off
.LBB0_2080:
	s_or_b64 exec, exec, s[8:9]
	v_lshlrev_b32_e32 v66, 16, v156
	s_waitcnt lgkmcnt(0)
	v_and_b32_e32 v67, 0xffff0000, v156
	v_lshlrev_b32_e32 v98, 16, v152
	v_and_b32_e32 v99, 0xffff0000, v152
	v_pk_add_f32 v[60:61], v[60:61], v[66:67]
	v_lshlrev_b32_e32 v66, 16, v157
	v_and_b32_e32 v67, 0xffff0000, v157
	v_pk_add_f32 v[52:53], v[52:53], v[98:99]
	v_lshlrev_b32_e32 v98, 16, v153
	v_and_b32_e32 v99, 0xffff0000, v153
	v_pk_add_f32 v[62:63], v[62:63], v[66:67]
	v_lshlrev_b32_e32 v66, 16, v158
	v_and_b32_e32 v67, 0xffff0000, v158
	v_pk_add_f32 v[54:55], v[54:55], v[98:99]
	v_lshlrev_b32_e32 v98, 16, v154
	v_and_b32_e32 v99, 0xffff0000, v154
	v_pk_add_f32 v[56:57], v[56:57], v[66:67]
	v_lshlrev_b32_e32 v66, 16, v159
	v_and_b32_e32 v67, 0xffff0000, v159
	v_pk_add_f32 v[48:49], v[48:49], v[98:99]
	v_lshlrev_b32_e32 v98, 16, v155
	v_and_b32_e32 v99, 0xffff0000, v155
	v_pk_add_f32 v[58:59], v[58:59], v[66:67]
	v_pk_mul_f32 v[66:67], v[60:61], v[60:61]
	v_pk_mul_f32 v[82:83], v[62:63], v[62:63]
	v_pk_add_f32 v[98:99], v[50:51], v[98:99]
	v_pk_mul_f32 v[50:51], v[52:53], v[52:53]
	v_pk_mul_f32 v[152:153], v[54:55], v[54:55]
	v_pk_mul_f32 v[156:157], v[56:57], v[56:57]
	v_pk_mul_f32 v[154:155], v[48:49], v[48:49]
	v_add_f32_e32 v152, v152, v153
	v_add_f32_e32 v50, v50, v51
	v_add_f32_e32 v82, v82, v83
	v_add_f32_e32 v66, v66, v67
	v_pk_mul_f32 v[158:159], v[58:59], v[58:59]
	v_pk_mul_f32 v[164:165], v[98:99], v[98:99]
	v_add_f32_e32 v50, v50, v152
	v_add_f32_e32 v51, v154, v155
	v_add_f32_e32 v66, v66, v82
	v_add_f32_e32 v67, v156, v157
	v_add_f32_e32 v164, v164, v165
	v_add_f32_e32 v50, v51, v50
	v_add_f32_e32 v51, v158, v159
	v_add_f32_e32 v66, v67, v66
	v_add_f32_e32 v50, v164, v50
	v_add_f32_e32 v51, v51, v66
	v_add_f32_e32 v50, v51, v50
	v_mov_b32_e32 v51, v50
	s_nop 1
	v_permlane16_swap_b32_e32 v51, v50
	v_lshlrev_b64 v[152:153], 8, v[190:191]
	s_waitcnt lgkmcnt(0)
	v_add_f32_e32 v50, v50, v51
	v_mov_b32_e32 v51, v50
	s_nop 1
	v_permlane32_swap_b32_e32 v51, v50
	s_and_saveexec_b64 s[8:9], vcc
	s_cbranch_execz .LBB0_2082
	s_waitcnt lgkmcnt(0)
	v_add_f32_e32 v66, v50, v51
	v_lshl_add_u64 v[50:51], s[6:7], 0, v[152:153]
	v_lshl_add_u64 v[50:51], s[0:1], 2, v[50:51]
	s_lshl_b32 s10, s29, 2
	s_mov_b32 s11, 0
	v_lshl_add_u64 v[50:51], v[50:51], 0, s[10:11]
	global_store_dword v[50:51], v66, off
.LBB0_2082:
	s_or_b64 exec, exec, s[8:9]
	v_lshlrev_b32_e32 v50, 16, v148
	s_waitcnt lgkmcnt(0)
	v_and_b32_e32 v51, 0xffff0000, v148
	v_lshlrev_b32_e32 v66, 16, v144
	v_and_b32_e32 v67, 0xffff0000, v144
	v_pk_add_f32 v[44:45], v[44:45], v[50:51]
	v_lshlrev_b32_e32 v50, 16, v149
	v_and_b32_e32 v51, 0xffff0000, v149
	v_pk_add_f32 v[36:37], v[36:37], v[66:67]
	v_lshlrev_b32_e32 v66, 16, v145
	v_and_b32_e32 v67, 0xffff0000, v145
	v_pk_add_f32 v[46:47], v[46:47], v[50:51]
	v_lshlrev_b32_e32 v50, 16, v150
	v_and_b32_e32 v51, 0xffff0000, v150
	v_pk_add_f32 v[38:39], v[38:39], v[66:67]
	v_lshlrev_b32_e32 v66, 16, v146
	v_and_b32_e32 v67, 0xffff0000, v146
	v_pk_add_f32 v[40:41], v[40:41], v[50:51]
	v_lshlrev_b32_e32 v50, 16, v151
	v_and_b32_e32 v51, 0xffff0000, v151
	v_pk_add_f32 v[32:33], v[32:33], v[66:67]
	v_lshlrev_b32_e32 v66, 16, v147
	v_and_b32_e32 v67, 0xffff0000, v147
	v_pk_add_f32 v[42:43], v[42:43], v[50:51]
	v_pk_mul_f32 v[50:51], v[44:45], v[44:45]
	v_pk_mul_f32 v[82:83], v[46:47], v[46:47]
	v_pk_add_f32 v[66:67], v[34:35], v[66:67]
	v_pk_mul_f32 v[34:35], v[36:37], v[36:37]
	v_pk_mul_f32 v[144:145], v[38:39], v[38:39]
	v_pk_mul_f32 v[148:149], v[40:41], v[40:41]
	v_pk_mul_f32 v[146:147], v[32:33], v[32:33]
	v_add_f32_e32 v144, v144, v145
	v_add_f32_e32 v34, v34, v35
	v_add_f32_e32 v82, v82, v83
	v_add_f32_e32 v50, v50, v51
	v_pk_mul_f32 v[150:151], v[42:43], v[42:43]
	v_pk_mul_f32 v[154:155], v[66:67], v[66:67]
	v_add_f32_e32 v34, v34, v144
	v_add_f32_e32 v35, v146, v147
	v_add_f32_e32 v50, v50, v82
	v_add_f32_e32 v51, v148, v149
	v_add_f32_e32 v154, v154, v155
	v_add_f32_e32 v34, v35, v34
	v_add_f32_e32 v35, v150, v151
	v_add_f32_e32 v50, v51, v50
	v_add_f32_e32 v34, v154, v34
	v_add_f32_e32 v35, v35, v50
	v_add_f32_e32 v34, v35, v34
	v_mov_b32_e32 v35, v34
	s_nop 1
	v_permlane16_swap_b32_e32 v35, v34
	v_lshlrev_b64 v[144:145], 8, v[188:189]
	s_waitcnt lgkmcnt(0)
	v_add_f32_e32 v34, v34, v35
	v_mov_b32_e32 v35, v34
	s_nop 1
	v_permlane32_swap_b32_e32 v35, v34
	s_and_saveexec_b64 s[8:9], vcc
	s_cbranch_execz .LBB0_2084
	s_waitcnt lgkmcnt(0)
	v_add_f32_e32 v50, v34, v35
	v_lshl_add_u64 v[34:35], s[6:7], 0, v[144:145]
	v_lshl_add_u64 v[34:35], s[0:1], 2, v[34:35]
	s_lshl_b32 s10, s29, 2
	s_mov_b32 s11, 0
	v_lshl_add_u64 v[34:35], v[34:35], 0, s[10:11]
	global_store_dword v[34:35], v50, off
.LBB0_2084:
	s_or_b64 exec, exec, s[8:9]
	v_lshlrev_b32_e32 v34, 16, v140
	s_waitcnt lgkmcnt(0)
	v_and_b32_e32 v35, 0xffff0000, v140
	v_pk_add_f32 v[28:29], v[28:29], v[34:35]
	v_lshlrev_b32_e32 v34, 16, v141
	v_and_b32_e32 v35, 0xffff0000, v141
	v_pk_add_f32 v[30:31], v[30:31], v[34:35]
	v_lshlrev_b32_e32 v34, 16, v142
	v_and_b32_e32 v35, 0xffff0000, v142
	v_pk_add_f32 v[24:25], v[24:25], v[34:35]
	v_lshlrev_b32_e32 v34, 16, v143
	v_and_b32_e32 v35, 0xffff0000, v143
	v_pk_add_f32 v[26:27], v[26:27], v[34:35]
	v_lshlrev_b32_e32 v34, 16, v136
	v_and_b32_e32 v35, 0xffff0000, v136
	v_pk_add_f32 v[20:21], v[20:21], v[34:35]
	v_lshlrev_b32_e32 v34, 16, v137
	v_and_b32_e32 v35, 0xffff0000, v137
	v_pk_add_f32 v[22:23], v[22:23], v[34:35]
	v_lshlrev_b32_e32 v34, 16, v138
	v_and_b32_e32 v35, 0xffff0000, v138
	v_pk_add_f32 v[16:17], v[16:17], v[34:35]
	v_lshlrev_b32_e32 v34, 16, v139
	v_and_b32_e32 v35, 0xffff0000, v139
	v_pk_mul_f32 v[50:51], v[28:29], v[28:29]
	v_pk_mul_f32 v[82:83], v[30:31], v[30:31]
	v_pk_add_f32 v[34:35], v[18:19], v[34:35]
	v_pk_mul_f32 v[18:19], v[20:21], v[20:21]
	v_pk_mul_f32 v[136:137], v[22:23], v[22:23]
	v_pk_mul_f32 v[140:141], v[24:25], v[24:25]
	v_pk_mul_f32 v[138:139], v[16:17], v[16:17]
	v_add_f32_e32 v136, v136, v137
	v_add_f32_e32 v18, v18, v19
	v_add_f32_e32 v82, v82, v83
	v_add_f32_e32 v50, v50, v51
	v_pk_mul_f32 v[142:143], v[26:27], v[26:27]
	v_pk_mul_f32 v[146:147], v[34:35], v[34:35]
	v_add_f32_e32 v18, v18, v136
	v_add_f32_e32 v19, v138, v139
	v_add_f32_e32 v50, v50, v82
	v_add_f32_e32 v51, v140, v141
	v_add_f32_e32 v146, v146, v147
	v_add_f32_e32 v18, v19, v18
	v_add_f32_e32 v19, v142, v143
	v_add_f32_e32 v50, v51, v50
	v_add_f32_e32 v18, v146, v18
	v_add_f32_e32 v19, v19, v50
	v_add_f32_e32 v18, v19, v18
	v_mov_b32_e32 v19, v18
	s_nop 1
	v_permlane16_swap_b32_e32 v19, v18
	v_lshlrev_b64 v[140:141], 8, v[186:187]
	s_waitcnt lgkmcnt(0)
	v_add_f32_e32 v18, v18, v19
	v_mov_b32_e32 v19, v18
	s_nop 1
	v_permlane32_swap_b32_e32 v19, v18
	s_and_saveexec_b64 s[8:9], vcc
	s_cbranch_execz .LBB0_2086
	s_waitcnt lgkmcnt(0)
	v_add_f32_e32 v50, v18, v19
	v_lshl_add_u64 v[18:19], s[6:7], 0, v[140:141]
	v_lshl_add_u64 v[18:19], s[0:1], 2, v[18:19]
	s_lshl_b32 s10, s29, 2
	s_mov_b32 s11, 0
	v_lshl_add_u64 v[18:19], v[18:19], 0, s[10:11]
	global_store_dword v[18:19], v50, off
.LBB0_2086:
	s_or_b64 exec, exec, s[8:9]
	v_lshlrev_b32_e32 v18, 16, v132
	s_waitcnt lgkmcnt(0)
	v_and_b32_e32 v19, 0xffff0000, v132
	v_pk_add_f32 v[18:19], v[12:13], v[18:19]
	v_lshlrev_b32_e32 v12, 16, v133
	v_and_b32_e32 v13, 0xffff0000, v133
	v_pk_add_f32 v[82:83], v[14:15], v[12:13]
	v_lshlrev_b32_e32 v12, 16, v134
	v_and_b32_e32 v13, 0xffff0000, v134
	v_pk_add_f32 v[50:51], v[8:9], v[12:13]
	v_lshlrev_b32_e32 v8, 16, v135
	v_and_b32_e32 v9, 0xffff0000, v135
	v_lshlrev_b32_e32 v134, 16, v128
	v_and_b32_e32 v135, 0xffff0000, v128
	v_pk_add_f32 v[134:135], v[4:5], v[134:135]
	v_lshlrev_b32_e32 v4, 16, v129
	v_and_b32_e32 v5, 0xffff0000, v129
	v_pk_add_f32 v[136:137], v[6:7], v[4:5]
	v_lshlrev_b32_e32 v4, 16, v130
	v_and_b32_e32 v5, 0xffff0000, v130
	v_pk_add_f32 v[128:129], v[0:1], v[4:5]
	v_lshlrev_b32_e32 v0, 16, v131
	v_and_b32_e32 v1, 0xffff0000, v131
	v_pk_add_f32 v[130:131], v[2:3], v[0:1]
	v_pk_mul_f32 v[0:1], v[134:135], v[134:135]
	v_pk_mul_f32 v[2:3], v[136:137], v[136:137]
	v_pk_add_f32 v[132:133], v[10:11], v[8:9]
	v_pk_mul_f32 v[8:9], v[18:19], v[18:19]
	v_pk_mul_f32 v[10:11], v[82:83], v[82:83]
	v_add_f32_e32 v2, v2, v3
	v_add_f32_e32 v0, v0, v1
	v_pk_mul_f32 v[12:13], v[50:51], v[50:51]
	v_pk_mul_f32 v[4:5], v[128:129], v[128:129]
	v_add_f32_e32 v0, v0, v2
	v_add_f32_e32 v2, v10, v11
	v_add_f32_e32 v3, v8, v9
	v_pk_mul_f32 v[14:15], v[132:133], v[132:133]
	v_pk_mul_f32 v[6:7], v[130:131], v[130:131]
	v_add_f32_e32 v1, v4, v5
	v_add_f32_e32 v2, v3, v2
	v_add_f32_e32 v3, v12, v13
	v_add_f32_e32 v6, v6, v7
	v_add_f32_e32 v0, v1, v0
	v_add_f32_e32 v1, v14, v15
	v_add_f32_e32 v2, v3, v2
	v_add_f32_e32 v0, v6, v0
	v_add_f32_e32 v1, v1, v2
	v_add_f32_e32 v0, v1, v0
	v_mov_b32_e32 v1, v0
	s_nop 1
	v_permlane16_swap_b32_e32 v1, v0
	v_lshlrev_b64 v[138:139], 8, v[184:185]
	s_waitcnt lgkmcnt(0)
	v_add_f32_e32 v0, v0, v1
	v_mov_b32_e32 v1, v0
	s_nop 1
	v_permlane32_swap_b32_e32 v1, v0
	s_and_saveexec_b64 s[8:9], vcc
	s_cbranch_execz .LBB0_2088
	s_waitcnt lgkmcnt(0)
	v_add_f32_e32 v2, v0, v1
	v_lshl_add_u64 v[0:1], s[6:7], 0, v[138:139]
	v_lshl_add_u64 v[0:1], s[0:1], 2, v[0:1]
	s_lshl_b32 s0, s29, 2
	s_mov_b32 s1, 0
	v_lshl_add_u64 v[0:1], v[0:1], 0, s[0:1]
	global_store_dword v[0:1], v2, off

.LBB0_2160:
	v_ashrrev_i32_e32 v201, 31, v200
	v_lshl_add_u64 v[0:1], s[6:7], 0, v[204:205]
	v_lshlrev_b64 v[146:147], 2, v[200:201]
	v_lshl_add_u64 v[0:1], v[0:1], 0, v[146:147]
	global_load_dwordx4 v[148:151], v[0:1], off
	global_load_dwordx4 v[154:157], v[0:1], off offset:16
	v_lshlrev_b64 v[142:143], 2, v[202:203]
	v_lshl_add_u64 v[0:1], s[2:3], 0, v[142:143]
	global_load_dwordx4 v[12:15], v[0:1], off
	global_load_dwordx4 v[8:11], v[0:1], off offset:16
	global_load_dwordx4 v[4:7], v[0:1], off offset:512
	s_nop 0
	global_load_dwordx4 v[0:3], v[0:1], off offset:528
	s_waitcnt vmcnt(5)
	v_mov_b32_e32 v158, v149
	v_mov_b32_e32 v159, v150
	v_mov_b32_e32 v149, v151
	s_waitcnt vmcnt(4)
	v_mov_b32_e32 v150, v156
	v_mov_b32_e32 v151, v154
	v_mov_b32_e32 v154, v157
	v_pk_add_f32 v[148:149], v[158:159], v[148:149]
	v_pk_add_f32 v[150:151], v[150:151], v[154:155]
	v_add_f32_e32 v148, v148, v149
	v_add_f32_e32 v148, v148, v151
	v_add_f32_e32 v148, v150, v148
	v_mov_b32_e32 v149, v148
	s_nop 1
	v_permlane16_swap_b32_e32 v149, v148
	v_lshlrev_b64 v[150:151], 13, v[198:199]
	v_lshl_add_u64 v[150:151], s[92:93], 0, v[150:151]
	v_lshl_add_u64 v[154:155], s[6:7], 0, v[178:179]
	v_lshl_add_u64 v[150:151], v[150:151], 0, v[142:143]
	s_waitcnt lgkmcnt(0)
	v_add_f32_e32 v149, v148, v149
	v_mov_b32_e32 v156, v149
	s_nop 1
	v_permlane32_swap_b32_e32 v156, v149
	v_mov_b32_e32 v148, 0x358637bd
	v_lshl_add_u64 v[154:155], v[154:155], 0, v[146:147]
	s_waitcnt lgkmcnt(0)
	v_add_f32_e32 v149, v149, v156
	v_fmamk_f32 v149, v149, 0x3a000000, v148
	v_rsq_f32_e32 v156, v149
	s_nop 0
	v_pk_mul_f32 v[124:125], v[124:125], v[156:157] op_sel_hi:[1,0]
	v_pk_mul_f32 v[126:127], v[126:127], v[156:157] op_sel_hi:[1,0]
	v_pk_mul_f32 v[120:121], v[120:121], v[156:157] op_sel_hi:[1,0]
	v_pk_mul_f32 v[122:123], v[122:123], v[156:157] op_sel_hi:[1,0]
	v_pk_mul_f32 v[158:159], v[116:117], v[156:157] op_sel_hi:[1,0]
	v_pk_mul_f32 v[164:165], v[118:119], v[156:157] op_sel_hi:[1,0]
	v_pk_mul_f32 v[166:167], v[112:113], v[156:157] op_sel_hi:[1,0]
	v_pk_mul_f32 v[156:157], v[114:115], v[156:157] op_sel_hi:[1,0]
	s_waitcnt vmcnt(3)
	v_pk_mul_f32 v[114:115], v[14:15], v[126:127]
	v_pk_mul_f32 v[112:113], v[12:13], v[124:125]
	s_waitcnt vmcnt(2)
	v_pk_mul_f32 v[118:119], v[10:11], v[122:123]
	v_pk_mul_f32 v[116:117], v[8:9], v[120:121]
	s_waitcnt vmcnt(1)
	v_pk_mul_f32 v[122:123], v[6:7], v[164:165]
	v_pk_mul_f32 v[120:121], v[4:5], v[158:159]
	s_waitcnt vmcnt(0)
	v_pk_mul_f32 v[126:127], v[2:3], v[156:157]
	v_pk_mul_f32 v[124:125], v[0:1], v[166:167]
	global_store_dwordx4 v[150:151], v[112:115], off
	global_store_dwordx4 v[150:151], v[116:119], off offset:16
	global_store_dwordx4 v[150:151], v[120:123], off offset:512
	global_store_dwordx4 v[150:151], v[124:127], off offset:528
	global_load_dwordx4 v[112:115], v[154:155], off
	s_nop 0
	global_load_dwordx4 v[116:119], v[154:155], off offset:16
	s_waitcnt vmcnt(1)
	v_mov_b32_e32 v120, v113
	v_mov_b32_e32 v121, v114
	v_mov_b32_e32 v113, v115
	s_waitcnt vmcnt(0)
	v_mov_b32_e32 v114, v118
	v_mov_b32_e32 v115, v116
	v_mov_b32_e32 v116, v119
	v_pk_add_f32 v[112:113], v[120:121], v[112:113]
	v_pk_add_f32 v[114:115], v[114:115], v[116:117]
	v_add_f32_e32 v112, v112, v113
	v_add_f32_e32 v112, v112, v115
	v_add_f32_e32 v112, v114, v112
	v_mov_b32_e32 v113, v112
	s_nop 1
	v_permlane16_swap_b32_e32 v113, v112
	v_lshl_add_u64 v[114:115], s[6:7], 0, v[170:171]
	v_lshl_add_u64 v[120:121], v[114:115], 0, v[146:147]
	s_waitcnt lgkmcnt(0)
	v_add_f32_e32 v116, v112, v113
	ds_bpermute_b32 v117, v207, v116
	v_lshlrev_b64 v[112:113], 13, v[196:197]
	v_lshl_add_u64 v[112:113], s[92:93], 0, v[112:113]
	v_lshl_add_u64 v[118:119], v[112:113], 0, v[142:143]
	s_waitcnt lgkmcnt(0)
	v_add_f32_e32 v116, v116, v117
	v_fmamk_f32 v116, v116, 0x3a000000, v148
	v_rsq_f32_e32 v116, v116
	s_nop 0
	v_pk_mul_f32 v[108:109], v[108:109], v[116:117] op_sel_hi:[1,0]
	v_pk_mul_f32 v[110:111], v[110:111], v[116:117] op_sel_hi:[1,0]
	v_pk_mul_f32 v[104:105], v[104:105], v[116:117] op_sel_hi:[1,0]
	v_pk_mul_f32 v[106:107], v[106:107], v[116:117] op_sel_hi:[1,0]
	v_pk_mul_f32 v[112:113], v[100:101], v[116:117] op_sel_hi:[1,0]
	v_pk_mul_f32 v[114:115], v[102:103], v[116:117] op_sel_hi:[1,0]
	v_pk_mul_f32 v[96:97], v[96:97], v[116:117] op_sel_hi:[1,0]
	v_pk_mul_f32 v[116:117], v[176:177], v[116:117] op_sel_hi:[1,0]
	v_pk_mul_f32 v[102:103], v[14:15], v[110:111]
	v_pk_mul_f32 v[100:101], v[12:13], v[108:109]
	v_pk_mul_f32 v[106:107], v[10:11], v[106:107]
	v_pk_mul_f32 v[104:105], v[8:9], v[104:105]
	v_pk_mul_f32 v[110:111], v[6:7], v[114:115]
	v_pk_mul_f32 v[108:109], v[4:5], v[112:113]
	v_pk_mul_f32 v[114:115], v[2:3], v[116:117]
	v_pk_mul_f32 v[112:113], v[0:1], v[96:97]
	global_store_dwordx4 v[118:119], v[100:103], off
	global_store_dwordx4 v[118:119], v[104:107], off offset:16
	global_store_dwordx4 v[118:119], v[108:111], off offset:512
	global_store_dwordx4 v[118:119], v[112:115], off offset:528
	global_load_dwordx4 v[100:103], v[120:121], off
	s_nop 0
	global_load_dwordx4 v[104:107], v[120:121], off offset:16
	s_waitcnt vmcnt(1)
	v_mov_b32_e32 v96, v101
	v_mov_b32_e32 v97, v102
	v_mov_b32_e32 v101, v103
	s_waitcnt vmcnt(0)
	v_mov_b32_e32 v102, v106
	v_mov_b32_e32 v103, v104
	v_mov_b32_e32 v104, v107
	v_pk_add_f32 v[96:97], v[96:97], v[100:101]
	v_pk_add_f32 v[100:101], v[102:103], v[104:105]
	v_add_f32_e32 v96, v96, v97
	v_add_f32_e32 v96, v96, v101
	v_add_f32_e32 v96, v100, v96
	v_mov_b32_e32 v97, v96
	s_nop 1
	v_permlane16_swap_b32_e32 v97, v96
	v_lshl_add_u64 v[100:101], s[6:7], 0, v[162:163]
	v_lshl_add_u64 v[104:105], v[100:101], 0, v[146:147]
	s_waitcnt lgkmcnt(0)
	v_add_f32_e32 v102, v96, v97
	ds_bpermute_b32 v103, v207, v102
	v_lshlrev_b64 v[96:97], 13, v[194:195]
	v_lshl_add_u64 v[96:97], s[92:93], 0, v[96:97]
	v_lshl_add_u64 v[96:97], v[96:97], 0, v[142:143]
	s_waitcnt lgkmcnt(0)
	v_add_f32_e32 v102, v102, v103
	v_fmamk_f32 v102, v102, 0x3a000000, v148
	v_rsq_f32_e32 v102, v102
	s_nop 0
	v_pk_mul_f32 v[92:93], v[92:93], v[102:103] op_sel_hi:[1,0]
	v_pk_mul_f32 v[94:95], v[94:95], v[102:103] op_sel_hi:[1,0]
	v_pk_mul_f32 v[88:89], v[88:89], v[102:103] op_sel_hi:[1,0]
	v_pk_mul_f32 v[90:91], v[90:91], v[102:103] op_sel_hi:[1,0]
	v_pk_mul_f32 v[100:101], v[84:85], v[102:103] op_sel_hi:[1,0]
	v_pk_mul_f32 v[106:107], v[86:87], v[102:103] op_sel_hi:[1,0]
	v_pk_mul_f32 v[80:81], v[80:81], v[102:103] op_sel_hi:[1,0]
	v_pk_mul_f32 v[102:103], v[168:169], v[102:103] op_sel_hi:[1,0]
	v_pk_mul_f32 v[86:87], v[14:15], v[94:95]
	v_pk_mul_f32 v[84:85], v[12:13], v[92:93]
	v_pk_mul_f32 v[90:91], v[10:11], v[90:91]
	v_pk_mul_f32 v[88:89], v[8:9], v[88:89]
	v_pk_mul_f32 v[94:95], v[6:7], v[106:107]
	v_pk_mul_f32 v[92:93], v[4:5], v[100:101]
	v_pk_mul_f32 v[102:103], v[2:3], v[102:103]
	v_pk_mul_f32 v[100:101], v[0:1], v[80:81]
	global_store_dwordx4 v[96:97], v[84:87], off
	global_store_dwordx4 v[96:97], v[88:91], off offset:16
	global_store_dwordx4 v[96:97], v[92:95], off offset:512
	global_store_dwordx4 v[96:97], v[100:103], off offset:528
	global_load_dwordx4 v[84:87], v[104:105], off
	s_nop 0
	global_load_dwordx4 v[88:91], v[104:105], off offset:16
	s_waitcnt vmcnt(1)
	v_mov_b32_e32 v80, v85
	v_mov_b32_e32 v81, v86
	v_mov_b32_e32 v85, v87
	s_waitcnt vmcnt(0)
	v_mov_b32_e32 v86, v90
	v_mov_b32_e32 v87, v88
	v_mov_b32_e32 v88, v91
	v_pk_add_f32 v[80:81], v[80:81], v[84:85]
	v_pk_add_f32 v[84:85], v[86:87], v[88:89]
	v_add_f32_e32 v80, v80, v81
	v_add_f32_e32 v80, v80, v85
	v_add_f32_e32 v80, v84, v80
	v_mov_b32_e32 v81, v80
	s_nop 1
	v_permlane16_swap_b32_e32 v81, v80
	v_lshl_add_u64 v[84:85], s[6:7], 0, v[152:153]
	v_lshl_add_u64 v[88:89], v[84:85], 0, v[146:147]
	s_waitcnt lgkmcnt(0)
	v_add_f32_e32 v86, v80, v81
	ds_bpermute_b32 v87, v207, v86
	v_lshlrev_b64 v[80:81], 13, v[192:193]
	v_lshl_add_u64 v[80:81], s[92:93], 0, v[80:81]
	v_lshl_add_u64 v[80:81], v[80:81], 0, v[142:143]
	s_waitcnt lgkmcnt(0)
	v_add_f32_e32 v86, v86, v87
	v_fmamk_f32 v86, v86, 0x3a000000, v148
	v_rsq_f32_e32 v86, v86
	s_nop 0
	v_pk_mul_f32 v[76:77], v[76:77], v[86:87] op_sel_hi:[1,0]
	v_pk_mul_f32 v[78:79], v[78:79], v[86:87] op_sel_hi:[1,0]
	v_pk_mul_f32 v[72:73], v[72:73], v[86:87] op_sel_hi:[1,0]
	v_pk_mul_f32 v[74:75], v[74:75], v[86:87] op_sel_hi:[1,0]
	v_pk_mul_f32 v[84:85], v[68:69], v[86:87] op_sel_hi:[1,0]
	v_pk_mul_f32 v[90:91], v[70:71], v[86:87] op_sel_hi:[1,0]
	v_pk_mul_f32 v[64:65], v[64:65], v[86:87] op_sel_hi:[1,0]
	v_pk_mul_f32 v[86:87], v[160:161], v[86:87] op_sel_hi:[1,0]
	v_pk_mul_f32 v[70:71], v[14:15], v[78:79]
	v_pk_mul_f32 v[68:69], v[12:13], v[76:77]
	v_pk_mul_f32 v[74:75], v[10:11], v[74:75]
	v_pk_mul_f32 v[72:73], v[8:9], v[72:73]
	v_pk_mul_f32 v[78:79], v[6:7], v[90:91]
	v_pk_mul_f32 v[76:77], v[4:5], v[84:85]
	v_pk_mul_f32 v[86:87], v[2:3], v[86:87]
	v_pk_mul_f32 v[84:85], v[0:1], v[64:65]
	global_store_dwordx4 v[80:81], v[68:71], off
	global_store_dwordx4 v[80:81], v[72:75], off offset:16
	global_store_dwordx4 v[80:81], v[76:79], off offset:512
	global_store_dwordx4 v[80:81], v[84:87], off offset:528
	global_load_dwordx4 v[68:71], v[88:89], off
	s_nop 0
	global_load_dwordx4 v[72:75], v[88:89], off offset:16
	s_waitcnt vmcnt(1)
	v_mov_b32_e32 v64, v69
	v_mov_b32_e32 v65, v70
	v_mov_b32_e32 v69, v71
	s_waitcnt vmcnt(0)
	v_mov_b32_e32 v70, v74
	v_mov_b32_e32 v71, v72
	v_mov_b32_e32 v72, v75
	v_pk_add_f32 v[64:65], v[64:65], v[68:69]
	v_pk_add_f32 v[68:69], v[70:71], v[72:73]
	v_add_f32_e32 v64, v64, v65
	v_add_f32_e32 v64, v64, v69
	v_add_f32_e32 v64, v68, v64
	v_mov_b32_e32 v65, v64
	s_nop 1
	v_permlane16_swap_b32_e32 v65, v64
	v_lshl_add_u64 v[68:69], s[6:7], 0, v[144:145]
	v_lshl_add_u64 v[72:73], v[68:69], 0, v[146:147]
	s_waitcnt lgkmcnt(0)
	v_add_f32_e32 v70, v64, v65
	ds_bpermute_b32 v71, v207, v70
	v_lshlrev_b64 v[64:65], 13, v[190:191]
	v_lshl_add_u64 v[64:65], s[92:93], 0, v[64:65]
	v_lshl_add_u64 v[64:65], v[64:65], 0, v[142:143]
	s_waitcnt lgkmcnt(0)
	v_add_f32_e32 v70, v70, v71
	v_fmamk_f32 v70, v70, 0x3a000000, v148
	v_rsq_f32_e32 v70, v70
	s_nop 0
	v_pk_mul_f32 v[60:61], v[60:61], v[70:71] op_sel_hi:[1,0]
	v_pk_mul_f32 v[62:63], v[62:63], v[70:71] op_sel_hi:[1,0]
	v_pk_mul_f32 v[56:57], v[56:57], v[70:71] op_sel_hi:[1,0]
	v_pk_mul_f32 v[58:59], v[58:59], v[70:71] op_sel_hi:[1,0]
	v_pk_mul_f32 v[68:69], v[52:53], v[70:71] op_sel_hi:[1,0]
	v_pk_mul_f32 v[74:75], v[54:55], v[70:71] op_sel_hi:[1,0]
	v_pk_mul_f32 v[48:49], v[48:49], v[70:71] op_sel_hi:[1,0]
	v_pk_mul_f32 v[70:71], v[98:99], v[70:71] op_sel_hi:[1,0]
	v_pk_mul_f32 v[54:55], v[14:15], v[62:63]
	v_pk_mul_f32 v[52:53], v[12:13], v[60:61]
	v_pk_mul_f32 v[58:59], v[10:11], v[58:59]
	v_pk_mul_f32 v[56:57], v[8:9], v[56:57]
	v_pk_mul_f32 v[62:63], v[6:7], v[74:75]
	v_pk_mul_f32 v[60:61], v[4:5], v[68:69]
	v_pk_mul_f32 v[70:71], v[2:3], v[70:71]
	v_pk_mul_f32 v[68:69], v[0:1], v[48:49]
	global_store_dwordx4 v[64:65], v[52:55], off
	global_store_dwordx4 v[64:65], v[56:59], off offset:16
	global_store_dwordx4 v[64:65], v[60:63], off offset:512
	global_store_dwordx4 v[64:65], v[68:71], off offset:528
	global_load_dwordx4 v[52:55], v[72:73], off
	s_nop 0
	global_load_dwordx4 v[56:59], v[72:73], off offset:16
	s_waitcnt vmcnt(1)
	v_mov_b32_e32 v48, v53
	v_mov_b32_e32 v49, v54
	v_mov_b32_e32 v53, v55
	s_waitcnt vmcnt(0)
	v_mov_b32_e32 v54, v58
	v_mov_b32_e32 v55, v56
	v_mov_b32_e32 v56, v59
	v_pk_add_f32 v[48:49], v[48:49], v[52:53]
	v_pk_add_f32 v[52:53], v[54:55], v[56:57]
	v_add_f32_e32 v48, v48, v49
	v_add_f32_e32 v48, v48, v53
	v_add_f32_e32 v48, v52, v48
	v_mov_b32_e32 v49, v48
	s_nop 1
	v_permlane16_swap_b32_e32 v49, v48
	v_lshl_add_u64 v[52:53], s[6:7], 0, v[140:141]
	v_lshl_add_u64 v[56:57], v[52:53], 0, v[146:147]
	s_waitcnt lgkmcnt(0)
	v_add_f32_e32 v54, v48, v49
	ds_bpermute_b32 v55, v207, v54
	v_lshlrev_b64 v[48:49], 13, v[188:189]
	v_lshl_add_u64 v[48:49], s[92:93], 0, v[48:49]
	v_lshl_add_u64 v[48:49], v[48:49], 0, v[142:143]
	s_waitcnt lgkmcnt(0)
	v_add_f32_e32 v54, v54, v55
	v_fmamk_f32 v54, v54, 0x3a000000, v148
	v_rsq_f32_e32 v54, v54
	s_nop 0
	v_pk_mul_f32 v[44:45], v[44:45], v[54:55] op_sel_hi:[1,0]
	v_pk_mul_f32 v[46:47], v[46:47], v[54:55] op_sel_hi:[1,0]
	v_pk_mul_f32 v[40:41], v[40:41], v[54:55] op_sel_hi:[1,0]
	v_pk_mul_f32 v[42:43], v[42:43], v[54:55] op_sel_hi:[1,0]
	v_pk_mul_f32 v[52:53], v[36:37], v[54:55] op_sel_hi:[1,0]
	v_pk_mul_f32 v[58:59], v[38:39], v[54:55] op_sel_hi:[1,0]
	v_pk_mul_f32 v[32:33], v[32:33], v[54:55] op_sel_hi:[1,0]
	v_pk_mul_f32 v[54:55], v[66:67], v[54:55] op_sel_hi:[1,0]
	v_pk_mul_f32 v[38:39], v[14:15], v[46:47]
	v_pk_mul_f32 v[36:37], v[12:13], v[44:45]
	v_pk_mul_f32 v[42:43], v[10:11], v[42:43]
	v_pk_mul_f32 v[40:41], v[8:9], v[40:41]
	v_pk_mul_f32 v[46:47], v[6:7], v[58:59]
	v_pk_mul_f32 v[44:45], v[4:5], v[52:53]
	v_pk_mul_f32 v[54:55], v[2:3], v[54:55]
	v_pk_mul_f32 v[52:53], v[0:1], v[32:33]
	global_store_dwordx4 v[48:49], v[36:39], off
	global_store_dwordx4 v[48:49], v[40:43], off offset:16
	global_store_dwordx4 v[48:49], v[44:47], off offset:512
	global_store_dwordx4 v[48:49], v[52:55], off offset:528
	global_load_dwordx4 v[36:39], v[56:57], off
	s_nop 0
	global_load_dwordx4 v[40:43], v[56:57], off offset:16
	s_waitcnt vmcnt(1)
	v_mov_b32_e32 v32, v37
	v_mov_b32_e32 v33, v38
	v_mov_b32_e32 v37, v39
	s_waitcnt vmcnt(0)
	v_mov_b32_e32 v38, v42
	v_mov_b32_e32 v39, v40
	v_mov_b32_e32 v40, v43
	v_pk_add_f32 v[32:33], v[32:33], v[36:37]
	v_pk_add_f32 v[36:37], v[38:39], v[40:41]
	v_add_f32_e32 v32, v32, v33
	v_add_f32_e32 v32, v32, v37
	v_add_f32_e32 v32, v36, v32
	v_mov_b32_e32 v33, v32
	s_nop 1
	v_permlane16_swap_b32_e32 v33, v32
	v_lshl_add_u64 v[36:37], s[6:7], 0, v[138:139]
	v_lshl_add_u64 v[36:37], v[36:37], 0, v[146:147]
	s_waitcnt lgkmcnt(0)
	v_add_f32_e32 v38, v32, v33
	ds_bpermute_b32 v39, v207, v38
	v_lshlrev_b64 v[32:33], 13, v[186:187]
	v_lshl_add_u64 v[32:33], s[92:93], 0, v[32:33]
	v_lshl_add_u64 v[40:41], v[32:33], 0, v[142:143]
	s_waitcnt lgkmcnt(0)
	v_add_f32_e32 v38, v38, v39
	v_fmamk_f32 v38, v38, 0x3a000000, v148
	v_rsq_f32_e32 v38, v38
	s_nop 0
	v_pk_mul_f32 v[28:29], v[28:29], v[38:39] op_sel_hi:[1,0]
	v_pk_mul_f32 v[30:31], v[30:31], v[38:39] op_sel_hi:[1,0]
	v_pk_mul_f32 v[24:25], v[24:25], v[38:39] op_sel_hi:[1,0]
	v_pk_mul_f32 v[26:27], v[26:27], v[38:39] op_sel_hi:[1,0]
	v_pk_mul_f32 v[32:33], v[20:21], v[38:39] op_sel_hi:[1,0]
	v_pk_mul_f32 v[42:43], v[22:23], v[38:39] op_sel_hi:[1,0]
	v_pk_mul_f32 v[16:17], v[16:17], v[38:39] op_sel_hi:[1,0]
	v_pk_mul_f32 v[34:35], v[34:35], v[38:39] op_sel_hi:[1,0]
	v_pk_mul_f32 v[22:23], v[14:15], v[30:31]
	v_pk_mul_f32 v[20:21], v[12:13], v[28:29]
	v_pk_mul_f32 v[26:27], v[10:11], v[26:27]
	v_pk_mul_f32 v[24:25], v[8:9], v[24:25]
	v_pk_mul_f32 v[30:31], v[6:7], v[42:43]
	v_pk_mul_f32 v[28:29], v[4:5], v[32:33]
	v_pk_mul_f32 v[34:35], v[2:3], v[34:35]
	v_pk_mul_f32 v[32:33], v[0:1], v[16:17]
	global_store_dwordx4 v[40:41], v[20:23], off
	global_store_dwordx4 v[40:41], v[24:27], off offset:16
	global_store_dwordx4 v[40:41], v[28:31], off offset:512
	global_store_dwordx4 v[40:41], v[32:35], off offset:528
	global_load_dwordx4 v[20:23], v[36:37], off
	s_nop 0
	global_load_dwordx4 v[24:27], v[36:37], off offset:16
	s_waitcnt vmcnt(1)
	v_mov_b32_e32 v16, v21
	v_mov_b32_e32 v17, v22
	v_mov_b32_e32 v21, v23
	s_waitcnt vmcnt(0)
	v_mov_b32_e32 v22, v26
	v_mov_b32_e32 v23, v24
	v_mov_b32_e32 v24, v27
	v_pk_add_f32 v[16:17], v[16:17], v[20:21]
	v_pk_add_f32 v[20:21], v[22:23], v[24:25]
	v_add_f32_e32 v16, v16, v17
	v_add_f32_e32 v16, v16, v21
	v_add_f32_e32 v16, v20, v16
	v_mov_b32_e32 v17, v16
	s_nop 1
	v_permlane16_swap_b32_e32 v17, v16
	v_lshlrev_b64 v[20:21], 13, v[184:185]
	v_lshl_add_u64 v[20:21], s[92:93], 0, v[20:21]
	v_lshl_add_u64 v[20:21], v[20:21], 0, v[142:143]
	s_waitcnt lgkmcnt(0)
	v_add_f32_e32 v16, v16, v17
	ds_bpermute_b32 v17, v207, v16
	s_waitcnt lgkmcnt(0)
	v_add_f32_e32 v16, v16, v17
	v_fmac_f32_e32 v148, 0x3a000000, v16
	v_rsq_f32_e32 v16, v148
	s_nop 0
	v_pk_mul_f32 v[18:19], v[18:19], v[16:17] op_sel_hi:[1,0]
	v_pk_mul_f32 v[22:23], v[82:83], v[16:17] op_sel_hi:[1,0]
	v_pk_mul_f32 v[24:25], v[50:51], v[16:17] op_sel_hi:[1,0]
	v_pk_mul_f32 v[26:27], v[132:133], v[16:17] op_sel_hi:[1,0]
	v_pk_mul_f32 v[28:29], v[134:135], v[16:17] op_sel_hi:[1,0]
	v_pk_mul_f32 v[30:31], v[136:137], v[16:17] op_sel_hi:[1,0]
	v_pk_mul_f32 v[32:33], v[128:129], v[16:17] op_sel_hi:[1,0]
	v_pk_mul_f32 v[16:17], v[130:131], v[16:17] op_sel_hi:[1,0]
	v_pk_mul_f32 v[14:15], v[14:15], v[22:23]
	v_pk_mul_f32 v[12:13], v[12:13], v[18:19]
	v_pk_mul_f32 v[10:11], v[10:11], v[26:27]
	v_pk_mul_f32 v[8:9], v[8:9], v[24:25]
	v_pk_mul_f32 v[6:7], v[6:7], v[30:31]
	v_pk_mul_f32 v[4:5], v[4:5], v[28:29]
	v_pk_mul_f32 v[2:3], v[2:3], v[16:17]
	v_pk_mul_f32 v[0:1], v[0:1], v[32:33]
	global_store_dwordx4 v[20:21], v[12:15], off
	global_store_dwordx4 v[20:21], v[8:11], off offset:16
	global_store_dwordx4 v[20:21], v[4:7], off offset:512
	global_store_dwordx4 v[20:21], v[0:3], off offset:528
